# v8 + hyena FFT pair loops (10) fully unrolled x2, iteration-2 LDS reads hoisted into renamed VGPRs, twiddle setup under read latency
# baseline (speedup 1.0000x reference)
;   const int lq2 = lq1 - 2, Q1 = 1 << lq1, Q2 = 1 << lq2; const float invM1 = 1.f / (float)(4 << lq1), invM2 = 1.f / (float)(4 << lq2);
;   for (int gg = tid; gg < NBT * (N / 16); gg += NTHR) { const int g = gg & (N / 16 - 1); float2* z = z0 + (gg / (N / 16)) * N; const int jp = g & (Q2 - 1), base = ((g >> lq2) << (lq2 + 4)) + jp; float2 x[4][4];
; #pragma unroll
;     for (int q1 = 0; q1 < 4; ++q1)
; #pragma unroll
;       for (int q2 = 0; q2 < 4; ++q2) x[q1][q2] = z[base + q1 * Q1 + q2 * Q2];
; #pragma unroll
;     for (int q2 = 0; q2 < 4; ++q2) bfly_fwd(x[0][q2], x[1][q2], x[2][q2], x[3][q2], (float)(jp + q2 * Q2) * invM1, x[0][q2], x[1][q2], x[2][q2], x[3][q2]);
; template <int LOGN> DI void filtfft_item(const Params& p, int ch, int cc, const float* kr, float2* kh) {
;     ...
;   float tot = 0.f;
; #pragma unroll
;   for (int w = 0; w < 8; ++w) tot += redbuf[w];
;   const float nrm = rsqrtf(tot + EPS) * (1.f / N), bias = p.hy_bias[ch * 256 + cc] * (1.f / N);
;   fft_fwd<LOGN, true>(z, tid);
.LBB0_1516:
	s_or_b64 exec, exec, s[0:1]
	s_add_i32 s0, 16, 0x20000
	v_mov_b32_e32 v0, s0
	v_readlane_b32 s0, v240, 48
	s_or_b32 s96, s21, s75
	s_waitcnt lgkmcnt(0)
	s_barrier
	ds_read_b128 v[6:9], v0
	v_mov_b32_e32 v0, s0
	s_lshl_b64 s[0:1], s[96:97], 2
	s_add_u32 s0, s18, s0
	s_addc_u32 s1, s19, s1
	ds_read_b128 v[2:5], v0
	global_load_dword v0, v1, s[0:1]
	s_movk_i32 s0, 0x400
	v_cmp_gt_i32_e32 vcc, s0, v10
	v_lshlrev_b32_e32 v11, 4, v10
	s_and_saveexec_b64 s[0:1], vcc
	s_cbranch_execz .LBB0_1519
	v_lshlrev_b32_e32 v72, 4, v10
	v_mov_b32_e32 v73, v10
	v_ashrrev_i32_e32 v74, 31, v73
	v_lshrrev_b32_e32 v74, 22, v74
	v_add_lshl_u32 v74, v73, v74, 7
	v_and_b32_e32 v74, 0xfffe0000, v74
	v_and_b32_e32 v75, 0x3000, v72
	v_add_u32_e32 v74, 16, v74
	v_lshlrev_b32_e32 v75, 3, v75
	v_lshlrev_b32_sdwa v76, v151, v10 dst_sel:DWORD dst_unused:UNUSED_PAD src0_sel:DWORD src1_sel:BYTE_0
	v_add3_u32 v90, v74, v75, v76
	ds_read2st64_b64 v[74:77], v90 offset1:4
	ds_read2st64_b64 v[78:81], v90 offset0:8 offset1:12
	ds_read2st64_b64 v[82:85], v90 offset0:16 offset1:20
	ds_read2st64_b64 v[86:89], v90 offset0:24 offset1:28
	ds_read2st64_b64 v[92:95], v90 offset0:32 offset1:36
	ds_read2st64_b64 v[96:99], v90 offset0:40 offset1:44
	ds_read2st64_b64 v[100:103], v90 offset0:48 offset1:52
	ds_read2st64_b64 v[104:107], v90 offset0:56 offset1:60
	v_add_u32_e32 v218, 0x200, v73
	v_add_u32_e32 v241, 0x2000, v72
	v_ashrrev_i32_e32 v252, 31, v218
	v_lshrrev_b32_e32 v252, 22, v252
	v_add_lshl_u32 v252, v218, v252, 7
	v_and_b32_e32 v252, 0xfffe0000, v252
	v_and_b32_e32 v253, 0x3000, v241
	v_add_u32_e32 v252, 16, v252
	v_lshlrev_b32_e32 v253, 3, v253
	v_lshlrev_b32_sdwa v254, v151, v10 dst_sel:DWORD dst_unused:UNUSED_PAD src0_sel:DWORD src1_sel:BYTE_0
	v_add3_u32 v219, v252, v253, v254
	ds_read2st64_b64 v[220:223], v219 offset1:4
	ds_read2st64_b64 v[224:227], v219 offset0:8 offset1:12
	ds_read2st64_b64 v[228:231], v219 offset0:16 offset1:20
	ds_read2st64_b64 v[232:235], v219 offset0:24 offset1:28
	ds_read2st64_b64 v[236:239], v219 offset0:32 offset1:36
	ds_read2st64_b64 v[244:247], v219 offset0:40 offset1:44
	ds_read2st64_b64 v[248:251], v219 offset0:48 offset1:52
	ds_read2st64_b64 v[252:255], v219 offset0:56 offset1:60
	s_movk_i32 s10, 0x100
	v_cvt_f32_ubyte0_e32 v13, v10
	v_or_b32_sdwa v15, v10, s10 dst_sel:DWORD dst_unused:UNUSED_PAD src0_sel:BYTE_0 src1_sel:DWORD
	v_mul_f32_e32 v14, 0x39800000, v13
	v_cvt_f32_u32_e32 v15, v15
	v_sin_f32_e32 v12, v14
	v_cos_f32_e32 v14, v14
	s_movk_i32 s10, 0x200
	v_mul_f32_e32 v15, 0x39800000, v15
	v_sin_f32_e32 v22, v15
	v_mul_f32_e64 v17, v14, -v12
	v_mul_f32_e32 v16, v12, v12
	v_add_f32_e32 v18, v17, v17
	v_cos_f32_e32 v24, v15
	v_or_b32_sdwa v17, v10, s10 dst_sel:DWORD dst_unused:UNUSED_PAD src0_sel:BYTE_0 src1_sel:DWORD
	v_fma_f32 v16, v14, v14, -v16
	v_cvt_f32_u32_e32 v17, v17
	v_mul_f32_e32 v15, v12, v16
	v_fma_f32 v26, v14, v18, -v15
	v_mul_f32_e32 v15, v22, v22
	v_fma_f32 v28, v24, v24, -v15
	v_mul_f32_e64 v15, v24, -v22
	v_add_f32_e32 v30, v15, v15
	v_mul_f32_e32 v15, 0x39800000, v17
	v_sin_f32_e32 v34, v15
	s_movk_i32 s10, 0x300
	v_cos_f32_e32 v36, v15
	v_or_b32_sdwa v17, v10, s10 dst_sel:DWORD dst_unused:UNUSED_PAD src0_sel:BYTE_0 src1_sel:DWORD
	v_cvt_f32_u32_e32 v17, v17
	v_mul_f32_e32 v15, v22, v28
	v_fma_f32 v38, v24, v30, -v15
	v_mul_f32_e32 v15, v34, v34
	v_fma_f32 v40, v36, v36, -v15
	v_mul_f32_e64 v15, v36, -v34
	v_add_f32_e32 v42, v15, v15
	v_mul_f32_e32 v15, 0x39800000, v17
	v_sin_f32_e32 v46, v15
	v_cos_f32_e32 v48, v15
	v_mul_f32_e32 v13, 0x3a800000, v13
	v_mul_f32_e32 v15, v34, v40
	v_sin_f32_e32 v58, v13
	v_fma_f32 v50, v36, v42, -v15
	v_mul_f32_e32 v15, v46, v46
	v_cos_f32_e32 v60, v13
	v_fma_f32 v52, v48, v48, -v15
	v_mul_f32_e64 v15, v48, -v46
	v_add_f32_e32 v54, v15, v15
	v_mul_f32_e32 v13, v46, v52
	v_fma_f32 v62, v48, v54, -v13
	v_mul_f32_e32 v13, v58, v58
	v_fma_f32 v64, v60, v60, -v13
	v_mul_f32_e64 v13, v60, -v58
	v_add_f32_e32 v66, v13, v13
	v_mul_f32_e32 v20, v12, v18
	v_mul_f32_e32 v32, v22, v30
	v_mul_f32_e32 v44, v34, v42
	v_mul_f32_e32 v56, v46, v54
	v_mul_f32_e32 v68, v58, v66
	v_mul_f32_e32 v13, v58, v64
	v_fmac_f32_e32 v20, v14, v16
	v_fmac_f32_e32 v32, v24, v28
	v_fmac_f32_e32 v44, v36, v40
	v_fmac_f32_e32 v56, v48, v52
	v_fmac_f32_e32 v68, v60, v64
	v_fma_f32 v70, v60, v66, -v13
	v_mov_b32_e32 v61, v60
	v_mov_b32_e32 v59, v58
	v_mov_b32_e32 v65, v64
	v_mov_b32_e32 v67, v66
	v_mov_b32_e32 v69, v68
	v_mov_b32_e32 v71, v70
	v_mov_b32_e32 v15, v14
	v_mov_b32_e32 v13, v12
	v_mov_b32_e32 v37, v36
	v_mov_b32_e32 v35, v34
	v_mov_b32_e32 v25, v24
	v_mov_b32_e32 v23, v22
	v_mov_b32_e32 v49, v48
	v_mov_b32_e32 v47, v46
	v_mov_b32_e32 v17, v16
	v_mov_b32_e32 v41, v40
	v_mov_b32_e32 v29, v28
	v_mov_b32_e32 v53, v52
	v_mov_b32_e32 v21, v20
	v_mov_b32_e32 v27, v26
	v_mov_b32_e32 v45, v44
	v_mov_b32_e32 v51, v50
	v_mov_b32_e32 v33, v32
	v_mov_b32_e32 v39, v38
	v_mov_b32_e32 v57, v56
	v_mov_b32_e32 v63, v62
	v_mov_b32_e32 v19, v18
	v_mov_b32_e32 v31, v30
	v_mov_b32_e32 v43, v42
	v_mov_b32_e32 v55, v54
	s_mov_b64 s[12:13], 0
	s_nop 0
	s_waitcnt lgkmcnt(11)
	v_pk_add_f32 v[108:109], v[74:75], v[92:93]
	v_pk_add_f32 v[114:115], v[76:77], v[94:95]
	s_waitcnt lgkmcnt(9)
	v_pk_add_f32 v[110:111], v[82:83], v[100:101]
	v_pk_add_f32 v[116:117], v[84:85], v[102:103]
	v_pk_add_f32 v[120:121], v[78:79], v[96:97]
	s_waitcnt lgkmcnt(8)
; DI float2 twid(float r) { return float2{__builtin_amdgcn_cosf(r), -__builtin_amdgcn_sinf(r)}; }
; DI void bfly_fwd(float2 a0, float2 a1, float2 a2, float2 a3, float r, float2& o0, float2& o1, float2& o2, float2& o3) {
;   float2 t0 = {a0.x + a2.x, a0.y + a2.y}, t1 = {a0.x - a2.x, a0.y - a2.y}, t2 = {a1.x + a3.x, a1.y + a3.y}, t3 = {a1.x - a3.x, a1.y - a3.y};
;   float2 b0 = {t0.x + t2.x, t0.y + t2.y}, b2 = {t0.x - t2.x, t0.y - t2.y}, b1 = {t1.x + t3.y, t1.y - t3.x}, b3 = {t1.x - t3.y, t1.y + t3.x};
;   float2 w1 = twid(r), w2 = cmul(w1, w1), w3 = cmul(w2, w1);
;   o0 = b0; o1 = cmul(b1, w1); o2 = cmul(b2, w2); o3 = cmul(b3, w3);
; }
;     ...
;   for (int gg = tid; gg < NBT * (N / 16); gg += NTHR) { const int g = gg & (N / 16 - 1); float2* z = z0 + (gg / (N / 16)) * N; const int jp = g & (Q2 - 1), base = ((g >> lq2) << (lq2 + 4)) + jp; float2 x[4][4];
; #pragma unroll
;     for (int q1 = 0; q1 < 4; ++q1)
; #pragma unroll
;       for (int q2 = 0; q2 < 4; ++q2) x[q1][q2] = z[base + q1 * Q1 + q2 * Q2];
; #pragma unroll
;     for (int q2 = 0; q2 < 4; ++q2) bfly_fwd(x[0][q2], x[1][q2], x[2][q2], x[3][q2], (float)(jp + q2 * Q2) * invM1, x[0][q2], x[1][q2], x[2][q2], x[3][q2]);
; #pragma unroll
;     for (int q1 = 0; q1 < 4; ++q1) bfly_fwd(x[q1][0], x[q1][1], x[q1][2], x[q1][3], (float)jp * invM2, x[q1][0], x[q1][1], x[q1][2], x[q1][3]);
; #pragma unroll
;     for (int q1 = 0; q1 < 4; ++q1)
; #pragma unroll
;       for (int q2 = 0; q2 < 4; ++q2) z[base + q1 * Q1 + q2 * Q2] = x[q1][q2]; }
	v_pk_add_f32 v[122:123], v[86:87], v[104:105]
	v_pk_add_f32 v[126:127], v[80:81], v[98:99]
	v_pk_add_f32 v[128:129], v[88:89], v[106:107]
	v_pk_add_f32 v[112:113], v[108:109], v[110:111]
	v_pk_add_f32 v[118:119], v[114:115], v[116:117]
	v_pk_add_f32 v[124:125], v[120:121], v[122:123]
	v_pk_add_f32 v[130:131], v[126:127], v[128:129]
	v_pk_add_f32 v[132:133], v[112:113], v[124:125]
	v_pk_add_f32 v[134:135], v[118:119], v[130:131]
	v_pk_add_f32 v[112:113], v[112:113], v[124:125] neg_lo:[0,1] neg_hi:[0,1]
	v_pk_add_f32 v[118:119], v[118:119], v[130:131] neg_lo:[0,1] neg_hi:[0,1]
	v_pk_add_f32 v[136:137], v[132:133], v[134:135]
	v_pk_add_f32 v[124:125], v[112:113], v[118:119] op_sel:[0,1] op_sel_hi:[1,0]
	v_pk_add_f32 v[112:113], v[112:113], v[118:119] op_sel:[0,1] op_sel_hi:[1,0] neg_lo:[0,1] neg_hi:[0,1]
	v_mov_b32_e32 v118, v124
	v_pk_mov_b32 v[130:131], v[112:113], v[124:125] op_sel:[1,0]
	v_mov_b32_e32 v119, v113
	v_pk_mul_f32 v[130:131], v[58:59], v[130:131]
	v_pk_add_f32 v[74:75], v[74:75], v[92:93] neg_lo:[0,1] neg_hi:[0,1]
	v_pk_fma_f32 v[138:139], v[60:61], v[124:125], v[130:131]
	v_pk_fma_f32 v[118:119], v[60:61], v[118:119], v[130:131] neg_lo:[0,0,1] neg_hi:[0,0,1]
	v_pk_add_f32 v[82:83], v[82:83], v[100:101] neg_lo:[0,1] neg_hi:[0,1]
	v_mov_b32_e32 v139, v119
	v_pk_add_f32 v[118:119], v[132:133], v[134:135] neg_lo:[0,1] neg_hi:[0,1]
	v_pk_add_f32 v[92:93], v[74:75], v[82:83] op_sel:[0,1] op_sel_hi:[1,0]
	v_pk_mul_f32 v[130:131], v[66:67], v[118:119]
	v_pk_add_f32 v[74:75], v[74:75], v[82:83] op_sel:[0,1] op_sel_hi:[1,0] neg_lo:[0,1] neg_hi:[0,1]
	v_pk_fma_f32 v[132:133], v[64:65], v[118:119], v[130:131] op_sel:[0,0,1] op_sel_hi:[1,1,0] neg_lo:[0,0,1] neg_hi:[0,0,1]
	v_pk_fma_f32 v[118:119], v[64:65], v[118:119], v[130:131] op_sel:[0,0,1] op_sel_hi:[1,1,0]
	v_pk_mov_b32 v[100:101], v[74:75], v[92:93] op_sel:[1,0]
	v_mov_b32_e32 v133, v119
	v_mov_b32_e32 v119, v125
	v_pk_mov_b32 v[124:125], v[124:125], v[112:113] op_sel:[1,0]
	v_mov_b32_e32 v118, v112
	v_pk_mul_f32 v[124:125], v[70:71], v[124:125]
	v_mov_b32_e32 v82, v92
	v_pk_fma_f32 v[112:113], v[68:69], v[112:113], v[124:125] neg_lo:[0,0,1] neg_hi:[0,0,1]
	v_pk_fma_f32 v[118:119], v[68:69], v[118:119], v[124:125]
	v_mov_b32_e32 v83, v75
	v_mov_b32_e32 v113, v119
	v_pk_mul_f32 v[100:101], v[12:13], v[100:101]
	ds_write2st64_b64 v90, v[132:133], v[112:113] offset0:8 offset1:12
	v_pk_fma_f32 v[112:113], v[14:15], v[92:93], v[100:101]
	v_pk_fma_f32 v[82:83], v[14:15], v[82:83], v[100:101] neg_lo:[0,0,1] neg_hi:[0,0,1]
	v_pk_add_f32 v[76:77], v[76:77], v[94:95] neg_lo:[0,1] neg_hi:[0,1]
	v_mov_b32_e32 v113, v83
	v_pk_add_f32 v[82:83], v[84:85], v[102:103] neg_lo:[0,1] neg_hi:[0,1]
	v_pk_add_f32 v[78:79], v[78:79], v[96:97] neg_lo:[0,1] neg_hi:[0,1]
	v_pk_add_f32 v[84:85], v[76:77], v[82:83] op_sel:[0,1] op_sel_hi:[1,0]
	v_pk_add_f32 v[76:77], v[76:77], v[82:83] op_sel:[0,1] op_sel_hi:[1,0] neg_lo:[0,1] neg_hi:[0,1]
	v_mov_b32_e32 v82, v84
	v_pk_mov_b32 v[94:95], v[76:77], v[84:85] op_sel:[1,0]
	v_mov_b32_e32 v83, v77
	v_pk_mul_f32 v[94:95], v[22:23], v[94:95]
	v_pk_add_f32 v[80:81], v[80:81], v[98:99] neg_lo:[0,1] neg_hi:[0,1]
	v_pk_fma_f32 v[100:101], v[24:25], v[84:85], v[94:95]
	v_pk_fma_f32 v[82:83], v[24:25], v[82:83], v[94:95] neg_lo:[0,0,1] neg_hi:[0,0,1]
	v_add_u32_e32 v72, 0x2000, v72
	v_mov_b32_e32 v101, v83
	v_pk_add_f32 v[82:83], v[86:87], v[104:105] neg_lo:[0,1] neg_hi:[0,1]
	s_nop 0
	v_pk_add_f32 v[86:87], v[78:79], v[82:83] op_sel:[0,1] op_sel_hi:[1,0]
	v_pk_add_f32 v[78:79], v[78:79], v[82:83] op_sel:[0,1] op_sel_hi:[1,0] neg_lo:[0,1] neg_hi:[0,1]
	v_mov_b32_e32 v82, v86
	v_pk_mov_b32 v[94:95], v[78:79], v[86:87] op_sel:[1,0]
	v_mov_b32_e32 v83, v79
	v_pk_mul_f32 v[94:95], v[34:35], v[94:95]
	ds_write2st64_b64 v90, v[136:137], v[138:139] offset1:4
	v_pk_fma_f32 v[96:97], v[36:37], v[86:87], v[94:95]
	v_pk_fma_f32 v[82:83], v[36:37], v[82:83], v[94:95] neg_lo:[0,0,1] neg_hi:[0,0,1]
	s_nop 0
	v_mov_b32_e32 v97, v83
	v_pk_add_f32 v[82:83], v[88:89], v[106:107] neg_lo:[0,1] neg_hi:[0,1]
	s_nop 0
	v_pk_add_f32 v[88:89], v[80:81], v[82:83] op_sel:[0,1] op_sel_hi:[1,0]
	v_pk_add_f32 v[80:81], v[80:81], v[82:83] op_sel:[0,1] op_sel_hi:[1,0] neg_lo:[0,1] neg_hi:[0,1]
	v_mov_b32_e32 v82, v88
	v_pk_mov_b32 v[94:95], v[80:81], v[88:89] op_sel:[1,0]
	v_mov_b32_e32 v83, v81
	v_pk_mul_f32 v[94:95], v[46:47], v[94:95]
	s_nop 0
	v_pk_fma_f32 v[98:99], v[48:49], v[88:89], v[94:95]
	v_pk_fma_f32 v[82:83], v[48:49], v[82:83], v[94:95] neg_lo:[0,0,1] neg_hi:[0,0,1]
	s_nop 0
	v_mov_b32_e32 v99, v83
	v_pk_add_f32 v[82:83], v[112:113], v[96:97]
	v_pk_add_f32 v[94:95], v[100:101], v[98:99]
	v_pk_add_f32 v[96:97], v[112:113], v[96:97] neg_lo:[0,1] neg_hi:[0,1]
	v_pk_add_f32 v[98:99], v[100:101], v[98:99] neg_lo:[0,1] neg_hi:[0,1]
	v_pk_add_f32 v[102:103], v[82:83], v[94:95]
	v_pk_add_f32 v[100:101], v[96:97], v[98:99] op_sel:[0,1] op_sel_hi:[1,0]
	v_pk_add_f32 v[96:97], v[96:97], v[98:99] op_sel:[0,1] op_sel_hi:[1,0] neg_lo:[0,1] neg_hi:[0,1]
	v_mov_b32_e32 v98, v100
	v_pk_mov_b32 v[104:105], v[96:97], v[100:101] op_sel:[1,0]
	v_mov_b32_e32 v99, v97
	v_pk_mul_f32 v[104:105], v[58:59], v[104:105]
	v_pk_add_f32 v[82:83], v[82:83], v[94:95] neg_lo:[0,1] neg_hi:[0,1]
	v_pk_fma_f32 v[106:107], v[60:61], v[100:101], v[104:105]
	v_pk_fma_f32 v[98:99], v[60:61], v[98:99], v[104:105] neg_lo:[0,0,1] neg_hi:[0,0,1]
	v_pk_mul_f32 v[94:95], v[66:67], v[82:83]
	v_mov_b32_e32 v107, v99
	v_pk_fma_f32 v[98:99], v[64:65], v[82:83], v[94:95] op_sel:[0,0,1] op_sel_hi:[1,1,0] neg_lo:[0,0,1] neg_hi:[0,0,1]
	v_pk_fma_f32 v[82:83], v[64:65], v[82:83], v[94:95] op_sel:[0,0,1] op_sel_hi:[1,1,0]
; DI float2 twid(float r) { return float2{__builtin_amdgcn_cosf(r), -__builtin_amdgcn_sinf(r)}; }
; DI void bfly_fwd(float2 a0, float2 a1, float2 a2, float2 a3, float r, float2& o0, float2& o1, float2& o2, float2& o3) {
;   float2 t0 = {a0.x + a2.x, a0.y + a2.y}, t1 = {a0.x - a2.x, a0.y - a2.y}, t2 = {a1.x + a3.x, a1.y + a3.y}, t3 = {a1.x - a3.x, a1.y - a3.y};
;   float2 b0 = {t0.x + t2.x, t0.y + t2.y}, b2 = {t0.x - t2.x, t0.y - t2.y}, b1 = {t1.x + t3.y, t1.y - t3.x}, b3 = {t1.x - t3.y, t1.y + t3.x};
;   float2 w1 = twid(r), w2 = cmul(w1, w1), w3 = cmul(w2, w1);
;   o0 = b0; o1 = cmul(b1, w1); o2 = cmul(b2, w2); o3 = cmul(b3, w3);
; }
;     ...
;   for (int gg = tid; gg < NBT * (N / 16); gg += NTHR) { const int g = gg & (N / 16 - 1); float2* z = z0 + (gg / (N / 16)) * N; const int jp = g & (Q2 - 1), base = ((g >> lq2) << (lq2 + 4)) + jp; float2 x[4][4];
; #pragma unroll
;     for (int q1 = 0; q1 < 4; ++q1)
; #pragma unroll
;       for (int q2 = 0; q2 < 4; ++q2) x[q1][q2] = z[base + q1 * Q1 + q2 * Q2];
; #pragma unroll
;     for (int q2 = 0; q2 < 4; ++q2) bfly_fwd(x[0][q2], x[1][q2], x[2][q2], x[3][q2], (float)(jp + q2 * Q2) * invM1, x[0][q2], x[1][q2], x[2][q2], x[3][q2]);
; #pragma unroll
;     for (int q1 = 0; q1 < 4; ++q1) bfly_fwd(x[q1][0], x[q1][1], x[q1][2], x[q1][3], (float)jp * invM2, x[q1][0], x[q1][1], x[q1][2], x[q1][3]);
; #pragma unroll
;     for (int q1 = 0; q1 < 4; ++q1)
; #pragma unroll
;       for (int q2 = 0; q2 < 4; ++q2) z[base + q1 * Q1 + q2 * Q2] = x[q1][q2]; }
	v_pk_mov_b32 v[94:95], v[100:101], v[96:97] op_sel:[1,0]
	v_mov_b32_e32 v99, v83
	v_mov_b32_e32 v82, v96
	v_mov_b32_e32 v83, v101
	v_pk_mul_f32 v[94:95], v[70:71], v[94:95]
	ds_write2st64_b64 v90, v[102:103], v[106:107] offset0:16 offset1:20
	v_pk_fma_f32 v[96:97], v[68:69], v[96:97], v[94:95] neg_lo:[0,0,1] neg_hi:[0,0,1]
	v_pk_fma_f32 v[82:83], v[68:69], v[82:83], v[94:95]
	s_nop 0
	v_mov_b32_e32 v97, v83
	v_pk_add_f32 v[82:83], v[108:109], v[110:111] neg_lo:[0,1] neg_hi:[0,1]
	ds_write2st64_b64 v90, v[98:99], v[96:97] offset0:24 offset1:28
	v_pk_mul_f32 v[94:95], v[18:19], v[82:83] op_sel:[0,1] op_sel_hi:[1,0]
	s_nop 0
	v_pk_fma_f32 v[96:97], v[16:17], v[82:83], v[94:95] neg_lo:[0,0,1] neg_hi:[0,0,1]
	v_pk_fma_f32 v[82:83], v[16:17], v[82:83], v[94:95]
	s_nop 0
	v_mov_b32_e32 v97, v83
	v_pk_add_f32 v[82:83], v[114:115], v[116:117] neg_lo:[0,1] neg_hi:[0,1]
	s_nop 0
	v_pk_mul_f32 v[94:95], v[30:31], v[82:83] op_sel:[0,1] op_sel_hi:[1,0]
	s_nop 0
	v_pk_fma_f32 v[98:99], v[28:29], v[82:83], v[94:95] neg_lo:[0,0,1] neg_hi:[0,0,1]
	v_pk_fma_f32 v[82:83], v[28:29], v[82:83], v[94:95]
	s_nop 0
	v_mov_b32_e32 v99, v83
	v_pk_add_f32 v[82:83], v[120:121], v[122:123] neg_lo:[0,1] neg_hi:[0,1]
	s_nop 0
	v_pk_mul_f32 v[94:95], v[42:43], v[82:83] op_sel:[0,1] op_sel_hi:[1,0]
	s_nop 0
	v_pk_fma_f32 v[100:101], v[40:41], v[82:83], v[94:95] neg_lo:[0,0,1] neg_hi:[0,0,1]
	v_pk_fma_f32 v[82:83], v[40:41], v[82:83], v[94:95]
	s_nop 0
	v_mov_b32_e32 v101, v83
	v_pk_add_f32 v[82:83], v[126:127], v[128:129] neg_lo:[0,1] neg_hi:[0,1]
	s_nop 0
	v_pk_mul_f32 v[94:95], v[54:55], v[82:83] op_sel:[0,1] op_sel_hi:[1,0]
	s_nop 0
	v_pk_fma_f32 v[102:103], v[52:53], v[82:83], v[94:95] neg_lo:[0,0,1] neg_hi:[0,0,1]
	v_pk_fma_f32 v[82:83], v[52:53], v[82:83], v[94:95]
	s_nop 0
	v_mov_b32_e32 v103, v83
	v_pk_add_f32 v[82:83], v[96:97], v[100:101]
	v_pk_add_f32 v[94:95], v[98:99], v[102:103]
	v_pk_add_f32 v[96:97], v[96:97], v[100:101] neg_lo:[0,1] neg_hi:[0,1]
	v_pk_add_f32 v[98:99], v[98:99], v[102:103] neg_lo:[0,1] neg_hi:[0,1]
	v_pk_add_f32 v[104:105], v[82:83], v[94:95]
	v_pk_add_f32 v[100:101], v[96:97], v[98:99] op_sel:[0,1] op_sel_hi:[1,0]
	v_pk_add_f32 v[96:97], v[96:97], v[98:99] op_sel:[0,1] op_sel_hi:[1,0] neg_lo:[0,1] neg_hi:[0,1]
	v_mov_b32_e32 v98, v100
	v_pk_mov_b32 v[102:103], v[96:97], v[100:101] op_sel:[1,0]
	v_mov_b32_e32 v99, v97
	v_pk_mul_f32 v[102:103], v[58:59], v[102:103]
	v_pk_add_f32 v[82:83], v[82:83], v[94:95] neg_lo:[0,1] neg_hi:[0,1]
	v_pk_fma_f32 v[106:107], v[60:61], v[100:101], v[102:103]
	v_pk_fma_f32 v[98:99], v[60:61], v[98:99], v[102:103] neg_lo:[0,0,1] neg_hi:[0,0,1]
	v_pk_mul_f32 v[94:95], v[66:67], v[82:83]
	v_mov_b32_e32 v107, v99
	v_pk_fma_f32 v[98:99], v[64:65], v[82:83], v[94:95] op_sel:[0,0,1] op_sel_hi:[1,1,0] neg_lo:[0,0,1] neg_hi:[0,0,1]
	v_pk_fma_f32 v[82:83], v[64:65], v[82:83], v[94:95] op_sel:[0,0,1] op_sel_hi:[1,1,0]
	v_pk_mov_b32 v[94:95], v[100:101], v[96:97] op_sel:[1,0]
	v_mov_b32_e32 v99, v83
	v_mov_b32_e32 v82, v96
	v_mov_b32_e32 v83, v101
	v_pk_mul_f32 v[94:95], v[70:71], v[94:95]
	ds_write2st64_b64 v90, v[104:105], v[106:107] offset0:32 offset1:36
	v_pk_fma_f32 v[96:97], v[68:69], v[96:97], v[94:95] neg_lo:[0,0,1] neg_hi:[0,0,1]
	v_pk_fma_f32 v[82:83], v[68:69], v[82:83], v[94:95]
	s_nop 0
	v_mov_b32_e32 v97, v83
	v_mov_b32_e32 v83, v93
	v_pk_mov_b32 v[92:93], v[92:93], v[74:75] op_sel:[1,0]
	v_mov_b32_e32 v82, v74
	v_pk_mul_f32 v[92:93], v[26:27], v[92:93]
	ds_write2st64_b64 v90, v[98:99], v[96:97] offset0:40 offset1:44
	v_pk_fma_f32 v[74:75], v[20:21], v[74:75], v[92:93] neg_lo:[0,0,1] neg_hi:[0,0,1]
	v_pk_fma_f32 v[82:83], v[20:21], v[82:83], v[92:93]
	s_nop 0
	v_mov_b32_e32 v75, v83
	v_mov_b32_e32 v83, v85
	v_pk_mov_b32 v[84:85], v[84:85], v[76:77] op_sel:[1,0]
	v_mov_b32_e32 v82, v76
	v_pk_mul_f32 v[84:85], v[38:39], v[84:85]
	s_nop 0
	v_pk_fma_f32 v[76:77], v[32:33], v[76:77], v[84:85] neg_lo:[0,0,1] neg_hi:[0,0,1]
	v_pk_fma_f32 v[82:83], v[32:33], v[82:83], v[84:85]
	v_pk_mov_b32 v[84:85], v[86:87], v[78:79] op_sel:[1,0]
	v_mov_b32_e32 v77, v83
	v_mov_b32_e32 v82, v78
	v_mov_b32_e32 v83, v87
	v_pk_mul_f32 v[84:85], v[50:51], v[84:85]
	s_nop 0
	v_pk_fma_f32 v[78:79], v[44:45], v[78:79], v[84:85] neg_lo:[0,0,1] neg_hi:[0,0,1]
	v_pk_fma_f32 v[82:83], v[44:45], v[82:83], v[84:85]
	v_pk_mov_b32 v[84:85], v[88:89], v[80:81] op_sel:[1,0]
	v_mov_b32_e32 v79, v83
	v_mov_b32_e32 v82, v80
	v_mov_b32_e32 v83, v89
	v_pk_mul_f32 v[84:85], v[62:63], v[84:85]
	s_nop 0
	v_pk_fma_f32 v[80:81], v[56:57], v[80:81], v[84:85] neg_lo:[0,0,1] neg_hi:[0,0,1]
	v_pk_fma_f32 v[82:83], v[56:57], v[82:83], v[84:85]
	s_nop 0
	v_mov_b32_e32 v81, v83
	v_pk_add_f32 v[82:83], v[74:75], v[78:79]
	v_pk_add_f32 v[84:85], v[76:77], v[80:81]
	v_pk_add_f32 v[74:75], v[74:75], v[78:79] neg_lo:[0,1] neg_hi:[0,1]
	v_pk_add_f32 v[76:77], v[76:77], v[80:81] neg_lo:[0,1] neg_hi:[0,1]
	v_pk_add_f32 v[86:87], v[82:83], v[84:85]
	v_pk_add_f32 v[78:79], v[74:75], v[76:77] op_sel:[0,1] op_sel_hi:[1,0]
	v_pk_add_f32 v[74:75], v[74:75], v[76:77] op_sel:[0,1] op_sel_hi:[1,0] neg_lo:[0,1] neg_hi:[0,1]
	v_mov_b32_e32 v76, v78
	v_pk_mov_b32 v[80:81], v[74:75], v[78:79] op_sel:[1,0]
	v_mov_b32_e32 v77, v75
	v_pk_mul_f32 v[80:81], v[58:59], v[80:81]
	s_nop 0
	v_pk_fma_f32 v[88:89], v[60:61], v[78:79], v[80:81]
	v_pk_fma_f32 v[76:77], v[60:61], v[76:77], v[80:81] neg_lo:[0,0,1] neg_hi:[0,0,1]
	s_nop 0
	v_mov_b32_e32 v89, v77
	v_pk_add_f32 v[76:77], v[82:83], v[84:85] neg_lo:[0,1] neg_hi:[0,1]
	ds_write2st64_b64 v90, v[86:87], v[88:89] offset0:48 offset1:52
	v_pk_mul_f32 v[80:81], v[66:67], v[76:77]
	s_nop 0
	v_pk_fma_f32 v[82:83], v[64:65], v[76:77], v[80:81] op_sel:[0,0,1] op_sel_hi:[1,1,0] neg_lo:[0,0,1] neg_hi:[0,0,1]
	v_pk_fma_f32 v[76:77], v[64:65], v[76:77], v[80:81] op_sel:[0,0,1] op_sel_hi:[1,1,0]
	s_nop 0
	v_mov_b32_e32 v83, v77
	v_mov_b32_e32 v77, v79
	v_pk_mov_b32 v[78:79], v[78:79], v[74:75] op_sel:[1,0]
	v_mov_b32_e32 v76, v74
	v_pk_mul_f32 v[78:79], v[70:71], v[78:79]
	s_nop 0
	v_pk_fma_f32 v[74:75], v[68:69], v[74:75], v[78:79] neg_lo:[0,0,1] neg_hi:[0,0,1]
	v_pk_fma_f32 v[76:77], v[68:69], v[76:77], v[78:79]
	s_nop 0
	v_mov_b32_e32 v75, v77
	ds_write2st64_b64 v90, v[82:83], v[74:75] offset0:56 offset1:60
	s_nop 0
	v_add_u32_e32 v73, 0x200, v73
	s_nop 0
	s_waitcnt lgkmcnt(11)
; DI float2 twid(float r) { return float2{__builtin_amdgcn_cosf(r), -__builtin_amdgcn_sinf(r)}; }
; DI void bfly_fwd(float2 a0, float2 a1, float2 a2, float2 a3, float r, float2& o0, float2& o1, float2& o2, float2& o3) {
;   float2 t0 = {a0.x + a2.x, a0.y + a2.y}, t1 = {a0.x - a2.x, a0.y - a2.y}, t2 = {a1.x + a3.x, a1.y + a3.y}, t3 = {a1.x - a3.x, a1.y - a3.y};
;   float2 b0 = {t0.x + t2.x, t0.y + t2.y}, b2 = {t0.x - t2.x, t0.y - t2.y}, b1 = {t1.x + t3.y, t1.y - t3.x}, b3 = {t1.x - t3.y, t1.y + t3.x};
;   float2 w1 = twid(r), w2 = cmul(w1, w1), w3 = cmul(w2, w1);
;   o0 = b0; o1 = cmul(b1, w1); o2 = cmul(b2, w2); o3 = cmul(b3, w3);
; }
;     ...
;   for (int gg = tid; gg < NBT * (N / 16); gg += NTHR) { const int g = gg & (N / 16 - 1); float2* z = z0 + (gg / (N / 16)) * N; const int jp = g & (Q2 - 1), base = ((g >> lq2) << (lq2 + 4)) + jp; float2 x[4][4];
; #pragma unroll
;     for (int q1 = 0; q1 < 4; ++q1)
; #pragma unroll
;       for (int q2 = 0; q2 < 4; ++q2) x[q1][q2] = z[base + q1 * Q1 + q2 * Q2];
; #pragma unroll
;     for (int q2 = 0; q2 < 4; ++q2) bfly_fwd(x[0][q2], x[1][q2], x[2][q2], x[3][q2], (float)(jp + q2 * Q2) * invM1, x[0][q2], x[1][q2], x[2][q2], x[3][q2]);
; #pragma unroll
;     for (int q1 = 0; q1 < 4; ++q1) bfly_fwd(x[q1][0], x[q1][1], x[q1][2], x[q1][3], (float)jp * invM2, x[q1][0], x[q1][1], x[q1][2], x[q1][3]);
; #pragma unroll
;     for (int q1 = 0; q1 < 4; ++q1)
; #pragma unroll
;       for (int q2 = 0; q2 < 4; ++q2) z[base + q1 * Q1 + q2 * Q2] = x[q1][q2]; }
	v_pk_add_f32 v[108:109], v[220:221], v[236:237]
	v_pk_add_f32 v[114:115], v[222:223], v[238:239]
	s_waitcnt lgkmcnt(9)
	v_pk_add_f32 v[110:111], v[228:229], v[248:249]
	v_pk_add_f32 v[116:117], v[230:231], v[250:251]
	v_pk_add_f32 v[120:121], v[224:225], v[244:245]
	s_waitcnt lgkmcnt(8)
	v_pk_add_f32 v[122:123], v[232:233], v[252:253]
	v_pk_add_f32 v[126:127], v[226:227], v[246:247]
	v_pk_add_f32 v[128:129], v[234:235], v[254:255]
	v_pk_add_f32 v[112:113], v[108:109], v[110:111]
	v_pk_add_f32 v[118:119], v[114:115], v[116:117]
	v_pk_add_f32 v[124:125], v[120:121], v[122:123]
	v_pk_add_f32 v[130:131], v[126:127], v[128:129]
	v_pk_add_f32 v[132:133], v[112:113], v[124:125]
	v_pk_add_f32 v[134:135], v[118:119], v[130:131]
	v_pk_add_f32 v[112:113], v[112:113], v[124:125] neg_lo:[0,1] neg_hi:[0,1]
	v_pk_add_f32 v[118:119], v[118:119], v[130:131] neg_lo:[0,1] neg_hi:[0,1]
	v_pk_add_f32 v[136:137], v[132:133], v[134:135]
	v_pk_add_f32 v[124:125], v[112:113], v[118:119] op_sel:[0,1] op_sel_hi:[1,0]
	v_pk_add_f32 v[112:113], v[112:113], v[118:119] op_sel:[0,1] op_sel_hi:[1,0] neg_lo:[0,1] neg_hi:[0,1]
	v_mov_b32_e32 v118, v124
	v_pk_mov_b32 v[130:131], v[112:113], v[124:125] op_sel:[1,0]
	v_mov_b32_e32 v119, v113
	v_pk_mul_f32 v[130:131], v[58:59], v[130:131]
	v_pk_add_f32 v[220:221], v[220:221], v[236:237] neg_lo:[0,1] neg_hi:[0,1]
	v_pk_fma_f32 v[138:139], v[60:61], v[124:125], v[130:131]
	v_pk_fma_f32 v[118:119], v[60:61], v[118:119], v[130:131] neg_lo:[0,0,1] neg_hi:[0,0,1]
	v_pk_add_f32 v[228:229], v[228:229], v[248:249] neg_lo:[0,1] neg_hi:[0,1]
	v_mov_b32_e32 v139, v119
	v_pk_add_f32 v[118:119], v[132:133], v[134:135] neg_lo:[0,1] neg_hi:[0,1]
	v_pk_add_f32 v[236:237], v[220:221], v[228:229] op_sel:[0,1] op_sel_hi:[1,0]
	v_pk_mul_f32 v[130:131], v[66:67], v[118:119]
	v_pk_add_f32 v[220:221], v[220:221], v[228:229] op_sel:[0,1] op_sel_hi:[1,0] neg_lo:[0,1] neg_hi:[0,1]
	v_pk_fma_f32 v[132:133], v[64:65], v[118:119], v[130:131] op_sel:[0,0,1] op_sel_hi:[1,1,0] neg_lo:[0,0,1] neg_hi:[0,0,1]
	v_pk_fma_f32 v[118:119], v[64:65], v[118:119], v[130:131] op_sel:[0,0,1] op_sel_hi:[1,1,0]
	v_pk_mov_b32 v[248:249], v[220:221], v[236:237] op_sel:[1,0]
	v_mov_b32_e32 v133, v119
	v_mov_b32_e32 v119, v125
	v_pk_mov_b32 v[124:125], v[124:125], v[112:113] op_sel:[1,0]
	v_mov_b32_e32 v118, v112
	v_pk_mul_f32 v[124:125], v[70:71], v[124:125]
	v_mov_b32_e32 v228, v236
	v_pk_fma_f32 v[112:113], v[68:69], v[112:113], v[124:125] neg_lo:[0,0,1] neg_hi:[0,0,1]
	v_pk_fma_f32 v[118:119], v[68:69], v[118:119], v[124:125]
	v_mov_b32_e32 v229, v221
	v_mov_b32_e32 v113, v119
	v_pk_mul_f32 v[248:249], v[12:13], v[248:249]
	ds_write2st64_b64 v219, v[132:133], v[112:113] offset0:8 offset1:12
	v_pk_fma_f32 v[112:113], v[14:15], v[236:237], v[248:249]
	v_pk_fma_f32 v[228:229], v[14:15], v[228:229], v[248:249] neg_lo:[0,0,1] neg_hi:[0,0,1]
	v_pk_add_f32 v[222:223], v[222:223], v[238:239] neg_lo:[0,1] neg_hi:[0,1]
	v_mov_b32_e32 v113, v229
	v_pk_add_f32 v[228:229], v[230:231], v[250:251] neg_lo:[0,1] neg_hi:[0,1]
	v_pk_add_f32 v[224:225], v[224:225], v[244:245] neg_lo:[0,1] neg_hi:[0,1]
	v_pk_add_f32 v[230:231], v[222:223], v[228:229] op_sel:[0,1] op_sel_hi:[1,0]
	v_pk_add_f32 v[222:223], v[222:223], v[228:229] op_sel:[0,1] op_sel_hi:[1,0] neg_lo:[0,1] neg_hi:[0,1]
	v_mov_b32_e32 v228, v230
	v_pk_mov_b32 v[238:239], v[222:223], v[230:231] op_sel:[1,0]
	v_mov_b32_e32 v229, v223
	v_pk_mul_f32 v[238:239], v[22:23], v[238:239]
	v_pk_add_f32 v[226:227], v[226:227], v[246:247] neg_lo:[0,1] neg_hi:[0,1]
	v_pk_fma_f32 v[248:249], v[24:25], v[230:231], v[238:239]
	v_pk_fma_f32 v[228:229], v[24:25], v[228:229], v[238:239] neg_lo:[0,0,1] neg_hi:[0,0,1]
	v_add_u32_e32 v72, 0x2000, v72
	v_mov_b32_e32 v249, v229
	v_pk_add_f32 v[228:229], v[232:233], v[252:253] neg_lo:[0,1] neg_hi:[0,1]
	s_nop 0
	v_pk_add_f32 v[232:233], v[224:225], v[228:229] op_sel:[0,1] op_sel_hi:[1,0]
	v_pk_add_f32 v[224:225], v[224:225], v[228:229] op_sel:[0,1] op_sel_hi:[1,0] neg_lo:[0,1] neg_hi:[0,1]
	v_mov_b32_e32 v228, v232
	v_pk_mov_b32 v[238:239], v[224:225], v[232:233] op_sel:[1,0]
	v_mov_b32_e32 v229, v225
	v_pk_mul_f32 v[238:239], v[34:35], v[238:239]
	ds_write2st64_b64 v219, v[136:137], v[138:139] offset1:4
	v_pk_fma_f32 v[244:245], v[36:37], v[232:233], v[238:239]
	v_pk_fma_f32 v[228:229], v[36:37], v[228:229], v[238:239] neg_lo:[0,0,1] neg_hi:[0,0,1]
	s_nop 0
	v_mov_b32_e32 v245, v229
	v_pk_add_f32 v[228:229], v[234:235], v[254:255] neg_lo:[0,1] neg_hi:[0,1]
	s_nop 0
	v_pk_add_f32 v[234:235], v[226:227], v[228:229] op_sel:[0,1] op_sel_hi:[1,0]
	v_pk_add_f32 v[226:227], v[226:227], v[228:229] op_sel:[0,1] op_sel_hi:[1,0] neg_lo:[0,1] neg_hi:[0,1]
	v_mov_b32_e32 v228, v234
	v_pk_mov_b32 v[238:239], v[226:227], v[234:235] op_sel:[1,0]
	v_mov_b32_e32 v229, v227
	v_pk_mul_f32 v[238:239], v[46:47], v[238:239]
	s_nop 0
	v_pk_fma_f32 v[246:247], v[48:49], v[234:235], v[238:239]
	v_pk_fma_f32 v[228:229], v[48:49], v[228:229], v[238:239] neg_lo:[0,0,1] neg_hi:[0,0,1]
	s_nop 0
	v_mov_b32_e32 v247, v229
	v_pk_add_f32 v[228:229], v[112:113], v[244:245]
	v_pk_add_f32 v[238:239], v[248:249], v[246:247]
	v_pk_add_f32 v[244:245], v[112:113], v[244:245] neg_lo:[0,1] neg_hi:[0,1]
	v_pk_add_f32 v[246:247], v[248:249], v[246:247] neg_lo:[0,1] neg_hi:[0,1]
	v_pk_add_f32 v[250:251], v[228:229], v[238:239]
	v_pk_add_f32 v[248:249], v[244:245], v[246:247] op_sel:[0,1] op_sel_hi:[1,0]
	v_pk_add_f32 v[244:245], v[244:245], v[246:247] op_sel:[0,1] op_sel_hi:[1,0] neg_lo:[0,1] neg_hi:[0,1]
	v_mov_b32_e32 v246, v248
	v_pk_mov_b32 v[252:253], v[244:245], v[248:249] op_sel:[1,0]
	v_mov_b32_e32 v247, v245
	v_pk_mul_f32 v[252:253], v[58:59], v[252:253]
; DI float2 twid(float r) { return float2{__builtin_amdgcn_cosf(r), -__builtin_amdgcn_sinf(r)}; }
; DI void bfly_fwd(float2 a0, float2 a1, float2 a2, float2 a3, float r, float2& o0, float2& o1, float2& o2, float2& o3) {
;   float2 t0 = {a0.x + a2.x, a0.y + a2.y}, t1 = {a0.x - a2.x, a0.y - a2.y}, t2 = {a1.x + a3.x, a1.y + a3.y}, t3 = {a1.x - a3.x, a1.y - a3.y};
;   float2 b0 = {t0.x + t2.x, t0.y + t2.y}, b2 = {t0.x - t2.x, t0.y - t2.y}, b1 = {t1.x + t3.y, t1.y - t3.x}, b3 = {t1.x - t3.y, t1.y + t3.x};
;   float2 w1 = twid(r), w2 = cmul(w1, w1), w3 = cmul(w2, w1);
;   o0 = b0; o1 = cmul(b1, w1); o2 = cmul(b2, w2); o3 = cmul(b3, w3);
; }
;     ...
;   for (int gg = tid; gg < NBT * (N / 16); gg += NTHR) { const int g = gg & (N / 16 - 1); float2* z = z0 + (gg / (N / 16)) * N; const int jp = g & (Q2 - 1), base = ((g >> lq2) << (lq2 + 4)) + jp; float2 x[4][4];
; #pragma unroll
;     for (int q1 = 0; q1 < 4; ++q1)
; #pragma unroll
;       for (int q2 = 0; q2 < 4; ++q2) x[q1][q2] = z[base + q1 * Q1 + q2 * Q2];
; #pragma unroll
;     for (int q2 = 0; q2 < 4; ++q2) bfly_fwd(x[0][q2], x[1][q2], x[2][q2], x[3][q2], (float)(jp + q2 * Q2) * invM1, x[0][q2], x[1][q2], x[2][q2], x[3][q2]);
; #pragma unroll
;     for (int q1 = 0; q1 < 4; ++q1) bfly_fwd(x[q1][0], x[q1][1], x[q1][2], x[q1][3], (float)jp * invM2, x[q1][0], x[q1][1], x[q1][2], x[q1][3]);
; #pragma unroll
;     for (int q1 = 0; q1 < 4; ++q1)
; #pragma unroll
;       for (int q2 = 0; q2 < 4; ++q2) z[base + q1 * Q1 + q2 * Q2] = x[q1][q2]; }
	v_pk_add_f32 v[228:229], v[228:229], v[238:239] neg_lo:[0,1] neg_hi:[0,1]
	v_pk_fma_f32 v[254:255], v[60:61], v[248:249], v[252:253]
	v_pk_fma_f32 v[246:247], v[60:61], v[246:247], v[252:253] neg_lo:[0,0,1] neg_hi:[0,0,1]
	v_pk_mul_f32 v[238:239], v[66:67], v[228:229]
	v_mov_b32_e32 v255, v247
	v_pk_fma_f32 v[246:247], v[64:65], v[228:229], v[238:239] op_sel:[0,0,1] op_sel_hi:[1,1,0] neg_lo:[0,0,1] neg_hi:[0,0,1]
	v_pk_fma_f32 v[228:229], v[64:65], v[228:229], v[238:239] op_sel:[0,0,1] op_sel_hi:[1,1,0]
	v_pk_mov_b32 v[238:239], v[248:249], v[244:245] op_sel:[1,0]
	v_mov_b32_e32 v247, v229
	v_mov_b32_e32 v228, v244
	v_mov_b32_e32 v229, v249
	v_pk_mul_f32 v[238:239], v[70:71], v[238:239]
	ds_write2st64_b64 v219, v[250:251], v[254:255] offset0:16 offset1:20
	v_pk_fma_f32 v[244:245], v[68:69], v[244:245], v[238:239] neg_lo:[0,0,1] neg_hi:[0,0,1]
	v_pk_fma_f32 v[228:229], v[68:69], v[228:229], v[238:239]
	s_nop 0
	v_mov_b32_e32 v245, v229
	v_pk_add_f32 v[228:229], v[108:109], v[110:111] neg_lo:[0,1] neg_hi:[0,1]
	ds_write2st64_b64 v219, v[246:247], v[244:245] offset0:24 offset1:28
	v_pk_mul_f32 v[238:239], v[18:19], v[228:229] op_sel:[0,1] op_sel_hi:[1,0]
	s_nop 0
	v_pk_fma_f32 v[244:245], v[16:17], v[228:229], v[238:239] neg_lo:[0,0,1] neg_hi:[0,0,1]
	v_pk_fma_f32 v[228:229], v[16:17], v[228:229], v[238:239]
	s_nop 0
	v_mov_b32_e32 v245, v229
	v_pk_add_f32 v[228:229], v[114:115], v[116:117] neg_lo:[0,1] neg_hi:[0,1]
	s_nop 0
	v_pk_mul_f32 v[238:239], v[30:31], v[228:229] op_sel:[0,1] op_sel_hi:[1,0]
	s_nop 0
	v_pk_fma_f32 v[246:247], v[28:29], v[228:229], v[238:239] neg_lo:[0,0,1] neg_hi:[0,0,1]
	v_pk_fma_f32 v[228:229], v[28:29], v[228:229], v[238:239]
	s_nop 0
	v_mov_b32_e32 v247, v229
	v_pk_add_f32 v[228:229], v[120:121], v[122:123] neg_lo:[0,1] neg_hi:[0,1]
	s_nop 0
	v_pk_mul_f32 v[238:239], v[42:43], v[228:229] op_sel:[0,1] op_sel_hi:[1,0]
	s_nop 0
	v_pk_fma_f32 v[248:249], v[40:41], v[228:229], v[238:239] neg_lo:[0,0,1] neg_hi:[0,0,1]
	v_pk_fma_f32 v[228:229], v[40:41], v[228:229], v[238:239]
	s_nop 0
	v_mov_b32_e32 v249, v229
	v_pk_add_f32 v[228:229], v[126:127], v[128:129] neg_lo:[0,1] neg_hi:[0,1]
	s_nop 0
	v_pk_mul_f32 v[238:239], v[54:55], v[228:229] op_sel:[0,1] op_sel_hi:[1,0]
	s_nop 0
	v_pk_fma_f32 v[250:251], v[52:53], v[228:229], v[238:239] neg_lo:[0,0,1] neg_hi:[0,0,1]
	v_pk_fma_f32 v[228:229], v[52:53], v[228:229], v[238:239]
	s_nop 0
	v_mov_b32_e32 v251, v229
	v_pk_add_f32 v[228:229], v[244:245], v[248:249]
	v_pk_add_f32 v[238:239], v[246:247], v[250:251]
	v_pk_add_f32 v[244:245], v[244:245], v[248:249] neg_lo:[0,1] neg_hi:[0,1]
	v_pk_add_f32 v[246:247], v[246:247], v[250:251] neg_lo:[0,1] neg_hi:[0,1]
	v_pk_add_f32 v[252:253], v[228:229], v[238:239]
	v_pk_add_f32 v[248:249], v[244:245], v[246:247] op_sel:[0,1] op_sel_hi:[1,0]
	v_pk_add_f32 v[244:245], v[244:245], v[246:247] op_sel:[0,1] op_sel_hi:[1,0] neg_lo:[0,1] neg_hi:[0,1]
	v_mov_b32_e32 v246, v248
	v_pk_mov_b32 v[250:251], v[244:245], v[248:249] op_sel:[1,0]
	v_mov_b32_e32 v247, v245
	v_pk_mul_f32 v[250:251], v[58:59], v[250:251]
	v_pk_add_f32 v[228:229], v[228:229], v[238:239] neg_lo:[0,1] neg_hi:[0,1]
	v_pk_fma_f32 v[254:255], v[60:61], v[248:249], v[250:251]
	v_pk_fma_f32 v[246:247], v[60:61], v[246:247], v[250:251] neg_lo:[0,0,1] neg_hi:[0,0,1]
	v_pk_mul_f32 v[238:239], v[66:67], v[228:229]
	v_mov_b32_e32 v255, v247
	v_pk_fma_f32 v[246:247], v[64:65], v[228:229], v[238:239] op_sel:[0,0,1] op_sel_hi:[1,1,0] neg_lo:[0,0,1] neg_hi:[0,0,1]
	v_pk_fma_f32 v[228:229], v[64:65], v[228:229], v[238:239] op_sel:[0,0,1] op_sel_hi:[1,1,0]
	v_pk_mov_b32 v[238:239], v[248:249], v[244:245] op_sel:[1,0]
	v_mov_b32_e32 v247, v229
	v_mov_b32_e32 v228, v244
	v_mov_b32_e32 v229, v249
	v_pk_mul_f32 v[238:239], v[70:71], v[238:239]
	ds_write2st64_b64 v219, v[252:253], v[254:255] offset0:32 offset1:36
	v_pk_fma_f32 v[244:245], v[68:69], v[244:245], v[238:239] neg_lo:[0,0,1] neg_hi:[0,0,1]
	v_pk_fma_f32 v[228:229], v[68:69], v[228:229], v[238:239]
	s_nop 0
	v_mov_b32_e32 v245, v229
	v_mov_b32_e32 v229, v237
	v_pk_mov_b32 v[236:237], v[236:237], v[220:221] op_sel:[1,0]
	v_mov_b32_e32 v228, v220
	v_pk_mul_f32 v[236:237], v[26:27], v[236:237]
	ds_write2st64_b64 v219, v[246:247], v[244:245] offset0:40 offset1:44
	v_pk_fma_f32 v[220:221], v[20:21], v[220:221], v[236:237] neg_lo:[0,0,1] neg_hi:[0,0,1]
	v_pk_fma_f32 v[228:229], v[20:21], v[228:229], v[236:237]
	s_nop 0
	v_mov_b32_e32 v221, v229
	v_mov_b32_e32 v229, v231
	v_pk_mov_b32 v[230:231], v[230:231], v[222:223] op_sel:[1,0]
	v_mov_b32_e32 v228, v222
	v_pk_mul_f32 v[230:231], v[38:39], v[230:231]
	s_nop 0
	v_pk_fma_f32 v[222:223], v[32:33], v[222:223], v[230:231] neg_lo:[0,0,1] neg_hi:[0,0,1]
	v_pk_fma_f32 v[228:229], v[32:33], v[228:229], v[230:231]
	v_pk_mov_b32 v[230:231], v[232:233], v[224:225] op_sel:[1,0]
	v_mov_b32_e32 v223, v229
	v_mov_b32_e32 v228, v224
	v_mov_b32_e32 v229, v233
	v_pk_mul_f32 v[230:231], v[50:51], v[230:231]
	s_nop 0
	v_pk_fma_f32 v[224:225], v[44:45], v[224:225], v[230:231] neg_lo:[0,0,1] neg_hi:[0,0,1]
	v_pk_fma_f32 v[228:229], v[44:45], v[228:229], v[230:231]
	v_pk_mov_b32 v[230:231], v[234:235], v[226:227] op_sel:[1,0]
	v_mov_b32_e32 v225, v229
	v_mov_b32_e32 v228, v226
	v_mov_b32_e32 v229, v235
	v_pk_mul_f32 v[230:231], v[62:63], v[230:231]
	s_nop 0
	v_pk_fma_f32 v[226:227], v[56:57], v[226:227], v[230:231] neg_lo:[0,0,1] neg_hi:[0,0,1]
	v_pk_fma_f32 v[228:229], v[56:57], v[228:229], v[230:231]
	s_nop 0
	v_mov_b32_e32 v227, v229
	v_pk_add_f32 v[228:229], v[220:221], v[224:225]
	v_pk_add_f32 v[230:231], v[222:223], v[226:227]
	v_pk_add_f32 v[220:221], v[220:221], v[224:225] neg_lo:[0,1] neg_hi:[0,1]
;   const int lq2 = lq1 - 2, Q1 = 1 << lq1, Q2 = 1 << lq2; const float invM1 = 1.f / (float)(4 << lq1), invM2 = 1.f / (float)(4 << lq2);
;   for (int gg = tid; gg < NBT * (N / 16); gg += NTHR) { const int g = gg & (N / 16 - 1); float2* z = z0 + (gg / (N / 16)) * N; const int jp = g & (Q2 - 1), base = ((g >> lq2) << (lq2 + 4)) + jp; float2 x[4][4];
; #pragma unroll
;     for (int q1 = 0; q1 < 4; ++q1)
; #pragma unroll
;       for (int q2 = 0; q2 < 4; ++q2) x[q1][q2] = z[base + q1 * Q1 + q2 * Q2];
; #pragma unroll
;     for (int q2 = 0; q2 < 4; ++q2) bfly_fwd(x[0][q2], x[1][q2], x[2][q2], x[3][q2], (float)(jp + q2 * Q2) * invM1, x[0][q2], x[1][q2], x[2][q2], x[3][q2]);
; #pragma unroll
;     for (int q1 = 0; q1 < 4; ++q1) bfly_fwd(x[q1][0], x[q1][1], x[q1][2], x[q1][3], (float)jp * invM2, x[q1][0], x[q1][1], x[q1][2], x[q1][3]);
; #pragma unroll
;     for (int q1 = 0; q1 < 4; ++q1)
; #pragma unroll
;       for (int q2 = 0; q2 < 4; ++q2) z[base + q1 * Q1 + q2 * Q2] = x[q1][q2]; }
; template <int LOGN, bool R2DONE = false> DI void fft_fwd(float2* z, int tid) {
;     ...
;     fft_pair_fwd<N>(z, tid, 10); fft_pair_fwd<N>(z, tid, 6); fft_level_fwd<N>(z, tid, 2); fft_level_fwd<N>(z, tid, 0);
	v_pk_add_f32 v[222:223], v[222:223], v[226:227] neg_lo:[0,1] neg_hi:[0,1]
	v_pk_add_f32 v[232:233], v[228:229], v[230:231]
	v_pk_add_f32 v[224:225], v[220:221], v[222:223] op_sel:[0,1] op_sel_hi:[1,0]
	v_pk_add_f32 v[220:221], v[220:221], v[222:223] op_sel:[0,1] op_sel_hi:[1,0] neg_lo:[0,1] neg_hi:[0,1]
	v_mov_b32_e32 v222, v224
	v_pk_mov_b32 v[226:227], v[220:221], v[224:225] op_sel:[1,0]
	v_mov_b32_e32 v223, v221
	v_pk_mul_f32 v[226:227], v[58:59], v[226:227]
	s_nop 0
	v_pk_fma_f32 v[234:235], v[60:61], v[224:225], v[226:227]
	v_pk_fma_f32 v[222:223], v[60:61], v[222:223], v[226:227] neg_lo:[0,0,1] neg_hi:[0,0,1]
	s_nop 0
	v_mov_b32_e32 v235, v223
	v_pk_add_f32 v[222:223], v[228:229], v[230:231] neg_lo:[0,1] neg_hi:[0,1]
	ds_write2st64_b64 v219, v[232:233], v[234:235] offset0:48 offset1:52
	v_pk_mul_f32 v[226:227], v[66:67], v[222:223]
	s_nop 0
	v_pk_fma_f32 v[228:229], v[64:65], v[222:223], v[226:227] op_sel:[0,0,1] op_sel_hi:[1,1,0] neg_lo:[0,0,1] neg_hi:[0,0,1]
	v_pk_fma_f32 v[222:223], v[64:65], v[222:223], v[226:227] op_sel:[0,0,1] op_sel_hi:[1,1,0]
	s_nop 0
	v_mov_b32_e32 v229, v223
	v_mov_b32_e32 v223, v225
	v_pk_mov_b32 v[224:225], v[224:225], v[220:221] op_sel:[1,0]
	v_mov_b32_e32 v222, v220
	v_pk_mul_f32 v[224:225], v[70:71], v[224:225]
	s_nop 0
	v_pk_fma_f32 v[220:221], v[68:69], v[220:221], v[224:225] neg_lo:[0,0,1] neg_hi:[0,0,1]
	v_pk_fma_f32 v[222:223], v[68:69], v[222:223], v[224:225]
	s_nop 0
	v_mov_b32_e32 v221, v223
	ds_write2st64_b64 v219, v[228:229], v[220:221] offset0:56 offset1:60
	s_nop 0
	v_add_u32_e32 v74, 0x200, v73
	s_nop 0
	v_mov_b32_e32 v73, v74
.LBB0_1519:
	s_or_b64 exec, exec, s[0:1]
	s_waitcnt lgkmcnt(0)
	s_barrier
	s_and_saveexec_b64 s[0:1], vcc
	s_cbranch_execz .LBB0_1522
	v_and_b32_e32 v72, 15, v10
	v_mov_b32_e32 v73, v10
	v_ashrrev_i32_e32 v74, 31, v73
	v_lshrrev_b32_e32 v74, 22, v74
	v_add_lshl_u32 v74, v73, v74, 7
	v_and_b32_e32 v74, 0xfffe0000, v74
	v_and_b32_e32 v75, 0x3f00, v11
	v_add_u32_e32 v74, 16, v74
	v_lshlrev_b32_e32 v75, 3, v75
	v_lshlrev_b32_e32 v76, 3, v72
	v_add3_u32 v90, v74, v75, v76
	ds_read2_b64 v[74:77], v90 offset1:16
	ds_read2_b64 v[78:81], v90 offset0:32 offset1:48
	ds_read2_b64 v[82:85], v90 offset0:64 offset1:80
	ds_read2_b64 v[86:89], v90 offset0:96 offset1:112
	ds_read2_b64 v[92:95], v90 offset0:128 offset1:144
	ds_read2_b64 v[96:99], v90 offset0:160 offset1:176
	ds_read2_b64 v[100:103], v90 offset0:192 offset1:208
	ds_read2_b64 v[104:107], v90 offset0:224 offset1:240
	v_add_u32_e32 v218, 0x200, v73
	v_add_u32_e32 v241, 0x2000, v11
	v_ashrrev_i32_e32 v252, 31, v218
	v_lshrrev_b32_e32 v252, 22, v252
	v_add_lshl_u32 v252, v218, v252, 7
	v_and_b32_e32 v252, 0xfffe0000, v252
	v_and_b32_e32 v253, 0x3f00, v241
	v_add_u32_e32 v252, 16, v252
	v_lshlrev_b32_e32 v253, 3, v253
	v_lshlrev_b32_e32 v254, 3, v72
	v_add3_u32 v219, v252, v253, v254
	ds_read2_b64 v[220:223], v219 offset1:16
	ds_read2_b64 v[224:227], v219 offset0:32 offset1:48
	ds_read2_b64 v[228:231], v219 offset0:64 offset1:80
	ds_read2_b64 v[232:235], v219 offset0:96 offset1:112
	ds_read2_b64 v[236:239], v219 offset0:128 offset1:144
	ds_read2_b64 v[244:247], v219 offset0:160 offset1:176
	ds_read2_b64 v[248:251], v219 offset0:192 offset1:208
	ds_read2_b64 v[252:255], v219 offset0:224 offset1:240
	v_cvt_f32_ubyte0_e32 v13, v72
	v_mul_f32_e32 v14, 0x3b800000, v13
	v_sin_f32_e32 v12, v14
	v_cos_f32_e32 v14, v14
	v_mul_f32_e32 v13, 0x3c800000, v13
	v_sin_f32_e32 v58, v13
	v_mul_f32_e32 v15, v12, v12
	v_fma_f32 v16, v14, v14, -v15
	v_or_b32_e32 v15, 16, v72
	v_cvt_f32_ubyte0_e32 v15, v15
	v_mul_f32_e32 v15, 0x3b800000, v15
	v_sin_f32_e32 v22, v15
	v_cos_f32_e32 v24, v15
	v_mul_f32_e64 v17, v14, -v12
	v_add_f32_e32 v18, v17, v17
	v_mul_f32_e32 v15, v12, v16
	v_fma_f32 v26, v14, v18, -v15
	v_mul_f32_e32 v15, v22, v22
	v_fma_f32 v28, v24, v24, -v15
	v_mul_f32_e64 v15, v24, -v22
	v_add_f32_e32 v30, v15, v15
	v_or_b32_e32 v15, 32, v72
	v_cvt_f32_ubyte0_e32 v15, v15
	v_mul_f32_e32 v15, 0x3b800000, v15
	v_sin_f32_e32 v34, v15
	v_cos_f32_e32 v36, v15
	v_mul_f32_e32 v15, v22, v28
	v_fma_f32 v38, v24, v30, -v15
	v_mul_f32_e32 v15, v34, v34
	v_fma_f32 v40, v36, v36, -v15
	v_mul_f32_e64 v15, v36, -v34
	v_add_f32_e32 v42, v15, v15
	v_or_b32_e32 v15, 48, v72
	v_cvt_f32_ubyte0_e32 v15, v15
	v_mul_f32_e32 v15, 0x3b800000, v15
	v_sin_f32_e32 v46, v15
	v_cos_f32_e32 v48, v15
	v_mul_f32_e32 v15, v34, v40
	v_fma_f32 v50, v36, v42, -v15
	v_mul_f32_e32 v15, v46, v46
	v_cos_f32_e32 v60, v13
	v_fma_f32 v52, v48, v48, -v15
	v_mul_f32_e64 v15, v48, -v46
	v_add_f32_e32 v54, v15, v15
	v_mul_f32_e32 v13, v46, v52
	v_fma_f32 v62, v48, v54, -v13
	v_mul_f32_e32 v13, v58, v58
	v_fma_f32 v64, v60, v60, -v13
	v_mul_f32_e64 v13, v60, -v58
	v_add_f32_e32 v66, v13, v13
	v_mul_f32_e32 v20, v12, v18
	v_mul_f32_e32 v32, v22, v30
	v_mul_f32_e32 v44, v34, v42
	v_mul_f32_e32 v56, v46, v54
	v_mul_f32_e32 v68, v58, v66
	v_mul_f32_e32 v13, v58, v64
	v_fmac_f32_e32 v20, v14, v16
	v_fmac_f32_e32 v32, v24, v28
	v_fmac_f32_e32 v44, v36, v40
	v_fmac_f32_e32 v56, v48, v52
	v_fmac_f32_e32 v68, v60, v64
	v_fma_f32 v70, v60, v66, -v13
	v_mov_b32_e32 v61, v60
	v_mov_b32_e32 v59, v58
	v_mov_b32_e32 v65, v64
	v_mov_b32_e32 v67, v66
	v_mov_b32_e32 v69, v68
	v_mov_b32_e32 v71, v70
	v_mov_b32_e32 v15, v14
	v_mov_b32_e32 v13, v12
	v_mov_b32_e32 v37, v36
	v_mov_b32_e32 v35, v34
	v_mov_b32_e32 v25, v24
	v_mov_b32_e32 v23, v22
	v_mov_b32_e32 v49, v48
	v_mov_b32_e32 v47, v46
	v_mov_b32_e32 v17, v16
	v_mov_b32_e32 v41, v40
	v_mov_b32_e32 v29, v28
	v_mov_b32_e32 v53, v52
	v_mov_b32_e32 v21, v20
	v_mov_b32_e32 v27, v26
	v_mov_b32_e32 v45, v44
	v_mov_b32_e32 v51, v50
	v_mov_b32_e32 v33, v32
	v_mov_b32_e32 v39, v38
	v_mov_b32_e32 v57, v56
	v_mov_b32_e32 v63, v62
	v_mov_b32_e32 v19, v18
	v_mov_b32_e32 v31, v30
	v_mov_b32_e32 v43, v42
	v_mov_b32_e32 v55, v54
	s_mov_b64 s[10:11], 0
	s_nop 0
	s_waitcnt lgkmcnt(11)
; DI float2 twid(float r) { return float2{__builtin_amdgcn_cosf(r), -__builtin_amdgcn_sinf(r)}; }
; DI void bfly_fwd(float2 a0, float2 a1, float2 a2, float2 a3, float r, float2& o0, float2& o1, float2& o2, float2& o3) {
;   float2 t0 = {a0.x + a2.x, a0.y + a2.y}, t1 = {a0.x - a2.x, a0.y - a2.y}, t2 = {a1.x + a3.x, a1.y + a3.y}, t3 = {a1.x - a3.x, a1.y - a3.y};
;   float2 b0 = {t0.x + t2.x, t0.y + t2.y}, b2 = {t0.x - t2.x, t0.y - t2.y}, b1 = {t1.x + t3.y, t1.y - t3.x}, b3 = {t1.x - t3.y, t1.y + t3.x};
;   float2 w1 = twid(r), w2 = cmul(w1, w1), w3 = cmul(w2, w1);
;   o0 = b0; o1 = cmul(b1, w1); o2 = cmul(b2, w2); o3 = cmul(b3, w3);
; }
;     ...
;   for (int gg = tid; gg < NBT * (N / 16); gg += NTHR) { const int g = gg & (N / 16 - 1); float2* z = z0 + (gg / (N / 16)) * N; const int jp = g & (Q2 - 1), base = ((g >> lq2) << (lq2 + 4)) + jp; float2 x[4][4];
; #pragma unroll
;     for (int q1 = 0; q1 < 4; ++q1)
; #pragma unroll
;       for (int q2 = 0; q2 < 4; ++q2) x[q1][q2] = z[base + q1 * Q1 + q2 * Q2];
; #pragma unroll
;     for (int q2 = 0; q2 < 4; ++q2) bfly_fwd(x[0][q2], x[1][q2], x[2][q2], x[3][q2], (float)(jp + q2 * Q2) * invM1, x[0][q2], x[1][q2], x[2][q2], x[3][q2]);
; #pragma unroll
;     for (int q1 = 0; q1 < 4; ++q1) bfly_fwd(x[q1][0], x[q1][1], x[q1][2], x[q1][3], (float)jp * invM2, x[q1][0], x[q1][1], x[q1][2], x[q1][3]);
; #pragma unroll
;     for (int q1 = 0; q1 < 4; ++q1)
; #pragma unroll
;       for (int q2 = 0; q2 < 4; ++q2) z[base + q1 * Q1 + q2 * Q2] = x[q1][q2]; }
	v_pk_add_f32 v[108:109], v[74:75], v[92:93]
	v_pk_add_f32 v[114:115], v[76:77], v[94:95]
	s_waitcnt lgkmcnt(9)
	v_pk_add_f32 v[110:111], v[82:83], v[100:101]
	v_pk_add_f32 v[116:117], v[84:85], v[102:103]
	v_pk_add_f32 v[120:121], v[78:79], v[96:97]
	s_waitcnt lgkmcnt(8)
	v_pk_add_f32 v[122:123], v[86:87], v[104:105]
	v_pk_add_f32 v[126:127], v[80:81], v[98:99]
	v_pk_add_f32 v[128:129], v[88:89], v[106:107]
	v_pk_add_f32 v[112:113], v[108:109], v[110:111]
	v_pk_add_f32 v[118:119], v[114:115], v[116:117]
	v_pk_add_f32 v[124:125], v[120:121], v[122:123]
	v_pk_add_f32 v[130:131], v[126:127], v[128:129]
	v_pk_add_f32 v[132:133], v[112:113], v[124:125]
	v_pk_add_f32 v[134:135], v[118:119], v[130:131]
	v_pk_add_f32 v[112:113], v[112:113], v[124:125] neg_lo:[0,1] neg_hi:[0,1]
	v_pk_add_f32 v[118:119], v[118:119], v[130:131] neg_lo:[0,1] neg_hi:[0,1]
	v_pk_add_f32 v[136:137], v[132:133], v[134:135]
	v_pk_add_f32 v[124:125], v[112:113], v[118:119] op_sel:[0,1] op_sel_hi:[1,0]
	v_pk_add_f32 v[112:113], v[112:113], v[118:119] op_sel:[0,1] op_sel_hi:[1,0] neg_lo:[0,1] neg_hi:[0,1]
	v_mov_b32_e32 v118, v124
	v_pk_mov_b32 v[130:131], v[112:113], v[124:125] op_sel:[1,0]
	v_mov_b32_e32 v119, v113
	v_pk_mul_f32 v[130:131], v[58:59], v[130:131]
	v_pk_add_f32 v[74:75], v[74:75], v[92:93] neg_lo:[0,1] neg_hi:[0,1]
	v_pk_fma_f32 v[138:139], v[60:61], v[124:125], v[130:131]
	v_pk_fma_f32 v[118:119], v[60:61], v[118:119], v[130:131] neg_lo:[0,0,1] neg_hi:[0,0,1]
	v_pk_add_f32 v[82:83], v[82:83], v[100:101] neg_lo:[0,1] neg_hi:[0,1]
	v_mov_b32_e32 v139, v119
	v_pk_add_f32 v[118:119], v[132:133], v[134:135] neg_lo:[0,1] neg_hi:[0,1]
	v_pk_add_f32 v[92:93], v[74:75], v[82:83] op_sel:[0,1] op_sel_hi:[1,0]
	v_pk_mul_f32 v[130:131], v[66:67], v[118:119]
	v_pk_add_f32 v[74:75], v[74:75], v[82:83] op_sel:[0,1] op_sel_hi:[1,0] neg_lo:[0,1] neg_hi:[0,1]
	v_pk_fma_f32 v[132:133], v[64:65], v[118:119], v[130:131] op_sel:[0,0,1] op_sel_hi:[1,1,0] neg_lo:[0,0,1] neg_hi:[0,0,1]
	v_pk_fma_f32 v[118:119], v[64:65], v[118:119], v[130:131] op_sel:[0,0,1] op_sel_hi:[1,1,0]
	v_pk_mov_b32 v[100:101], v[74:75], v[92:93] op_sel:[1,0]
	v_mov_b32_e32 v133, v119
	v_mov_b32_e32 v119, v125
	v_pk_mov_b32 v[124:125], v[124:125], v[112:113] op_sel:[1,0]
	v_mov_b32_e32 v118, v112
	v_pk_mul_f32 v[124:125], v[70:71], v[124:125]
	v_mov_b32_e32 v82, v92
	v_pk_fma_f32 v[112:113], v[68:69], v[112:113], v[124:125] neg_lo:[0,0,1] neg_hi:[0,0,1]
	v_pk_fma_f32 v[118:119], v[68:69], v[118:119], v[124:125]
	v_mov_b32_e32 v83, v75
	v_mov_b32_e32 v113, v119
	v_pk_mul_f32 v[100:101], v[12:13], v[100:101]
	ds_write2_b64 v90, v[132:133], v[112:113] offset0:32 offset1:48
	v_pk_fma_f32 v[112:113], v[14:15], v[92:93], v[100:101]
	v_pk_fma_f32 v[82:83], v[14:15], v[82:83], v[100:101] neg_lo:[0,0,1] neg_hi:[0,0,1]
	v_pk_add_f32 v[76:77], v[76:77], v[94:95] neg_lo:[0,1] neg_hi:[0,1]
	v_mov_b32_e32 v113, v83
	v_pk_add_f32 v[82:83], v[84:85], v[102:103] neg_lo:[0,1] neg_hi:[0,1]
	v_pk_add_f32 v[78:79], v[78:79], v[96:97] neg_lo:[0,1] neg_hi:[0,1]
	v_pk_add_f32 v[84:85], v[76:77], v[82:83] op_sel:[0,1] op_sel_hi:[1,0]
	v_pk_add_f32 v[76:77], v[76:77], v[82:83] op_sel:[0,1] op_sel_hi:[1,0] neg_lo:[0,1] neg_hi:[0,1]
	v_mov_b32_e32 v82, v84
	v_pk_mov_b32 v[94:95], v[76:77], v[84:85] op_sel:[1,0]
	v_mov_b32_e32 v83, v77
	v_pk_mul_f32 v[94:95], v[22:23], v[94:95]
	v_pk_add_f32 v[80:81], v[80:81], v[98:99] neg_lo:[0,1] neg_hi:[0,1]
	v_pk_fma_f32 v[100:101], v[24:25], v[84:85], v[94:95]
	v_pk_fma_f32 v[82:83], v[24:25], v[82:83], v[94:95] neg_lo:[0,0,1] neg_hi:[0,0,1]
	v_add_u32_e32 v11, 0x2000, v11
	v_mov_b32_e32 v101, v83
	v_pk_add_f32 v[82:83], v[86:87], v[104:105] neg_lo:[0,1] neg_hi:[0,1]
	s_nop 0
	v_pk_add_f32 v[86:87], v[78:79], v[82:83] op_sel:[0,1] op_sel_hi:[1,0]
	v_pk_add_f32 v[78:79], v[78:79], v[82:83] op_sel:[0,1] op_sel_hi:[1,0] neg_lo:[0,1] neg_hi:[0,1]
	v_mov_b32_e32 v82, v86
	v_pk_mov_b32 v[94:95], v[78:79], v[86:87] op_sel:[1,0]
	v_mov_b32_e32 v83, v79
	v_pk_mul_f32 v[94:95], v[34:35], v[94:95]
	ds_write2_b64 v90, v[136:137], v[138:139] offset1:16
	v_pk_fma_f32 v[96:97], v[36:37], v[86:87], v[94:95]
	v_pk_fma_f32 v[82:83], v[36:37], v[82:83], v[94:95] neg_lo:[0,0,1] neg_hi:[0,0,1]
	s_nop 0
	v_mov_b32_e32 v97, v83
	v_pk_add_f32 v[82:83], v[88:89], v[106:107] neg_lo:[0,1] neg_hi:[0,1]
	s_nop 0
	v_pk_add_f32 v[88:89], v[80:81], v[82:83] op_sel:[0,1] op_sel_hi:[1,0]
	v_pk_add_f32 v[80:81], v[80:81], v[82:83] op_sel:[0,1] op_sel_hi:[1,0] neg_lo:[0,1] neg_hi:[0,1]
	v_mov_b32_e32 v82, v88
	v_pk_mov_b32 v[94:95], v[80:81], v[88:89] op_sel:[1,0]
	v_mov_b32_e32 v83, v81
	v_pk_mul_f32 v[94:95], v[46:47], v[94:95]
	s_nop 0
	v_pk_fma_f32 v[98:99], v[48:49], v[88:89], v[94:95]
	v_pk_fma_f32 v[82:83], v[48:49], v[82:83], v[94:95] neg_lo:[0,0,1] neg_hi:[0,0,1]
	s_nop 0
	v_mov_b32_e32 v99, v83
	v_pk_add_f32 v[82:83], v[112:113], v[96:97]
	v_pk_add_f32 v[94:95], v[100:101], v[98:99]
	v_pk_add_f32 v[96:97], v[112:113], v[96:97] neg_lo:[0,1] neg_hi:[0,1]
	v_pk_add_f32 v[98:99], v[100:101], v[98:99] neg_lo:[0,1] neg_hi:[0,1]
	v_pk_add_f32 v[102:103], v[82:83], v[94:95]
	v_pk_add_f32 v[100:101], v[96:97], v[98:99] op_sel:[0,1] op_sel_hi:[1,0]
	v_pk_add_f32 v[96:97], v[96:97], v[98:99] op_sel:[0,1] op_sel_hi:[1,0] neg_lo:[0,1] neg_hi:[0,1]
	v_mov_b32_e32 v98, v100
	v_pk_mov_b32 v[104:105], v[96:97], v[100:101] op_sel:[1,0]
	v_mov_b32_e32 v99, v97
	v_pk_mul_f32 v[104:105], v[58:59], v[104:105]
	v_pk_add_f32 v[82:83], v[82:83], v[94:95] neg_lo:[0,1] neg_hi:[0,1]
	v_pk_fma_f32 v[106:107], v[60:61], v[100:101], v[104:105]
	v_pk_fma_f32 v[98:99], v[60:61], v[98:99], v[104:105] neg_lo:[0,0,1] neg_hi:[0,0,1]
	v_pk_mul_f32 v[94:95], v[66:67], v[82:83]
; DI float2 twid(float r) { return float2{__builtin_amdgcn_cosf(r), -__builtin_amdgcn_sinf(r)}; }
; DI void bfly_fwd(float2 a0, float2 a1, float2 a2, float2 a3, float r, float2& o0, float2& o1, float2& o2, float2& o3) {
;   float2 t0 = {a0.x + a2.x, a0.y + a2.y}, t1 = {a0.x - a2.x, a0.y - a2.y}, t2 = {a1.x + a3.x, a1.y + a3.y}, t3 = {a1.x - a3.x, a1.y - a3.y};
;   float2 b0 = {t0.x + t2.x, t0.y + t2.y}, b2 = {t0.x - t2.x, t0.y - t2.y}, b1 = {t1.x + t3.y, t1.y - t3.x}, b3 = {t1.x - t3.y, t1.y + t3.x};
;   float2 w1 = twid(r), w2 = cmul(w1, w1), w3 = cmul(w2, w1);
;   o0 = b0; o1 = cmul(b1, w1); o2 = cmul(b2, w2); o3 = cmul(b3, w3);
; }
;     ...
;   for (int gg = tid; gg < NBT * (N / 16); gg += NTHR) { const int g = gg & (N / 16 - 1); float2* z = z0 + (gg / (N / 16)) * N; const int jp = g & (Q2 - 1), base = ((g >> lq2) << (lq2 + 4)) + jp; float2 x[4][4];
; #pragma unroll
;     for (int q1 = 0; q1 < 4; ++q1)
; #pragma unroll
;       for (int q2 = 0; q2 < 4; ++q2) x[q1][q2] = z[base + q1 * Q1 + q2 * Q2];
; #pragma unroll
;     for (int q2 = 0; q2 < 4; ++q2) bfly_fwd(x[0][q2], x[1][q2], x[2][q2], x[3][q2], (float)(jp + q2 * Q2) * invM1, x[0][q2], x[1][q2], x[2][q2], x[3][q2]);
; #pragma unroll
;     for (int q1 = 0; q1 < 4; ++q1) bfly_fwd(x[q1][0], x[q1][1], x[q1][2], x[q1][3], (float)jp * invM2, x[q1][0], x[q1][1], x[q1][2], x[q1][3]);
; #pragma unroll
;     for (int q1 = 0; q1 < 4; ++q1)
; #pragma unroll
;       for (int q2 = 0; q2 < 4; ++q2) z[base + q1 * Q1 + q2 * Q2] = x[q1][q2]; }
	v_mov_b32_e32 v107, v99
	v_pk_fma_f32 v[98:99], v[64:65], v[82:83], v[94:95] op_sel:[0,0,1] op_sel_hi:[1,1,0] neg_lo:[0,0,1] neg_hi:[0,0,1]
	v_pk_fma_f32 v[82:83], v[64:65], v[82:83], v[94:95] op_sel:[0,0,1] op_sel_hi:[1,1,0]
	v_pk_mov_b32 v[94:95], v[100:101], v[96:97] op_sel:[1,0]
	v_mov_b32_e32 v99, v83
	v_mov_b32_e32 v82, v96
	v_mov_b32_e32 v83, v101
	v_pk_mul_f32 v[94:95], v[70:71], v[94:95]
	ds_write2_b64 v90, v[102:103], v[106:107] offset0:64 offset1:80
	v_pk_fma_f32 v[96:97], v[68:69], v[96:97], v[94:95] neg_lo:[0,0,1] neg_hi:[0,0,1]
	v_pk_fma_f32 v[82:83], v[68:69], v[82:83], v[94:95]
	s_nop 0
	v_mov_b32_e32 v97, v83
	v_pk_add_f32 v[82:83], v[108:109], v[110:111] neg_lo:[0,1] neg_hi:[0,1]
	ds_write2_b64 v90, v[98:99], v[96:97] offset0:96 offset1:112
	v_pk_mul_f32 v[94:95], v[18:19], v[82:83] op_sel:[0,1] op_sel_hi:[1,0]
	s_nop 0
	v_pk_fma_f32 v[96:97], v[16:17], v[82:83], v[94:95] neg_lo:[0,0,1] neg_hi:[0,0,1]
	v_pk_fma_f32 v[82:83], v[16:17], v[82:83], v[94:95]
	s_nop 0
	v_mov_b32_e32 v97, v83
	v_pk_add_f32 v[82:83], v[114:115], v[116:117] neg_lo:[0,1] neg_hi:[0,1]
	s_nop 0
	v_pk_mul_f32 v[94:95], v[30:31], v[82:83] op_sel:[0,1] op_sel_hi:[1,0]
	s_nop 0
	v_pk_fma_f32 v[98:99], v[28:29], v[82:83], v[94:95] neg_lo:[0,0,1] neg_hi:[0,0,1]
	v_pk_fma_f32 v[82:83], v[28:29], v[82:83], v[94:95]
	s_nop 0
	v_mov_b32_e32 v99, v83
	v_pk_add_f32 v[82:83], v[120:121], v[122:123] neg_lo:[0,1] neg_hi:[0,1]
	s_nop 0
	v_pk_mul_f32 v[94:95], v[42:43], v[82:83] op_sel:[0,1] op_sel_hi:[1,0]
	s_nop 0
	v_pk_fma_f32 v[100:101], v[40:41], v[82:83], v[94:95] neg_lo:[0,0,1] neg_hi:[0,0,1]
	v_pk_fma_f32 v[82:83], v[40:41], v[82:83], v[94:95]
	s_nop 0
	v_mov_b32_e32 v101, v83
	v_pk_add_f32 v[82:83], v[126:127], v[128:129] neg_lo:[0,1] neg_hi:[0,1]
	s_nop 0
	v_pk_mul_f32 v[94:95], v[54:55], v[82:83] op_sel:[0,1] op_sel_hi:[1,0]
	s_nop 0
	v_pk_fma_f32 v[102:103], v[52:53], v[82:83], v[94:95] neg_lo:[0,0,1] neg_hi:[0,0,1]
	v_pk_fma_f32 v[82:83], v[52:53], v[82:83], v[94:95]
	s_nop 0
	v_mov_b32_e32 v103, v83
	v_pk_add_f32 v[82:83], v[96:97], v[100:101]
	v_pk_add_f32 v[94:95], v[98:99], v[102:103]
	v_pk_add_f32 v[96:97], v[96:97], v[100:101] neg_lo:[0,1] neg_hi:[0,1]
	v_pk_add_f32 v[98:99], v[98:99], v[102:103] neg_lo:[0,1] neg_hi:[0,1]
	v_pk_add_f32 v[104:105], v[82:83], v[94:95]
	v_pk_add_f32 v[100:101], v[96:97], v[98:99] op_sel:[0,1] op_sel_hi:[1,0]
	v_pk_add_f32 v[96:97], v[96:97], v[98:99] op_sel:[0,1] op_sel_hi:[1,0] neg_lo:[0,1] neg_hi:[0,1]
	v_mov_b32_e32 v98, v100
	v_pk_mov_b32 v[102:103], v[96:97], v[100:101] op_sel:[1,0]
	v_mov_b32_e32 v99, v97
	v_pk_mul_f32 v[102:103], v[58:59], v[102:103]
	v_pk_add_f32 v[82:83], v[82:83], v[94:95] neg_lo:[0,1] neg_hi:[0,1]
	v_pk_fma_f32 v[106:107], v[60:61], v[100:101], v[102:103]
	v_pk_fma_f32 v[98:99], v[60:61], v[98:99], v[102:103] neg_lo:[0,0,1] neg_hi:[0,0,1]
	v_pk_mul_f32 v[94:95], v[66:67], v[82:83]
	v_mov_b32_e32 v107, v99
	v_pk_fma_f32 v[98:99], v[64:65], v[82:83], v[94:95] op_sel:[0,0,1] op_sel_hi:[1,1,0] neg_lo:[0,0,1] neg_hi:[0,0,1]
	v_pk_fma_f32 v[82:83], v[64:65], v[82:83], v[94:95] op_sel:[0,0,1] op_sel_hi:[1,1,0]
	v_pk_mov_b32 v[94:95], v[100:101], v[96:97] op_sel:[1,0]
	v_mov_b32_e32 v99, v83
	v_mov_b32_e32 v82, v96
	v_mov_b32_e32 v83, v101
	v_pk_mul_f32 v[94:95], v[70:71], v[94:95]
	ds_write2_b64 v90, v[104:105], v[106:107] offset0:128 offset1:144
	v_pk_fma_f32 v[96:97], v[68:69], v[96:97], v[94:95] neg_lo:[0,0,1] neg_hi:[0,0,1]
	v_pk_fma_f32 v[82:83], v[68:69], v[82:83], v[94:95]
	s_nop 0
	v_mov_b32_e32 v97, v83
	v_mov_b32_e32 v83, v93
	v_pk_mov_b32 v[92:93], v[92:93], v[74:75] op_sel:[1,0]
	v_mov_b32_e32 v82, v74
	v_pk_mul_f32 v[92:93], v[26:27], v[92:93]
	ds_write2_b64 v90, v[98:99], v[96:97] offset0:160 offset1:176
	v_pk_fma_f32 v[74:75], v[20:21], v[74:75], v[92:93] neg_lo:[0,0,1] neg_hi:[0,0,1]
	v_pk_fma_f32 v[82:83], v[20:21], v[82:83], v[92:93]
	s_nop 0
	v_mov_b32_e32 v75, v83
	v_mov_b32_e32 v83, v85
	v_pk_mov_b32 v[84:85], v[84:85], v[76:77] op_sel:[1,0]
	v_mov_b32_e32 v82, v76
	v_pk_mul_f32 v[84:85], v[38:39], v[84:85]
	s_nop 0
	v_pk_fma_f32 v[76:77], v[32:33], v[76:77], v[84:85] neg_lo:[0,0,1] neg_hi:[0,0,1]
	v_pk_fma_f32 v[82:83], v[32:33], v[82:83], v[84:85]
	v_pk_mov_b32 v[84:85], v[86:87], v[78:79] op_sel:[1,0]
	v_mov_b32_e32 v77, v83
	v_mov_b32_e32 v82, v78
	v_mov_b32_e32 v83, v87
	v_pk_mul_f32 v[84:85], v[50:51], v[84:85]
	s_nop 0
	v_pk_fma_f32 v[78:79], v[44:45], v[78:79], v[84:85] neg_lo:[0,0,1] neg_hi:[0,0,1]
	v_pk_fma_f32 v[82:83], v[44:45], v[82:83], v[84:85]
	v_pk_mov_b32 v[84:85], v[88:89], v[80:81] op_sel:[1,0]
	v_mov_b32_e32 v79, v83
	v_mov_b32_e32 v82, v80
	v_mov_b32_e32 v83, v89
	v_pk_mul_f32 v[84:85], v[62:63], v[84:85]
	s_nop 0
	v_pk_fma_f32 v[80:81], v[56:57], v[80:81], v[84:85] neg_lo:[0,0,1] neg_hi:[0,0,1]
	v_pk_fma_f32 v[82:83], v[56:57], v[82:83], v[84:85]
	s_nop 0
	v_mov_b32_e32 v81, v83
	v_pk_add_f32 v[82:83], v[74:75], v[78:79]
	v_pk_add_f32 v[84:85], v[76:77], v[80:81]
	v_pk_add_f32 v[74:75], v[74:75], v[78:79] neg_lo:[0,1] neg_hi:[0,1]
	v_pk_add_f32 v[76:77], v[76:77], v[80:81] neg_lo:[0,1] neg_hi:[0,1]
	v_pk_add_f32 v[86:87], v[82:83], v[84:85]
	v_pk_add_f32 v[78:79], v[74:75], v[76:77] op_sel:[0,1] op_sel_hi:[1,0]
	v_pk_add_f32 v[74:75], v[74:75], v[76:77] op_sel:[0,1] op_sel_hi:[1,0] neg_lo:[0,1] neg_hi:[0,1]
	v_mov_b32_e32 v76, v78
	v_pk_mov_b32 v[80:81], v[74:75], v[78:79] op_sel:[1,0]
	v_mov_b32_e32 v77, v75
	v_pk_mul_f32 v[80:81], v[58:59], v[80:81]
	s_nop 0
	v_pk_fma_f32 v[88:89], v[60:61], v[78:79], v[80:81]
	v_pk_fma_f32 v[76:77], v[60:61], v[76:77], v[80:81] neg_lo:[0,0,1] neg_hi:[0,0,1]
	s_nop 0
	v_mov_b32_e32 v89, v77
	v_pk_add_f32 v[76:77], v[82:83], v[84:85] neg_lo:[0,1] neg_hi:[0,1]
	ds_write2_b64 v90, v[86:87], v[88:89] offset0:192 offset1:208
	v_pk_mul_f32 v[80:81], v[66:67], v[76:77]
	s_nop 0
	v_pk_fma_f32 v[82:83], v[64:65], v[76:77], v[80:81] op_sel:[0,0,1] op_sel_hi:[1,1,0] neg_lo:[0,0,1] neg_hi:[0,0,1]
	v_pk_fma_f32 v[76:77], v[64:65], v[76:77], v[80:81] op_sel:[0,0,1] op_sel_hi:[1,1,0]
	s_nop 0
	v_mov_b32_e32 v83, v77
	v_mov_b32_e32 v77, v79
	v_pk_mov_b32 v[78:79], v[78:79], v[74:75] op_sel:[1,0]
	v_mov_b32_e32 v76, v74
	v_pk_mul_f32 v[78:79], v[70:71], v[78:79]
	s_nop 0
	v_pk_fma_f32 v[74:75], v[68:69], v[74:75], v[78:79] neg_lo:[0,0,1] neg_hi:[0,0,1]
	v_pk_fma_f32 v[76:77], v[68:69], v[76:77], v[78:79]
	s_nop 0
	v_mov_b32_e32 v75, v77
	ds_write2_b64 v90, v[82:83], v[74:75] offset0:224 offset1:240
	s_nop 0
	v_add_u32_e32 v73, 0x200, v73
	s_nop 0
	s_waitcnt lgkmcnt(11)
; DI float2 twid(float r) { return float2{__builtin_amdgcn_cosf(r), -__builtin_amdgcn_sinf(r)}; }
; DI void bfly_fwd(float2 a0, float2 a1, float2 a2, float2 a3, float r, float2& o0, float2& o1, float2& o2, float2& o3) {
;   float2 t0 = {a0.x + a2.x, a0.y + a2.y}, t1 = {a0.x - a2.x, a0.y - a2.y}, t2 = {a1.x + a3.x, a1.y + a3.y}, t3 = {a1.x - a3.x, a1.y - a3.y};
;   float2 b0 = {t0.x + t2.x, t0.y + t2.y}, b2 = {t0.x - t2.x, t0.y - t2.y}, b1 = {t1.x + t3.y, t1.y - t3.x}, b3 = {t1.x - t3.y, t1.y + t3.x};
;   float2 w1 = twid(r), w2 = cmul(w1, w1), w3 = cmul(w2, w1);
;   o0 = b0; o1 = cmul(b1, w1); o2 = cmul(b2, w2); o3 = cmul(b3, w3);
; }
;     ...
;   for (int gg = tid; gg < NBT * (N / 16); gg += NTHR) { const int g = gg & (N / 16 - 1); float2* z = z0 + (gg / (N / 16)) * N; const int jp = g & (Q2 - 1), base = ((g >> lq2) << (lq2 + 4)) + jp; float2 x[4][4];
; #pragma unroll
;     for (int q1 = 0; q1 < 4; ++q1)
; #pragma unroll
;       for (int q2 = 0; q2 < 4; ++q2) x[q1][q2] = z[base + q1 * Q1 + q2 * Q2];
; #pragma unroll
;     for (int q2 = 0; q2 < 4; ++q2) bfly_fwd(x[0][q2], x[1][q2], x[2][q2], x[3][q2], (float)(jp + q2 * Q2) * invM1, x[0][q2], x[1][q2], x[2][q2], x[3][q2]);
; #pragma unroll
;     for (int q1 = 0; q1 < 4; ++q1) bfly_fwd(x[q1][0], x[q1][1], x[q1][2], x[q1][3], (float)jp * invM2, x[q1][0], x[q1][1], x[q1][2], x[q1][3]);
; #pragma unroll
;     for (int q1 = 0; q1 < 4; ++q1)
; #pragma unroll
;       for (int q2 = 0; q2 < 4; ++q2) z[base + q1 * Q1 + q2 * Q2] = x[q1][q2]; }
	v_pk_add_f32 v[108:109], v[220:221], v[236:237]
	v_pk_add_f32 v[114:115], v[222:223], v[238:239]
	s_waitcnt lgkmcnt(9)
	v_pk_add_f32 v[110:111], v[228:229], v[248:249]
	v_pk_add_f32 v[116:117], v[230:231], v[250:251]
	v_pk_add_f32 v[120:121], v[224:225], v[244:245]
	s_waitcnt lgkmcnt(8)
	v_pk_add_f32 v[122:123], v[232:233], v[252:253]
	v_pk_add_f32 v[126:127], v[226:227], v[246:247]
	v_pk_add_f32 v[128:129], v[234:235], v[254:255]
	v_pk_add_f32 v[112:113], v[108:109], v[110:111]
	v_pk_add_f32 v[118:119], v[114:115], v[116:117]
	v_pk_add_f32 v[124:125], v[120:121], v[122:123]
	v_pk_add_f32 v[130:131], v[126:127], v[128:129]
	v_pk_add_f32 v[132:133], v[112:113], v[124:125]
	v_pk_add_f32 v[134:135], v[118:119], v[130:131]
	v_pk_add_f32 v[112:113], v[112:113], v[124:125] neg_lo:[0,1] neg_hi:[0,1]
	v_pk_add_f32 v[118:119], v[118:119], v[130:131] neg_lo:[0,1] neg_hi:[0,1]
	v_pk_add_f32 v[136:137], v[132:133], v[134:135]
	v_pk_add_f32 v[124:125], v[112:113], v[118:119] op_sel:[0,1] op_sel_hi:[1,0]
	v_pk_add_f32 v[112:113], v[112:113], v[118:119] op_sel:[0,1] op_sel_hi:[1,0] neg_lo:[0,1] neg_hi:[0,1]
	v_mov_b32_e32 v118, v124
	v_pk_mov_b32 v[130:131], v[112:113], v[124:125] op_sel:[1,0]
	v_mov_b32_e32 v119, v113
	v_pk_mul_f32 v[130:131], v[58:59], v[130:131]
	v_pk_add_f32 v[220:221], v[220:221], v[236:237] neg_lo:[0,1] neg_hi:[0,1]
	v_pk_fma_f32 v[138:139], v[60:61], v[124:125], v[130:131]
	v_pk_fma_f32 v[118:119], v[60:61], v[118:119], v[130:131] neg_lo:[0,0,1] neg_hi:[0,0,1]
	v_pk_add_f32 v[228:229], v[228:229], v[248:249] neg_lo:[0,1] neg_hi:[0,1]
	v_mov_b32_e32 v139, v119
	v_pk_add_f32 v[118:119], v[132:133], v[134:135] neg_lo:[0,1] neg_hi:[0,1]
	v_pk_add_f32 v[236:237], v[220:221], v[228:229] op_sel:[0,1] op_sel_hi:[1,0]
	v_pk_mul_f32 v[130:131], v[66:67], v[118:119]
	v_pk_add_f32 v[220:221], v[220:221], v[228:229] op_sel:[0,1] op_sel_hi:[1,0] neg_lo:[0,1] neg_hi:[0,1]
	v_pk_fma_f32 v[132:133], v[64:65], v[118:119], v[130:131] op_sel:[0,0,1] op_sel_hi:[1,1,0] neg_lo:[0,0,1] neg_hi:[0,0,1]
	v_pk_fma_f32 v[118:119], v[64:65], v[118:119], v[130:131] op_sel:[0,0,1] op_sel_hi:[1,1,0]
	v_pk_mov_b32 v[248:249], v[220:221], v[236:237] op_sel:[1,0]
	v_mov_b32_e32 v133, v119
	v_mov_b32_e32 v119, v125
	v_pk_mov_b32 v[124:125], v[124:125], v[112:113] op_sel:[1,0]
	v_mov_b32_e32 v118, v112
	v_pk_mul_f32 v[124:125], v[70:71], v[124:125]
	v_mov_b32_e32 v228, v236
	v_pk_fma_f32 v[112:113], v[68:69], v[112:113], v[124:125] neg_lo:[0,0,1] neg_hi:[0,0,1]
	v_pk_fma_f32 v[118:119], v[68:69], v[118:119], v[124:125]
	v_mov_b32_e32 v229, v221
	v_mov_b32_e32 v113, v119
	v_pk_mul_f32 v[248:249], v[12:13], v[248:249]
	ds_write2_b64 v219, v[132:133], v[112:113] offset0:32 offset1:48
	v_pk_fma_f32 v[112:113], v[14:15], v[236:237], v[248:249]
	v_pk_fma_f32 v[228:229], v[14:15], v[228:229], v[248:249] neg_lo:[0,0,1] neg_hi:[0,0,1]
	v_pk_add_f32 v[222:223], v[222:223], v[238:239] neg_lo:[0,1] neg_hi:[0,1]
	v_mov_b32_e32 v113, v229
	v_pk_add_f32 v[228:229], v[230:231], v[250:251] neg_lo:[0,1] neg_hi:[0,1]
	v_pk_add_f32 v[224:225], v[224:225], v[244:245] neg_lo:[0,1] neg_hi:[0,1]
	v_pk_add_f32 v[230:231], v[222:223], v[228:229] op_sel:[0,1] op_sel_hi:[1,0]
	v_pk_add_f32 v[222:223], v[222:223], v[228:229] op_sel:[0,1] op_sel_hi:[1,0] neg_lo:[0,1] neg_hi:[0,1]
	v_mov_b32_e32 v228, v230
	v_pk_mov_b32 v[238:239], v[222:223], v[230:231] op_sel:[1,0]
	v_mov_b32_e32 v229, v223
	v_pk_mul_f32 v[238:239], v[22:23], v[238:239]
	v_pk_add_f32 v[226:227], v[226:227], v[246:247] neg_lo:[0,1] neg_hi:[0,1]
	v_pk_fma_f32 v[248:249], v[24:25], v[230:231], v[238:239]
	v_pk_fma_f32 v[228:229], v[24:25], v[228:229], v[238:239] neg_lo:[0,0,1] neg_hi:[0,0,1]
	v_add_u32_e32 v11, 0x2000, v11
	v_mov_b32_e32 v249, v229
	v_pk_add_f32 v[228:229], v[232:233], v[252:253] neg_lo:[0,1] neg_hi:[0,1]
	s_nop 0
	v_pk_add_f32 v[232:233], v[224:225], v[228:229] op_sel:[0,1] op_sel_hi:[1,0]
	v_pk_add_f32 v[224:225], v[224:225], v[228:229] op_sel:[0,1] op_sel_hi:[1,0] neg_lo:[0,1] neg_hi:[0,1]
	v_mov_b32_e32 v228, v232
	v_pk_mov_b32 v[238:239], v[224:225], v[232:233] op_sel:[1,0]
	v_mov_b32_e32 v229, v225
	v_pk_mul_f32 v[238:239], v[34:35], v[238:239]
	ds_write2_b64 v219, v[136:137], v[138:139] offset1:16
	v_pk_fma_f32 v[244:245], v[36:37], v[232:233], v[238:239]
	v_pk_fma_f32 v[228:229], v[36:37], v[228:229], v[238:239] neg_lo:[0,0,1] neg_hi:[0,0,1]
	s_nop 0
	v_mov_b32_e32 v245, v229
	v_pk_add_f32 v[228:229], v[234:235], v[254:255] neg_lo:[0,1] neg_hi:[0,1]
	s_nop 0
	v_pk_add_f32 v[234:235], v[226:227], v[228:229] op_sel:[0,1] op_sel_hi:[1,0]
	v_pk_add_f32 v[226:227], v[226:227], v[228:229] op_sel:[0,1] op_sel_hi:[1,0] neg_lo:[0,1] neg_hi:[0,1]
	v_mov_b32_e32 v228, v234
	v_pk_mov_b32 v[238:239], v[226:227], v[234:235] op_sel:[1,0]
	v_mov_b32_e32 v229, v227
	v_pk_mul_f32 v[238:239], v[46:47], v[238:239]
	s_nop 0
	v_pk_fma_f32 v[246:247], v[48:49], v[234:235], v[238:239]
	v_pk_fma_f32 v[228:229], v[48:49], v[228:229], v[238:239] neg_lo:[0,0,1] neg_hi:[0,0,1]
	s_nop 0
	v_mov_b32_e32 v247, v229
	v_pk_add_f32 v[228:229], v[112:113], v[244:245]
	v_pk_add_f32 v[238:239], v[248:249], v[246:247]
	v_pk_add_f32 v[244:245], v[112:113], v[244:245] neg_lo:[0,1] neg_hi:[0,1]
	v_pk_add_f32 v[246:247], v[248:249], v[246:247] neg_lo:[0,1] neg_hi:[0,1]
	v_pk_add_f32 v[250:251], v[228:229], v[238:239]
	v_pk_add_f32 v[248:249], v[244:245], v[246:247] op_sel:[0,1] op_sel_hi:[1,0]
	v_pk_add_f32 v[244:245], v[244:245], v[246:247] op_sel:[0,1] op_sel_hi:[1,0] neg_lo:[0,1] neg_hi:[0,1]
	v_mov_b32_e32 v246, v248
	v_pk_mov_b32 v[252:253], v[244:245], v[248:249] op_sel:[1,0]
	v_mov_b32_e32 v247, v245
	v_pk_mul_f32 v[252:253], v[58:59], v[252:253]
; DI float2 twid(float r) { return float2{__builtin_amdgcn_cosf(r), -__builtin_amdgcn_sinf(r)}; }
; DI void bfly_fwd(float2 a0, float2 a1, float2 a2, float2 a3, float r, float2& o0, float2& o1, float2& o2, float2& o3) {
;   float2 t0 = {a0.x + a2.x, a0.y + a2.y}, t1 = {a0.x - a2.x, a0.y - a2.y}, t2 = {a1.x + a3.x, a1.y + a3.y}, t3 = {a1.x - a3.x, a1.y - a3.y};
;   float2 b0 = {t0.x + t2.x, t0.y + t2.y}, b2 = {t0.x - t2.x, t0.y - t2.y}, b1 = {t1.x + t3.y, t1.y - t3.x}, b3 = {t1.x - t3.y, t1.y + t3.x};
;   float2 w1 = twid(r), w2 = cmul(w1, w1), w3 = cmul(w2, w1);
;   o0 = b0; o1 = cmul(b1, w1); o2 = cmul(b2, w2); o3 = cmul(b3, w3);
; }
;     ...
;   for (int gg = tid; gg < NBT * (N / 16); gg += NTHR) { const int g = gg & (N / 16 - 1); float2* z = z0 + (gg / (N / 16)) * N; const int jp = g & (Q2 - 1), base = ((g >> lq2) << (lq2 + 4)) + jp; float2 x[4][4];
; #pragma unroll
;     for (int q1 = 0; q1 < 4; ++q1)
; #pragma unroll
;       for (int q2 = 0; q2 < 4; ++q2) x[q1][q2] = z[base + q1 * Q1 + q2 * Q2];
; #pragma unroll
;     for (int q2 = 0; q2 < 4; ++q2) bfly_fwd(x[0][q2], x[1][q2], x[2][q2], x[3][q2], (float)(jp + q2 * Q2) * invM1, x[0][q2], x[1][q2], x[2][q2], x[3][q2]);
; #pragma unroll
;     for (int q1 = 0; q1 < 4; ++q1) bfly_fwd(x[q1][0], x[q1][1], x[q1][2], x[q1][3], (float)jp * invM2, x[q1][0], x[q1][1], x[q1][2], x[q1][3]);
; #pragma unroll
;     for (int q1 = 0; q1 < 4; ++q1)
; #pragma unroll
;       for (int q2 = 0; q2 < 4; ++q2) z[base + q1 * Q1 + q2 * Q2] = x[q1][q2]; }
	v_pk_add_f32 v[228:229], v[228:229], v[238:239] neg_lo:[0,1] neg_hi:[0,1]
	v_pk_fma_f32 v[254:255], v[60:61], v[248:249], v[252:253]
	v_pk_fma_f32 v[246:247], v[60:61], v[246:247], v[252:253] neg_lo:[0,0,1] neg_hi:[0,0,1]
	v_pk_mul_f32 v[238:239], v[66:67], v[228:229]
	v_mov_b32_e32 v255, v247
	v_pk_fma_f32 v[246:247], v[64:65], v[228:229], v[238:239] op_sel:[0,0,1] op_sel_hi:[1,1,0] neg_lo:[0,0,1] neg_hi:[0,0,1]
	v_pk_fma_f32 v[228:229], v[64:65], v[228:229], v[238:239] op_sel:[0,0,1] op_sel_hi:[1,1,0]
	v_pk_mov_b32 v[238:239], v[248:249], v[244:245] op_sel:[1,0]
	v_mov_b32_e32 v247, v229
	v_mov_b32_e32 v228, v244
	v_mov_b32_e32 v229, v249
	v_pk_mul_f32 v[238:239], v[70:71], v[238:239]
	ds_write2_b64 v219, v[250:251], v[254:255] offset0:64 offset1:80
	v_pk_fma_f32 v[244:245], v[68:69], v[244:245], v[238:239] neg_lo:[0,0,1] neg_hi:[0,0,1]
	v_pk_fma_f32 v[228:229], v[68:69], v[228:229], v[238:239]
	s_nop 0
	v_mov_b32_e32 v245, v229
	v_pk_add_f32 v[228:229], v[108:109], v[110:111] neg_lo:[0,1] neg_hi:[0,1]
	ds_write2_b64 v219, v[246:247], v[244:245] offset0:96 offset1:112
	v_pk_mul_f32 v[238:239], v[18:19], v[228:229] op_sel:[0,1] op_sel_hi:[1,0]
	s_nop 0
	v_pk_fma_f32 v[244:245], v[16:17], v[228:229], v[238:239] neg_lo:[0,0,1] neg_hi:[0,0,1]
	v_pk_fma_f32 v[228:229], v[16:17], v[228:229], v[238:239]
	s_nop 0
	v_mov_b32_e32 v245, v229
	v_pk_add_f32 v[228:229], v[114:115], v[116:117] neg_lo:[0,1] neg_hi:[0,1]
	s_nop 0
	v_pk_mul_f32 v[238:239], v[30:31], v[228:229] op_sel:[0,1] op_sel_hi:[1,0]
	s_nop 0
	v_pk_fma_f32 v[246:247], v[28:29], v[228:229], v[238:239] neg_lo:[0,0,1] neg_hi:[0,0,1]
	v_pk_fma_f32 v[228:229], v[28:29], v[228:229], v[238:239]
	s_nop 0
	v_mov_b32_e32 v247, v229
	v_pk_add_f32 v[228:229], v[120:121], v[122:123] neg_lo:[0,1] neg_hi:[0,1]
	s_nop 0
	v_pk_mul_f32 v[238:239], v[42:43], v[228:229] op_sel:[0,1] op_sel_hi:[1,0]
	s_nop 0
	v_pk_fma_f32 v[248:249], v[40:41], v[228:229], v[238:239] neg_lo:[0,0,1] neg_hi:[0,0,1]
	v_pk_fma_f32 v[228:229], v[40:41], v[228:229], v[238:239]
	s_nop 0
	v_mov_b32_e32 v249, v229
	v_pk_add_f32 v[228:229], v[126:127], v[128:129] neg_lo:[0,1] neg_hi:[0,1]
	s_nop 0
	v_pk_mul_f32 v[238:239], v[54:55], v[228:229] op_sel:[0,1] op_sel_hi:[1,0]
	s_nop 0
	v_pk_fma_f32 v[250:251], v[52:53], v[228:229], v[238:239] neg_lo:[0,0,1] neg_hi:[0,0,1]
	v_pk_fma_f32 v[228:229], v[52:53], v[228:229], v[238:239]
	s_nop 0
	v_mov_b32_e32 v251, v229
	v_pk_add_f32 v[228:229], v[244:245], v[248:249]
	v_pk_add_f32 v[238:239], v[246:247], v[250:251]
	v_pk_add_f32 v[244:245], v[244:245], v[248:249] neg_lo:[0,1] neg_hi:[0,1]
	v_pk_add_f32 v[246:247], v[246:247], v[250:251] neg_lo:[0,1] neg_hi:[0,1]
	v_pk_add_f32 v[252:253], v[228:229], v[238:239]
	v_pk_add_f32 v[248:249], v[244:245], v[246:247] op_sel:[0,1] op_sel_hi:[1,0]
	v_pk_add_f32 v[244:245], v[244:245], v[246:247] op_sel:[0,1] op_sel_hi:[1,0] neg_lo:[0,1] neg_hi:[0,1]
	v_mov_b32_e32 v246, v248
	v_pk_mov_b32 v[250:251], v[244:245], v[248:249] op_sel:[1,0]
	v_mov_b32_e32 v247, v245
	v_pk_mul_f32 v[250:251], v[58:59], v[250:251]
	v_pk_add_f32 v[228:229], v[228:229], v[238:239] neg_lo:[0,1] neg_hi:[0,1]
	v_pk_fma_f32 v[254:255], v[60:61], v[248:249], v[250:251]
	v_pk_fma_f32 v[246:247], v[60:61], v[246:247], v[250:251] neg_lo:[0,0,1] neg_hi:[0,0,1]
	v_pk_mul_f32 v[238:239], v[66:67], v[228:229]
	v_mov_b32_e32 v255, v247
	v_pk_fma_f32 v[246:247], v[64:65], v[228:229], v[238:239] op_sel:[0,0,1] op_sel_hi:[1,1,0] neg_lo:[0,0,1] neg_hi:[0,0,1]
	v_pk_fma_f32 v[228:229], v[64:65], v[228:229], v[238:239] op_sel:[0,0,1] op_sel_hi:[1,1,0]
	v_pk_mov_b32 v[238:239], v[248:249], v[244:245] op_sel:[1,0]
; DI float2 twid(float r) { return float2{__builtin_amdgcn_cosf(r), -__builtin_amdgcn_sinf(r)}; }
; DI void bfly_fwd(float2 a0, float2 a1, float2 a2, float2 a3, float r, float2& o0, float2& o1, float2& o2, float2& o3) {
;   float2 t0 = {a0.x + a2.x, a0.y + a2.y}, t1 = {a0.x - a2.x, a0.y - a2.y}, t2 = {a1.x + a3.x, a1.y + a3.y}, t3 = {a1.x - a3.x, a1.y - a3.y};
;   float2 b0 = {t0.x + t2.x, t0.y + t2.y}, b2 = {t0.x - t2.x, t0.y - t2.y}, b1 = {t1.x + t3.y, t1.y - t3.x}, b3 = {t1.x - t3.y, t1.y + t3.x};
;   float2 w1 = twid(r), w2 = cmul(w1, w1), w3 = cmul(w2, w1);
;   o0 = b0; o1 = cmul(b1, w1); o2 = cmul(b2, w2); o3 = cmul(b3, w3);
; }
;     ...
;   for (int gg = tid; gg < NBT * (N / 16); gg += NTHR) { const int g = gg & (N / 16 - 1); float2* z = z0 + (gg / (N / 16)) * N; const int jp = g & (Q2 - 1), base = ((g >> lq2) << (lq2 + 4)) + jp; float2 x[4][4];
; #pragma unroll
;     for (int q1 = 0; q1 < 4; ++q1)
; #pragma unroll
;       for (int q2 = 0; q2 < 4; ++q2) x[q1][q2] = z[base + q1 * Q1 + q2 * Q2];
; #pragma unroll
;     for (int q2 = 0; q2 < 4; ++q2) bfly_fwd(x[0][q2], x[1][q2], x[2][q2], x[3][q2], (float)(jp + q2 * Q2) * invM1, x[0][q2], x[1][q2], x[2][q2], x[3][q2]);
; #pragma unroll
;     for (int q1 = 0; q1 < 4; ++q1) bfly_fwd(x[q1][0], x[q1][1], x[q1][2], x[q1][3], (float)jp * invM2, x[q1][0], x[q1][1], x[q1][2], x[q1][3]);
; #pragma unroll
;     for (int q1 = 0; q1 < 4; ++q1)
; #pragma unroll
;       for (int q2 = 0; q2 < 4; ++q2) z[base + q1 * Q1 + q2 * Q2] = x[q1][q2]; }
	v_mov_b32_e32 v247, v229
	v_mov_b32_e32 v228, v244
	v_mov_b32_e32 v229, v249
	v_pk_mul_f32 v[238:239], v[70:71], v[238:239]
	ds_write2_b64 v219, v[252:253], v[254:255] offset0:128 offset1:144
	v_pk_fma_f32 v[244:245], v[68:69], v[244:245], v[238:239] neg_lo:[0,0,1] neg_hi:[0,0,1]
	v_pk_fma_f32 v[228:229], v[68:69], v[228:229], v[238:239]
	s_nop 0
	v_mov_b32_e32 v245, v229
	v_mov_b32_e32 v229, v237
	v_pk_mov_b32 v[236:237], v[236:237], v[220:221] op_sel:[1,0]
	v_mov_b32_e32 v228, v220
	v_pk_mul_f32 v[236:237], v[26:27], v[236:237]
	ds_write2_b64 v219, v[246:247], v[244:245] offset0:160 offset1:176
	v_pk_fma_f32 v[220:221], v[20:21], v[220:221], v[236:237] neg_lo:[0,0,1] neg_hi:[0,0,1]
	v_pk_fma_f32 v[228:229], v[20:21], v[228:229], v[236:237]
	s_nop 0
	v_mov_b32_e32 v221, v229
	v_mov_b32_e32 v229, v231
	v_pk_mov_b32 v[230:231], v[230:231], v[222:223] op_sel:[1,0]
	v_mov_b32_e32 v228, v222
	v_pk_mul_f32 v[230:231], v[38:39], v[230:231]
	s_nop 0
	v_pk_fma_f32 v[222:223], v[32:33], v[222:223], v[230:231] neg_lo:[0,0,1] neg_hi:[0,0,1]
	v_pk_fma_f32 v[228:229], v[32:33], v[228:229], v[230:231]
	v_pk_mov_b32 v[230:231], v[232:233], v[224:225] op_sel:[1,0]
	v_mov_b32_e32 v223, v229
	v_mov_b32_e32 v228, v224
	v_mov_b32_e32 v229, v233
	v_pk_mul_f32 v[230:231], v[50:51], v[230:231]
	s_nop 0
	v_pk_fma_f32 v[224:225], v[44:45], v[224:225], v[230:231] neg_lo:[0,0,1] neg_hi:[0,0,1]
	v_pk_fma_f32 v[228:229], v[44:45], v[228:229], v[230:231]
	v_pk_mov_b32 v[230:231], v[234:235], v[226:227] op_sel:[1,0]
	v_mov_b32_e32 v225, v229
	v_mov_b32_e32 v228, v226
	v_mov_b32_e32 v229, v235
	v_pk_mul_f32 v[230:231], v[62:63], v[230:231]
	s_nop 0
	v_pk_fma_f32 v[226:227], v[56:57], v[226:227], v[230:231] neg_lo:[0,0,1] neg_hi:[0,0,1]
	v_pk_fma_f32 v[228:229], v[56:57], v[228:229], v[230:231]
	s_nop 0
	v_mov_b32_e32 v227, v229
	v_pk_add_f32 v[228:229], v[220:221], v[224:225]
	v_pk_add_f32 v[230:231], v[222:223], v[226:227]
	v_pk_add_f32 v[220:221], v[220:221], v[224:225] neg_lo:[0,1] neg_hi:[0,1]
	v_pk_add_f32 v[222:223], v[222:223], v[226:227] neg_lo:[0,1] neg_hi:[0,1]
	v_pk_add_f32 v[232:233], v[228:229], v[230:231]
	v_pk_add_f32 v[224:225], v[220:221], v[222:223] op_sel:[0,1] op_sel_hi:[1,0]
	v_pk_add_f32 v[220:221], v[220:221], v[222:223] op_sel:[0,1] op_sel_hi:[1,0] neg_lo:[0,1] neg_hi:[0,1]
	v_mov_b32_e32 v222, v224
	v_pk_mov_b32 v[226:227], v[220:221], v[224:225] op_sel:[1,0]
	v_mov_b32_e32 v223, v221
	v_pk_mul_f32 v[226:227], v[58:59], v[226:227]
	s_nop 0
	v_pk_fma_f32 v[234:235], v[60:61], v[224:225], v[226:227]
	v_pk_fma_f32 v[222:223], v[60:61], v[222:223], v[226:227] neg_lo:[0,0,1] neg_hi:[0,0,1]
	s_nop 0
	v_mov_b32_e32 v235, v223
	v_pk_add_f32 v[222:223], v[228:229], v[230:231] neg_lo:[0,1] neg_hi:[0,1]
	ds_write2_b64 v219, v[232:233], v[234:235] offset0:192 offset1:208
	v_pk_mul_f32 v[226:227], v[66:67], v[222:223]
	s_nop 0
	v_pk_fma_f32 v[228:229], v[64:65], v[222:223], v[226:227] op_sel:[0,0,1] op_sel_hi:[1,1,0] neg_lo:[0,0,1] neg_hi:[0,0,1]
	v_pk_fma_f32 v[222:223], v[64:65], v[222:223], v[226:227] op_sel:[0,0,1] op_sel_hi:[1,1,0]
	s_nop 0
	v_mov_b32_e32 v229, v223
	v_mov_b32_e32 v223, v225
	v_pk_mov_b32 v[224:225], v[224:225], v[220:221] op_sel:[1,0]
	v_mov_b32_e32 v222, v220
	v_pk_mul_f32 v[224:225], v[70:71], v[224:225]
	s_nop 0
	v_pk_fma_f32 v[220:221], v[68:69], v[220:221], v[224:225] neg_lo:[0,0,1] neg_hi:[0,0,1]
	v_pk_fma_f32 v[222:223], v[68:69], v[222:223], v[224:225]
	s_nop 0
	v_mov_b32_e32 v221, v223
	ds_write2_b64 v219, v[228:229], v[220:221] offset0:224 offset1:240
	s_nop 0
	v_add_u32_e32 v74, 0x200, v73
	s_nop 0
	v_mov_b32_e32 v73, v74

;   const int lq2 = lq1 - 2, Q1 = 1 << lq1, Q2 = 1 << lq2; const float invM1 = 1.f / (float)(4 << lq1), invM2 = 1.f / (float)(4 << lq2);
;   for (int gg = tid; gg < NBT * (N / 16); gg += NTHR) { const int g = gg & (N / 16 - 1); float2* z = z0 + (gg / (N / 16)) * N; const int jp = g & (Q2 - 1), base = ((g >> lq2) << (lq2 + 4)) + jp; float2 x[4][4];
; #pragma unroll
;     for (int q1 = 0; q1 < 4; ++q1)
; #pragma unroll
;       for (int q2 = 0; q2 < 4; ++q2) x[q1][q2] = z[base + q1 * Q1 + q2 * Q2];
; #pragma unroll
;     for (int q2 = 0; q2 < 4; ++q2) bfly_fwd(x[0][q2], x[1][q2], x[2][q2], x[3][q2], (float)(jp + q2 * Q2) * invM1, x[0][q2], x[1][q2], x[2][q2], x[3][q2]);
;   fft_pair_fwd<N, 2>(z, tid, 10); fft_pair_fwd<N, 2>(z, tid, 6); fft_level_fwd<N, 2>(z, tid, 2); fft_level_fwd<N, 2>(z, tid, 0); }
.LBB0_1598:
	s_or_b64 exec, exec, s[0:1]
	s_movk_i32 s0, 0x400
	v_cmp_gt_i32_e32 vcc, s0, v75
	s_movk_i32 s0, 0x100
	v_or_b32_sdwa v77, v75, s0 dst_sel:DWORD dst_unused:UNUSED_PAD src0_sel:BYTE_0 src1_sel:DWORD
	s_movk_i32 s0, 0x200
	v_lshlrev_b32_e32 v62, 7, v75
	v_cvt_f32_ubyte0_e32 v2, v75
	v_or_b32_sdwa v76, v75, s0 dst_sel:DWORD dst_unused:UNUSED_PAD src0_sel:BYTE_0 src1_sel:DWORD
	s_movk_i32 s0, 0x300
	v_and_b32_e32 v79, 0x8000, v62
	v_lshlrev_b32_sdwa v80, v151, v75 dst_sel:DWORD dst_unused:UNUSED_PAD src0_sel:DWORD src1_sel:BYTE_0
	v_mul_f32_e32 v78, 0x39800000, v2
	v_or_b32_sdwa v0, v75, s0 dst_sel:DWORD dst_unused:UNUSED_PAD src0_sel:BYTE_0 src1_sel:DWORD
	v_mul_f32_e32 v81, 0x3a800000, v2
	s_waitcnt lgkmcnt(0)
	s_barrier
	s_and_saveexec_b64 s[0:1], vcc
	s_cbranch_execz .LBB0_1601
	v_add3_u32 v63, 16, v79, v80
	v_mov_b32_e32 v64, v75
	v_ashrrev_i32_e32 v65, 31, v64
	v_lshrrev_b32_e32 v65, 23, v65
	v_add_lshl_u32 v65, v64, v65, 7
	v_and_b32_e32 v65, 0xffff0000, v65
	v_add_u32_e32 v65, v63, v65
	ds_read2st64_b64 v[66:69], v65 offset1:4
	ds_read2st64_b64 v[70:73], v65 offset0:8 offset1:12
	ds_read2st64_b64 v[82:85], v65 offset0:16 offset1:20
	ds_read2st64_b64 v[86:89], v65 offset0:24 offset1:28
	ds_read2st64_b64 v[90:93], v65 offset0:32 offset1:36
	ds_read2st64_b64 v[94:97], v65 offset0:40 offset1:44
	ds_read2st64_b64 v[98:101], v65 offset0:48 offset1:52
	ds_read2st64_b64 v[102:105], v65 offset0:56 offset1:60
	v_add_u32_e32 v218, 0x200, v64
	v_ashrrev_i32_e32 v219, 31, v218
	v_lshrrev_b32_e32 v219, 23, v219
	v_add_lshl_u32 v219, v218, v219, 7
	v_and_b32_e32 v219, 0xffff0000, v219
	v_add_u32_e32 v219, v63, v219
	ds_read2st64_b64 v[220:223], v219 offset1:4
	ds_read2st64_b64 v[224:227], v219 offset0:8 offset1:12
	ds_read2st64_b64 v[228:231], v219 offset0:16 offset1:20
	ds_read2st64_b64 v[232:235], v219 offset0:24 offset1:28
	ds_read2st64_b64 v[236:239], v219 offset0:32 offset1:36
	ds_read2st64_b64 v[244:247], v219 offset0:40 offset1:44
	ds_read2st64_b64 v[248:251], v219 offset0:48 offset1:52
	ds_read2st64_b64 v[252:255], v219 offset0:56 offset1:60
	v_sin_f32_e32 v2, v78
	v_cos_f32_e32 v4, v78
	v_sin_f32_e32 v48, v81
	v_cos_f32_e32 v50, v81
	v_mul_f32_e32 v3, v2, v2
	v_fma_f32 v6, v4, v4, -v3
	v_cvt_f32_u32_e32 v3, v77
	v_mul_f32_e64 v5, v4, -v2
	v_add_f32_e32 v8, v5, v5
	v_cvt_f32_u32_e32 v5, v76
	v_mul_f32_e32 v3, 0x39800000, v3
	v_sin_f32_e32 v12, v3
	v_cos_f32_e32 v14, v3
	v_mul_f32_e32 v3, v2, v6
	v_fma_f32 v16, v4, v8, -v3
	v_mul_f32_e32 v3, v12, v12
	v_fma_f32 v18, v14, v14, -v3
	v_mul_f32_e64 v3, v14, -v12
	v_add_f32_e32 v20, v3, v3
	v_mul_f32_e32 v3, 0x39800000, v5
	v_sin_f32_e32 v24, v3
	v_cos_f32_e32 v26, v3
	v_cvt_f32_u32_e32 v5, v0
	v_mul_f32_e32 v3, v12, v18
	v_fma_f32 v28, v14, v20, -v3
	v_mul_f32_e32 v3, v24, v24
	v_fma_f32 v30, v26, v26, -v3
	v_mul_f32_e64 v3, v26, -v24
	v_add_f32_e32 v32, v3, v3
	v_mul_f32_e32 v3, 0x39800000, v5
	v_sin_f32_e32 v36, v3
	v_cos_f32_e32 v38, v3
	v_mul_f32_e32 v3, v24, v30
	v_fma_f32 v40, v26, v32, -v3
	v_mul_f32_e32 v3, v36, v36
	v_fma_f32 v42, v38, v38, -v3
	v_mul_f32_e64 v3, v38, -v36
	v_add_f32_e32 v44, v3, v3
	v_mul_f32_e32 v3, v36, v42
	v_fma_f32 v52, v38, v44, -v3
	v_mul_f32_e32 v3, v48, v48
	v_fma_f32 v54, v50, v50, -v3
	v_mul_f32_e64 v3, v50, -v48
	v_add_f32_e32 v56, v3, v3
	v_mul_f32_e32 v10, v2, v8
	v_mul_f32_e32 v22, v12, v20
	v_mul_f32_e32 v34, v24, v32
	v_mul_f32_e32 v46, v36, v44
	v_mul_f32_e32 v58, v48, v56
	v_mul_f32_e32 v3, v48, v54
	v_fmac_f32_e32 v10, v4, v6
	v_fmac_f32_e32 v22, v14, v18
	v_fmac_f32_e32 v34, v26, v30
	v_fmac_f32_e32 v46, v38, v42
	v_fmac_f32_e32 v58, v50, v54
	v_fma_f32 v60, v50, v56, -v3
	v_mov_b32_e32 v51, v50
	v_mov_b32_e32 v49, v48
	v_mov_b32_e32 v55, v54
	v_mov_b32_e32 v57, v56
	v_mov_b32_e32 v59, v58
	v_mov_b32_e32 v61, v60
	v_mov_b32_e32 v5, v4
	v_mov_b32_e32 v3, v2
	v_mov_b32_e32 v27, v26
	v_mov_b32_e32 v25, v24
	v_mov_b32_e32 v15, v14
	v_mov_b32_e32 v13, v12
	v_mov_b32_e32 v39, v38
	v_mov_b32_e32 v37, v36
	v_mov_b32_e32 v7, v6
	v_mov_b32_e32 v31, v30
	v_mov_b32_e32 v19, v18
	v_mov_b32_e32 v43, v42
	v_mov_b32_e32 v11, v10
	v_mov_b32_e32 v17, v16
	v_mov_b32_e32 v35, v34
	v_mov_b32_e32 v41, v40
	v_mov_b32_e32 v23, v22
	v_mov_b32_e32 v29, v28
	v_mov_b32_e32 v47, v46
	v_mov_b32_e32 v53, v52
	v_mov_b32_e32 v9, v8
	v_mov_b32_e32 v21, v20
	v_mov_b32_e32 v33, v32
	v_mov_b32_e32 v45, v44
	s_mov_b64 s[80:81], 0
	s_nop 0
	s_waitcnt lgkmcnt(11)
	v_pk_add_f32 v[106:107], v[66:67], v[90:91]
	v_pk_add_f32 v[112:113], v[68:69], v[92:93]
	s_waitcnt lgkmcnt(9)
	v_pk_add_f32 v[108:109], v[82:83], v[98:99]
	v_pk_add_f32 v[114:115], v[84:85], v[100:101]
	v_pk_add_f32 v[118:119], v[70:71], v[94:95]
	s_waitcnt lgkmcnt(8)
; DI float2 twid(float r) { return float2{__builtin_amdgcn_cosf(r), -__builtin_amdgcn_sinf(r)}; }
; DI void bfly_fwd(float2 a0, float2 a1, float2 a2, float2 a3, float r, float2& o0, float2& o1, float2& o2, float2& o3) {
;   float2 t0 = {a0.x + a2.x, a0.y + a2.y}, t1 = {a0.x - a2.x, a0.y - a2.y}, t2 = {a1.x + a3.x, a1.y + a3.y}, t3 = {a1.x - a3.x, a1.y - a3.y};
;   float2 b0 = {t0.x + t2.x, t0.y + t2.y}, b2 = {t0.x - t2.x, t0.y - t2.y}, b1 = {t1.x + t3.y, t1.y - t3.x}, b3 = {t1.x - t3.y, t1.y + t3.x};
;   float2 w1 = twid(r), w2 = cmul(w1, w1), w3 = cmul(w2, w1);
;   o0 = b0; o1 = cmul(b1, w1); o2 = cmul(b2, w2); o3 = cmul(b3, w3);
; }
;     ...
;   for (int gg = tid; gg < NBT * (N / 16); gg += NTHR) { const int g = gg & (N / 16 - 1); float2* z = z0 + (gg / (N / 16)) * N; const int jp = g & (Q2 - 1), base = ((g >> lq2) << (lq2 + 4)) + jp; float2 x[4][4];
; #pragma unroll
;     for (int q1 = 0; q1 < 4; ++q1)
; #pragma unroll
;       for (int q2 = 0; q2 < 4; ++q2) x[q1][q2] = z[base + q1 * Q1 + q2 * Q2];
; #pragma unroll
;     for (int q2 = 0; q2 < 4; ++q2) bfly_fwd(x[0][q2], x[1][q2], x[2][q2], x[3][q2], (float)(jp + q2 * Q2) * invM1, x[0][q2], x[1][q2], x[2][q2], x[3][q2]);
; #pragma unroll
;     for (int q1 = 0; q1 < 4; ++q1) bfly_fwd(x[q1][0], x[q1][1], x[q1][2], x[q1][3], (float)jp * invM2, x[q1][0], x[q1][1], x[q1][2], x[q1][3]);
; #pragma unroll
;     for (int q1 = 0; q1 < 4; ++q1)
; #pragma unroll
;       for (int q2 = 0; q2 < 4; ++q2) z[base + q1 * Q1 + q2 * Q2] = x[q1][q2]; }
	v_pk_add_f32 v[120:121], v[86:87], v[102:103]
	v_pk_add_f32 v[124:125], v[72:73], v[96:97]
	v_pk_add_f32 v[126:127], v[88:89], v[104:105]
	v_pk_add_f32 v[110:111], v[106:107], v[108:109]
	v_pk_add_f32 v[116:117], v[112:113], v[114:115]
	v_pk_add_f32 v[122:123], v[118:119], v[120:121]
	v_pk_add_f32 v[128:129], v[124:125], v[126:127]
	v_pk_add_f32 v[130:131], v[110:111], v[122:123]
	v_pk_add_f32 v[132:133], v[116:117], v[128:129]
	v_pk_add_f32 v[110:111], v[110:111], v[122:123] neg_lo:[0,1] neg_hi:[0,1]
	v_pk_add_f32 v[116:117], v[116:117], v[128:129] neg_lo:[0,1] neg_hi:[0,1]
	v_pk_add_f32 v[134:135], v[130:131], v[132:133]
	v_pk_add_f32 v[122:123], v[110:111], v[116:117] op_sel:[0,1] op_sel_hi:[1,0]
	v_pk_add_f32 v[110:111], v[110:111], v[116:117] op_sel:[0,1] op_sel_hi:[1,0] neg_lo:[0,1] neg_hi:[0,1]
	v_mov_b32_e32 v116, v122
	v_pk_mov_b32 v[128:129], v[110:111], v[122:123] op_sel:[1,0]
	v_mov_b32_e32 v117, v111
	v_pk_mul_f32 v[128:129], v[48:49], v[128:129]
	v_pk_add_f32 v[66:67], v[66:67], v[90:91] neg_lo:[0,1] neg_hi:[0,1]
	v_pk_fma_f32 v[136:137], v[50:51], v[122:123], v[128:129]
	v_pk_fma_f32 v[116:117], v[50:51], v[116:117], v[128:129] neg_lo:[0,0,1] neg_hi:[0,0,1]
	v_pk_add_f32 v[82:83], v[82:83], v[98:99] neg_lo:[0,1] neg_hi:[0,1]
	v_mov_b32_e32 v137, v117
	v_pk_add_f32 v[116:117], v[130:131], v[132:133] neg_lo:[0,1] neg_hi:[0,1]
	v_pk_add_f32 v[90:91], v[66:67], v[82:83] op_sel:[0,1] op_sel_hi:[1,0]
	v_pk_mul_f32 v[128:129], v[56:57], v[116:117]
	v_pk_add_f32 v[66:67], v[66:67], v[82:83] op_sel:[0,1] op_sel_hi:[1,0] neg_lo:[0,1] neg_hi:[0,1]
	v_pk_fma_f32 v[130:131], v[54:55], v[116:117], v[128:129] op_sel:[0,0,1] op_sel_hi:[1,1,0] neg_lo:[0,0,1] neg_hi:[0,0,1]
	v_pk_fma_f32 v[116:117], v[54:55], v[116:117], v[128:129] op_sel:[0,0,1] op_sel_hi:[1,1,0]
	v_pk_mov_b32 v[98:99], v[66:67], v[90:91] op_sel:[1,0]
	v_mov_b32_e32 v131, v117
	v_mov_b32_e32 v117, v123
	v_pk_mov_b32 v[122:123], v[122:123], v[110:111] op_sel:[1,0]
	v_mov_b32_e32 v116, v110
	v_pk_mul_f32 v[122:123], v[60:61], v[122:123]
	v_mov_b32_e32 v82, v90
	v_pk_fma_f32 v[110:111], v[58:59], v[110:111], v[122:123] neg_lo:[0,0,1] neg_hi:[0,0,1]
	v_pk_fma_f32 v[116:117], v[58:59], v[116:117], v[122:123]
	v_mov_b32_e32 v83, v67
	v_mov_b32_e32 v111, v117
	v_pk_mul_f32 v[98:99], v[2:3], v[98:99]
	ds_write2st64_b64 v65, v[130:131], v[110:111] offset0:8 offset1:12
	v_pk_fma_f32 v[110:111], v[4:5], v[90:91], v[98:99]
	v_pk_fma_f32 v[82:83], v[4:5], v[82:83], v[98:99] neg_lo:[0,0,1] neg_hi:[0,0,1]
	v_pk_add_f32 v[68:69], v[68:69], v[92:93] neg_lo:[0,1] neg_hi:[0,1]
	v_mov_b32_e32 v111, v83
	v_pk_add_f32 v[82:83], v[84:85], v[100:101] neg_lo:[0,1] neg_hi:[0,1]
	v_pk_add_f32 v[70:71], v[70:71], v[94:95] neg_lo:[0,1] neg_hi:[0,1]
	v_pk_add_f32 v[84:85], v[68:69], v[82:83] op_sel:[0,1] op_sel_hi:[1,0]
	v_pk_add_f32 v[68:69], v[68:69], v[82:83] op_sel:[0,1] op_sel_hi:[1,0] neg_lo:[0,1] neg_hi:[0,1]
	v_mov_b32_e32 v82, v84
	v_pk_mov_b32 v[92:93], v[68:69], v[84:85] op_sel:[1,0]
	v_mov_b32_e32 v83, v69
	v_pk_mul_f32 v[92:93], v[12:13], v[92:93]
	v_pk_add_f32 v[72:73], v[72:73], v[96:97] neg_lo:[0,1] neg_hi:[0,1]
	v_pk_fma_f32 v[98:99], v[14:15], v[84:85], v[92:93]
	v_pk_fma_f32 v[82:83], v[14:15], v[82:83], v[92:93] neg_lo:[0,0,1] neg_hi:[0,0,1]
	ds_write2st64_b64 v65, v[134:135], v[136:137] offset1:4
	v_mov_b32_e32 v99, v83
	v_pk_add_f32 v[82:83], v[86:87], v[102:103] neg_lo:[0,1] neg_hi:[0,1]
	s_nop 0
	v_pk_add_f32 v[86:87], v[70:71], v[82:83] op_sel:[0,1] op_sel_hi:[1,0]
	v_pk_add_f32 v[70:71], v[70:71], v[82:83] op_sel:[0,1] op_sel_hi:[1,0] neg_lo:[0,1] neg_hi:[0,1]
	v_mov_b32_e32 v82, v86
	v_pk_mov_b32 v[92:93], v[70:71], v[86:87] op_sel:[1,0]
	v_mov_b32_e32 v83, v71
	v_pk_mul_f32 v[92:93], v[24:25], v[92:93]
	s_nop 0
	v_pk_fma_f32 v[94:95], v[26:27], v[86:87], v[92:93]
	v_pk_fma_f32 v[82:83], v[26:27], v[82:83], v[92:93] neg_lo:[0,0,1] neg_hi:[0,0,1]
	s_nop 0
	v_mov_b32_e32 v95, v83
	v_pk_add_f32 v[82:83], v[88:89], v[104:105] neg_lo:[0,1] neg_hi:[0,1]
	s_nop 0
	v_pk_add_f32 v[88:89], v[72:73], v[82:83] op_sel:[0,1] op_sel_hi:[1,0]
	v_pk_add_f32 v[72:73], v[72:73], v[82:83] op_sel:[0,1] op_sel_hi:[1,0] neg_lo:[0,1] neg_hi:[0,1]
	v_mov_b32_e32 v82, v88
	v_pk_mov_b32 v[92:93], v[72:73], v[88:89] op_sel:[1,0]
	v_mov_b32_e32 v83, v73
	v_pk_mul_f32 v[92:93], v[36:37], v[92:93]
	s_nop 0
	v_pk_fma_f32 v[96:97], v[38:39], v[88:89], v[92:93]
	v_pk_fma_f32 v[82:83], v[38:39], v[82:83], v[92:93] neg_lo:[0,0,1] neg_hi:[0,0,1]
	s_nop 0
	v_mov_b32_e32 v97, v83
	v_pk_add_f32 v[82:83], v[110:111], v[94:95]
	v_pk_add_f32 v[92:93], v[98:99], v[96:97]
	v_pk_add_f32 v[94:95], v[110:111], v[94:95] neg_lo:[0,1] neg_hi:[0,1]
	v_pk_add_f32 v[96:97], v[98:99], v[96:97] neg_lo:[0,1] neg_hi:[0,1]
	v_pk_add_f32 v[100:101], v[82:83], v[92:93]
	v_pk_add_f32 v[98:99], v[94:95], v[96:97] op_sel:[0,1] op_sel_hi:[1,0]
	v_pk_add_f32 v[94:95], v[94:95], v[96:97] op_sel:[0,1] op_sel_hi:[1,0] neg_lo:[0,1] neg_hi:[0,1]
	v_mov_b32_e32 v96, v98
	v_pk_mov_b32 v[102:103], v[94:95], v[98:99] op_sel:[1,0]
	v_mov_b32_e32 v97, v95
	v_pk_mul_f32 v[102:103], v[48:49], v[102:103]
	v_pk_add_f32 v[82:83], v[82:83], v[92:93] neg_lo:[0,1] neg_hi:[0,1]
	v_pk_fma_f32 v[104:105], v[50:51], v[98:99], v[102:103]
	v_pk_fma_f32 v[96:97], v[50:51], v[96:97], v[102:103] neg_lo:[0,0,1] neg_hi:[0,0,1]
	v_pk_mul_f32 v[92:93], v[56:57], v[82:83]
	v_mov_b32_e32 v105, v97
	v_pk_fma_f32 v[96:97], v[54:55], v[82:83], v[92:93] op_sel:[0,0,1] op_sel_hi:[1,1,0] neg_lo:[0,0,1] neg_hi:[0,0,1]
	v_pk_fma_f32 v[82:83], v[54:55], v[82:83], v[92:93] op_sel:[0,0,1] op_sel_hi:[1,1,0]
	v_pk_mov_b32 v[92:93], v[98:99], v[94:95] op_sel:[1,0]
	v_mov_b32_e32 v97, v83
; DI float2 twid(float r) { return float2{__builtin_amdgcn_cosf(r), -__builtin_amdgcn_sinf(r)}; }
; DI void bfly_fwd(float2 a0, float2 a1, float2 a2, float2 a3, float r, float2& o0, float2& o1, float2& o2, float2& o3) {
;   float2 t0 = {a0.x + a2.x, a0.y + a2.y}, t1 = {a0.x - a2.x, a0.y - a2.y}, t2 = {a1.x + a3.x, a1.y + a3.y}, t3 = {a1.x - a3.x, a1.y - a3.y};
;   float2 b0 = {t0.x + t2.x, t0.y + t2.y}, b2 = {t0.x - t2.x, t0.y - t2.y}, b1 = {t1.x + t3.y, t1.y - t3.x}, b3 = {t1.x - t3.y, t1.y + t3.x};
;   float2 w1 = twid(r), w2 = cmul(w1, w1), w3 = cmul(w2, w1);
;   o0 = b0; o1 = cmul(b1, w1); o2 = cmul(b2, w2); o3 = cmul(b3, w3);
; }
;     ...
;   for (int gg = tid; gg < NBT * (N / 16); gg += NTHR) { const int g = gg & (N / 16 - 1); float2* z = z0 + (gg / (N / 16)) * N; const int jp = g & (Q2 - 1), base = ((g >> lq2) << (lq2 + 4)) + jp; float2 x[4][4];
; #pragma unroll
;     for (int q1 = 0; q1 < 4; ++q1)
; #pragma unroll
;       for (int q2 = 0; q2 < 4; ++q2) x[q1][q2] = z[base + q1 * Q1 + q2 * Q2];
; #pragma unroll
;     for (int q2 = 0; q2 < 4; ++q2) bfly_fwd(x[0][q2], x[1][q2], x[2][q2], x[3][q2], (float)(jp + q2 * Q2) * invM1, x[0][q2], x[1][q2], x[2][q2], x[3][q2]);
; #pragma unroll
;     for (int q1 = 0; q1 < 4; ++q1) bfly_fwd(x[q1][0], x[q1][1], x[q1][2], x[q1][3], (float)jp * invM2, x[q1][0], x[q1][1], x[q1][2], x[q1][3]);
; #pragma unroll
;     for (int q1 = 0; q1 < 4; ++q1)
; #pragma unroll
;       for (int q2 = 0; q2 < 4; ++q2) z[base + q1 * Q1 + q2 * Q2] = x[q1][q2]; }
	v_mov_b32_e32 v82, v94
	v_mov_b32_e32 v83, v99
	v_pk_mul_f32 v[92:93], v[60:61], v[92:93]
	ds_write2st64_b64 v65, v[100:101], v[104:105] offset0:16 offset1:20
	v_pk_fma_f32 v[94:95], v[58:59], v[94:95], v[92:93] neg_lo:[0,0,1] neg_hi:[0,0,1]
	v_pk_fma_f32 v[82:83], v[58:59], v[82:83], v[92:93]
	s_nop 0
	v_mov_b32_e32 v95, v83
	v_pk_add_f32 v[82:83], v[106:107], v[108:109] neg_lo:[0,1] neg_hi:[0,1]
	ds_write2st64_b64 v65, v[96:97], v[94:95] offset0:24 offset1:28
	v_pk_mul_f32 v[92:93], v[8:9], v[82:83] op_sel:[0,1] op_sel_hi:[1,0]
	s_nop 0
	v_pk_fma_f32 v[94:95], v[6:7], v[82:83], v[92:93] neg_lo:[0,0,1] neg_hi:[0,0,1]
	v_pk_fma_f32 v[82:83], v[6:7], v[82:83], v[92:93]
	s_nop 0
	v_mov_b32_e32 v95, v83
	v_pk_add_f32 v[82:83], v[112:113], v[114:115] neg_lo:[0,1] neg_hi:[0,1]
	s_nop 0
	v_pk_mul_f32 v[92:93], v[20:21], v[82:83] op_sel:[0,1] op_sel_hi:[1,0]
	s_nop 0
	v_pk_fma_f32 v[96:97], v[18:19], v[82:83], v[92:93] neg_lo:[0,0,1] neg_hi:[0,0,1]
	v_pk_fma_f32 v[82:83], v[18:19], v[82:83], v[92:93]
	s_nop 0
	v_mov_b32_e32 v97, v83
	v_pk_add_f32 v[82:83], v[118:119], v[120:121] neg_lo:[0,1] neg_hi:[0,1]
	s_nop 0
	v_pk_mul_f32 v[92:93], v[32:33], v[82:83] op_sel:[0,1] op_sel_hi:[1,0]
	s_nop 0
	v_pk_fma_f32 v[98:99], v[30:31], v[82:83], v[92:93] neg_lo:[0,0,1] neg_hi:[0,0,1]
	v_pk_fma_f32 v[82:83], v[30:31], v[82:83], v[92:93]
	s_nop 0
	v_mov_b32_e32 v99, v83
	v_pk_add_f32 v[82:83], v[124:125], v[126:127] neg_lo:[0,1] neg_hi:[0,1]
	s_nop 0
	v_pk_mul_f32 v[92:93], v[44:45], v[82:83] op_sel:[0,1] op_sel_hi:[1,0]
	s_nop 0
	v_pk_fma_f32 v[100:101], v[42:43], v[82:83], v[92:93] neg_lo:[0,0,1] neg_hi:[0,0,1]
	v_pk_fma_f32 v[82:83], v[42:43], v[82:83], v[92:93]
	s_nop 0
	v_mov_b32_e32 v101, v83
	v_pk_add_f32 v[82:83], v[94:95], v[98:99]
	v_pk_add_f32 v[92:93], v[96:97], v[100:101]
	v_pk_add_f32 v[94:95], v[94:95], v[98:99] neg_lo:[0,1] neg_hi:[0,1]
	v_pk_add_f32 v[96:97], v[96:97], v[100:101] neg_lo:[0,1] neg_hi:[0,1]
	v_pk_add_f32 v[102:103], v[82:83], v[92:93]
	v_pk_add_f32 v[98:99], v[94:95], v[96:97] op_sel:[0,1] op_sel_hi:[1,0]
	v_pk_add_f32 v[94:95], v[94:95], v[96:97] op_sel:[0,1] op_sel_hi:[1,0] neg_lo:[0,1] neg_hi:[0,1]
	v_mov_b32_e32 v96, v98
	v_pk_mov_b32 v[100:101], v[94:95], v[98:99] op_sel:[1,0]
	v_mov_b32_e32 v97, v95
	v_pk_mul_f32 v[100:101], v[48:49], v[100:101]
	v_pk_add_f32 v[82:83], v[82:83], v[92:93] neg_lo:[0,1] neg_hi:[0,1]
	v_pk_fma_f32 v[104:105], v[50:51], v[98:99], v[100:101]
	v_pk_fma_f32 v[96:97], v[50:51], v[96:97], v[100:101] neg_lo:[0,0,1] neg_hi:[0,0,1]
	v_pk_mul_f32 v[92:93], v[56:57], v[82:83]
	v_mov_b32_e32 v105, v97
	v_pk_fma_f32 v[96:97], v[54:55], v[82:83], v[92:93] op_sel:[0,0,1] op_sel_hi:[1,1,0] neg_lo:[0,0,1] neg_hi:[0,0,1]
	v_pk_fma_f32 v[82:83], v[54:55], v[82:83], v[92:93] op_sel:[0,0,1] op_sel_hi:[1,1,0]
	v_pk_mov_b32 v[92:93], v[98:99], v[94:95] op_sel:[1,0]
	v_mov_b32_e32 v97, v83
	v_mov_b32_e32 v82, v94
	v_mov_b32_e32 v83, v99
	v_pk_mul_f32 v[92:93], v[60:61], v[92:93]
	ds_write2st64_b64 v65, v[102:103], v[104:105] offset0:32 offset1:36
	v_pk_fma_f32 v[94:95], v[58:59], v[94:95], v[92:93] neg_lo:[0,0,1] neg_hi:[0,0,1]
	v_pk_fma_f32 v[82:83], v[58:59], v[82:83], v[92:93]
	s_nop 0
	v_mov_b32_e32 v95, v83
	v_mov_b32_e32 v83, v91
	v_pk_mov_b32 v[90:91], v[90:91], v[66:67] op_sel:[1,0]
	v_mov_b32_e32 v82, v66
	v_pk_mul_f32 v[90:91], v[16:17], v[90:91]
	ds_write2st64_b64 v65, v[96:97], v[94:95] offset0:40 offset1:44
	v_pk_fma_f32 v[66:67], v[10:11], v[66:67], v[90:91] neg_lo:[0,0,1] neg_hi:[0,0,1]
	v_pk_fma_f32 v[82:83], v[10:11], v[82:83], v[90:91]
	s_nop 0
	v_mov_b32_e32 v67, v83
	v_mov_b32_e32 v83, v85
	v_pk_mov_b32 v[84:85], v[84:85], v[68:69] op_sel:[1,0]
	v_mov_b32_e32 v82, v68
	v_pk_mul_f32 v[84:85], v[28:29], v[84:85]
	s_nop 0
	v_pk_fma_f32 v[68:69], v[22:23], v[68:69], v[84:85] neg_lo:[0,0,1] neg_hi:[0,0,1]
	v_pk_fma_f32 v[82:83], v[22:23], v[82:83], v[84:85]
	v_pk_mov_b32 v[84:85], v[86:87], v[70:71] op_sel:[1,0]
	v_mov_b32_e32 v69, v83
	v_mov_b32_e32 v82, v70
	v_mov_b32_e32 v83, v87
	v_pk_mul_f32 v[84:85], v[40:41], v[84:85]
	s_nop 0
	v_pk_fma_f32 v[70:71], v[34:35], v[70:71], v[84:85] neg_lo:[0,0,1] neg_hi:[0,0,1]
	v_pk_fma_f32 v[82:83], v[34:35], v[82:83], v[84:85]
	v_pk_mov_b32 v[84:85], v[88:89], v[72:73] op_sel:[1,0]
	v_mov_b32_e32 v71, v83
	v_mov_b32_e32 v82, v72
	v_mov_b32_e32 v83, v89
	v_pk_mul_f32 v[84:85], v[52:53], v[84:85]
	s_nop 0
	v_pk_fma_f32 v[72:73], v[46:47], v[72:73], v[84:85] neg_lo:[0,0,1] neg_hi:[0,0,1]
	v_pk_fma_f32 v[82:83], v[46:47], v[82:83], v[84:85]
	s_nop 0
	v_mov_b32_e32 v73, v83
	v_pk_add_f32 v[82:83], v[66:67], v[70:71]
	v_pk_add_f32 v[84:85], v[68:69], v[72:73]
	v_pk_add_f32 v[66:67], v[66:67], v[70:71] neg_lo:[0,1] neg_hi:[0,1]
	v_pk_add_f32 v[68:69], v[68:69], v[72:73] neg_lo:[0,1] neg_hi:[0,1]
	v_pk_add_f32 v[86:87], v[82:83], v[84:85]
	v_pk_add_f32 v[70:71], v[66:67], v[68:69] op_sel:[0,1] op_sel_hi:[1,0]
	v_pk_add_f32 v[66:67], v[66:67], v[68:69] op_sel:[0,1] op_sel_hi:[1,0] neg_lo:[0,1] neg_hi:[0,1]
	v_mov_b32_e32 v68, v70
	v_pk_mov_b32 v[72:73], v[66:67], v[70:71] op_sel:[1,0]
	v_mov_b32_e32 v69, v67
	v_pk_mul_f32 v[72:73], v[48:49], v[72:73]
	s_nop 0
	v_pk_fma_f32 v[88:89], v[50:51], v[70:71], v[72:73]
	v_pk_fma_f32 v[68:69], v[50:51], v[68:69], v[72:73] neg_lo:[0,0,1] neg_hi:[0,0,1]
	s_nop 0
	v_mov_b32_e32 v89, v69
	v_pk_add_f32 v[68:69], v[82:83], v[84:85] neg_lo:[0,1] neg_hi:[0,1]
	ds_write2st64_b64 v65, v[86:87], v[88:89] offset0:48 offset1:52
	v_pk_mul_f32 v[72:73], v[56:57], v[68:69]
	s_nop 0
	v_pk_fma_f32 v[82:83], v[54:55], v[68:69], v[72:73] op_sel:[0,0,1] op_sel_hi:[1,1,0] neg_lo:[0,0,1] neg_hi:[0,0,1]
	v_pk_fma_f32 v[68:69], v[54:55], v[68:69], v[72:73] op_sel:[0,0,1] op_sel_hi:[1,1,0]
	s_nop 0
	v_mov_b32_e32 v83, v69
	v_mov_b32_e32 v69, v71
	v_pk_mov_b32 v[70:71], v[70:71], v[66:67] op_sel:[1,0]
	v_mov_b32_e32 v68, v66
	v_pk_mul_f32 v[70:71], v[60:61], v[70:71]
	s_nop 0
	v_pk_fma_f32 v[66:67], v[58:59], v[66:67], v[70:71] neg_lo:[0,0,1] neg_hi:[0,0,1]
	v_pk_fma_f32 v[68:69], v[58:59], v[68:69], v[70:71]
	s_nop 0
	v_mov_b32_e32 v67, v69
	ds_write2st64_b64 v65, v[82:83], v[66:67] offset0:56 offset1:60
	s_nop 0
	v_add_u32_e32 v64, 0x200, v64
	s_nop 0
	s_waitcnt lgkmcnt(11)
; DI float2 twid(float r) { return float2{__builtin_amdgcn_cosf(r), -__builtin_amdgcn_sinf(r)}; }
; DI void bfly_fwd(float2 a0, float2 a1, float2 a2, float2 a3, float r, float2& o0, float2& o1, float2& o2, float2& o3) {
;   float2 t0 = {a0.x + a2.x, a0.y + a2.y}, t1 = {a0.x - a2.x, a0.y - a2.y}, t2 = {a1.x + a3.x, a1.y + a3.y}, t3 = {a1.x - a3.x, a1.y - a3.y};
;   float2 b0 = {t0.x + t2.x, t0.y + t2.y}, b2 = {t0.x - t2.x, t0.y - t2.y}, b1 = {t1.x + t3.y, t1.y - t3.x}, b3 = {t1.x - t3.y, t1.y + t3.x};
;   float2 w1 = twid(r), w2 = cmul(w1, w1), w3 = cmul(w2, w1);
;   o0 = b0; o1 = cmul(b1, w1); o2 = cmul(b2, w2); o3 = cmul(b3, w3);
; }
;     ...
;   for (int gg = tid; gg < NBT * (N / 16); gg += NTHR) { const int g = gg & (N / 16 - 1); float2* z = z0 + (gg / (N / 16)) * N; const int jp = g & (Q2 - 1), base = ((g >> lq2) << (lq2 + 4)) + jp; float2 x[4][4];
; #pragma unroll
;     for (int q1 = 0; q1 < 4; ++q1)
; #pragma unroll
;       for (int q2 = 0; q2 < 4; ++q2) x[q1][q2] = z[base + q1 * Q1 + q2 * Q2];
; #pragma unroll
;     for (int q2 = 0; q2 < 4; ++q2) bfly_fwd(x[0][q2], x[1][q2], x[2][q2], x[3][q2], (float)(jp + q2 * Q2) * invM1, x[0][q2], x[1][q2], x[2][q2], x[3][q2]);
; #pragma unroll
;     for (int q1 = 0; q1 < 4; ++q1) bfly_fwd(x[q1][0], x[q1][1], x[q1][2], x[q1][3], (float)jp * invM2, x[q1][0], x[q1][1], x[q1][2], x[q1][3]);
; #pragma unroll
;     for (int q1 = 0; q1 < 4; ++q1)
; #pragma unroll
;       for (int q2 = 0; q2 < 4; ++q2) z[base + q1 * Q1 + q2 * Q2] = x[q1][q2]; }
	v_pk_add_f32 v[106:107], v[220:221], v[236:237]
	v_pk_add_f32 v[112:113], v[222:223], v[238:239]
	s_waitcnt lgkmcnt(9)
	v_pk_add_f32 v[108:109], v[228:229], v[248:249]
	v_pk_add_f32 v[114:115], v[230:231], v[250:251]
	v_pk_add_f32 v[118:119], v[224:225], v[244:245]
	s_waitcnt lgkmcnt(8)
	v_pk_add_f32 v[120:121], v[232:233], v[252:253]
	v_pk_add_f32 v[124:125], v[226:227], v[246:247]
	v_pk_add_f32 v[126:127], v[234:235], v[254:255]
	v_pk_add_f32 v[110:111], v[106:107], v[108:109]
	v_pk_add_f32 v[116:117], v[112:113], v[114:115]
	v_pk_add_f32 v[122:123], v[118:119], v[120:121]
	v_pk_add_f32 v[128:129], v[124:125], v[126:127]
	v_pk_add_f32 v[130:131], v[110:111], v[122:123]
	v_pk_add_f32 v[132:133], v[116:117], v[128:129]
	v_pk_add_f32 v[110:111], v[110:111], v[122:123] neg_lo:[0,1] neg_hi:[0,1]
	v_pk_add_f32 v[116:117], v[116:117], v[128:129] neg_lo:[0,1] neg_hi:[0,1]
	v_pk_add_f32 v[134:135], v[130:131], v[132:133]
	v_pk_add_f32 v[122:123], v[110:111], v[116:117] op_sel:[0,1] op_sel_hi:[1,0]
	v_pk_add_f32 v[110:111], v[110:111], v[116:117] op_sel:[0,1] op_sel_hi:[1,0] neg_lo:[0,1] neg_hi:[0,1]
	v_mov_b32_e32 v116, v122
	v_pk_mov_b32 v[128:129], v[110:111], v[122:123] op_sel:[1,0]
	v_mov_b32_e32 v117, v111
	v_pk_mul_f32 v[128:129], v[48:49], v[128:129]
	v_pk_add_f32 v[220:221], v[220:221], v[236:237] neg_lo:[0,1] neg_hi:[0,1]
	v_pk_fma_f32 v[136:137], v[50:51], v[122:123], v[128:129]
	v_pk_fma_f32 v[116:117], v[50:51], v[116:117], v[128:129] neg_lo:[0,0,1] neg_hi:[0,0,1]
	v_pk_add_f32 v[228:229], v[228:229], v[248:249] neg_lo:[0,1] neg_hi:[0,1]
	v_mov_b32_e32 v137, v117
	v_pk_add_f32 v[116:117], v[130:131], v[132:133] neg_lo:[0,1] neg_hi:[0,1]
	v_pk_add_f32 v[236:237], v[220:221], v[228:229] op_sel:[0,1] op_sel_hi:[1,0]
	v_pk_mul_f32 v[128:129], v[56:57], v[116:117]
	v_pk_add_f32 v[220:221], v[220:221], v[228:229] op_sel:[0,1] op_sel_hi:[1,0] neg_lo:[0,1] neg_hi:[0,1]
	v_pk_fma_f32 v[130:131], v[54:55], v[116:117], v[128:129] op_sel:[0,0,1] op_sel_hi:[1,1,0] neg_lo:[0,0,1] neg_hi:[0,0,1]
	v_pk_fma_f32 v[116:117], v[54:55], v[116:117], v[128:129] op_sel:[0,0,1] op_sel_hi:[1,1,0]
	v_pk_mov_b32 v[248:249], v[220:221], v[236:237] op_sel:[1,0]
	v_mov_b32_e32 v131, v117
	v_mov_b32_e32 v117, v123
	v_pk_mov_b32 v[122:123], v[122:123], v[110:111] op_sel:[1,0]
	v_mov_b32_e32 v116, v110
	v_pk_mul_f32 v[122:123], v[60:61], v[122:123]
	v_mov_b32_e32 v228, v236
	v_pk_fma_f32 v[110:111], v[58:59], v[110:111], v[122:123] neg_lo:[0,0,1] neg_hi:[0,0,1]
	v_pk_fma_f32 v[116:117], v[58:59], v[116:117], v[122:123]
	v_mov_b32_e32 v229, v221
	v_mov_b32_e32 v111, v117
	v_pk_mul_f32 v[248:249], v[2:3], v[248:249]
	ds_write2st64_b64 v219, v[130:131], v[110:111] offset0:8 offset1:12
	v_pk_fma_f32 v[110:111], v[4:5], v[236:237], v[248:249]
	v_pk_fma_f32 v[228:229], v[4:5], v[228:229], v[248:249] neg_lo:[0,0,1] neg_hi:[0,0,1]
	v_pk_add_f32 v[222:223], v[222:223], v[238:239] neg_lo:[0,1] neg_hi:[0,1]
	v_mov_b32_e32 v111, v229
	v_pk_add_f32 v[228:229], v[230:231], v[250:251] neg_lo:[0,1] neg_hi:[0,1]
	v_pk_add_f32 v[224:225], v[224:225], v[244:245] neg_lo:[0,1] neg_hi:[0,1]
	v_pk_add_f32 v[230:231], v[222:223], v[228:229] op_sel:[0,1] op_sel_hi:[1,0]
	v_pk_add_f32 v[222:223], v[222:223], v[228:229] op_sel:[0,1] op_sel_hi:[1,0] neg_lo:[0,1] neg_hi:[0,1]
	v_mov_b32_e32 v228, v230
	v_pk_mov_b32 v[238:239], v[222:223], v[230:231] op_sel:[1,0]
	v_mov_b32_e32 v229, v223
	v_pk_mul_f32 v[238:239], v[12:13], v[238:239]
	v_pk_add_f32 v[226:227], v[226:227], v[246:247] neg_lo:[0,1] neg_hi:[0,1]
	v_pk_fma_f32 v[248:249], v[14:15], v[230:231], v[238:239]
	v_pk_fma_f32 v[228:229], v[14:15], v[228:229], v[238:239] neg_lo:[0,0,1] neg_hi:[0,0,1]
	ds_write2st64_b64 v219, v[134:135], v[136:137] offset1:4
	v_mov_b32_e32 v249, v229
	v_pk_add_f32 v[228:229], v[232:233], v[252:253] neg_lo:[0,1] neg_hi:[0,1]
	s_nop 0
	v_pk_add_f32 v[232:233], v[224:225], v[228:229] op_sel:[0,1] op_sel_hi:[1,0]
	v_pk_add_f32 v[224:225], v[224:225], v[228:229] op_sel:[0,1] op_sel_hi:[1,0] neg_lo:[0,1] neg_hi:[0,1]
	v_mov_b32_e32 v228, v232
	v_pk_mov_b32 v[238:239], v[224:225], v[232:233] op_sel:[1,0]
	v_mov_b32_e32 v229, v225
	v_pk_mul_f32 v[238:239], v[24:25], v[238:239]
	s_nop 0
	v_pk_fma_f32 v[244:245], v[26:27], v[232:233], v[238:239]
	v_pk_fma_f32 v[228:229], v[26:27], v[228:229], v[238:239] neg_lo:[0,0,1] neg_hi:[0,0,1]
	s_nop 0
	v_mov_b32_e32 v245, v229
	v_pk_add_f32 v[228:229], v[234:235], v[254:255] neg_lo:[0,1] neg_hi:[0,1]
	s_nop 0
	v_pk_add_f32 v[234:235], v[226:227], v[228:229] op_sel:[0,1] op_sel_hi:[1,0]
	v_pk_add_f32 v[226:227], v[226:227], v[228:229] op_sel:[0,1] op_sel_hi:[1,0] neg_lo:[0,1] neg_hi:[0,1]
	v_mov_b32_e32 v228, v234
	v_pk_mov_b32 v[238:239], v[226:227], v[234:235] op_sel:[1,0]
	v_mov_b32_e32 v229, v227
	v_pk_mul_f32 v[238:239], v[36:37], v[238:239]
	s_nop 0
	v_pk_fma_f32 v[246:247], v[38:39], v[234:235], v[238:239]
	v_pk_fma_f32 v[228:229], v[38:39], v[228:229], v[238:239] neg_lo:[0,0,1] neg_hi:[0,0,1]
	s_nop 0
	v_mov_b32_e32 v247, v229
	v_pk_add_f32 v[228:229], v[110:111], v[244:245]
	v_pk_add_f32 v[238:239], v[248:249], v[246:247]
	v_pk_add_f32 v[244:245], v[110:111], v[244:245] neg_lo:[0,1] neg_hi:[0,1]
	v_pk_add_f32 v[246:247], v[248:249], v[246:247] neg_lo:[0,1] neg_hi:[0,1]
	v_pk_add_f32 v[250:251], v[228:229], v[238:239]
	v_pk_add_f32 v[248:249], v[244:245], v[246:247] op_sel:[0,1] op_sel_hi:[1,0]
	v_pk_add_f32 v[244:245], v[244:245], v[246:247] op_sel:[0,1] op_sel_hi:[1,0] neg_lo:[0,1] neg_hi:[0,1]
	v_mov_b32_e32 v246, v248
	v_pk_mov_b32 v[252:253], v[244:245], v[248:249] op_sel:[1,0]
	v_mov_b32_e32 v247, v245
	v_pk_mul_f32 v[252:253], v[48:49], v[252:253]
; DI float2 twid(float r) { return float2{__builtin_amdgcn_cosf(r), -__builtin_amdgcn_sinf(r)}; }
; DI void bfly_fwd(float2 a0, float2 a1, float2 a2, float2 a3, float r, float2& o0, float2& o1, float2& o2, float2& o3) {
;   float2 t0 = {a0.x + a2.x, a0.y + a2.y}, t1 = {a0.x - a2.x, a0.y - a2.y}, t2 = {a1.x + a3.x, a1.y + a3.y}, t3 = {a1.x - a3.x, a1.y - a3.y};
;   float2 b0 = {t0.x + t2.x, t0.y + t2.y}, b2 = {t0.x - t2.x, t0.y - t2.y}, b1 = {t1.x + t3.y, t1.y - t3.x}, b3 = {t1.x - t3.y, t1.y + t3.x};
;   float2 w1 = twid(r), w2 = cmul(w1, w1), w3 = cmul(w2, w1);
;   o0 = b0; o1 = cmul(b1, w1); o2 = cmul(b2, w2); o3 = cmul(b3, w3);
; }
;     ...
;   for (int gg = tid; gg < NBT * (N / 16); gg += NTHR) { const int g = gg & (N / 16 - 1); float2* z = z0 + (gg / (N / 16)) * N; const int jp = g & (Q2 - 1), base = ((g >> lq2) << (lq2 + 4)) + jp; float2 x[4][4];
; #pragma unroll
;     for (int q1 = 0; q1 < 4; ++q1)
; #pragma unroll
;       for (int q2 = 0; q2 < 4; ++q2) x[q1][q2] = z[base + q1 * Q1 + q2 * Q2];
; #pragma unroll
;     for (int q2 = 0; q2 < 4; ++q2) bfly_fwd(x[0][q2], x[1][q2], x[2][q2], x[3][q2], (float)(jp + q2 * Q2) * invM1, x[0][q2], x[1][q2], x[2][q2], x[3][q2]);
; #pragma unroll
;     for (int q1 = 0; q1 < 4; ++q1) bfly_fwd(x[q1][0], x[q1][1], x[q1][2], x[q1][3], (float)jp * invM2, x[q1][0], x[q1][1], x[q1][2], x[q1][3]);
; #pragma unroll
;     for (int q1 = 0; q1 < 4; ++q1)
; #pragma unroll
;       for (int q2 = 0; q2 < 4; ++q2) z[base + q1 * Q1 + q2 * Q2] = x[q1][q2]; }
	v_pk_add_f32 v[228:229], v[228:229], v[238:239] neg_lo:[0,1] neg_hi:[0,1]
	v_pk_fma_f32 v[254:255], v[50:51], v[248:249], v[252:253]
	v_pk_fma_f32 v[246:247], v[50:51], v[246:247], v[252:253] neg_lo:[0,0,1] neg_hi:[0,0,1]
	v_pk_mul_f32 v[238:239], v[56:57], v[228:229]
	v_mov_b32_e32 v255, v247
	v_pk_fma_f32 v[246:247], v[54:55], v[228:229], v[238:239] op_sel:[0,0,1] op_sel_hi:[1,1,0] neg_lo:[0,0,1] neg_hi:[0,0,1]
	v_pk_fma_f32 v[228:229], v[54:55], v[228:229], v[238:239] op_sel:[0,0,1] op_sel_hi:[1,1,0]
	v_pk_mov_b32 v[238:239], v[248:249], v[244:245] op_sel:[1,0]
	v_mov_b32_e32 v247, v229
	v_mov_b32_e32 v228, v244
	v_mov_b32_e32 v229, v249
	v_pk_mul_f32 v[238:239], v[60:61], v[238:239]
	ds_write2st64_b64 v219, v[250:251], v[254:255] offset0:16 offset1:20
	v_pk_fma_f32 v[244:245], v[58:59], v[244:245], v[238:239] neg_lo:[0,0,1] neg_hi:[0,0,1]
	v_pk_fma_f32 v[228:229], v[58:59], v[228:229], v[238:239]
	s_nop 0
	v_mov_b32_e32 v245, v229
	v_pk_add_f32 v[228:229], v[106:107], v[108:109] neg_lo:[0,1] neg_hi:[0,1]
	ds_write2st64_b64 v219, v[246:247], v[244:245] offset0:24 offset1:28
	v_pk_mul_f32 v[238:239], v[8:9], v[228:229] op_sel:[0,1] op_sel_hi:[1,0]
	s_nop 0
	v_pk_fma_f32 v[244:245], v[6:7], v[228:229], v[238:239] neg_lo:[0,0,1] neg_hi:[0,0,1]
	v_pk_fma_f32 v[228:229], v[6:7], v[228:229], v[238:239]
	s_nop 0
	v_mov_b32_e32 v245, v229
	v_pk_add_f32 v[228:229], v[112:113], v[114:115] neg_lo:[0,1] neg_hi:[0,1]
	s_nop 0
	v_pk_mul_f32 v[238:239], v[20:21], v[228:229] op_sel:[0,1] op_sel_hi:[1,0]
	s_nop 0
	v_pk_fma_f32 v[246:247], v[18:19], v[228:229], v[238:239] neg_lo:[0,0,1] neg_hi:[0,0,1]
	v_pk_fma_f32 v[228:229], v[18:19], v[228:229], v[238:239]
	s_nop 0
	v_mov_b32_e32 v247, v229
	v_pk_add_f32 v[228:229], v[118:119], v[120:121] neg_lo:[0,1] neg_hi:[0,1]
	s_nop 0
	v_pk_mul_f32 v[238:239], v[32:33], v[228:229] op_sel:[0,1] op_sel_hi:[1,0]
	s_nop 0
	v_pk_fma_f32 v[248:249], v[30:31], v[228:229], v[238:239] neg_lo:[0,0,1] neg_hi:[0,0,1]
	v_pk_fma_f32 v[228:229], v[30:31], v[228:229], v[238:239]
	s_nop 0
	v_mov_b32_e32 v249, v229
	v_pk_add_f32 v[228:229], v[124:125], v[126:127] neg_lo:[0,1] neg_hi:[0,1]
	s_nop 0
	v_pk_mul_f32 v[238:239], v[44:45], v[228:229] op_sel:[0,1] op_sel_hi:[1,0]
	s_nop 0
	v_pk_fma_f32 v[250:251], v[42:43], v[228:229], v[238:239] neg_lo:[0,0,1] neg_hi:[0,0,1]
	v_pk_fma_f32 v[228:229], v[42:43], v[228:229], v[238:239]
	s_nop 0
	v_mov_b32_e32 v251, v229
	v_pk_add_f32 v[228:229], v[244:245], v[248:249]
	v_pk_add_f32 v[238:239], v[246:247], v[250:251]
	v_pk_add_f32 v[244:245], v[244:245], v[248:249] neg_lo:[0,1] neg_hi:[0,1]
	v_pk_add_f32 v[246:247], v[246:247], v[250:251] neg_lo:[0,1] neg_hi:[0,1]
	v_pk_add_f32 v[252:253], v[228:229], v[238:239]
	v_pk_add_f32 v[248:249], v[244:245], v[246:247] op_sel:[0,1] op_sel_hi:[1,0]
	v_pk_add_f32 v[244:245], v[244:245], v[246:247] op_sel:[0,1] op_sel_hi:[1,0] neg_lo:[0,1] neg_hi:[0,1]
	v_mov_b32_e32 v246, v248
	v_pk_mov_b32 v[250:251], v[244:245], v[248:249] op_sel:[1,0]
	v_mov_b32_e32 v247, v245
	v_pk_mul_f32 v[250:251], v[48:49], v[250:251]
	v_pk_add_f32 v[228:229], v[228:229], v[238:239] neg_lo:[0,1] neg_hi:[0,1]
	v_pk_fma_f32 v[254:255], v[50:51], v[248:249], v[250:251]
	v_pk_fma_f32 v[246:247], v[50:51], v[246:247], v[250:251] neg_lo:[0,0,1] neg_hi:[0,0,1]
	v_pk_mul_f32 v[238:239], v[56:57], v[228:229]
	v_mov_b32_e32 v255, v247
	v_pk_fma_f32 v[246:247], v[54:55], v[228:229], v[238:239] op_sel:[0,0,1] op_sel_hi:[1,1,0] neg_lo:[0,0,1] neg_hi:[0,0,1]
	v_pk_fma_f32 v[228:229], v[54:55], v[228:229], v[238:239] op_sel:[0,0,1] op_sel_hi:[1,1,0]
	v_pk_mov_b32 v[238:239], v[248:249], v[244:245] op_sel:[1,0]
	v_mov_b32_e32 v247, v229
	v_mov_b32_e32 v228, v244
	v_mov_b32_e32 v229, v249
	v_pk_mul_f32 v[238:239], v[60:61], v[238:239]
	ds_write2st64_b64 v219, v[252:253], v[254:255] offset0:32 offset1:36
	v_pk_fma_f32 v[244:245], v[58:59], v[244:245], v[238:239] neg_lo:[0,0,1] neg_hi:[0,0,1]
	v_pk_fma_f32 v[228:229], v[58:59], v[228:229], v[238:239]
	s_nop 0
	v_mov_b32_e32 v245, v229
	v_mov_b32_e32 v229, v237
	v_pk_mov_b32 v[236:237], v[236:237], v[220:221] op_sel:[1,0]
	v_mov_b32_e32 v228, v220
	v_pk_mul_f32 v[236:237], v[16:17], v[236:237]
	ds_write2st64_b64 v219, v[246:247], v[244:245] offset0:40 offset1:44
	v_pk_fma_f32 v[220:221], v[10:11], v[220:221], v[236:237] neg_lo:[0,0,1] neg_hi:[0,0,1]
	v_pk_fma_f32 v[228:229], v[10:11], v[228:229], v[236:237]
	s_nop 0
	v_mov_b32_e32 v221, v229
	v_mov_b32_e32 v229, v231
	v_pk_mov_b32 v[230:231], v[230:231], v[222:223] op_sel:[1,0]
	v_mov_b32_e32 v228, v222
	v_pk_mul_f32 v[230:231], v[28:29], v[230:231]
	s_nop 0
	v_pk_fma_f32 v[222:223], v[22:23], v[222:223], v[230:231] neg_lo:[0,0,1] neg_hi:[0,0,1]
	v_pk_fma_f32 v[228:229], v[22:23], v[228:229], v[230:231]
	v_pk_mov_b32 v[230:231], v[232:233], v[224:225] op_sel:[1,0]
	v_mov_b32_e32 v223, v229
	v_mov_b32_e32 v228, v224
	v_mov_b32_e32 v229, v233
	v_pk_mul_f32 v[230:231], v[40:41], v[230:231]
	s_nop 0
	v_pk_fma_f32 v[224:225], v[34:35], v[224:225], v[230:231] neg_lo:[0,0,1] neg_hi:[0,0,1]
	v_pk_fma_f32 v[228:229], v[34:35], v[228:229], v[230:231]
	v_pk_mov_b32 v[230:231], v[234:235], v[226:227] op_sel:[1,0]
	v_mov_b32_e32 v225, v229
	v_mov_b32_e32 v228, v226
	v_mov_b32_e32 v229, v235
	v_pk_mul_f32 v[230:231], v[52:53], v[230:231]
	s_nop 0
	v_pk_fma_f32 v[226:227], v[46:47], v[226:227], v[230:231] neg_lo:[0,0,1] neg_hi:[0,0,1]
	v_pk_fma_f32 v[228:229], v[46:47], v[228:229], v[230:231]
	s_nop 0
	v_mov_b32_e32 v227, v229
	v_pk_add_f32 v[228:229], v[220:221], v[224:225]
	v_pk_add_f32 v[230:231], v[222:223], v[226:227]
	v_pk_add_f32 v[220:221], v[220:221], v[224:225] neg_lo:[0,1] neg_hi:[0,1]
; DI float2 twid(float r) { return float2{__builtin_amdgcn_cosf(r), -__builtin_amdgcn_sinf(r)}; }
; DI void bfly_fwd(float2 a0, float2 a1, float2 a2, float2 a3, float r, float2& o0, float2& o1, float2& o2, float2& o3) {
;   float2 t0 = {a0.x + a2.x, a0.y + a2.y}, t1 = {a0.x - a2.x, a0.y - a2.y}, t2 = {a1.x + a3.x, a1.y + a3.y}, t3 = {a1.x - a3.x, a1.y - a3.y};
;   float2 b0 = {t0.x + t2.x, t0.y + t2.y}, b2 = {t0.x - t2.x, t0.y - t2.y}, b1 = {t1.x + t3.y, t1.y - t3.x}, b3 = {t1.x - t3.y, t1.y + t3.x};
;   float2 w1 = twid(r), w2 = cmul(w1, w1), w3 = cmul(w2, w1);
;   o0 = b0; o1 = cmul(b1, w1); o2 = cmul(b2, w2); o3 = cmul(b3, w3);
; }
;   const int lq2 = lq1 - 2, Q1 = 1 << lq1, Q2 = 1 << lq2; const float invM1 = 1.f / (float)(4 << lq1), invM2 = 1.f / (float)(4 << lq2);
;   for (int gg = tid; gg < NBT * (N / 16); gg += NTHR) { const int g = gg & (N / 16 - 1); float2* z = z0 + (gg / (N / 16)) * N; const int jp = g & (Q2 - 1), base = ((g >> lq2) << (lq2 + 4)) + jp; float2 x[4][4];
; #pragma unroll
;     for (int q1 = 0; q1 < 4; ++q1)
; #pragma unroll
;       for (int q2 = 0; q2 < 4; ++q2) x[q1][q2] = z[base + q1 * Q1 + q2 * Q2];
; #pragma unroll
;     for (int q2 = 0; q2 < 4; ++q2) bfly_fwd(x[0][q2], x[1][q2], x[2][q2], x[3][q2], (float)(jp + q2 * Q2) * invM1, x[0][q2], x[1][q2], x[2][q2], x[3][q2]);
; #pragma unroll
;     for (int q1 = 0; q1 < 4; ++q1) bfly_fwd(x[q1][0], x[q1][1], x[q1][2], x[q1][3], (float)jp * invM2, x[q1][0], x[q1][1], x[q1][2], x[q1][3]);
; #pragma unroll
;     for (int q1 = 0; q1 < 4; ++q1)
; #pragma unroll
;       for (int q2 = 0; q2 < 4; ++q2) z[base + q1 * Q1 + q2 * Q2] = x[q1][q2]; }
;   __syncthreads();
; }
	v_pk_add_f32 v[222:223], v[222:223], v[226:227] neg_lo:[0,1] neg_hi:[0,1]
	v_pk_add_f32 v[232:233], v[228:229], v[230:231]
	v_pk_add_f32 v[224:225], v[220:221], v[222:223] op_sel:[0,1] op_sel_hi:[1,0]
	v_pk_add_f32 v[220:221], v[220:221], v[222:223] op_sel:[0,1] op_sel_hi:[1,0] neg_lo:[0,1] neg_hi:[0,1]
	v_mov_b32_e32 v222, v224
	v_pk_mov_b32 v[226:227], v[220:221], v[224:225] op_sel:[1,0]
	v_mov_b32_e32 v223, v221
	v_pk_mul_f32 v[226:227], v[48:49], v[226:227]
	s_nop 0
	v_pk_fma_f32 v[234:235], v[50:51], v[224:225], v[226:227]
	v_pk_fma_f32 v[222:223], v[50:51], v[222:223], v[226:227] neg_lo:[0,0,1] neg_hi:[0,0,1]
	s_nop 0
	v_mov_b32_e32 v235, v223
	v_pk_add_f32 v[222:223], v[228:229], v[230:231] neg_lo:[0,1] neg_hi:[0,1]
	ds_write2st64_b64 v219, v[232:233], v[234:235] offset0:48 offset1:52
	v_pk_mul_f32 v[226:227], v[56:57], v[222:223]
	s_nop 0
	v_pk_fma_f32 v[228:229], v[54:55], v[222:223], v[226:227] op_sel:[0,0,1] op_sel_hi:[1,1,0] neg_lo:[0,0,1] neg_hi:[0,0,1]
	v_pk_fma_f32 v[222:223], v[54:55], v[222:223], v[226:227] op_sel:[0,0,1] op_sel_hi:[1,1,0]
	s_nop 0
	v_mov_b32_e32 v229, v223
	v_mov_b32_e32 v223, v225
	v_pk_mov_b32 v[224:225], v[224:225], v[220:221] op_sel:[1,0]
	v_mov_b32_e32 v222, v220
	v_pk_mul_f32 v[224:225], v[60:61], v[224:225]
	s_nop 0
	v_pk_fma_f32 v[220:221], v[58:59], v[220:221], v[224:225] neg_lo:[0,0,1] neg_hi:[0,0,1]
	v_pk_fma_f32 v[222:223], v[58:59], v[222:223], v[224:225]
	s_nop 0
	v_mov_b32_e32 v221, v223
	ds_write2st64_b64 v219, v[228:229], v[220:221] offset0:56 offset1:60
	s_nop 0
	v_add_u32_e32 v65, 0x200, v64
	s_nop 0
	v_mov_b32_e32 v64, v65
.LBB0_1601:
	s_or_b64 exec, exec, s[0:1]
	v_and_b32_e32 v2, 15, v75
	v_and_b32_e32 v66, 0xf800, v62
	v_lshlrev_b32_e32 v67, 3, v2
	v_cvt_f32_ubyte0_e32 v65, v2
	v_or_b32_e32 v64, 16, v2
	v_or_b32_e32 v63, 32, v2
	v_or_b32_e32 v62, 48, v2
	s_waitcnt lgkmcnt(0)
	s_barrier
	s_and_saveexec_b64 s[0:1], vcc
	s_cbranch_execz .LBB0_1604
	v_add3_u32 v68, 16, v66, v67
	v_mov_b32_e32 v69, v75
	v_ashrrev_i32_e32 v70, 31, v69
	v_lshrrev_b32_e32 v70, 23, v70
	v_add_lshl_u32 v70, v69, v70, 7
	v_and_b32_e32 v70, 0xffff0000, v70
	v_add_u32_e32 v142, v68, v70
	ds_read2_b64 v[70:73], v142 offset1:16
	ds_read2_b64 v[82:85], v142 offset0:32 offset1:48
	ds_read2_b64 v[86:89], v142 offset0:64 offset1:80
	ds_read2_b64 v[90:93], v142 offset0:96 offset1:112
	ds_read2_b64 v[94:97], v142 offset0:128 offset1:144
	ds_read2_b64 v[98:101], v142 offset0:160 offset1:176
	ds_read2_b64 v[102:105], v142 offset0:192 offset1:208
	ds_read2_b64 v[106:109], v142 offset0:224 offset1:240
	v_add_u32_e32 v218, 0x200, v69
	v_ashrrev_i32_e32 v252, 31, v218
	v_lshrrev_b32_e32 v252, 23, v252
	v_add_lshl_u32 v252, v218, v252, 7
	v_and_b32_e32 v252, 0xffff0000, v252
	v_add_u32_e32 v219, v68, v252
	ds_read2_b64 v[220:223], v219 offset1:16
	ds_read2_b64 v[224:227], v219 offset0:32 offset1:48
	ds_read2_b64 v[228:231], v219 offset0:64 offset1:80
	ds_read2_b64 v[232:235], v219 offset0:96 offset1:112
	ds_read2_b64 v[236:239], v219 offset0:128 offset1:144
	ds_read2_b64 v[244:247], v219 offset0:160 offset1:176
	ds_read2_b64 v[248:251], v219 offset0:192 offset1:208
	ds_read2_b64 v[252:255], v219 offset0:224 offset1:240
	v_mul_f32_e32 v3, 0x3b800000, v65
	v_sin_f32_e32 v2, v3
	v_cos_f32_e32 v4, v3
	s_mov_b64 s[80:81], 0
	v_mul_f32_e32 v3, v2, v2
	v_fma_f32 v6, v4, v4, -v3
	v_cvt_f32_ubyte0_e32 v3, v64
	v_mul_f32_e32 v3, 0x3b800000, v3
	v_sin_f32_e32 v12, v3
	v_cos_f32_e32 v14, v3
	v_mul_f32_e64 v5, v4, -v2
	v_add_f32_e32 v8, v5, v5
	v_mul_f32_e32 v3, v2, v6
	v_fma_f32 v16, v4, v8, -v3
	v_mul_f32_e32 v3, v12, v12
	v_fma_f32 v18, v14, v14, -v3
	v_mul_f32_e64 v3, v14, -v12
	v_add_f32_e32 v20, v3, v3
	v_cvt_f32_ubyte0_e32 v3, v63
	v_mul_f32_e32 v3, 0x3b800000, v3
	v_sin_f32_e32 v24, v3
	v_cos_f32_e32 v26, v3
	v_mul_f32_e32 v3, v12, v18
	v_fma_f32 v28, v14, v20, -v3
	v_mul_f32_e32 v3, v24, v24
	v_fma_f32 v30, v26, v26, -v3
	v_mul_f32_e64 v3, v26, -v24
	v_add_f32_e32 v32, v3, v3
	v_cvt_f32_ubyte0_e32 v3, v62
	v_mul_f32_e32 v3, 0x3b800000, v3
	v_sin_f32_e32 v36, v3
	v_cos_f32_e32 v38, v3
	v_mul_f32_e32 v3, v24, v30
	v_fma_f32 v40, v26, v32, -v3
	v_mul_f32_e32 v3, v36, v36
	v_fma_f32 v42, v38, v38, -v3
	v_mul_f32_e64 v3, v38, -v36
	v_add_f32_e32 v44, v3, v3
	v_mul_f32_e32 v3, 0x3c800000, v65
	v_sin_f32_e32 v48, v3
	v_cos_f32_e32 v50, v3
	v_mul_f32_e32 v3, v36, v42
	v_fma_f32 v52, v38, v44, -v3
	v_mul_f32_e32 v3, v48, v48
	v_fma_f32 v54, v50, v50, -v3
	v_mul_f32_e64 v3, v50, -v48
	v_add_f32_e32 v56, v3, v3
	v_mul_f32_e32 v10, v2, v8
	v_mul_f32_e32 v22, v12, v20
	v_mul_f32_e32 v34, v24, v32
	v_mul_f32_e32 v46, v36, v44
	v_mul_f32_e32 v58, v48, v56
	v_mul_f32_e32 v3, v48, v54
	v_fmac_f32_e32 v10, v4, v6
	v_fmac_f32_e32 v22, v14, v18
	v_fmac_f32_e32 v34, v26, v30
	v_fmac_f32_e32 v46, v38, v42
	v_fmac_f32_e32 v58, v50, v54
	v_fma_f32 v60, v50, v56, -v3
	v_mov_b32_e32 v51, v50
	v_mov_b32_e32 v49, v48
	v_mov_b32_e32 v55, v54
	v_mov_b32_e32 v57, v56
	v_mov_b32_e32 v59, v58
	v_mov_b32_e32 v61, v60
	v_mov_b32_e32 v5, v4
	v_mov_b32_e32 v3, v2
	v_mov_b32_e32 v27, v26
	v_mov_b32_e32 v25, v24
	v_mov_b32_e32 v15, v14
	v_mov_b32_e32 v13, v12
	v_mov_b32_e32 v39, v38
	v_mov_b32_e32 v37, v36
	v_mov_b32_e32 v7, v6
	v_mov_b32_e32 v31, v30
	v_mov_b32_e32 v19, v18
	v_mov_b32_e32 v43, v42
	v_mov_b32_e32 v11, v10
	v_mov_b32_e32 v17, v16
	v_mov_b32_e32 v35, v34
	v_mov_b32_e32 v41, v40
	v_mov_b32_e32 v23, v22
	v_mov_b32_e32 v29, v28
	v_mov_b32_e32 v47, v46
	v_mov_b32_e32 v53, v52
	v_mov_b32_e32 v9, v8
	v_mov_b32_e32 v21, v20
	v_mov_b32_e32 v33, v32
	v_mov_b32_e32 v45, v44
	s_nop 0
	s_waitcnt lgkmcnt(11)
; DI float2 twid(float r) { return float2{__builtin_amdgcn_cosf(r), -__builtin_amdgcn_sinf(r)}; }
; DI void bfly_fwd(float2 a0, float2 a1, float2 a2, float2 a3, float r, float2& o0, float2& o1, float2& o2, float2& o3) {
;   float2 t0 = {a0.x + a2.x, a0.y + a2.y}, t1 = {a0.x - a2.x, a0.y - a2.y}, t2 = {a1.x + a3.x, a1.y + a3.y}, t3 = {a1.x - a3.x, a1.y - a3.y};
;   float2 b0 = {t0.x + t2.x, t0.y + t2.y}, b2 = {t0.x - t2.x, t0.y - t2.y}, b1 = {t1.x + t3.y, t1.y - t3.x}, b3 = {t1.x - t3.y, t1.y + t3.x};
;   float2 w1 = twid(r), w2 = cmul(w1, w1), w3 = cmul(w2, w1);
;   o0 = b0; o1 = cmul(b1, w1); o2 = cmul(b2, w2); o3 = cmul(b3, w3);
; }
;     ...
;   for (int gg = tid; gg < NBT * (N / 16); gg += NTHR) { const int g = gg & (N / 16 - 1); float2* z = z0 + (gg / (N / 16)) * N; const int jp = g & (Q2 - 1), base = ((g >> lq2) << (lq2 + 4)) + jp; float2 x[4][4];
; #pragma unroll
;     for (int q1 = 0; q1 < 4; ++q1)
; #pragma unroll
;       for (int q2 = 0; q2 < 4; ++q2) x[q1][q2] = z[base + q1 * Q1 + q2 * Q2];
; #pragma unroll
;     for (int q2 = 0; q2 < 4; ++q2) bfly_fwd(x[0][q2], x[1][q2], x[2][q2], x[3][q2], (float)(jp + q2 * Q2) * invM1, x[0][q2], x[1][q2], x[2][q2], x[3][q2]);
; #pragma unroll
;     for (int q1 = 0; q1 < 4; ++q1) bfly_fwd(x[q1][0], x[q1][1], x[q1][2], x[q1][3], (float)jp * invM2, x[q1][0], x[q1][1], x[q1][2], x[q1][3]);
; #pragma unroll
;     for (int q1 = 0; q1 < 4; ++q1)
; #pragma unroll
;       for (int q2 = 0; q2 < 4; ++q2) z[base + q1 * Q1 + q2 * Q2] = x[q1][q2]; }
	v_pk_add_f32 v[110:111], v[70:71], v[94:95]
	v_pk_add_f32 v[116:117], v[72:73], v[96:97]
	s_waitcnt lgkmcnt(9)
	v_pk_add_f32 v[112:113], v[86:87], v[102:103]
	v_pk_add_f32 v[118:119], v[88:89], v[104:105]
	v_pk_add_f32 v[122:123], v[82:83], v[98:99]
	s_waitcnt lgkmcnt(8)
	v_pk_add_f32 v[124:125], v[90:91], v[106:107]
	v_pk_add_f32 v[128:129], v[84:85], v[100:101]
	v_pk_add_f32 v[130:131], v[92:93], v[108:109]
	v_pk_add_f32 v[114:115], v[110:111], v[112:113]
	v_pk_add_f32 v[120:121], v[116:117], v[118:119]
	v_pk_add_f32 v[126:127], v[122:123], v[124:125]
	v_pk_add_f32 v[132:133], v[128:129], v[130:131]
	v_pk_add_f32 v[134:135], v[114:115], v[126:127]
	v_pk_add_f32 v[136:137], v[120:121], v[132:133]
	v_pk_add_f32 v[114:115], v[114:115], v[126:127] neg_lo:[0,1] neg_hi:[0,1]
	v_pk_add_f32 v[120:121], v[120:121], v[132:133] neg_lo:[0,1] neg_hi:[0,1]
	v_pk_add_f32 v[138:139], v[134:135], v[136:137]
	v_pk_add_f32 v[126:127], v[114:115], v[120:121] op_sel:[0,1] op_sel_hi:[1,0]
	v_pk_add_f32 v[114:115], v[114:115], v[120:121] op_sel:[0,1] op_sel_hi:[1,0] neg_lo:[0,1] neg_hi:[0,1]
	v_mov_b32_e32 v120, v126
	v_pk_mov_b32 v[132:133], v[114:115], v[126:127] op_sel:[1,0]
	v_mov_b32_e32 v121, v115
	v_pk_mul_f32 v[132:133], v[48:49], v[132:133]
	v_pk_add_f32 v[70:71], v[70:71], v[94:95] neg_lo:[0,1] neg_hi:[0,1]
	v_pk_fma_f32 v[140:141], v[50:51], v[126:127], v[132:133]
	v_pk_fma_f32 v[120:121], v[50:51], v[120:121], v[132:133] neg_lo:[0,0,1] neg_hi:[0,0,1]
	v_pk_add_f32 v[86:87], v[86:87], v[102:103] neg_lo:[0,1] neg_hi:[0,1]
	v_mov_b32_e32 v141, v121
	v_pk_add_f32 v[120:121], v[134:135], v[136:137] neg_lo:[0,1] neg_hi:[0,1]
	v_pk_add_f32 v[94:95], v[70:71], v[86:87] op_sel:[0,1] op_sel_hi:[1,0]
	v_pk_mul_f32 v[132:133], v[56:57], v[120:121]
	v_pk_add_f32 v[70:71], v[70:71], v[86:87] op_sel:[0,1] op_sel_hi:[1,0] neg_lo:[0,1] neg_hi:[0,1]
	v_pk_fma_f32 v[134:135], v[54:55], v[120:121], v[132:133] op_sel:[0,0,1] op_sel_hi:[1,1,0] neg_lo:[0,0,1] neg_hi:[0,0,1]
	v_pk_fma_f32 v[120:121], v[54:55], v[120:121], v[132:133] op_sel:[0,0,1] op_sel_hi:[1,1,0]
	v_pk_mov_b32 v[102:103], v[70:71], v[94:95] op_sel:[1,0]
	v_mov_b32_e32 v135, v121
	v_mov_b32_e32 v121, v127
	v_pk_mov_b32 v[126:127], v[126:127], v[114:115] op_sel:[1,0]
	v_mov_b32_e32 v120, v114
	v_pk_mul_f32 v[126:127], v[60:61], v[126:127]
	v_mov_b32_e32 v86, v94
	v_pk_fma_f32 v[114:115], v[58:59], v[114:115], v[126:127] neg_lo:[0,0,1] neg_hi:[0,0,1]
	v_pk_fma_f32 v[120:121], v[58:59], v[120:121], v[126:127]
	v_mov_b32_e32 v87, v71
	v_mov_b32_e32 v115, v121
	v_pk_mul_f32 v[102:103], v[2:3], v[102:103]
	ds_write2_b64 v142, v[134:135], v[114:115] offset0:32 offset1:48
	v_pk_fma_f32 v[114:115], v[4:5], v[94:95], v[102:103]
	v_pk_fma_f32 v[86:87], v[4:5], v[86:87], v[102:103] neg_lo:[0,0,1] neg_hi:[0,0,1]
	v_pk_add_f32 v[72:73], v[72:73], v[96:97] neg_lo:[0,1] neg_hi:[0,1]
	v_mov_b32_e32 v115, v87
	v_pk_add_f32 v[86:87], v[88:89], v[104:105] neg_lo:[0,1] neg_hi:[0,1]
	v_pk_add_f32 v[82:83], v[82:83], v[98:99] neg_lo:[0,1] neg_hi:[0,1]
	v_pk_add_f32 v[88:89], v[72:73], v[86:87] op_sel:[0,1] op_sel_hi:[1,0]
	v_pk_add_f32 v[72:73], v[72:73], v[86:87] op_sel:[0,1] op_sel_hi:[1,0] neg_lo:[0,1] neg_hi:[0,1]
	v_mov_b32_e32 v86, v88
	v_pk_mov_b32 v[96:97], v[72:73], v[88:89] op_sel:[1,0]
	v_mov_b32_e32 v87, v73
	v_pk_mul_f32 v[96:97], v[12:13], v[96:97]
	v_pk_add_f32 v[84:85], v[84:85], v[100:101] neg_lo:[0,1] neg_hi:[0,1]
	v_pk_fma_f32 v[102:103], v[14:15], v[88:89], v[96:97]
	v_pk_fma_f32 v[86:87], v[14:15], v[86:87], v[96:97] neg_lo:[0,0,1] neg_hi:[0,0,1]
	s_nop 0
	v_mov_b32_e32 v103, v87
	v_pk_add_f32 v[86:87], v[90:91], v[106:107] neg_lo:[0,1] neg_hi:[0,1]
	ds_write2_b64 v142, v[138:139], v[140:141] offset1:16
	v_pk_add_f32 v[90:91], v[82:83], v[86:87] op_sel:[0,1] op_sel_hi:[1,0]
	v_pk_add_f32 v[82:83], v[82:83], v[86:87] op_sel:[0,1] op_sel_hi:[1,0] neg_lo:[0,1] neg_hi:[0,1]
	v_mov_b32_e32 v86, v90
	v_pk_mov_b32 v[96:97], v[82:83], v[90:91] op_sel:[1,0]
	v_mov_b32_e32 v87, v83
	v_pk_mul_f32 v[96:97], v[24:25], v[96:97]
	s_nop 0
	v_pk_fma_f32 v[98:99], v[26:27], v[90:91], v[96:97]
	v_pk_fma_f32 v[86:87], v[26:27], v[86:87], v[96:97] neg_lo:[0,0,1] neg_hi:[0,0,1]
	s_nop 0
	v_mov_b32_e32 v99, v87
	v_pk_add_f32 v[86:87], v[92:93], v[108:109] neg_lo:[0,1] neg_hi:[0,1]
	s_nop 0
	v_pk_add_f32 v[92:93], v[84:85], v[86:87] op_sel:[0,1] op_sel_hi:[1,0]
	v_pk_add_f32 v[84:85], v[84:85], v[86:87] op_sel:[0,1] op_sel_hi:[1,0] neg_lo:[0,1] neg_hi:[0,1]
	v_mov_b32_e32 v86, v92
	v_pk_mov_b32 v[96:97], v[84:85], v[92:93] op_sel:[1,0]
	v_mov_b32_e32 v87, v85
	v_pk_mul_f32 v[96:97], v[36:37], v[96:97]
	s_nop 0
	v_pk_fma_f32 v[100:101], v[38:39], v[92:93], v[96:97]
	v_pk_fma_f32 v[86:87], v[38:39], v[86:87], v[96:97] neg_lo:[0,0,1] neg_hi:[0,0,1]
	s_nop 0
	v_mov_b32_e32 v101, v87
	v_pk_add_f32 v[86:87], v[114:115], v[98:99]
	v_pk_add_f32 v[96:97], v[102:103], v[100:101]
	v_pk_add_f32 v[98:99], v[114:115], v[98:99] neg_lo:[0,1] neg_hi:[0,1]
	v_pk_add_f32 v[100:101], v[102:103], v[100:101] neg_lo:[0,1] neg_hi:[0,1]
	v_pk_add_f32 v[104:105], v[86:87], v[96:97]
	v_pk_add_f32 v[102:103], v[98:99], v[100:101] op_sel:[0,1] op_sel_hi:[1,0]
	v_pk_add_f32 v[98:99], v[98:99], v[100:101] op_sel:[0,1] op_sel_hi:[1,0] neg_lo:[0,1] neg_hi:[0,1]
	v_mov_b32_e32 v100, v102
	v_pk_mov_b32 v[106:107], v[98:99], v[102:103] op_sel:[1,0]
	v_mov_b32_e32 v101, v99
	v_pk_mul_f32 v[106:107], v[48:49], v[106:107]
	v_pk_add_f32 v[86:87], v[86:87], v[96:97] neg_lo:[0,1] neg_hi:[0,1]
	v_pk_fma_f32 v[108:109], v[50:51], v[102:103], v[106:107]
	v_pk_fma_f32 v[100:101], v[50:51], v[100:101], v[106:107] neg_lo:[0,0,1] neg_hi:[0,0,1]
	v_pk_mul_f32 v[96:97], v[56:57], v[86:87]
; DI float2 twid(float r) { return float2{__builtin_amdgcn_cosf(r), -__builtin_amdgcn_sinf(r)}; }
; DI void bfly_fwd(float2 a0, float2 a1, float2 a2, float2 a3, float r, float2& o0, float2& o1, float2& o2, float2& o3) {
;   float2 t0 = {a0.x + a2.x, a0.y + a2.y}, t1 = {a0.x - a2.x, a0.y - a2.y}, t2 = {a1.x + a3.x, a1.y + a3.y}, t3 = {a1.x - a3.x, a1.y - a3.y};
;   float2 b0 = {t0.x + t2.x, t0.y + t2.y}, b2 = {t0.x - t2.x, t0.y - t2.y}, b1 = {t1.x + t3.y, t1.y - t3.x}, b3 = {t1.x - t3.y, t1.y + t3.x};
;   float2 w1 = twid(r), w2 = cmul(w1, w1), w3 = cmul(w2, w1);
;   o0 = b0; o1 = cmul(b1, w1); o2 = cmul(b2, w2); o3 = cmul(b3, w3);
; }
;     ...
;   for (int gg = tid; gg < NBT * (N / 16); gg += NTHR) { const int g = gg & (N / 16 - 1); float2* z = z0 + (gg / (N / 16)) * N; const int jp = g & (Q2 - 1), base = ((g >> lq2) << (lq2 + 4)) + jp; float2 x[4][4];
; #pragma unroll
;     for (int q1 = 0; q1 < 4; ++q1)
; #pragma unroll
;       for (int q2 = 0; q2 < 4; ++q2) x[q1][q2] = z[base + q1 * Q1 + q2 * Q2];
; #pragma unroll
;     for (int q2 = 0; q2 < 4; ++q2) bfly_fwd(x[0][q2], x[1][q2], x[2][q2], x[3][q2], (float)(jp + q2 * Q2) * invM1, x[0][q2], x[1][q2], x[2][q2], x[3][q2]);
; #pragma unroll
;     for (int q1 = 0; q1 < 4; ++q1) bfly_fwd(x[q1][0], x[q1][1], x[q1][2], x[q1][3], (float)jp * invM2, x[q1][0], x[q1][1], x[q1][2], x[q1][3]);
; #pragma unroll
;     for (int q1 = 0; q1 < 4; ++q1)
; #pragma unroll
;       for (int q2 = 0; q2 < 4; ++q2) z[base + q1 * Q1 + q2 * Q2] = x[q1][q2]; }
	v_mov_b32_e32 v109, v101
	v_pk_fma_f32 v[100:101], v[54:55], v[86:87], v[96:97] op_sel:[0,0,1] op_sel_hi:[1,1,0] neg_lo:[0,0,1] neg_hi:[0,0,1]
	v_pk_fma_f32 v[86:87], v[54:55], v[86:87], v[96:97] op_sel:[0,0,1] op_sel_hi:[1,1,0]
	v_pk_mov_b32 v[96:97], v[102:103], v[98:99] op_sel:[1,0]
	v_mov_b32_e32 v101, v87
	v_mov_b32_e32 v86, v98
	v_mov_b32_e32 v87, v103
	v_pk_mul_f32 v[96:97], v[60:61], v[96:97]
	ds_write2_b64 v142, v[104:105], v[108:109] offset0:64 offset1:80
	v_pk_fma_f32 v[98:99], v[58:59], v[98:99], v[96:97] neg_lo:[0,0,1] neg_hi:[0,0,1]
	v_pk_fma_f32 v[86:87], v[58:59], v[86:87], v[96:97]
	s_nop 0
	v_mov_b32_e32 v99, v87
	v_pk_add_f32 v[86:87], v[110:111], v[112:113] neg_lo:[0,1] neg_hi:[0,1]
	ds_write2_b64 v142, v[100:101], v[98:99] offset0:96 offset1:112
	v_pk_mul_f32 v[96:97], v[8:9], v[86:87] op_sel:[0,1] op_sel_hi:[1,0]
	s_nop 0
	v_pk_fma_f32 v[98:99], v[6:7], v[86:87], v[96:97] neg_lo:[0,0,1] neg_hi:[0,0,1]
	v_pk_fma_f32 v[86:87], v[6:7], v[86:87], v[96:97]
	s_nop 0
	v_mov_b32_e32 v99, v87
	v_pk_add_f32 v[86:87], v[116:117], v[118:119] neg_lo:[0,1] neg_hi:[0,1]
	s_nop 0
	v_pk_mul_f32 v[96:97], v[20:21], v[86:87] op_sel:[0,1] op_sel_hi:[1,0]
	s_nop 0
	v_pk_fma_f32 v[100:101], v[18:19], v[86:87], v[96:97] neg_lo:[0,0,1] neg_hi:[0,0,1]
	v_pk_fma_f32 v[86:87], v[18:19], v[86:87], v[96:97]
	s_nop 0
	v_mov_b32_e32 v101, v87
	v_pk_add_f32 v[86:87], v[122:123], v[124:125] neg_lo:[0,1] neg_hi:[0,1]
	s_nop 0
	v_pk_mul_f32 v[96:97], v[32:33], v[86:87] op_sel:[0,1] op_sel_hi:[1,0]
	s_nop 0
	v_pk_fma_f32 v[102:103], v[30:31], v[86:87], v[96:97] neg_lo:[0,0,1] neg_hi:[0,0,1]
	v_pk_fma_f32 v[86:87], v[30:31], v[86:87], v[96:97]
	s_nop 0
	v_mov_b32_e32 v103, v87
	v_pk_add_f32 v[86:87], v[128:129], v[130:131] neg_lo:[0,1] neg_hi:[0,1]
	s_nop 0
	v_pk_mul_f32 v[96:97], v[44:45], v[86:87] op_sel:[0,1] op_sel_hi:[1,0]
	s_nop 0
	v_pk_fma_f32 v[104:105], v[42:43], v[86:87], v[96:97] neg_lo:[0,0,1] neg_hi:[0,0,1]
	v_pk_fma_f32 v[86:87], v[42:43], v[86:87], v[96:97]
	s_nop 0
	v_mov_b32_e32 v105, v87
	v_pk_add_f32 v[86:87], v[98:99], v[102:103]
	v_pk_add_f32 v[96:97], v[100:101], v[104:105]
	v_pk_add_f32 v[98:99], v[98:99], v[102:103] neg_lo:[0,1] neg_hi:[0,1]
	v_pk_add_f32 v[100:101], v[100:101], v[104:105] neg_lo:[0,1] neg_hi:[0,1]
	v_pk_add_f32 v[106:107], v[86:87], v[96:97]
	v_pk_add_f32 v[102:103], v[98:99], v[100:101] op_sel:[0,1] op_sel_hi:[1,0]
	v_pk_add_f32 v[98:99], v[98:99], v[100:101] op_sel:[0,1] op_sel_hi:[1,0] neg_lo:[0,1] neg_hi:[0,1]
	v_mov_b32_e32 v100, v102
	v_pk_mov_b32 v[104:105], v[98:99], v[102:103] op_sel:[1,0]
	v_mov_b32_e32 v101, v99
	v_pk_mul_f32 v[104:105], v[48:49], v[104:105]
	v_pk_add_f32 v[86:87], v[86:87], v[96:97] neg_lo:[0,1] neg_hi:[0,1]
	v_pk_fma_f32 v[108:109], v[50:51], v[102:103], v[104:105]
	v_pk_fma_f32 v[100:101], v[50:51], v[100:101], v[104:105] neg_lo:[0,0,1] neg_hi:[0,0,1]
	v_pk_mul_f32 v[96:97], v[56:57], v[86:87]
	v_mov_b32_e32 v109, v101
	v_pk_fma_f32 v[100:101], v[54:55], v[86:87], v[96:97] op_sel:[0,0,1] op_sel_hi:[1,1,0] neg_lo:[0,0,1] neg_hi:[0,0,1]
	v_pk_fma_f32 v[86:87], v[54:55], v[86:87], v[96:97] op_sel:[0,0,1] op_sel_hi:[1,1,0]
	v_pk_mov_b32 v[96:97], v[102:103], v[98:99] op_sel:[1,0]
	v_mov_b32_e32 v101, v87
	v_mov_b32_e32 v86, v98
	v_mov_b32_e32 v87, v103
	v_pk_mul_f32 v[96:97], v[60:61], v[96:97]
	ds_write2_b64 v142, v[106:107], v[108:109] offset0:128 offset1:144
	v_pk_fma_f32 v[98:99], v[58:59], v[98:99], v[96:97] neg_lo:[0,0,1] neg_hi:[0,0,1]
	v_pk_fma_f32 v[86:87], v[58:59], v[86:87], v[96:97]
	s_nop 0
	v_mov_b32_e32 v99, v87
	v_mov_b32_e32 v87, v95
	v_pk_mov_b32 v[94:95], v[94:95], v[70:71] op_sel:[1,0]
	v_mov_b32_e32 v86, v70
	v_pk_mul_f32 v[94:95], v[16:17], v[94:95]
	ds_write2_b64 v142, v[100:101], v[98:99] offset0:160 offset1:176
	v_pk_fma_f32 v[70:71], v[10:11], v[70:71], v[94:95] neg_lo:[0,0,1] neg_hi:[0,0,1]
	v_pk_fma_f32 v[86:87], v[10:11], v[86:87], v[94:95]
	s_nop 0
	v_mov_b32_e32 v71, v87
	v_mov_b32_e32 v87, v89
	v_pk_mov_b32 v[88:89], v[88:89], v[72:73] op_sel:[1,0]
	v_mov_b32_e32 v86, v72
	v_pk_mul_f32 v[88:89], v[28:29], v[88:89]
	s_nop 0
	v_pk_fma_f32 v[72:73], v[22:23], v[72:73], v[88:89] neg_lo:[0,0,1] neg_hi:[0,0,1]
	v_pk_fma_f32 v[86:87], v[22:23], v[86:87], v[88:89]
	v_pk_mov_b32 v[88:89], v[90:91], v[82:83] op_sel:[1,0]
	v_mov_b32_e32 v73, v87
	v_mov_b32_e32 v86, v82
	v_mov_b32_e32 v87, v91
	v_pk_mul_f32 v[88:89], v[40:41], v[88:89]
	s_nop 0
	v_pk_fma_f32 v[82:83], v[34:35], v[82:83], v[88:89] neg_lo:[0,0,1] neg_hi:[0,0,1]
	v_pk_fma_f32 v[86:87], v[34:35], v[86:87], v[88:89]
	v_pk_mov_b32 v[88:89], v[92:93], v[84:85] op_sel:[1,0]
	v_mov_b32_e32 v83, v87
	v_mov_b32_e32 v86, v84
	v_mov_b32_e32 v87, v93
	v_pk_mul_f32 v[88:89], v[52:53], v[88:89]
	s_nop 0
	v_pk_fma_f32 v[84:85], v[46:47], v[84:85], v[88:89] neg_lo:[0,0,1] neg_hi:[0,0,1]
	v_pk_fma_f32 v[86:87], v[46:47], v[86:87], v[88:89]
	s_nop 0
	v_mov_b32_e32 v85, v87
	v_pk_add_f32 v[86:87], v[70:71], v[82:83]
	v_pk_add_f32 v[88:89], v[72:73], v[84:85]
	v_pk_add_f32 v[70:71], v[70:71], v[82:83] neg_lo:[0,1] neg_hi:[0,1]
	v_pk_add_f32 v[72:73], v[72:73], v[84:85] neg_lo:[0,1] neg_hi:[0,1]
	v_pk_add_f32 v[90:91], v[86:87], v[88:89]
	v_pk_add_f32 v[82:83], v[70:71], v[72:73] op_sel:[0,1] op_sel_hi:[1,0]
	v_pk_add_f32 v[70:71], v[70:71], v[72:73] op_sel:[0,1] op_sel_hi:[1,0] neg_lo:[0,1] neg_hi:[0,1]
	v_mov_b32_e32 v72, v82
	v_pk_mov_b32 v[84:85], v[70:71], v[82:83] op_sel:[1,0]
	v_mov_b32_e32 v73, v71
	v_pk_mul_f32 v[84:85], v[48:49], v[84:85]
	s_nop 0
	v_pk_fma_f32 v[92:93], v[50:51], v[82:83], v[84:85]
	v_pk_fma_f32 v[72:73], v[50:51], v[72:73], v[84:85] neg_lo:[0,0,1] neg_hi:[0,0,1]
	s_nop 0
	v_mov_b32_e32 v93, v73
	v_pk_add_f32 v[72:73], v[86:87], v[88:89] neg_lo:[0,1] neg_hi:[0,1]
	ds_write2_b64 v142, v[90:91], v[92:93] offset0:192 offset1:208
	v_pk_mul_f32 v[84:85], v[56:57], v[72:73]
	s_nop 0
	v_pk_fma_f32 v[86:87], v[54:55], v[72:73], v[84:85] op_sel:[0,0,1] op_sel_hi:[1,1,0] neg_lo:[0,0,1] neg_hi:[0,0,1]
	v_pk_fma_f32 v[72:73], v[54:55], v[72:73], v[84:85] op_sel:[0,0,1] op_sel_hi:[1,1,0]
	s_nop 0
	v_mov_b32_e32 v87, v73
	v_mov_b32_e32 v73, v83
	v_pk_mov_b32 v[82:83], v[82:83], v[70:71] op_sel:[1,0]
	v_mov_b32_e32 v72, v70
	v_pk_mul_f32 v[82:83], v[60:61], v[82:83]
	s_nop 0
	v_pk_fma_f32 v[70:71], v[58:59], v[70:71], v[82:83] neg_lo:[0,0,1] neg_hi:[0,0,1]
	v_pk_fma_f32 v[72:73], v[58:59], v[72:73], v[82:83]
	s_nop 0
	v_mov_b32_e32 v71, v73
	ds_write2_b64 v142, v[86:87], v[70:71] offset0:224 offset1:240
	s_nop 0
	v_add_u32_e32 v69, 0x200, v69
	s_nop 0
	s_waitcnt lgkmcnt(11)
; DI float2 twid(float r) { return float2{__builtin_amdgcn_cosf(r), -__builtin_amdgcn_sinf(r)}; }
; DI void bfly_fwd(float2 a0, float2 a1, float2 a2, float2 a3, float r, float2& o0, float2& o1, float2& o2, float2& o3) {
;   float2 t0 = {a0.x + a2.x, a0.y + a2.y}, t1 = {a0.x - a2.x, a0.y - a2.y}, t2 = {a1.x + a3.x, a1.y + a3.y}, t3 = {a1.x - a3.x, a1.y - a3.y};
;   float2 b0 = {t0.x + t2.x, t0.y + t2.y}, b2 = {t0.x - t2.x, t0.y - t2.y}, b1 = {t1.x + t3.y, t1.y - t3.x}, b3 = {t1.x - t3.y, t1.y + t3.x};
;   float2 w1 = twid(r), w2 = cmul(w1, w1), w3 = cmul(w2, w1);
;   o0 = b0; o1 = cmul(b1, w1); o2 = cmul(b2, w2); o3 = cmul(b3, w3);
; }
;     ...
;   for (int gg = tid; gg < NBT * (N / 16); gg += NTHR) { const int g = gg & (N / 16 - 1); float2* z = z0 + (gg / (N / 16)) * N; const int jp = g & (Q2 - 1), base = ((g >> lq2) << (lq2 + 4)) + jp; float2 x[4][4];
; #pragma unroll
;     for (int q1 = 0; q1 < 4; ++q1)
; #pragma unroll
;       for (int q2 = 0; q2 < 4; ++q2) x[q1][q2] = z[base + q1 * Q1 + q2 * Q2];
; #pragma unroll
;     for (int q2 = 0; q2 < 4; ++q2) bfly_fwd(x[0][q2], x[1][q2], x[2][q2], x[3][q2], (float)(jp + q2 * Q2) * invM1, x[0][q2], x[1][q2], x[2][q2], x[3][q2]);
; #pragma unroll
;     for (int q1 = 0; q1 < 4; ++q1) bfly_fwd(x[q1][0], x[q1][1], x[q1][2], x[q1][3], (float)jp * invM2, x[q1][0], x[q1][1], x[q1][2], x[q1][3]);
; #pragma unroll
;     for (int q1 = 0; q1 < 4; ++q1)
; #pragma unroll
;       for (int q2 = 0; q2 < 4; ++q2) z[base + q1 * Q1 + q2 * Q2] = x[q1][q2]; }
	v_pk_add_f32 v[110:111], v[220:221], v[236:237]
	v_pk_add_f32 v[116:117], v[222:223], v[238:239]
	s_waitcnt lgkmcnt(9)
	v_pk_add_f32 v[112:113], v[228:229], v[248:249]
	v_pk_add_f32 v[118:119], v[230:231], v[250:251]
	v_pk_add_f32 v[122:123], v[224:225], v[244:245]
	s_waitcnt lgkmcnt(8)
	v_pk_add_f32 v[124:125], v[232:233], v[252:253]
	v_pk_add_f32 v[128:129], v[226:227], v[246:247]
	v_pk_add_f32 v[130:131], v[234:235], v[254:255]
	v_pk_add_f32 v[114:115], v[110:111], v[112:113]
	v_pk_add_f32 v[120:121], v[116:117], v[118:119]
	v_pk_add_f32 v[126:127], v[122:123], v[124:125]
	v_pk_add_f32 v[132:133], v[128:129], v[130:131]
	v_pk_add_f32 v[134:135], v[114:115], v[126:127]
	v_pk_add_f32 v[136:137], v[120:121], v[132:133]
	v_pk_add_f32 v[114:115], v[114:115], v[126:127] neg_lo:[0,1] neg_hi:[0,1]
	v_pk_add_f32 v[120:121], v[120:121], v[132:133] neg_lo:[0,1] neg_hi:[0,1]
	v_pk_add_f32 v[138:139], v[134:135], v[136:137]
	v_pk_add_f32 v[126:127], v[114:115], v[120:121] op_sel:[0,1] op_sel_hi:[1,0]
	v_pk_add_f32 v[114:115], v[114:115], v[120:121] op_sel:[0,1] op_sel_hi:[1,0] neg_lo:[0,1] neg_hi:[0,1]
	v_mov_b32_e32 v120, v126
	v_pk_mov_b32 v[132:133], v[114:115], v[126:127] op_sel:[1,0]
	v_mov_b32_e32 v121, v115
	v_pk_mul_f32 v[132:133], v[48:49], v[132:133]
	v_pk_add_f32 v[220:221], v[220:221], v[236:237] neg_lo:[0,1] neg_hi:[0,1]
	v_pk_fma_f32 v[140:141], v[50:51], v[126:127], v[132:133]
	v_pk_fma_f32 v[120:121], v[50:51], v[120:121], v[132:133] neg_lo:[0,0,1] neg_hi:[0,0,1]
	v_pk_add_f32 v[228:229], v[228:229], v[248:249] neg_lo:[0,1] neg_hi:[0,1]
	v_mov_b32_e32 v141, v121
	v_pk_add_f32 v[120:121], v[134:135], v[136:137] neg_lo:[0,1] neg_hi:[0,1]
	v_pk_add_f32 v[236:237], v[220:221], v[228:229] op_sel:[0,1] op_sel_hi:[1,0]
	v_pk_mul_f32 v[132:133], v[56:57], v[120:121]
	v_pk_add_f32 v[220:221], v[220:221], v[228:229] op_sel:[0,1] op_sel_hi:[1,0] neg_lo:[0,1] neg_hi:[0,1]
	v_pk_fma_f32 v[134:135], v[54:55], v[120:121], v[132:133] op_sel:[0,0,1] op_sel_hi:[1,1,0] neg_lo:[0,0,1] neg_hi:[0,0,1]
	v_pk_fma_f32 v[120:121], v[54:55], v[120:121], v[132:133] op_sel:[0,0,1] op_sel_hi:[1,1,0]
	v_pk_mov_b32 v[248:249], v[220:221], v[236:237] op_sel:[1,0]
	v_mov_b32_e32 v135, v121
	v_mov_b32_e32 v121, v127
	v_pk_mov_b32 v[126:127], v[126:127], v[114:115] op_sel:[1,0]
	v_mov_b32_e32 v120, v114
	v_pk_mul_f32 v[126:127], v[60:61], v[126:127]
	v_mov_b32_e32 v228, v236
	v_pk_fma_f32 v[114:115], v[58:59], v[114:115], v[126:127] neg_lo:[0,0,1] neg_hi:[0,0,1]
	v_pk_fma_f32 v[120:121], v[58:59], v[120:121], v[126:127]
	v_mov_b32_e32 v229, v221
	v_mov_b32_e32 v115, v121
	v_pk_mul_f32 v[248:249], v[2:3], v[248:249]
	ds_write2_b64 v219, v[134:135], v[114:115] offset0:32 offset1:48
	v_pk_fma_f32 v[114:115], v[4:5], v[236:237], v[248:249]
	v_pk_fma_f32 v[228:229], v[4:5], v[228:229], v[248:249] neg_lo:[0,0,1] neg_hi:[0,0,1]
	v_pk_add_f32 v[222:223], v[222:223], v[238:239] neg_lo:[0,1] neg_hi:[0,1]
	v_mov_b32_e32 v115, v229
	v_pk_add_f32 v[228:229], v[230:231], v[250:251] neg_lo:[0,1] neg_hi:[0,1]
	v_pk_add_f32 v[224:225], v[224:225], v[244:245] neg_lo:[0,1] neg_hi:[0,1]
	v_pk_add_f32 v[230:231], v[222:223], v[228:229] op_sel:[0,1] op_sel_hi:[1,0]
	v_pk_add_f32 v[222:223], v[222:223], v[228:229] op_sel:[0,1] op_sel_hi:[1,0] neg_lo:[0,1] neg_hi:[0,1]
	v_mov_b32_e32 v228, v230
	v_pk_mov_b32 v[238:239], v[222:223], v[230:231] op_sel:[1,0]
	v_mov_b32_e32 v229, v223
	v_pk_mul_f32 v[238:239], v[12:13], v[238:239]
	v_pk_add_f32 v[226:227], v[226:227], v[246:247] neg_lo:[0,1] neg_hi:[0,1]
	v_pk_fma_f32 v[248:249], v[14:15], v[230:231], v[238:239]
	v_pk_fma_f32 v[228:229], v[14:15], v[228:229], v[238:239] neg_lo:[0,0,1] neg_hi:[0,0,1]
	s_nop 0
	v_mov_b32_e32 v249, v229
	v_pk_add_f32 v[228:229], v[232:233], v[252:253] neg_lo:[0,1] neg_hi:[0,1]
	ds_write2_b64 v219, v[138:139], v[140:141] offset1:16
	v_pk_add_f32 v[232:233], v[224:225], v[228:229] op_sel:[0,1] op_sel_hi:[1,0]
	v_pk_add_f32 v[224:225], v[224:225], v[228:229] op_sel:[0,1] op_sel_hi:[1,0] neg_lo:[0,1] neg_hi:[0,1]
	v_mov_b32_e32 v228, v232
	v_pk_mov_b32 v[238:239], v[224:225], v[232:233] op_sel:[1,0]
	v_mov_b32_e32 v229, v225
	v_pk_mul_f32 v[238:239], v[24:25], v[238:239]
	s_nop 0
	v_pk_fma_f32 v[244:245], v[26:27], v[232:233], v[238:239]
	v_pk_fma_f32 v[228:229], v[26:27], v[228:229], v[238:239] neg_lo:[0,0,1] neg_hi:[0,0,1]
	s_nop 0
	v_mov_b32_e32 v245, v229
	v_pk_add_f32 v[228:229], v[234:235], v[254:255] neg_lo:[0,1] neg_hi:[0,1]
	s_nop 0
	v_pk_add_f32 v[234:235], v[226:227], v[228:229] op_sel:[0,1] op_sel_hi:[1,0]
	v_pk_add_f32 v[226:227], v[226:227], v[228:229] op_sel:[0,1] op_sel_hi:[1,0] neg_lo:[0,1] neg_hi:[0,1]
	v_mov_b32_e32 v228, v234
	v_pk_mov_b32 v[238:239], v[226:227], v[234:235] op_sel:[1,0]
	v_mov_b32_e32 v229, v227
	v_pk_mul_f32 v[238:239], v[36:37], v[238:239]
	s_nop 0
	v_pk_fma_f32 v[246:247], v[38:39], v[234:235], v[238:239]
	v_pk_fma_f32 v[228:229], v[38:39], v[228:229], v[238:239] neg_lo:[0,0,1] neg_hi:[0,0,1]
	s_nop 0
	v_mov_b32_e32 v247, v229
	v_pk_add_f32 v[228:229], v[114:115], v[244:245]
	v_pk_add_f32 v[238:239], v[248:249], v[246:247]
	v_pk_add_f32 v[244:245], v[114:115], v[244:245] neg_lo:[0,1] neg_hi:[0,1]
	v_pk_add_f32 v[246:247], v[248:249], v[246:247] neg_lo:[0,1] neg_hi:[0,1]
	v_pk_add_f32 v[250:251], v[228:229], v[238:239]
	v_pk_add_f32 v[248:249], v[244:245], v[246:247] op_sel:[0,1] op_sel_hi:[1,0]
	v_pk_add_f32 v[244:245], v[244:245], v[246:247] op_sel:[0,1] op_sel_hi:[1,0] neg_lo:[0,1] neg_hi:[0,1]
	v_mov_b32_e32 v246, v248
	v_pk_mov_b32 v[252:253], v[244:245], v[248:249] op_sel:[1,0]
	v_mov_b32_e32 v247, v245
	v_pk_mul_f32 v[252:253], v[48:49], v[252:253]
; DI float2 twid(float r) { return float2{__builtin_amdgcn_cosf(r), -__builtin_amdgcn_sinf(r)}; }
; DI void bfly_fwd(float2 a0, float2 a1, float2 a2, float2 a3, float r, float2& o0, float2& o1, float2& o2, float2& o3) {
;   float2 t0 = {a0.x + a2.x, a0.y + a2.y}, t1 = {a0.x - a2.x, a0.y - a2.y}, t2 = {a1.x + a3.x, a1.y + a3.y}, t3 = {a1.x - a3.x, a1.y - a3.y};
;   float2 b0 = {t0.x + t2.x, t0.y + t2.y}, b2 = {t0.x - t2.x, t0.y - t2.y}, b1 = {t1.x + t3.y, t1.y - t3.x}, b3 = {t1.x - t3.y, t1.y + t3.x};
;   float2 w1 = twid(r), w2 = cmul(w1, w1), w3 = cmul(w2, w1);
;   o0 = b0; o1 = cmul(b1, w1); o2 = cmul(b2, w2); o3 = cmul(b3, w3);
; }
;     ...
;   for (int gg = tid; gg < NBT * (N / 16); gg += NTHR) { const int g = gg & (N / 16 - 1); float2* z = z0 + (gg / (N / 16)) * N; const int jp = g & (Q2 - 1), base = ((g >> lq2) << (lq2 + 4)) + jp; float2 x[4][4];
; #pragma unroll
;     for (int q1 = 0; q1 < 4; ++q1)
; #pragma unroll
;       for (int q2 = 0; q2 < 4; ++q2) x[q1][q2] = z[base + q1 * Q1 + q2 * Q2];
; #pragma unroll
;     for (int q2 = 0; q2 < 4; ++q2) bfly_fwd(x[0][q2], x[1][q2], x[2][q2], x[3][q2], (float)(jp + q2 * Q2) * invM1, x[0][q2], x[1][q2], x[2][q2], x[3][q2]);
; #pragma unroll
;     for (int q1 = 0; q1 < 4; ++q1) bfly_fwd(x[q1][0], x[q1][1], x[q1][2], x[q1][3], (float)jp * invM2, x[q1][0], x[q1][1], x[q1][2], x[q1][3]);
; #pragma unroll
;     for (int q1 = 0; q1 < 4; ++q1)
; #pragma unroll
;       for (int q2 = 0; q2 < 4; ++q2) z[base + q1 * Q1 + q2 * Q2] = x[q1][q2]; }
	v_pk_add_f32 v[228:229], v[228:229], v[238:239] neg_lo:[0,1] neg_hi:[0,1]
	v_pk_fma_f32 v[254:255], v[50:51], v[248:249], v[252:253]
	v_pk_fma_f32 v[246:247], v[50:51], v[246:247], v[252:253] neg_lo:[0,0,1] neg_hi:[0,0,1]
	v_pk_mul_f32 v[238:239], v[56:57], v[228:229]
	v_mov_b32_e32 v255, v247
	v_pk_fma_f32 v[246:247], v[54:55], v[228:229], v[238:239] op_sel:[0,0,1] op_sel_hi:[1,1,0] neg_lo:[0,0,1] neg_hi:[0,0,1]
	v_pk_fma_f32 v[228:229], v[54:55], v[228:229], v[238:239] op_sel:[0,0,1] op_sel_hi:[1,1,0]
	v_pk_mov_b32 v[238:239], v[248:249], v[244:245] op_sel:[1,0]
	v_mov_b32_e32 v247, v229
	v_mov_b32_e32 v228, v244
	v_mov_b32_e32 v229, v249
	v_pk_mul_f32 v[238:239], v[60:61], v[238:239]
	ds_write2_b64 v219, v[250:251], v[254:255] offset0:64 offset1:80
	v_pk_fma_f32 v[244:245], v[58:59], v[244:245], v[238:239] neg_lo:[0,0,1] neg_hi:[0,0,1]
	v_pk_fma_f32 v[228:229], v[58:59], v[228:229], v[238:239]
	s_nop 0
	v_mov_b32_e32 v245, v229
	v_pk_add_f32 v[228:229], v[110:111], v[112:113] neg_lo:[0,1] neg_hi:[0,1]
	ds_write2_b64 v219, v[246:247], v[244:245] offset0:96 offset1:112
	v_pk_mul_f32 v[238:239], v[8:9], v[228:229] op_sel:[0,1] op_sel_hi:[1,0]
	s_nop 0
	v_pk_fma_f32 v[244:245], v[6:7], v[228:229], v[238:239] neg_lo:[0,0,1] neg_hi:[0,0,1]
	v_pk_fma_f32 v[228:229], v[6:7], v[228:229], v[238:239]
	s_nop 0
	v_mov_b32_e32 v245, v229
	v_pk_add_f32 v[228:229], v[116:117], v[118:119] neg_lo:[0,1] neg_hi:[0,1]
	s_nop 0
	v_pk_mul_f32 v[238:239], v[20:21], v[228:229] op_sel:[0,1] op_sel_hi:[1,0]
	s_nop 0
	v_pk_fma_f32 v[246:247], v[18:19], v[228:229], v[238:239] neg_lo:[0,0,1] neg_hi:[0,0,1]
	v_pk_fma_f32 v[228:229], v[18:19], v[228:229], v[238:239]
	s_nop 0
	v_mov_b32_e32 v247, v229
	v_pk_add_f32 v[228:229], v[122:123], v[124:125] neg_lo:[0,1] neg_hi:[0,1]
	s_nop 0
	v_pk_mul_f32 v[238:239], v[32:33], v[228:229] op_sel:[0,1] op_sel_hi:[1,0]
	s_nop 0
	v_pk_fma_f32 v[248:249], v[30:31], v[228:229], v[238:239] neg_lo:[0,0,1] neg_hi:[0,0,1]
	v_pk_fma_f32 v[228:229], v[30:31], v[228:229], v[238:239]
	s_nop 0
	v_mov_b32_e32 v249, v229
	v_pk_add_f32 v[228:229], v[128:129], v[130:131] neg_lo:[0,1] neg_hi:[0,1]
	s_nop 0
	v_pk_mul_f32 v[238:239], v[44:45], v[228:229] op_sel:[0,1] op_sel_hi:[1,0]
	s_nop 0
	v_pk_fma_f32 v[250:251], v[42:43], v[228:229], v[238:239] neg_lo:[0,0,1] neg_hi:[0,0,1]
	v_pk_fma_f32 v[228:229], v[42:43], v[228:229], v[238:239]
	s_nop 0
	v_mov_b32_e32 v251, v229
	v_pk_add_f32 v[228:229], v[244:245], v[248:249]
	v_pk_add_f32 v[238:239], v[246:247], v[250:251]
	v_pk_add_f32 v[244:245], v[244:245], v[248:249] neg_lo:[0,1] neg_hi:[0,1]
	v_pk_add_f32 v[246:247], v[246:247], v[250:251] neg_lo:[0,1] neg_hi:[0,1]
	v_pk_add_f32 v[252:253], v[228:229], v[238:239]
	v_pk_add_f32 v[248:249], v[244:245], v[246:247] op_sel:[0,1] op_sel_hi:[1,0]
	v_pk_add_f32 v[244:245], v[244:245], v[246:247] op_sel:[0,1] op_sel_hi:[1,0] neg_lo:[0,1] neg_hi:[0,1]
	v_mov_b32_e32 v246, v248
	v_pk_mov_b32 v[250:251], v[244:245], v[248:249] op_sel:[1,0]
	v_mov_b32_e32 v247, v245
	v_pk_mul_f32 v[250:251], v[48:49], v[250:251]
	v_pk_add_f32 v[228:229], v[228:229], v[238:239] neg_lo:[0,1] neg_hi:[0,1]
	v_pk_fma_f32 v[254:255], v[50:51], v[248:249], v[250:251]
	v_pk_fma_f32 v[246:247], v[50:51], v[246:247], v[250:251] neg_lo:[0,0,1] neg_hi:[0,0,1]
	v_pk_mul_f32 v[238:239], v[56:57], v[228:229]
	v_mov_b32_e32 v255, v247
	v_pk_fma_f32 v[246:247], v[54:55], v[228:229], v[238:239] op_sel:[0,0,1] op_sel_hi:[1,1,0] neg_lo:[0,0,1] neg_hi:[0,0,1]
	v_pk_fma_f32 v[228:229], v[54:55], v[228:229], v[238:239] op_sel:[0,0,1] op_sel_hi:[1,1,0]
	v_pk_mov_b32 v[238:239], v[248:249], v[244:245] op_sel:[1,0]
; DI float2 twid(float r) { return float2{__builtin_amdgcn_cosf(r), -__builtin_amdgcn_sinf(r)}; }
; DI void bfly_fwd(float2 a0, float2 a1, float2 a2, float2 a3, float r, float2& o0, float2& o1, float2& o2, float2& o3) {
;   float2 t0 = {a0.x + a2.x, a0.y + a2.y}, t1 = {a0.x - a2.x, a0.y - a2.y}, t2 = {a1.x + a3.x, a1.y + a3.y}, t3 = {a1.x - a3.x, a1.y - a3.y};
;   float2 b0 = {t0.x + t2.x, t0.y + t2.y}, b2 = {t0.x - t2.x, t0.y - t2.y}, b1 = {t1.x + t3.y, t1.y - t3.x}, b3 = {t1.x - t3.y, t1.y + t3.x};
;   float2 w1 = twid(r), w2 = cmul(w1, w1), w3 = cmul(w2, w1);
;   o0 = b0; o1 = cmul(b1, w1); o2 = cmul(b2, w2); o3 = cmul(b3, w3);
; }
;     ...
;   for (int gg = tid; gg < NBT * (N / 16); gg += NTHR) { const int g = gg & (N / 16 - 1); float2* z = z0 + (gg / (N / 16)) * N; const int jp = g & (Q2 - 1), base = ((g >> lq2) << (lq2 + 4)) + jp; float2 x[4][4];
; #pragma unroll
;     for (int q1 = 0; q1 < 4; ++q1)
; #pragma unroll
;       for (int q2 = 0; q2 < 4; ++q2) x[q1][q2] = z[base + q1 * Q1 + q2 * Q2];
; #pragma unroll
;     for (int q2 = 0; q2 < 4; ++q2) bfly_fwd(x[0][q2], x[1][q2], x[2][q2], x[3][q2], (float)(jp + q2 * Q2) * invM1, x[0][q2], x[1][q2], x[2][q2], x[3][q2]);
; #pragma unroll
;     for (int q1 = 0; q1 < 4; ++q1) bfly_fwd(x[q1][0], x[q1][1], x[q1][2], x[q1][3], (float)jp * invM2, x[q1][0], x[q1][1], x[q1][2], x[q1][3]);
; #pragma unroll
;     for (int q1 = 0; q1 < 4; ++q1)
; #pragma unroll
;       for (int q2 = 0; q2 < 4; ++q2) z[base + q1 * Q1 + q2 * Q2] = x[q1][q2]; }
	v_mov_b32_e32 v247, v229
	v_mov_b32_e32 v228, v244
	v_mov_b32_e32 v229, v249
	v_pk_mul_f32 v[238:239], v[60:61], v[238:239]
	ds_write2_b64 v219, v[252:253], v[254:255] offset0:128 offset1:144
	v_pk_fma_f32 v[244:245], v[58:59], v[244:245], v[238:239] neg_lo:[0,0,1] neg_hi:[0,0,1]
	v_pk_fma_f32 v[228:229], v[58:59], v[228:229], v[238:239]
	s_nop 0
	v_mov_b32_e32 v245, v229
	v_mov_b32_e32 v229, v237
	v_pk_mov_b32 v[236:237], v[236:237], v[220:221] op_sel:[1,0]
	v_mov_b32_e32 v228, v220
	v_pk_mul_f32 v[236:237], v[16:17], v[236:237]
	ds_write2_b64 v219, v[246:247], v[244:245] offset0:160 offset1:176
	v_pk_fma_f32 v[220:221], v[10:11], v[220:221], v[236:237] neg_lo:[0,0,1] neg_hi:[0,0,1]
	v_pk_fma_f32 v[228:229], v[10:11], v[228:229], v[236:237]
	s_nop 0
	v_mov_b32_e32 v221, v229
	v_mov_b32_e32 v229, v231
	v_pk_mov_b32 v[230:231], v[230:231], v[222:223] op_sel:[1,0]
	v_mov_b32_e32 v228, v222
	v_pk_mul_f32 v[230:231], v[28:29], v[230:231]
	s_nop 0
	v_pk_fma_f32 v[222:223], v[22:23], v[222:223], v[230:231] neg_lo:[0,0,1] neg_hi:[0,0,1]
	v_pk_fma_f32 v[228:229], v[22:23], v[228:229], v[230:231]
	v_pk_mov_b32 v[230:231], v[232:233], v[224:225] op_sel:[1,0]
	v_mov_b32_e32 v223, v229
	v_mov_b32_e32 v228, v224
	v_mov_b32_e32 v229, v233
	v_pk_mul_f32 v[230:231], v[40:41], v[230:231]
	s_nop 0
	v_pk_fma_f32 v[224:225], v[34:35], v[224:225], v[230:231] neg_lo:[0,0,1] neg_hi:[0,0,1]
	v_pk_fma_f32 v[228:229], v[34:35], v[228:229], v[230:231]
	v_pk_mov_b32 v[230:231], v[234:235], v[226:227] op_sel:[1,0]
	v_mov_b32_e32 v225, v229
	v_mov_b32_e32 v228, v226
	v_mov_b32_e32 v229, v235
	v_pk_mul_f32 v[230:231], v[52:53], v[230:231]
	s_nop 0
	v_pk_fma_f32 v[226:227], v[46:47], v[226:227], v[230:231] neg_lo:[0,0,1] neg_hi:[0,0,1]
	v_pk_fma_f32 v[228:229], v[46:47], v[228:229], v[230:231]
	s_nop 0
	v_mov_b32_e32 v227, v229
	v_pk_add_f32 v[228:229], v[220:221], v[224:225]
	v_pk_add_f32 v[230:231], v[222:223], v[226:227]
	v_pk_add_f32 v[220:221], v[220:221], v[224:225] neg_lo:[0,1] neg_hi:[0,1]
	v_pk_add_f32 v[222:223], v[222:223], v[226:227] neg_lo:[0,1] neg_hi:[0,1]
	v_pk_add_f32 v[232:233], v[228:229], v[230:231]
	v_pk_add_f32 v[224:225], v[220:221], v[222:223] op_sel:[0,1] op_sel_hi:[1,0]
	v_pk_add_f32 v[220:221], v[220:221], v[222:223] op_sel:[0,1] op_sel_hi:[1,0] neg_lo:[0,1] neg_hi:[0,1]
	v_mov_b32_e32 v222, v224
	v_pk_mov_b32 v[226:227], v[220:221], v[224:225] op_sel:[1,0]
	v_mov_b32_e32 v223, v221
	v_pk_mul_f32 v[226:227], v[48:49], v[226:227]
	s_nop 0
	v_pk_fma_f32 v[234:235], v[50:51], v[224:225], v[226:227]
	v_pk_fma_f32 v[222:223], v[50:51], v[222:223], v[226:227] neg_lo:[0,0,1] neg_hi:[0,0,1]
	s_nop 0
	v_mov_b32_e32 v235, v223
	v_pk_add_f32 v[222:223], v[228:229], v[230:231] neg_lo:[0,1] neg_hi:[0,1]
	ds_write2_b64 v219, v[232:233], v[234:235] offset0:192 offset1:208
	v_pk_mul_f32 v[226:227], v[56:57], v[222:223]
	s_nop 0
	v_pk_fma_f32 v[228:229], v[54:55], v[222:223], v[226:227] op_sel:[0,0,1] op_sel_hi:[1,1,0] neg_lo:[0,0,1] neg_hi:[0,0,1]
	v_pk_fma_f32 v[222:223], v[54:55], v[222:223], v[226:227] op_sel:[0,0,1] op_sel_hi:[1,1,0]
	s_nop 0
	v_mov_b32_e32 v229, v223
	v_mov_b32_e32 v223, v225
	v_pk_mov_b32 v[224:225], v[224:225], v[220:221] op_sel:[1,0]
	v_mov_b32_e32 v222, v220
	v_pk_mul_f32 v[224:225], v[60:61], v[224:225]
	s_nop 0
	v_pk_fma_f32 v[220:221], v[58:59], v[220:221], v[224:225] neg_lo:[0,0,1] neg_hi:[0,0,1]
	v_pk_fma_f32 v[222:223], v[58:59], v[222:223], v[224:225]
	s_nop 0
	v_mov_b32_e32 v221, v223
	ds_write2_b64 v219, v[228:229], v[220:221] offset0:224 offset1:240
	s_nop 0
	v_add_u32_e32 v70, 0x200, v69
	s_nop 0
	v_mov_b32_e32 v69, v70

; DI float2 twid(float r) { return float2{__builtin_amdgcn_cosf(r), -__builtin_amdgcn_sinf(r)}; }
; DI void bfly_inv(float2 s0, float2 s1, float2 s2, float2 s3, float r, float2& o0, float2& o1, float2& o2, float2& o3) {
;   float2 w1 = twid(r), w2 = cmul(w1, w1), w3 = cmul(w2, w1);
;   float2 c0 = s0, c1 = cmulc(s1, w1), c2 = cmulc(s2, w2), c3 = cmulc(s3, w3);
;   float2 t0 = {c0.x + c2.x, c0.y + c2.y}, t1 = {c0.x - c2.x, c0.y - c2.y}, t2 = {c1.x + c3.x, c1.y + c3.y}, t3 = {c1.x - c3.x, c1.y - c3.y};
;   o0 = float2{t0.x + t2.x, t0.y + t2.y}; o2 = float2{t0.x - t2.x, t0.y - t2.y}; o1 = float2{t1.x - t3.y, t1.y + t3.x}; o3 = float2{t1.x + t3.y, t1.y - t3.x};
; }
;   const int lq1 = lq2 + 2, Q1 = 1 << lq1, Q2 = 1 << lq2; const float invM1 = 1.f / (float)(4 << lq1), invM2 = 1.f / (float)(4 << lq2);
;   for (int gg = tid; gg < NBT * (N / 16); gg += NTHR) { const int g = gg & (N / 16 - 1); float2* z = z0 + (gg / (N / 16)) * N; const int jp = g & (Q2 - 1), base = ((g >> lq2) << (lq2 + 4)) + jp; float2 x[4][4];
; #pragma unroll
;     for (int q1 = 0; q1 < 4; ++q1)
; #pragma unroll
;       for (int q2 = 0; q2 < 4; ++q2) x[q1][q2] = z[base + q1 * Q1 + q2 * Q2];
; #pragma unroll
;     for (int q1 = 0; q1 < 4; ++q1) bfly_inv(x[q1][0], x[q1][1], x[q1][2], x[q1][3], (float)jp * invM2, x[q1][0], x[q1][1], x[q1][2], x[q1][3]);
; #pragma unroll
;     for (int q2 = 0; q2 < 4; ++q2) bfly_inv(x[0][q2], x[1][q2], x[2][q2], x[3][q2], (float)(jp + q2 * Q2) * invM1, x[0][q2], x[1][q2], x[2][q2], x[3][q2]);
; #pragma unroll
;     for (int q1 = 0; q1 < 4; ++q1)
; #pragma unroll
;       for (int q2 = 0; q2 < 4; ++q2) z[base + q1 * Q1 + q2 * Q2] = x[q1][q2]; }
.LBB0_1616:
	s_or_b64 exec, exec, s[0:1]
	s_waitcnt lgkmcnt(0)
	s_barrier
	s_and_saveexec_b64 s[0:1], vcc
	s_cbranch_execz .LBB0_1619
	v_add3_u32 v20, 16, v66, v67
	v_mov_b32_e32 v82, v75
	v_ashrrev_i32_e32 v13, 31, v82
	v_lshrrev_b32_e32 v13, 23, v13
	v_add_lshl_u32 v13, v82, v13, 7
	v_and_b32_e32 v13, 0xffff0000, v13
	v_add_u32_e32 v83, v20, v13
	ds_read2_b64 v[84:87], v83 offset0:32 offset1:48
	ds_read2_b64 v[88:91], v83 offset1:16
	s_nop 0
	v_mul_f32_e32 v2, 0x3c800000, v65
	v_sin_f32_e32 v3, v2
	v_cos_f32_e32 v4, v2
	s_mov_b64 s[80:81], 0
	v_xor_b32_e32 v8, 0x80000000, v3
	v_mov_b32_e32 v2, v4
	v_mov_b32_e32 v6, v8
	v_mov_b32_e32 v7, v3
	v_mov_b32_e32 v5, v4
	v_mov_b32_e32 v9, v4
	v_pk_mul_f32 v[10:11], v[2:3], v[6:7]
	v_mov_b32_e32 v56, v4
	v_pk_fma_f32 v[6:7], v[4:5], v[8:9], v[10:11] op_sel_hi:[0,1,1] neg_lo:[0,0,1] neg_hi:[0,0,1]
	v_pk_fma_f32 v[8:9], v[4:5], v[8:9], v[10:11] op_sel_hi:[0,1,1]
	s_nop 0
	v_pk_mov_b32 v[10:11], v[6:7], v[8:9] op_sel:[1,0]
	v_mul_f32_e32 v6, 0x3b800000, v65
	v_sin_f32_e32 v12, v6
	v_cos_f32_e32 v14, v6
	v_mov_b32_e32 v16, v8
	v_mov_b32_e32 v17, v7
	v_mul_f32_e32 v6, v12, v12
	v_fma_f32 v22, v14, v14, -v6
	v_cvt_f32_ubyte0_e32 v6, v64
	v_mul_f32_e32 v6, 0x3b800000, v6
	v_sin_f32_e32 v25, v6
	v_cos_f32_e32 v27, v6
	v_pk_mul_f32 v[18:19], v[2:3], v[10:11] op_sel:[1,0]
	v_mul_f32_e64 v9, v14, -v12
	v_pk_fma_f32 v[10:11], v[4:5], v[16:17], v[18:19] op_sel_hi:[0,1,1]
	v_pk_fma_f32 v[16:17], v[4:5], v[16:17], v[18:19] op_sel_hi:[0,1,1] neg_lo:[0,0,1] neg_hi:[0,0,1]
	v_add_f32_e32 v18, v9, v9
	v_mul_f32_e32 v6, v12, v22
	v_fma_f32 v60, v14, v18, -v6
	v_mul_f32_e32 v6, v25, v25
	v_fma_f32 v28, v27, v27, -v6
	v_mul_f32_e64 v6, v27, -v25
	v_add_f32_e32 v30, v6, v6
	v_cvt_f32_ubyte0_e32 v6, v63
	v_mul_f32_e32 v6, 0x3b800000, v6
	v_sin_f32_e32 v33, v6
	v_cos_f32_e32 v35, v6
	v_mul_f32_e32 v6, v25, v28
	v_fma_f32 v26, v27, v30, -v6
	v_mul_f32_e32 v6, v33, v33
	v_fma_f32 v36, v35, v35, -v6
	v_mul_f32_e64 v6, v35, -v33
	v_add_f32_e32 v38, v6, v6
	v_cvt_f32_ubyte0_e32 v6, v62
	v_mul_f32_e32 v6, 0x3b800000, v6
	v_sin_f32_e32 v40, v6
	v_cos_f32_e32 v42, v6
	v_mul_f32_e32 v21, v12, v18
	v_mul_f32_e32 v24, v25, v30
	v_xor_b32_e32 v43, 0x80000000, v40
	v_mov_b32_e32 v41, v42
	v_mov_b32_e32 v44, v40
	v_mov_b32_e32 v45, v43
	v_pk_mul_f32 v[46:47], v[40:41], v[44:45]
	v_mul_f32_e32 v32, v33, v38
	v_pk_fma_f32 v[44:45], v[42:43], v[42:43], v[46:47] op_sel_hi:[0,1,1] neg_lo:[0,0,1] neg_hi:[0,0,1]
	v_pk_fma_f32 v[62:63], v[42:43], v[42:43], v[46:47] op_sel_hi:[0,1,1]
	s_nop 0
	v_pk_mov_b32 v[48:49], v[62:63], v[44:45] op_sel:[1,0]
	v_mul_f32_e32 v6, v33, v36
	v_mov_b32_e32 v46, v44
	v_mov_b32_e32 v47, v63
	v_pk_mul_f32 v[48:49], v[40:41], v[48:49] op_sel_hi:[0,1]
	v_fmac_f32_e32 v21, v14, v22
	v_fmac_f32_e32 v24, v27, v28
	v_fmac_f32_e32 v32, v35, v36
	v_fma_f32 v34, v35, v38, -v6
	v_pk_fma_f32 v[58:59], v[42:43], v[46:47], v[48:49] op_sel_hi:[0,1,1]
	v_pk_fma_f32 v[46:47], v[42:43], v[46:47], v[48:49] op_sel_hi:[0,1,1] neg_lo:[0,0,1] neg_hi:[0,0,1]
	v_mov_b32_e32 v19, v12
	v_mov_b32_e32 v17, v11
	v_mov_b32_e32 v46, v58
	v_mov_b32_e32 v9, v8
	v_mov_b32_e32 v29, v28
	v_mov_b32_e32 v31, v30
	v_pk_mov_b32 v[48:49], v[26:27], v[24:25] op_sel:[1,0]
	v_pk_mov_b32 v[50:51], v[24:25], v[26:27] op_sel:[1,0]
	v_mov_b32_e32 v37, v36
	v_pk_mov_b32 v[52:53], v[34:35], v[32:33] op_sel:[1,0]
	v_pk_mov_b32 v[54:55], v[32:33], v[34:35] op_sel:[1,0]
	v_mov_b32_e32 v57, v16
	v_mov_b32_e32 v10, v3
	v_pk_mov_b32 v[58:59], v[62:63], v[58:59] op_sel:[1,0]
	v_mov_b32_e32 v45, v47
	v_mov_b32_e32 v43, v44
	v_mov_b32_e32 v41, v63
	v_mov_b32_e32 v61, v16
	v_mov_b32_e32 v62, v3
	v_mov_b32_e32 v63, v3
	v_mov_b32_e32 v6, v7
	v_mov_b32_e32 v64, v4
	v_mov_b32_e32 v65, v11
	v_mov_b32_e32 v66, v3
	v_mov_b32_e32 v67, v16
	v_mov_b32_e32 v68, v11
	v_mov_b32_e32 v69, v11
	v_mov_b32_e32 v70, v16
	v_mov_b32_e32 v71, v16
	v_mov_b32_e32 v23, v14
	v_pk_mov_b32 v[72:73], v[20:21], v[18:19] op_sel:[1,0]
	v_mov_b32_e32 v39, v38
	s_waitcnt lgkmcnt(1)
	v_mul_f32_e32 v117, v7, v84
	s_waitcnt lgkmcnt(0)
	v_mul_f32_e32 v92, v3, v91
	v_mul_f32_e32 v122, v8, v84
	v_mul_f32_e32 v84, v17, v87
	v_pk_fma_f32 v[110:111], v[2:3], v[90:91], v[92:93] op_sel_hi:[1,1,0] neg_lo:[0,0,1] neg_hi:[0,0,1]
	v_mul_f32_e32 v112, v4, v91
	v_mul_f32_e32 v114, v3, v90
	v_mul_f32_e32 v119, v8, v85
	v_mul_f32_e32 v120, v7, v85
	v_pk_mul_f32 v[124:125], v[16:17], v[86:87] op_sel_hi:[1,0]
	v_pk_mul_f32 v[126:127], v[60:61], v[86:87]
	v_pk_fma_f32 v[128:129], v[16:17], v[86:87], v[84:85] op_sel_hi:[1,1,0] neg_lo:[1,0,0] neg_hi:[1,0,0]
	ds_read2_b64 v[84:87], v83 offset0:64 offset1:80
	ds_read2_b64 v[90:93], v83 offset0:96 offset1:112
	ds_read2_b64 v[94:97], v83 offset0:128 offset1:144
	ds_read2_b64 v[98:101], v83 offset0:160 offset1:176
	ds_read2_b64 v[102:105], v83 offset0:192 offset1:208
	ds_read2_b64 v[106:109], v83 offset0:224 offset1:240
	v_add_u32_e32 v218, 0x200, v82
	v_ashrrev_i32_e32 v252, 31, v218
	v_lshrrev_b32_e32 v252, 23, v252
	v_add_lshl_u32 v252, v218, v252, 7
	v_and_b32_e32 v252, 0xffff0000, v252
	v_add_u32_e32 v219, v20, v252
	ds_read2_b64 v[220:223], v219 offset0:32 offset1:48
	ds_read2_b64 v[224:227], v219 offset1:16
	ds_read2_b64 v[228:231], v219 offset0:64 offset1:80
	ds_read2_b64 v[232:235], v219 offset0:96 offset1:112
	ds_read2_b64 v[236:239], v219 offset0:128 offset1:144
	ds_read2_b64 v[244:247], v219 offset0:160 offset1:176
	ds_read2_b64 v[248:251], v219 offset0:192 offset1:208
	ds_read2_b64 v[252:255], v219 offset0:224 offset1:240
	s_waitcnt lgkmcnt(12)
	v_mov_b32_e32 v131, v93
	s_waitcnt lgkmcnt(11)
; DI float2 twid(float r) { return float2{__builtin_amdgcn_cosf(r), -__builtin_amdgcn_sinf(r)}; }
; DI void bfly_inv(float2 s0, float2 s1, float2 s2, float2 s3, float r, float2& o0, float2& o1, float2& o2, float2& o3) {
;   float2 w1 = twid(r), w2 = cmul(w1, w1), w3 = cmul(w2, w1);
;   float2 c0 = s0, c1 = cmulc(s1, w1), c2 = cmulc(s2, w2), c3 = cmulc(s3, w3);
;   float2 t0 = {c0.x + c2.x, c0.y + c2.y}, t1 = {c0.x - c2.x, c0.y - c2.y}, t2 = {c1.x + c3.x, c1.y + c3.y}, t3 = {c1.x - c3.x, c1.y - c3.y};
;   o0 = float2{t0.x + t2.x, t0.y + t2.y}; o2 = float2{t0.x - t2.x, t0.y - t2.y}; o1 = float2{t1.x - t3.y, t1.y + t3.x}; o3 = float2{t1.x + t3.y, t1.y - t3.x};
; }
;     ...
;   for (int gg = tid; gg < NBT * (N / 16); gg += NTHR) { const int g = gg & (N / 16 - 1); float2* z = z0 + (gg / (N / 16)) * N; const int jp = g & (Q2 - 1), base = ((g >> lq2) << (lq2 + 4)) + jp; float2 x[4][4];
; #pragma unroll
;     for (int q1 = 0; q1 < 4; ++q1)
; #pragma unroll
;       for (int q2 = 0; q2 < 4; ++q2) x[q1][q2] = z[base + q1 * Q1 + q2 * Q2];
; #pragma unroll
;     for (int q1 = 0; q1 < 4; ++q1) bfly_inv(x[q1][0], x[q1][1], x[q1][2], x[q1][3], (float)jp * invM2, x[q1][0], x[q1][1], x[q1][2], x[q1][3]);
; #pragma unroll
;     for (int q2 = 0; q2 < 4; ++q2) bfly_inv(x[0][q2], x[1][q2], x[2][q2], x[3][q2], (float)(jp + q2 * Q2) * invM1, x[0][q2], x[1][q2], x[2][q2], x[3][q2]);
; #pragma unroll
;     for (int q1 = 0; q1 < 4; ++q1)
; #pragma unroll
;       for (int q2 = 0; q2 < 4; ++q2) z[base + q1 * Q1 + q2 * Q2] = x[q1][q2]; }
	v_mov_b32_e32 v130, v97
	v_pk_mul_f32 v[130:131], v[56:57], v[130:131]
	v_mov_b32_e32 v132, v96
	v_mov_b32_e32 v133, v92
	v_pk_fma_f32 v[130:131], v[10:11], v[132:133], v[130:131]
	s_waitcnt lgkmcnt(10)
	v_pk_mov_b32 v[132:133], v[98:99], v[90:91] op_sel:[1,0]
	v_mov_b32_e32 v90, v98
	v_pk_mul_f32 v[138:139], v[8:9], v[90:91]
	s_waitcnt lgkmcnt(8)
	v_mov_b32_e32 v140, v107
	v_mov_b32_e32 v107, v98
	v_mov_b32_e32 v134, v105
	v_mov_b32_e32 v135, v97
	v_mov_b32_e32 v141, v99
	v_pk_mul_f32 v[98:99], v[8:9], v[106:107]
	v_pk_fma_f32 v[142:143], v[6:7], v[132:133], v[138:139]
	v_pk_fma_f32 v[138:139], v[6:7], v[132:133], v[138:139] neg_lo:[0,0,1] neg_hi:[0,0,1]
	v_pk_mov_b32 v[146:147], v[86:87], v[100:101] op_sel:[1,0]
	v_pk_mul_f32 v[132:133], v[8:9], v[132:133]
	v_pk_mul_f32 v[136:137], v[4:5], v[134:135]
	v_mov_b32_e32 v105, v96
	v_mov_b32_e32 v144, v86
	v_mov_b32_e32 v145, v101
	v_pk_mul_f32 v[146:147], v[66:67], v[146:147]
	v_mov_b32_e32 v156, v109
	v_mov_b32_e32 v109, v100
	v_pk_fma_f32 v[98:99], v[6:7], v[140:141], v[98:99] neg_lo:[0,0,1] neg_hi:[0,0,1]
	v_mov_b32_e32 v166, v96
	v_mov_b32_e32 v167, v93
	v_pk_mov_b32 v[92:93], v[96:97], v[92:93] op_sel:[1,0]
	v_pk_mul_f32 v[96:97], v[62:63], v[134:135]
	v_pk_mul_f32 v[134:135], v[8:9], v[140:141]
	v_pk_fma_f32 v[140:141], v[6:7], v[90:91], v[132:133] neg_lo:[0,0,1] neg_hi:[0,0,1]
	v_pk_fma_f32 v[90:91], v[6:7], v[90:91], v[132:133]
	v_mov_b32_e32 v133, v100
	v_mov_b32_e32 v100, v87
	v_mov_b32_e32 v139, v143
	v_pk_fma_f32 v[144:145], v[64:65], v[144:145], v[146:147] neg_lo:[0,0,1] neg_hi:[0,0,1]
	v_pk_mov_b32 v[146:147], v[94:95], v[84:85] op_sel:[1,0]
	v_pk_mul_f32 v[92:93], v[66:67], v[92:93]
	v_mov_b32_e32 v132, v86
	v_pk_mul_f32 v[86:87], v[56:57], v[100:101]
	v_pk_add_f32 v[146:147], v[146:147], v[138:139]
	v_pk_add_f32 v[160:161], v[144:145], v[130:131] op_sel:[1,0] op_sel_hi:[0,1]
	v_pk_fma_f32 v[92:93], v[64:65], v[166:167], v[92:93] neg_lo:[0,0,1] neg_hi:[0,0,1]
	v_mov_b32_e32 v91, v141
	v_pk_fma_f32 v[86:87], v[10:11], v[132:133], v[86:87]
	v_mov_b32_e32 v132, v94
	v_mov_b32_e32 v133, v85
	v_mov_b32_e32 v157, v101
	v_pk_mul_f32 v[158:159], v[70:71], v[108:109]
	v_pk_fma_f32 v[136:137], v[62:63], v[104:105], v[136:137]
	v_mov_b32_e32 v116, v147
	v_mov_b32_e32 v118, v161
	v_pk_add_f32 v[132:133], v[132:133], v[90:91]
	v_pk_fma_f32 v[96:97], v[4:5], v[104:105], v[96:97] neg_lo:[0,0,1] neg_hi:[0,0,1]
	v_pk_add_f32 v[104:105], v[86:87], v[92:93] op_sel:[1,0] op_sel_hi:[0,1]
	v_pk_fma_f32 v[158:159], v[68:69], v[156:157], v[158:159] neg_lo:[0,0,1] neg_hi:[0,0,1]
	v_pk_add_f32 v[116:117], v[116:117], v[118:119]
	v_mov_b32_e32 v118, v103
	v_mov_b32_e32 v119, v95
	v_pk_mul_f32 v[100:101], v[70:71], v[156:157]
	v_mov_b32_e32 v124, v133
	v_mov_b32_e32 v126, v105
	v_pk_add_f32 v[118:119], v[118:119], v[98:99]
	v_pk_add_f32 v[162:163], v[136:137], v[158:159]
	v_pk_fma_f32 v[106:107], v[6:7], v[106:107], v[134:135]
	v_pk_fma_f32 v[100:101], v[68:69], v[108:109], v[100:101]
	v_pk_add_f32 v[108:109], v[124:125], v[126:127]
	v_mov_b32_e32 v124, v102
	v_mov_b32_e32 v125, v94
	v_mov_b32_e32 v121, v118
	v_mov_b32_e32 v123, v162
	v_pk_add_f32 v[124:125], v[124:125], v[106:107]
	v_pk_add_f32 v[126:127], v[96:97], v[100:101]
	v_pk_add_f32 v[164:165], v[120:121], v[122:123]
	v_pk_add_f32 v[120:121], v[120:121], v[122:123] neg_lo:[0,1] neg_hi:[0,1]
	v_mov_b32_e32 v115, v124
	v_mov_b32_e32 v113, v126
	v_pk_mov_b32 v[168:169], v[88:89], v[88:89] op_sel:[1,0]
	v_mov_b32_e32 v122, v120
	v_mov_b32_e32 v123, v165
	v_pk_add_f32 v[112:113], v[114:115], v[112:113]
	v_mov_b32_e32 v13, v169
	v_mov_b32_e32 v129, v21
	v_mov_b32_e32 v169, v60
	v_pk_add_f32 v[114:115], v[132:133], v[104:105]
	v_pk_mul_f32 v[178:179], v[128:129], v[112:113]
	v_pk_add_f32 v[182:183], v[128:129], v[112:113]
	v_pk_mul_f32 v[164:165], v[168:169], v[164:165]
	v_pk_add_f32 v[122:123], v[168:169], v[122:123]
	v_pk_add_f32 v[134:135], v[146:147], v[160:161]
	v_mov_b32_e32 v178, v182
	v_mov_b32_e32 v164, v122
	v_pk_mul_f32 v[114:115], v[18:19], v[114:115]
	v_mov_b32_e32 v15, v110
	v_pk_add_f32 v[170:171], v[12:13], v[116:117]
	v_pk_mul_f32 v[172:173], v[12:13], v[116:117]
	v_pk_fma_f32 v[114:115], v[22:23], v[134:135], v[114:115] neg_lo:[0,0,1] neg_hi:[0,0,1]
	v_pk_add_f32 v[134:135], v[178:179], v[164:165]
	v_pk_mov_b32 v[116:117], v[116:117], v[120:121] op_sel:[1,0]
	v_mov_b32_e32 v113, v110
	v_mov_b32_e32 v129, v109
	v_pk_mov_b32 v[178:179], v[92:93], v[100:101] op_sel:[1,0]
	v_mov_b32_e32 v97, v144
	v_mov_b32_e32 v101, v131
	v_pk_add_f32 v[156:157], v[14:15], v[108:109]
	v_pk_mul_f32 v[166:167], v[14:15], v[108:109]
	v_pk_add_f32 v[88:89], v[88:89], v[116:117] neg_lo:[0,1] neg_hi:[0,1]
	v_pk_add_f32 v[108:109], v[112:113], v[128:129] neg_lo:[0,1] neg_hi:[0,1]
	v_mov_b32_e32 v116, v102
	v_mov_b32_e32 v117, v84
	v_mov_b32_e32 v120, v106
	v_mov_b32_e32 v121, v143
	v_pk_mov_b32 v[128:129], v[142:143], v[98:99] op_sel:[1,0]
	v_mov_b32_e32 v137, v86
	v_mov_b32_e32 v142, v86
	v_mov_b32_e32 v143, v96
	v_pk_add_f32 v[96:97], v[96:97], v[100:101] neg_lo:[0,1] neg_hi:[0,1]
	v_pk_mov_b32 v[100:101], v[130:131], v[158:159] op_sel:[1,0]
	v_mov_b32_e32 v91, v138
	v_mov_b32_e32 v131, v92
	v_mov_b32_e32 v86, v145
	v_pk_add_f32 v[116:117], v[116:117], v[120:121] neg_lo:[0,1] neg_hi:[0,1]
	v_mov_b32_e32 v120, v84
	v_mov_b32_e32 v121, v103
	v_pk_mov_b32 v[184:185], v[84:85], v[102:103] op_sel:[1,0]
	v_mov_b32_e32 v84, v103
	v_mov_b32_e32 v99, v141
	v_pk_add_f32 v[90:91], v[94:95], v[90:91] neg_lo:[0,1] neg_hi:[0,1]
	v_pk_add_f32 v[86:87], v[130:131], v[86:87] neg_lo:[0,1] neg_hi:[0,1]
	v_pk_add_f32 v[120:121], v[120:121], v[128:129] neg_lo:[0,1] neg_hi:[0,1]
; DI float2 twid(float r) { return float2{__builtin_amdgcn_cosf(r), -__builtin_amdgcn_sinf(r)}; }
; DI void bfly_inv(float2 s0, float2 s1, float2 s2, float2 s3, float r, float2& o0, float2& o1, float2& o2, float2& o3) {
;   float2 w1 = twid(r), w2 = cmul(w1, w1), w3 = cmul(w2, w1);
;   float2 c0 = s0, c1 = cmulc(s1, w1), c2 = cmulc(s2, w2), c3 = cmulc(s3, w3);
;   float2 t0 = {c0.x + c2.x, c0.y + c2.y}, t1 = {c0.x - c2.x, c0.y - c2.y}, t2 = {c1.x + c3.x, c1.y + c3.y}, t3 = {c1.x - c3.x, c1.y - c3.y};
;   o0 = float2{t0.x + t2.x, t0.y + t2.y}; o2 = float2{t0.x - t2.x, t0.y - t2.y}; o1 = float2{t1.x - t3.y, t1.y + t3.x}; o3 = float2{t1.x + t3.y, t1.y - t3.x};
; }
;     ...
;   for (int gg = tid; gg < NBT * (N / 16); gg += NTHR) { const int g = gg & (N / 16 - 1); float2* z = z0 + (gg / (N / 16)) * N; const int jp = g & (Q2 - 1), base = ((g >> lq2) << (lq2 + 4)) + jp; float2 x[4][4];
; #pragma unroll
;     for (int q1 = 0; q1 < 4; ++q1)
; #pragma unroll
;       for (int q2 = 0; q2 < 4; ++q2) x[q1][q2] = z[base + q1 * Q1 + q2 * Q2];
; #pragma unroll
;     for (int q1 = 0; q1 < 4; ++q1) bfly_inv(x[q1][0], x[q1][1], x[q1][2], x[q1][3], (float)jp * invM2, x[q1][0], x[q1][1], x[q1][2], x[q1][3]);
; #pragma unroll
;     for (int q2 = 0; q2 < 4; ++q2) bfly_inv(x[0][q2], x[1][q2], x[2][q2], x[3][q2], (float)(jp + q2 * Q2) * invM1, x[0][q2], x[1][q2], x[2][q2], x[3][q2]);
; #pragma unroll
;     for (int q1 = 0; q1 < 4; ++q1)
; #pragma unroll
;       for (int q2 = 0; q2 < 4; ++q2) z[base + q1 * Q1 + q2 * Q2] = x[q1][q2]; }
	v_mov_b32_e32 v128, v158
	v_mov_b32_e32 v129, v93
	v_pk_mov_b32 v[106:107], v[140:141], v[106:107] op_sel:[1,0]
	v_pk_add_f32 v[84:85], v[84:85], v[98:99] neg_lo:[0,1] neg_hi:[0,1]
	v_mov_b32_e32 v98, v144
	v_mov_b32_e32 v99, v136
	v_pk_add_f32 v[92:93], v[90:91], v[86:87] neg_lo:[0,1] neg_hi:[0,1]
	v_pk_add_f32 v[94:95], v[90:91], v[86:87]
	v_pk_add_f32 v[174:175], v[124:125], v[126:127]
	v_pk_mov_b32 v[164:165], v[168:169], v[22:23] op_sel:[1,0]
	v_pk_add_f32 v[128:129], v[136:137], v[128:129] neg_lo:[0,1] neg_hi:[0,1]
	v_pk_add_f32 v[106:107], v[184:185], v[106:107] neg_lo:[0,1] neg_hi:[0,1]
	v_pk_add_f32 v[98:99], v[98:99], v[100:101] neg_lo:[0,1] neg_hi:[0,1]
	v_mov_b32_e32 v103, v95
	v_pk_mov_b32 v[94:95], v[94:95], v[92:93] op_sel:[1,0]
	v_pk_add_f32 v[176:177], v[118:119], v[162:163]
	v_pk_mul_f32 v[164:165], v[164:165], v[174:175]
	v_pk_add_f32 v[142:143], v[142:143], v[178:179] neg_lo:[0,1] neg_hi:[0,1]
	v_pk_add_f32 v[100:101], v[106:107], v[98:99] neg_lo:[0,1] neg_hi:[0,1]
	v_mov_b32_e32 v102, v92
	v_pk_add_f32 v[116:117], v[116:117], v[128:129] neg_lo:[0,1] neg_hi:[0,1]
	v_pk_add_f32 v[128:129], v[106:107], v[98:99]
	v_pk_mul_f32 v[94:95], v[30:31], v[94:95]
	v_mov_b32_e32 v167, v157
	v_mov_b32_e32 v173, v171
	v_pk_fma_f32 v[168:169], v[72:73], v[176:177], v[164:165]
	v_pk_fma_f32 v[164:165], v[72:73], v[176:177], v[164:165] neg_lo:[0,0,1] neg_hi:[0,0,1]
	v_pk_add_f32 v[178:179], v[120:121], v[142:143]
	v_mov_b32_e32 v129, v101
	v_pk_add_f32 v[130:131], v[120:121], v[142:143] neg_lo:[0,1] neg_hi:[0,1]
	v_pk_add_f32 v[84:85], v[84:85], v[96:97]
	v_pk_fma_f32 v[92:93], v[28:29], v[92:93], v[94:95]
	v_pk_fma_f32 v[94:95], v[28:29], v[102:103], v[94:95] neg_lo:[0,0,1] neg_hi:[0,0,1]
	v_pk_add_f32 v[166:167], v[172:173], v[166:167]
	v_mov_b32_e32 v165, v169
	v_pk_add_f32 v[110:111], v[88:89], v[108:109] neg_lo:[0,1] neg_hi:[0,1]
	v_pk_add_f32 v[112:113], v[88:89], v[108:109]
	v_mov_b32_e32 v131, v179
	v_mov_b32_e32 v93, v95
	v_pk_mul_f32 v[84:85], v[26:27], v[84:85]
	v_pk_mul_f32 v[94:95], v[50:51], v[128:129]
	v_pk_add_f32 v[172:173], v[114:115], v[134:135]
	v_pk_add_f32 v[174:175], v[166:167], v[164:165]
	v_mov_b32_e32 v112, v110
	v_pk_fma_f32 v[84:85], v[24:25], v[116:117], v[84:85]
	v_pk_fma_f32 v[94:95], v[48:49], v[130:131], v[94:95] neg_lo:[0,0,1] neg_hi:[0,0,1]
	v_pk_add_f32 v[176:177], v[172:173], v[174:175]
	v_pk_add_f32 v[96:97], v[112:113], v[92:93]
	v_pk_add_f32 v[102:103], v[94:95], v[84:85]
	v_pk_mov_b32 v[176:177], v[176:177], v[176:177] op_sel:[1,0]
	v_pk_add_f32 v[116:117], v[96:97], v[102:103]
	ds_write2_b64 v83, v[176:177], v[116:117] offset1:16
	v_pk_mov_b32 v[116:117], v[170:171], v[122:123] op_sel:[1,0]
	v_pk_mov_b32 v[122:123], v[156:157], v[182:183] op_sel:[1,0]
	v_mov_b32_e32 v128, v104
	v_pk_add_f32 v[116:117], v[116:117], v[122:123] neg_lo:[0,1] neg_hi:[0,1]
	v_mov_b32_e32 v122, v132
	v_mov_b32_e32 v123, v146
	v_mov_b32_e32 v129, v160
	v_pk_add_f32 v[122:123], v[122:123], v[128:129] neg_lo:[0,1] neg_hi:[0,1]
	v_mov_b32_e32 v128, v124
	v_mov_b32_e32 v129, v147
	v_mov_b32_e32 v130, v126
	v_mov_b32_e32 v131, v161
	v_pk_mov_b32 v[124:125], v[132:133], v[124:125] op_sel:[1,0]
	v_pk_mov_b32 v[126:127], v[104:105], v[126:127] op_sel:[1,0]
	v_mov_b32_e32 v106, v90
	v_mov_b32_e32 v98, v86
	v_pk_add_f32 v[128:129], v[128:129], v[130:131] neg_lo:[0,1] neg_hi:[0,1]
	v_pk_add_f32 v[124:125], v[124:125], v[126:127] neg_lo:[0,1] neg_hi:[0,1]
	v_pk_mov_b32 v[126:127], v[146:147], v[118:119] op_sel:[1,0]
	v_pk_mov_b32 v[130:131], v[160:161], v[162:163] op_sel:[1,0]
	v_mov_b32_e32 v119, v133
	v_mov_b32_e32 v163, v105
	v_pk_add_f32 v[98:99], v[106:107], v[98:99]
	v_mov_b32_e32 v120, v91
	v_mov_b32_e32 v142, v87
	v_pk_add_f32 v[104:105], v[118:119], v[162:163] neg_lo:[0,1] neg_hi:[0,1]
	v_pk_mul_f32 v[118:119], v[38:39], v[122:123] op_sel:[0,1] op_sel_hi:[1,0]
	v_pk_add_f32 v[86:87], v[120:121], v[142:143] neg_lo:[0,1] neg_hi:[0,1]
	v_mov_b32_e32 v101, v98
	v_mul_f32_e32 v109, v42, v100
	v_pk_add_f32 v[126:127], v[126:127], v[130:131] neg_lo:[0,1] neg_hi:[0,1]
	v_pk_fma_f32 v[130:131], v[36:37], v[122:123], v[118:119]
	v_pk_fma_f32 v[118:119], v[36:37], v[122:123], v[118:119] neg_lo:[0,0,1] neg_hi:[0,0,1]
	v_pk_mul_f32 v[90:91], v[40:41], v[100:101]
	v_mov_b32_e32 v100, v99
	v_mov_b32_e32 v101, v87
	v_mul_f32_e32 v106, v47, v87
	v_pk_mul_f32 v[98:99], v[44:45], v[98:99]
	v_mul_f32_e32 v89, v40, v178
	v_mov_b32_e32 v131, v119
	v_pk_mul_f32 v[104:105], v[34:35], v[104:105]
	v_pk_mul_f32 v[118:119], v[54:55], v[124:125]
	v_mov_b32_e32 v179, v86
	v_pk_fma_f32 v[100:101], v[46:47], v[100:101], v[106:107] op_sel_hi:[1,1,0]
	v_pk_fma_f32 v[106:107], v[58:59], v[86:87], v[98:99]
	v_pk_fma_f32 v[86:87], v[58:59], v[86:87], v[98:99] neg_lo:[0,0,1] neg_hi:[0,0,1]
	v_pk_fma_f32 v[104:105], v[32:33], v[128:129], v[104:105]
	v_pk_fma_f32 v[118:119], v[52:53], v[126:127], v[118:119] neg_lo:[0,0,1] neg_hi:[0,0,1]
	v_pk_add_f32 v[88:89], v[88:89], v[108:109]
	v_pk_fma_f32 v[90:91], v[42:43], v[178:179], v[90:91] neg_lo:[0,0,1] neg_hi:[0,0,1]
	v_mov_b32_e32 v107, v87
	v_mov_b32_e32 v110, v100
	v_pk_add_f32 v[122:123], v[116:117], v[130:131]
	v_pk_add_f32 v[124:125], v[118:119], v[104:105]
	v_pk_add_f32 v[98:99], v[90:91], v[110:111]
	v_pk_add_f32 v[108:109], v[88:89], v[106:107]
	v_pk_add_f32 v[126:127], v[122:123], v[124:125]
	v_pk_add_f32 v[120:121], v[98:99], v[108:109]
	ds_write2_b64 v83, v[126:127], v[120:121] offset0:32 offset1:48
	v_pk_mov_b32 v[120:121], v[166:167], v[134:135] op_sel:[1,0]
	v_pk_mov_b32 v[126:127], v[168:169], v[114:115] op_sel:[1,0]
	v_mov_b32_e32 v167, v115
	v_mov_b32_e32 v165, v135
; DI float2 twid(float r) { return float2{__builtin_amdgcn_cosf(r), -__builtin_amdgcn_sinf(r)}; }
; DI void bfly_inv(float2 s0, float2 s1, float2 s2, float2 s3, float r, float2& o0, float2& o1, float2& o2, float2& o3) {
;   float2 w1 = twid(r), w2 = cmul(w1, w1), w3 = cmul(w2, w1);
;   float2 c0 = s0, c1 = cmulc(s1, w1), c2 = cmulc(s2, w2), c3 = cmulc(s3, w3);
;   float2 t0 = {c0.x + c2.x, c0.y + c2.y}, t1 = {c0.x - c2.x, c0.y - c2.y}, t2 = {c1.x + c3.x, c1.y + c3.y}, t3 = {c1.x - c3.x, c1.y - c3.y};
;   o0 = float2{t0.x + t2.x, t0.y + t2.y}; o2 = float2{t0.x - t2.x, t0.y - t2.y}; o1 = float2{t1.x - t3.y, t1.y + t3.x}; o3 = float2{t1.x + t3.y, t1.y - t3.x};
; }
;     ...
;   for (int gg = tid; gg < NBT * (N / 16); gg += NTHR) { const int g = gg & (N / 16 - 1); float2* z = z0 + (gg / (N / 16)) * N; const int jp = g & (Q2 - 1), base = ((g >> lq2) << (lq2 + 4)) + jp; float2 x[4][4];
; #pragma unroll
;     for (int q1 = 0; q1 < 4; ++q1)
; #pragma unroll
;       for (int q2 = 0; q2 < 4; ++q2) x[q1][q2] = z[base + q1 * Q1 + q2 * Q2];
; #pragma unroll
;     for (int q1 = 0; q1 < 4; ++q1) bfly_inv(x[q1][0], x[q1][1], x[q1][2], x[q1][3], (float)jp * invM2, x[q1][0], x[q1][1], x[q1][2], x[q1][3]);
; #pragma unroll
;     for (int q2 = 0; q2 < 4; ++q2) bfly_inv(x[0][q2], x[1][q2], x[2][q2], x[3][q2], (float)(jp + q2 * Q2) * invM1, x[0][q2], x[1][q2], x[2][q2], x[3][q2]);
; #pragma unroll
;     for (int q1 = 0; q1 < 4; ++q1)
; #pragma unroll
;       for (int q2 = 0; q2 < 4; ++q2) z[base + q1 * Q1 + q2 * Q2] = x[q1][q2]; }
	v_pk_add_f32 v[92:93], v[112:113], v[92:93] neg_lo:[0,1] neg_hi:[0,1]
	v_pk_mov_b32 v[112:113], v[84:85], v[94:95] op_sel:[1,0]
	v_pk_mov_b32 v[84:85], v[94:95], v[84:85] op_sel:[1,0]
	v_pk_add_f32 v[120:121], v[120:121], v[126:127] neg_lo:[0,1] neg_hi:[0,1]
	v_pk_add_f32 v[114:115], v[166:167], v[164:165] neg_lo:[0,1] neg_hi:[0,1]
	v_pk_add_f32 v[84:85], v[112:113], v[84:85] neg_lo:[0,1] neg_hi:[0,1]
	v_pk_add_f32 v[126:127], v[120:121], v[114:115] neg_lo:[0,1] neg_hi:[0,1]
	v_pk_add_f32 v[114:115], v[120:121], v[114:115]
	v_pk_add_f32 v[94:95], v[92:93], v[84:85] neg_lo:[0,1] neg_hi:[0,1]
	v_pk_add_f32 v[84:85], v[92:93], v[84:85]
	v_mov_b32_e32 v120, v126
	v_mov_b32_e32 v121, v115
	v_mov_b32_e32 v92, v94
	v_mov_b32_e32 v93, v85
	v_pk_mov_b32 v[112:113], v[104:105], v[118:119] op_sel:[1,0]
	v_pk_mov_b32 v[104:105], v[118:119], v[104:105] op_sel:[1,0]
	v_mov_b32_e32 v110, v88
	v_mov_b32_e32 v107, v91
	v_pk_mov_b32 v[88:89], v[88:89], v[90:91] op_sel:[1,0]
	v_pk_mov_b32 v[86:87], v[86:87], v[100:101] op_sel:[1,0]
	ds_write2_b64 v83, v[120:121], v[92:93] offset0:64 offset1:80
	v_pk_add_f32 v[92:93], v[116:117], v[130:131] neg_lo:[0,1] neg_hi:[0,1]
	v_pk_add_f32 v[104:105], v[112:113], v[104:105] neg_lo:[0,1] neg_hi:[0,1]
	v_pk_add_f32 v[106:107], v[110:111], v[106:107] neg_lo:[0,1] neg_hi:[0,1]
	v_pk_add_f32 v[86:87], v[88:89], v[86:87] neg_lo:[0,1] neg_hi:[0,1]
	v_pk_add_f32 v[112:113], v[92:93], v[104:105] neg_lo:[0,1] neg_hi:[0,1]
	v_pk_add_f32 v[92:93], v[92:93], v[104:105]
	v_pk_add_f32 v[88:89], v[106:107], v[86:87] neg_lo:[0,1] neg_hi:[0,1]
	v_pk_add_f32 v[86:87], v[106:107], v[86:87]
	v_mov_b32_e32 v104, v112
	v_mov_b32_e32 v105, v93
	v_mov_b32_e32 v90, v88
	v_mov_b32_e32 v91, v87
	ds_write2_b64 v83, v[104:105], v[90:91] offset0:96 offset1:112
	v_pk_mov_b32 v[90:91], v[174:175], v[172:173] op_sel:[1,0]
	v_pk_mov_b32 v[100:101], v[172:173], v[174:175] op_sel:[1,0]
	v_pk_add_f32 v[96:97], v[96:97], v[102:103] neg_lo:[0,1] neg_hi:[0,1]
	v_pk_add_f32 v[90:91], v[90:91], v[100:101] neg_lo:[0,1] neg_hi:[0,1]
	ds_write2_b64 v83, v[90:91], v[96:97] offset0:128 offset1:144
	v_mov_b32_e32 v96, v108
	v_mov_b32_e32 v97, v99
	v_mov_b32_e32 v99, v109
	s_nop 0
	v_pk_add_f32 v[90:91], v[122:123], v[124:125] neg_lo:[0,1] neg_hi:[0,1]
	v_pk_add_f32 v[96:97], v[96:97], v[98:99] neg_lo:[0,1] neg_hi:[0,1]
	v_mov_b32_e32 v115, v127
	v_mov_b32_e32 v85, v95
	v_mov_b32_e32 v93, v113
	v_mov_b32_e32 v87, v89
	s_nop 0
	ds_write2_b64 v83, v[90:91], v[96:97] offset0:160 offset1:176
	ds_write2_b64 v83, v[114:115], v[84:85] offset0:192 offset1:208
	ds_write2_b64 v83, v[92:93], v[86:87] offset0:224 offset1:240
	s_nop 0
	v_add_u32_e32 v82, 0x200, v82
	s_nop 0
	s_waitcnt lgkmcnt(15)
	v_mul_f32_e32 v117, v7, v220
	s_waitcnt lgkmcnt(14)
	v_mul_f32_e32 v92, v3, v227
	v_mul_f32_e32 v122, v8, v220
	v_mul_f32_e32 v220, v17, v223
	v_pk_fma_f32 v[110:111], v[2:3], v[226:227], v[92:93] op_sel_hi:[1,1,0] neg_lo:[0,0,1] neg_hi:[0,0,1]
	v_mul_f32_e32 v112, v4, v227
	v_mul_f32_e32 v114, v3, v226
	v_mul_f32_e32 v119, v8, v221
	v_mul_f32_e32 v120, v7, v221
	v_pk_mul_f32 v[124:125], v[16:17], v[222:223] op_sel_hi:[1,0]
	v_pk_mul_f32 v[126:127], v[60:61], v[222:223]
	v_pk_fma_f32 v[128:129], v[16:17], v[222:223], v[220:221] op_sel_hi:[1,1,0] neg_lo:[1,0,0] neg_hi:[1,0,0]
	s_nop 0
	s_waitcnt lgkmcnt(12)
	v_mov_b32_e32 v131, v235
	s_waitcnt lgkmcnt(11)
	v_mov_b32_e32 v130, v239
	v_pk_mul_f32 v[130:131], v[56:57], v[130:131]
	v_mov_b32_e32 v132, v238
	v_mov_b32_e32 v133, v234
	v_pk_fma_f32 v[130:131], v[10:11], v[132:133], v[130:131]
	s_waitcnt lgkmcnt(10)
	v_pk_mov_b32 v[132:133], v[244:245], v[232:233] op_sel:[1,0]
	v_mov_b32_e32 v232, v244
	v_pk_mul_f32 v[138:139], v[8:9], v[232:233]
	s_waitcnt lgkmcnt(8)
	v_mov_b32_e32 v140, v253
	v_mov_b32_e32 v253, v244
	v_mov_b32_e32 v134, v251
	v_mov_b32_e32 v135, v239
	v_mov_b32_e32 v141, v245
	v_pk_mul_f32 v[244:245], v[8:9], v[252:253]
	v_pk_fma_f32 v[142:143], v[6:7], v[132:133], v[138:139]
	v_pk_fma_f32 v[138:139], v[6:7], v[132:133], v[138:139] neg_lo:[0,0,1] neg_hi:[0,0,1]
	v_pk_mov_b32 v[146:147], v[230:231], v[246:247] op_sel:[1,0]
	v_pk_mul_f32 v[132:133], v[8:9], v[132:133]
	v_pk_mul_f32 v[136:137], v[4:5], v[134:135]
	v_mov_b32_e32 v251, v238
	v_mov_b32_e32 v144, v230
	v_mov_b32_e32 v145, v247
	v_pk_mul_f32 v[146:147], v[66:67], v[146:147]
	v_mov_b32_e32 v156, v255
	v_mov_b32_e32 v255, v246
	v_pk_fma_f32 v[244:245], v[6:7], v[140:141], v[244:245] neg_lo:[0,0,1] neg_hi:[0,0,1]
	v_mov_b32_e32 v166, v238
	v_mov_b32_e32 v167, v235
	v_pk_mov_b32 v[234:235], v[238:239], v[234:235] op_sel:[1,0]
	v_pk_mul_f32 v[238:239], v[62:63], v[134:135]
	v_pk_mul_f32 v[134:135], v[8:9], v[140:141]
	v_pk_fma_f32 v[140:141], v[6:7], v[232:233], v[132:133] neg_lo:[0,0,1] neg_hi:[0,0,1]
	v_pk_fma_f32 v[232:233], v[6:7], v[232:233], v[132:133]
	v_mov_b32_e32 v133, v246
	v_mov_b32_e32 v246, v231
	v_mov_b32_e32 v139, v143
	v_pk_fma_f32 v[144:145], v[64:65], v[144:145], v[146:147] neg_lo:[0,0,1] neg_hi:[0,0,1]
	v_pk_mov_b32 v[146:147], v[236:237], v[228:229] op_sel:[1,0]
	v_pk_mul_f32 v[234:235], v[66:67], v[234:235]
	v_mov_b32_e32 v132, v230
	v_pk_mul_f32 v[230:231], v[56:57], v[246:247]
	v_pk_add_f32 v[146:147], v[146:147], v[138:139]
	v_pk_add_f32 v[160:161], v[144:145], v[130:131] op_sel:[1,0] op_sel_hi:[0,1]
	v_pk_fma_f32 v[234:235], v[64:65], v[166:167], v[234:235] neg_lo:[0,0,1] neg_hi:[0,0,1]
	v_mov_b32_e32 v233, v141
	v_pk_fma_f32 v[230:231], v[10:11], v[132:133], v[230:231]
	v_mov_b32_e32 v132, v236
	v_mov_b32_e32 v133, v229
	v_mov_b32_e32 v157, v247
	v_pk_mul_f32 v[158:159], v[70:71], v[254:255]
	v_pk_fma_f32 v[136:137], v[62:63], v[250:251], v[136:137]
; DI float2 twid(float r) { return float2{__builtin_amdgcn_cosf(r), -__builtin_amdgcn_sinf(r)}; }
; DI void bfly_inv(float2 s0, float2 s1, float2 s2, float2 s3, float r, float2& o0, float2& o1, float2& o2, float2& o3) {
;   float2 w1 = twid(r), w2 = cmul(w1, w1), w3 = cmul(w2, w1);
;   float2 c0 = s0, c1 = cmulc(s1, w1), c2 = cmulc(s2, w2), c3 = cmulc(s3, w3);
;   float2 t0 = {c0.x + c2.x, c0.y + c2.y}, t1 = {c0.x - c2.x, c0.y - c2.y}, t2 = {c1.x + c3.x, c1.y + c3.y}, t3 = {c1.x - c3.x, c1.y - c3.y};
;   o0 = float2{t0.x + t2.x, t0.y + t2.y}; o2 = float2{t0.x - t2.x, t0.y - t2.y}; o1 = float2{t1.x - t3.y, t1.y + t3.x}; o3 = float2{t1.x + t3.y, t1.y - t3.x};
; }
;     ...
;   for (int gg = tid; gg < NBT * (N / 16); gg += NTHR) { const int g = gg & (N / 16 - 1); float2* z = z0 + (gg / (N / 16)) * N; const int jp = g & (Q2 - 1), base = ((g >> lq2) << (lq2 + 4)) + jp; float2 x[4][4];
; #pragma unroll
;     for (int q1 = 0; q1 < 4; ++q1)
; #pragma unroll
;       for (int q2 = 0; q2 < 4; ++q2) x[q1][q2] = z[base + q1 * Q1 + q2 * Q2];
; #pragma unroll
;     for (int q1 = 0; q1 < 4; ++q1) bfly_inv(x[q1][0], x[q1][1], x[q1][2], x[q1][3], (float)jp * invM2, x[q1][0], x[q1][1], x[q1][2], x[q1][3]);
; #pragma unroll
;     for (int q2 = 0; q2 < 4; ++q2) bfly_inv(x[0][q2], x[1][q2], x[2][q2], x[3][q2], (float)(jp + q2 * Q2) * invM1, x[0][q2], x[1][q2], x[2][q2], x[3][q2]);
; #pragma unroll
;     for (int q1 = 0; q1 < 4; ++q1)
; #pragma unroll
;       for (int q2 = 0; q2 < 4; ++q2) z[base + q1 * Q1 + q2 * Q2] = x[q1][q2]; }
	v_mov_b32_e32 v116, v147
	v_mov_b32_e32 v118, v161
	v_pk_add_f32 v[132:133], v[132:133], v[232:233]
	v_pk_fma_f32 v[238:239], v[4:5], v[250:251], v[238:239] neg_lo:[0,0,1] neg_hi:[0,0,1]
	v_pk_add_f32 v[250:251], v[230:231], v[234:235] op_sel:[1,0] op_sel_hi:[0,1]
	v_pk_fma_f32 v[158:159], v[68:69], v[156:157], v[158:159] neg_lo:[0,0,1] neg_hi:[0,0,1]
	v_pk_add_f32 v[116:117], v[116:117], v[118:119]
	v_mov_b32_e32 v118, v249
	v_mov_b32_e32 v119, v237
	v_pk_mul_f32 v[246:247], v[70:71], v[156:157]
	v_mov_b32_e32 v124, v133
	v_mov_b32_e32 v126, v251
	v_pk_add_f32 v[118:119], v[118:119], v[244:245]
	v_pk_add_f32 v[162:163], v[136:137], v[158:159]
	v_pk_fma_f32 v[252:253], v[6:7], v[252:253], v[134:135]
	v_pk_fma_f32 v[246:247], v[68:69], v[254:255], v[246:247]
	v_pk_add_f32 v[254:255], v[124:125], v[126:127]
	v_mov_b32_e32 v124, v248
	v_mov_b32_e32 v125, v236
	v_mov_b32_e32 v121, v118
	v_mov_b32_e32 v123, v162
	v_pk_add_f32 v[124:125], v[124:125], v[252:253]
	v_pk_add_f32 v[126:127], v[238:239], v[246:247]
	v_pk_add_f32 v[164:165], v[120:121], v[122:123]
	v_pk_add_f32 v[120:121], v[120:121], v[122:123] neg_lo:[0,1] neg_hi:[0,1]
	v_mov_b32_e32 v115, v124
	v_mov_b32_e32 v113, v126
	v_pk_mov_b32 v[168:169], v[224:225], v[224:225] op_sel:[1,0]
	v_mov_b32_e32 v122, v120
	v_mov_b32_e32 v123, v165
	v_pk_add_f32 v[112:113], v[114:115], v[112:113]
	v_mov_b32_e32 v13, v169
	v_mov_b32_e32 v129, v21
	v_mov_b32_e32 v169, v60
	v_pk_add_f32 v[114:115], v[132:133], v[250:251]
	v_pk_mul_f32 v[178:179], v[128:129], v[112:113]
	v_pk_add_f32 v[182:183], v[128:129], v[112:113]
	v_pk_mul_f32 v[164:165], v[168:169], v[164:165]
	v_pk_add_f32 v[122:123], v[168:169], v[122:123]
	v_pk_add_f32 v[134:135], v[146:147], v[160:161]
	v_mov_b32_e32 v178, v182
	v_mov_b32_e32 v164, v122
	v_pk_mul_f32 v[114:115], v[18:19], v[114:115]
	v_mov_b32_e32 v15, v110
	v_pk_add_f32 v[170:171], v[12:13], v[116:117]
	v_pk_mul_f32 v[172:173], v[12:13], v[116:117]
	v_pk_fma_f32 v[114:115], v[22:23], v[134:135], v[114:115] neg_lo:[0,0,1] neg_hi:[0,0,1]
	v_pk_add_f32 v[134:135], v[178:179], v[164:165]
	v_pk_mov_b32 v[116:117], v[116:117], v[120:121] op_sel:[1,0]
	v_mov_b32_e32 v113, v110
	v_mov_b32_e32 v129, v255
	v_pk_mov_b32 v[178:179], v[234:235], v[246:247] op_sel:[1,0]
	v_mov_b32_e32 v239, v144
	v_mov_b32_e32 v247, v131
	v_pk_add_f32 v[156:157], v[14:15], v[254:255]
	v_pk_mul_f32 v[166:167], v[14:15], v[254:255]
	v_pk_add_f32 v[224:225], v[224:225], v[116:117] neg_lo:[0,1] neg_hi:[0,1]
	v_pk_add_f32 v[254:255], v[112:113], v[128:129] neg_lo:[0,1] neg_hi:[0,1]
	v_mov_b32_e32 v116, v248
	v_mov_b32_e32 v117, v228
	v_mov_b32_e32 v120, v252
	v_mov_b32_e32 v121, v143
	v_pk_mov_b32 v[128:129], v[142:143], v[244:245] op_sel:[1,0]
	v_mov_b32_e32 v137, v230
	v_mov_b32_e32 v142, v230
	v_mov_b32_e32 v143, v238
	v_pk_add_f32 v[238:239], v[238:239], v[246:247] neg_lo:[0,1] neg_hi:[0,1]
	v_pk_mov_b32 v[246:247], v[130:131], v[158:159] op_sel:[1,0]
	v_mov_b32_e32 v233, v138
	v_mov_b32_e32 v131, v234
	v_mov_b32_e32 v230, v145
	v_pk_add_f32 v[116:117], v[116:117], v[120:121] neg_lo:[0,1] neg_hi:[0,1]
	v_mov_b32_e32 v120, v228
	v_mov_b32_e32 v121, v249
	v_pk_mov_b32 v[184:185], v[228:229], v[248:249] op_sel:[1,0]
	v_mov_b32_e32 v228, v249
	v_mov_b32_e32 v245, v141
	v_pk_add_f32 v[232:233], v[236:237], v[232:233] neg_lo:[0,1] neg_hi:[0,1]
	v_pk_add_f32 v[230:231], v[130:131], v[230:231] neg_lo:[0,1] neg_hi:[0,1]
	v_pk_add_f32 v[120:121], v[120:121], v[128:129] neg_lo:[0,1] neg_hi:[0,1]
	v_mov_b32_e32 v128, v158
	v_mov_b32_e32 v129, v235
	v_pk_mov_b32 v[252:253], v[140:141], v[252:253] op_sel:[1,0]
	v_pk_add_f32 v[228:229], v[228:229], v[244:245] neg_lo:[0,1] neg_hi:[0,1]
	v_mov_b32_e32 v244, v144
	v_mov_b32_e32 v245, v136
	v_pk_add_f32 v[234:235], v[232:233], v[230:231] neg_lo:[0,1] neg_hi:[0,1]
	v_pk_add_f32 v[236:237], v[232:233], v[230:231]
	v_pk_add_f32 v[174:175], v[124:125], v[126:127]
	v_pk_mov_b32 v[164:165], v[168:169], v[22:23] op_sel:[1,0]
	v_pk_add_f32 v[128:129], v[136:137], v[128:129] neg_lo:[0,1] neg_hi:[0,1]
	v_pk_add_f32 v[252:253], v[184:185], v[252:253] neg_lo:[0,1] neg_hi:[0,1]
	v_pk_add_f32 v[244:245], v[244:245], v[246:247] neg_lo:[0,1] neg_hi:[0,1]
	v_mov_b32_e32 v249, v237
	v_pk_mov_b32 v[236:237], v[236:237], v[234:235] op_sel:[1,0]
	v_pk_add_f32 v[176:177], v[118:119], v[162:163]
	v_pk_mul_f32 v[164:165], v[164:165], v[174:175]
	v_pk_add_f32 v[142:143], v[142:143], v[178:179] neg_lo:[0,1] neg_hi:[0,1]
	v_pk_add_f32 v[246:247], v[252:253], v[244:245] neg_lo:[0,1] neg_hi:[0,1]
	v_mov_b32_e32 v248, v234
	v_pk_add_f32 v[116:117], v[116:117], v[128:129] neg_lo:[0,1] neg_hi:[0,1]
	v_pk_add_f32 v[128:129], v[252:253], v[244:245]
	v_pk_mul_f32 v[236:237], v[30:31], v[236:237]
	v_mov_b32_e32 v167, v157
	v_mov_b32_e32 v173, v171
	v_pk_fma_f32 v[168:169], v[72:73], v[176:177], v[164:165]
	v_pk_fma_f32 v[164:165], v[72:73], v[176:177], v[164:165] neg_lo:[0,0,1] neg_hi:[0,0,1]
	v_pk_add_f32 v[178:179], v[120:121], v[142:143]
	v_mov_b32_e32 v129, v247
	v_pk_add_f32 v[130:131], v[120:121], v[142:143] neg_lo:[0,1] neg_hi:[0,1]
	v_pk_add_f32 v[228:229], v[228:229], v[238:239]
	v_pk_fma_f32 v[234:235], v[28:29], v[234:235], v[236:237]
	v_pk_fma_f32 v[236:237], v[28:29], v[248:249], v[236:237] neg_lo:[0,0,1] neg_hi:[0,0,1]
	v_pk_add_f32 v[166:167], v[172:173], v[166:167]
	v_mov_b32_e32 v165, v169
	v_pk_add_f32 v[110:111], v[224:225], v[254:255] neg_lo:[0,1] neg_hi:[0,1]
	v_pk_add_f32 v[112:113], v[224:225], v[254:255]
	v_mov_b32_e32 v131, v179
	v_mov_b32_e32 v235, v237
	v_pk_mul_f32 v[228:229], v[26:27], v[228:229]
	v_pk_mul_f32 v[236:237], v[50:51], v[128:129]
	v_pk_add_f32 v[172:173], v[114:115], v[134:135]
; DI float2 twid(float r) { return float2{__builtin_amdgcn_cosf(r), -__builtin_amdgcn_sinf(r)}; }
; DI void bfly_inv(float2 s0, float2 s1, float2 s2, float2 s3, float r, float2& o0, float2& o1, float2& o2, float2& o3) {
;   float2 w1 = twid(r), w2 = cmul(w1, w1), w3 = cmul(w2, w1);
;   float2 c0 = s0, c1 = cmulc(s1, w1), c2 = cmulc(s2, w2), c3 = cmulc(s3, w3);
;   float2 t0 = {c0.x + c2.x, c0.y + c2.y}, t1 = {c0.x - c2.x, c0.y - c2.y}, t2 = {c1.x + c3.x, c1.y + c3.y}, t3 = {c1.x - c3.x, c1.y - c3.y};
;   o0 = float2{t0.x + t2.x, t0.y + t2.y}; o2 = float2{t0.x - t2.x, t0.y - t2.y}; o1 = float2{t1.x - t3.y, t1.y + t3.x}; o3 = float2{t1.x + t3.y, t1.y - t3.x};
; }
;     ...
;   for (int gg = tid; gg < NBT * (N / 16); gg += NTHR) { const int g = gg & (N / 16 - 1); float2* z = z0 + (gg / (N / 16)) * N; const int jp = g & (Q2 - 1), base = ((g >> lq2) << (lq2 + 4)) + jp; float2 x[4][4];
; #pragma unroll
;     for (int q1 = 0; q1 < 4; ++q1)
; #pragma unroll
;       for (int q2 = 0; q2 < 4; ++q2) x[q1][q2] = z[base + q1 * Q1 + q2 * Q2];
; #pragma unroll
;     for (int q1 = 0; q1 < 4; ++q1) bfly_inv(x[q1][0], x[q1][1], x[q1][2], x[q1][3], (float)jp * invM2, x[q1][0], x[q1][1], x[q1][2], x[q1][3]);
; #pragma unroll
;     for (int q2 = 0; q2 < 4; ++q2) bfly_inv(x[0][q2], x[1][q2], x[2][q2], x[3][q2], (float)(jp + q2 * Q2) * invM1, x[0][q2], x[1][q2], x[2][q2], x[3][q2]);
; #pragma unroll
;     for (int q1 = 0; q1 < 4; ++q1)
; #pragma unroll
;       for (int q2 = 0; q2 < 4; ++q2) z[base + q1 * Q1 + q2 * Q2] = x[q1][q2]; }
	v_pk_add_f32 v[174:175], v[166:167], v[164:165]
	v_mov_b32_e32 v112, v110
	v_pk_fma_f32 v[228:229], v[24:25], v[116:117], v[228:229]
	v_pk_fma_f32 v[236:237], v[48:49], v[130:131], v[236:237] neg_lo:[0,0,1] neg_hi:[0,0,1]
	v_pk_add_f32 v[176:177], v[172:173], v[174:175]
	v_pk_add_f32 v[238:239], v[112:113], v[234:235]
	v_pk_add_f32 v[248:249], v[236:237], v[228:229]
	v_pk_mov_b32 v[176:177], v[176:177], v[176:177] op_sel:[1,0]
	v_pk_add_f32 v[116:117], v[238:239], v[248:249]
	ds_write2_b64 v219, v[176:177], v[116:117] offset1:16
	v_pk_mov_b32 v[116:117], v[170:171], v[122:123] op_sel:[1,0]
	v_pk_mov_b32 v[122:123], v[156:157], v[182:183] op_sel:[1,0]
	v_mov_b32_e32 v128, v250
	v_pk_add_f32 v[116:117], v[116:117], v[122:123] neg_lo:[0,1] neg_hi:[0,1]
	v_mov_b32_e32 v122, v132
	v_mov_b32_e32 v123, v146
	v_mov_b32_e32 v129, v160
	v_pk_add_f32 v[122:123], v[122:123], v[128:129] neg_lo:[0,1] neg_hi:[0,1]
	v_mov_b32_e32 v128, v124
	v_mov_b32_e32 v129, v147
	v_mov_b32_e32 v130, v126
	v_mov_b32_e32 v131, v161
	v_pk_mov_b32 v[124:125], v[132:133], v[124:125] op_sel:[1,0]
	v_pk_mov_b32 v[126:127], v[250:251], v[126:127] op_sel:[1,0]
	v_mov_b32_e32 v252, v232
	v_mov_b32_e32 v244, v230
	v_pk_add_f32 v[128:129], v[128:129], v[130:131] neg_lo:[0,1] neg_hi:[0,1]
	v_pk_add_f32 v[124:125], v[124:125], v[126:127] neg_lo:[0,1] neg_hi:[0,1]
	v_pk_mov_b32 v[126:127], v[146:147], v[118:119] op_sel:[1,0]
	v_pk_mov_b32 v[130:131], v[160:161], v[162:163] op_sel:[1,0]
	v_mov_b32_e32 v119, v133
	v_mov_b32_e32 v163, v251
	v_pk_add_f32 v[244:245], v[252:253], v[244:245]
	v_mov_b32_e32 v120, v233
	v_mov_b32_e32 v142, v231
	v_pk_add_f32 v[250:251], v[118:119], v[162:163] neg_lo:[0,1] neg_hi:[0,1]
	v_pk_mul_f32 v[118:119], v[38:39], v[122:123] op_sel:[0,1] op_sel_hi:[1,0]
	v_pk_add_f32 v[230:231], v[120:121], v[142:143] neg_lo:[0,1] neg_hi:[0,1]
	v_mov_b32_e32 v247, v244
	v_mul_f32_e32 v255, v42, v246
	v_pk_add_f32 v[126:127], v[126:127], v[130:131] neg_lo:[0,1] neg_hi:[0,1]
	v_pk_fma_f32 v[130:131], v[36:37], v[122:123], v[118:119]
	v_pk_fma_f32 v[118:119], v[36:37], v[122:123], v[118:119] neg_lo:[0,0,1] neg_hi:[0,0,1]
	v_pk_mul_f32 v[232:233], v[40:41], v[246:247]
	v_mov_b32_e32 v246, v245
	v_mov_b32_e32 v247, v231
	v_mul_f32_e32 v252, v47, v231
	v_pk_mul_f32 v[244:245], v[44:45], v[244:245]
	v_mul_f32_e32 v225, v40, v178
	v_mov_b32_e32 v131, v119
	v_pk_mul_f32 v[250:251], v[34:35], v[250:251]
	v_pk_mul_f32 v[118:119], v[54:55], v[124:125]
	v_mov_b32_e32 v179, v230
	v_pk_fma_f32 v[246:247], v[46:47], v[246:247], v[252:253] op_sel_hi:[1,1,0]
	v_pk_fma_f32 v[252:253], v[58:59], v[230:231], v[244:245]
	v_pk_fma_f32 v[230:231], v[58:59], v[230:231], v[244:245] neg_lo:[0,0,1] neg_hi:[0,0,1]
	v_pk_fma_f32 v[250:251], v[32:33], v[128:129], v[250:251]
	v_pk_fma_f32 v[118:119], v[52:53], v[126:127], v[118:119] neg_lo:[0,0,1] neg_hi:[0,0,1]
	v_pk_add_f32 v[224:225], v[224:225], v[254:255]
	v_pk_fma_f32 v[232:233], v[42:43], v[178:179], v[232:233] neg_lo:[0,0,1] neg_hi:[0,0,1]
	v_mov_b32_e32 v253, v231
	v_mov_b32_e32 v110, v246
	v_pk_add_f32 v[122:123], v[116:117], v[130:131]
	v_pk_add_f32 v[124:125], v[118:119], v[250:251]
	v_pk_add_f32 v[244:245], v[232:233], v[110:111]
	v_pk_add_f32 v[254:255], v[224:225], v[252:253]
	v_pk_add_f32 v[126:127], v[122:123], v[124:125]
	v_pk_add_f32 v[120:121], v[244:245], v[254:255]
	ds_write2_b64 v219, v[126:127], v[120:121] offset0:32 offset1:48
	v_pk_mov_b32 v[120:121], v[166:167], v[134:135] op_sel:[1,0]
	v_pk_mov_b32 v[126:127], v[168:169], v[114:115] op_sel:[1,0]
	v_mov_b32_e32 v167, v115
	v_mov_b32_e32 v165, v135
	v_pk_add_f32 v[234:235], v[112:113], v[234:235] neg_lo:[0,1] neg_hi:[0,1]
	v_pk_mov_b32 v[112:113], v[228:229], v[236:237] op_sel:[1,0]
	v_pk_mov_b32 v[228:229], v[236:237], v[228:229] op_sel:[1,0]
	v_pk_add_f32 v[120:121], v[120:121], v[126:127] neg_lo:[0,1] neg_hi:[0,1]
	v_pk_add_f32 v[114:115], v[166:167], v[164:165] neg_lo:[0,1] neg_hi:[0,1]
	v_pk_add_f32 v[228:229], v[112:113], v[228:229] neg_lo:[0,1] neg_hi:[0,1]
	v_pk_add_f32 v[126:127], v[120:121], v[114:115] neg_lo:[0,1] neg_hi:[0,1]
	v_pk_add_f32 v[114:115], v[120:121], v[114:115]
	v_pk_add_f32 v[236:237], v[234:235], v[228:229] neg_lo:[0,1] neg_hi:[0,1]
	v_pk_add_f32 v[228:229], v[234:235], v[228:229]
	v_mov_b32_e32 v120, v126
	v_mov_b32_e32 v121, v115
	v_mov_b32_e32 v234, v236
	v_mov_b32_e32 v235, v229
	v_pk_mov_b32 v[112:113], v[250:251], v[118:119] op_sel:[1,0]
	v_pk_mov_b32 v[250:251], v[118:119], v[250:251] op_sel:[1,0]
	v_mov_b32_e32 v110, v224
	v_mov_b32_e32 v253, v233
	v_pk_mov_b32 v[224:225], v[224:225], v[232:233] op_sel:[1,0]
	v_pk_mov_b32 v[230:231], v[230:231], v[246:247] op_sel:[1,0]
	ds_write2_b64 v219, v[120:121], v[234:235] offset0:64 offset1:80
	v_pk_add_f32 v[234:235], v[116:117], v[130:131] neg_lo:[0,1] neg_hi:[0,1]
	v_pk_add_f32 v[250:251], v[112:113], v[250:251] neg_lo:[0,1] neg_hi:[0,1]
	v_pk_add_f32 v[252:253], v[110:111], v[252:253] neg_lo:[0,1] neg_hi:[0,1]
	v_pk_add_f32 v[230:231], v[224:225], v[230:231] neg_lo:[0,1] neg_hi:[0,1]
	v_pk_add_f32 v[112:113], v[234:235], v[250:251] neg_lo:[0,1] neg_hi:[0,1]
	v_pk_add_f32 v[234:235], v[234:235], v[250:251]
	v_pk_add_f32 v[224:225], v[252:253], v[230:231] neg_lo:[0,1] neg_hi:[0,1]
	v_pk_add_f32 v[230:231], v[252:253], v[230:231]
	v_mov_b32_e32 v250, v112
	v_mov_b32_e32 v251, v235
	v_mov_b32_e32 v232, v224
	v_mov_b32_e32 v233, v231
	ds_write2_b64 v219, v[250:251], v[232:233] offset0:96 offset1:112
	v_pk_mov_b32 v[232:233], v[174:175], v[172:173] op_sel:[1,0]
	v_pk_mov_b32 v[246:247], v[172:173], v[174:175] op_sel:[1,0]
	v_pk_add_f32 v[238:239], v[238:239], v[248:249] neg_lo:[0,1] neg_hi:[0,1]
	v_pk_add_f32 v[232:233], v[232:233], v[246:247] neg_lo:[0,1] neg_hi:[0,1]
	ds_write2_b64 v219, v[232:233], v[238:239] offset0:128 offset1:144
	v_mov_b32_e32 v238, v254
	v_mov_b32_e32 v239, v245
	v_mov_b32_e32 v245, v255
	s_nop 0
	v_pk_add_f32 v[232:233], v[122:123], v[124:125] neg_lo:[0,1] neg_hi:[0,1]
	v_pk_add_f32 v[238:239], v[238:239], v[244:245] neg_lo:[0,1] neg_hi:[0,1]
	v_mov_b32_e32 v115, v127
	v_mov_b32_e32 v229, v237
	v_mov_b32_e32 v235, v113
	v_mov_b32_e32 v231, v225
	s_nop 0
	ds_write2_b64 v219, v[232:233], v[238:239] offset0:160 offset1:176
	ds_write2_b64 v219, v[114:115], v[228:229] offset0:192 offset1:208
	ds_write2_b64 v219, v[234:235], v[230:231] offset0:224 offset1:240
	s_nop 0
	v_add_u32_e32 v13, 0x200, v82
	s_nop 0
	v_mov_b32_e32 v82, v13
; DI float2 twid(float r) { return float2{__builtin_amdgcn_cosf(r), -__builtin_amdgcn_sinf(r)}; }
; DI void bfly_inv(float2 s0, float2 s1, float2 s2, float2 s3, float r, float2& o0, float2& o1, float2& o2, float2& o3) {
;   float2 w1 = twid(r), w2 = cmul(w1, w1), w3 = cmul(w2, w1);
;   float2 c0 = s0, c1 = cmulc(s1, w1), c2 = cmulc(s2, w2), c3 = cmulc(s3, w3);
;   float2 t0 = {c0.x + c2.x, c0.y + c2.y}, t1 = {c0.x - c2.x, c0.y - c2.y}, t2 = {c1.x + c3.x, c1.y + c3.y}, t3 = {c1.x - c3.x, c1.y - c3.y};
;   o0 = float2{t0.x + t2.x, t0.y + t2.y}; o2 = float2{t0.x - t2.x, t0.y - t2.y}; o1 = float2{t1.x - t3.y, t1.y + t3.x}; o3 = float2{t1.x + t3.y, t1.y - t3.x};
; }
;   const int lq1 = lq2 + 2, Q1 = 1 << lq1, Q2 = 1 << lq2; const float invM1 = 1.f / (float)(4 << lq1), invM2 = 1.f / (float)(4 << lq2);
;   for (int gg = tid; gg < NBT * (N / 16); gg += NTHR) { const int g = gg & (N / 16 - 1); float2* z = z0 + (gg / (N / 16)) * N; const int jp = g & (Q2 - 1), base = ((g >> lq2) << (lq2 + 4)) + jp; float2 x[4][4];
; #pragma unroll
;     for (int q1 = 0; q1 < 4; ++q1)
; #pragma unroll
;       for (int q2 = 0; q2 < 4; ++q2) x[q1][q2] = z[base + q1 * Q1 + q2 * Q2];
; #pragma unroll
;     for (int q1 = 0; q1 < 4; ++q1) bfly_inv(x[q1][0], x[q1][1], x[q1][2], x[q1][3], (float)jp * invM2, x[q1][0], x[q1][1], x[q1][2], x[q1][3]);
; #pragma unroll
;     for (int q2 = 0; q2 < 4; ++q2) bfly_inv(x[0][q2], x[1][q2], x[2][q2], x[3][q2], (float)(jp + q2 * Q2) * invM1, x[0][q2], x[1][q2], x[2][q2], x[3][q2]);
; #pragma unroll
;     for (int q1 = 0; q1 < 4; ++q1)
; #pragma unroll
;       for (int q2 = 0; q2 < 4; ++q2) z[base + q1 * Q1 + q2 * Q2] = x[q1][q2]; }
.LBB0_1619:
	s_or_b64 exec, exec, s[0:1]
	s_waitcnt lgkmcnt(0)
	s_barrier
	s_and_saveexec_b64 s[12:13], vcc
	s_cbranch_execz .LBB0_1622
	v_sin_f32_e32 v3, v81
	v_cos_f32_e32 v4, v81
	v_sin_f32_e32 v12, v78
	v_cos_f32_e32 v14, v78
	v_xor_b32_e32 v8, 0x80000000, v3
	v_mov_b32_e32 v2, v4
	v_mov_b32_e32 v6, v8
	v_mov_b32_e32 v7, v3
	v_mov_b32_e32 v5, v4
	v_mov_b32_e32 v9, v4
	v_pk_mul_f32 v[10:11], v[2:3], v[6:7]
	v_cvt_f32_u32_e32 v0, v0
	v_pk_fma_f32 v[6:7], v[4:5], v[8:9], v[10:11] op_sel_hi:[0,1,1] neg_lo:[0,0,1] neg_hi:[0,0,1]
	v_pk_fma_f32 v[8:9], v[4:5], v[8:9], v[10:11] op_sel_hi:[0,1,1]
	s_nop 0
	v_pk_mov_b32 v[10:11], v[6:7], v[8:9] op_sel:[1,0]
	v_mov_b32_e32 v16, v8
	v_mov_b32_e32 v17, v7
	v_pk_mul_f32 v[18:19], v[2:3], v[10:11] op_sel:[1,0]
	v_mul_f32_e64 v9, v14, -v12
	v_pk_fma_f32 v[10:11], v[4:5], v[16:17], v[18:19] op_sel_hi:[0,1,1]
	v_pk_fma_f32 v[16:17], v[4:5], v[16:17], v[18:19] op_sel_hi:[0,1,1] neg_lo:[0,0,1] neg_hi:[0,0,1]
	v_add_f32_e32 v18, v9, v9
	v_cvt_f32_u32_e32 v9, v77
	v_mul_f32_e32 v6, v12, v12
	v_fma_f32 v22, v14, v14, -v6
	v_mul_f32_e32 v0, 0x39800000, v0
	v_mul_f32_e32 v6, 0x39800000, v9
	v_sin_f32_e32 v25, v6
	v_cos_f32_e32 v27, v6
	v_cvt_f32_u32_e32 v9, v76
	v_mul_f32_e32 v6, v12, v22
	v_fma_f32 v60, v14, v18, -v6
	v_mul_f32_e32 v6, v25, v25
	v_fma_f32 v28, v27, v27, -v6
	v_mul_f32_e64 v6, v27, -v25
	v_sin_f32_e32 v40, v0
	v_add_f32_e32 v30, v6, v6
	v_mul_f32_e32 v6, 0x39800000, v9
	v_cos_f32_e32 v42, v0
	v_sin_f32_e32 v33, v6
	v_cos_f32_e32 v35, v6
	v_xor_b32_e32 v43, 0x80000000, v40
	v_mul_f32_e32 v6, v25, v28
	v_mov_b32_e32 v41, v42
	v_mov_b32_e32 v44, v40
	v_mov_b32_e32 v45, v43
	v_fma_f32 v26, v27, v30, -v6
	v_mul_f32_e32 v6, v33, v33
	v_pk_mul_f32 v[46:47], v[40:41], v[44:45]
	v_fma_f32 v36, v35, v35, -v6
	v_mul_f32_e64 v6, v35, -v33
	v_pk_fma_f32 v[44:45], v[42:43], v[42:43], v[46:47] op_sel_hi:[0,1,1] neg_lo:[0,0,1] neg_hi:[0,0,1]
	v_pk_fma_f32 v[62:63], v[42:43], v[42:43], v[46:47] op_sel_hi:[0,1,1]
	v_add_f32_e32 v38, v6, v6
	v_pk_mov_b32 v[48:49], v[62:63], v[44:45] op_sel:[1,0]
	v_mul_f32_e32 v21, v12, v18
	v_mul_f32_e32 v24, v25, v30
	v_mul_f32_e32 v32, v33, v38
	v_mul_f32_e32 v0, v33, v36
	v_mov_b32_e32 v46, v44
	v_mov_b32_e32 v47, v63
	v_pk_mul_f32 v[48:49], v[40:41], v[48:49] op_sel_hi:[0,1]
	v_add3_u32 v20, 16, v79, v80
	v_fmac_f32_e32 v21, v14, v22
	v_fmac_f32_e32 v24, v27, v28
	v_fmac_f32_e32 v32, v35, v36
	v_fma_f32 v34, v35, v38, -v0
	v_pk_fma_f32 v[58:59], v[42:43], v[46:47], v[48:49] op_sel_hi:[0,1,1]
	v_pk_fma_f32 v[46:47], v[42:43], v[46:47], v[48:49] op_sel_hi:[0,1,1] neg_lo:[0,0,1] neg_hi:[0,0,1]
	v_mov_b32_e32 v19, v12
	v_mov_b32_e32 v17, v11
	v_mov_b32_e32 v46, v58
	v_mov_b32_e32 v9, v8
	v_mov_b32_e32 v29, v28
	v_mov_b32_e32 v31, v30
	v_pk_mov_b32 v[48:49], v[26:27], v[24:25] op_sel:[1,0]
	v_pk_mov_b32 v[50:51], v[24:25], v[26:27] op_sel:[1,0]
	v_mov_b32_e32 v37, v36
	v_pk_mov_b32 v[52:53], v[34:35], v[32:33] op_sel:[1,0]
	v_pk_mov_b32 v[54:55], v[32:33], v[34:35] op_sel:[1,0]
	v_mov_b32_e32 v56, v4
	v_mov_b32_e32 v57, v16
	v_mov_b32_e32 v10, v3
	v_pk_mov_b32 v[58:59], v[62:63], v[58:59] op_sel:[1,0]
	v_mov_b32_e32 v45, v47
	v_mov_b32_e32 v43, v44
	v_mov_b32_e32 v41, v63
	v_mov_b32_e32 v61, v16
	v_mov_b32_e32 v62, v3
	v_mov_b32_e32 v63, v3
	v_mov_b32_e32 v6, v7
	v_mov_b32_e32 v64, v4
	v_mov_b32_e32 v65, v11
	v_mov_b32_e32 v66, v3
	v_mov_b32_e32 v67, v16
	v_mov_b32_e32 v68, v11
	v_mov_b32_e32 v69, v11
	v_mov_b32_e32 v70, v16
	v_mov_b32_e32 v71, v16
	v_mov_b32_e32 v23, v14
	v_pk_mov_b32 v[72:73], v[20:21], v[18:19] op_sel:[1,0]
	v_mov_b32_e32 v39, v38
	s_mov_b64 s[0:1], 0
	v_ashrrev_i32_e32 v0, 31, v75
	v_lshrrev_b32_e32 v0, 23, v0
	v_add_lshl_u32 v0, v75, v0, 7
	v_and_b32_e32 v0, 0xffff0000, v0
	v_add_u32_e32 v176, v20, v0
	ds_read2st64_b64 v[76:79], v176 offset0:8 offset1:12
	ds_read2st64_b64 v[80:83], v176 offset1:4
	s_nop 0
	s_waitcnt lgkmcnt(1)
	v_mul_f32_e32 v109, v7, v76
	s_waitcnt lgkmcnt(0)
	v_mul_f32_e32 v0, v3, v83
	v_pk_fma_f32 v[102:103], v[2:3], v[82:83], v[0:1] op_sel_hi:[1,1,0] neg_lo:[0,0,1] neg_hi:[0,0,1]
	v_mul_f32_e32 v0, v17, v79
	v_mul_f32_e32 v104, v4, v83
	v_mul_f32_e32 v106, v3, v82
	v_mul_f32_e32 v111, v8, v77
	v_mul_f32_e32 v112, v7, v77
	v_mul_f32_e32 v114, v8, v76
	v_pk_mul_f32 v[116:117], v[16:17], v[78:79] op_sel_hi:[1,0]
	v_pk_mul_f32 v[118:119], v[60:61], v[78:79]
	v_pk_fma_f32 v[120:121], v[16:17], v[78:79], v[0:1] op_sel_hi:[1,1,0] neg_lo:[1,0,0] neg_hi:[1,0,0]
	ds_read2st64_b64 v[76:79], v176 offset0:16 offset1:20
	ds_read2st64_b64 v[82:85], v176 offset0:24 offset1:28
	ds_read2st64_b64 v[86:89], v176 offset0:32 offset1:36
	ds_read2st64_b64 v[90:93], v176 offset0:40 offset1:44
	ds_read2st64_b64 v[94:97], v176 offset0:48 offset1:52
	ds_read2st64_b64 v[98:101], v176 offset0:56 offset1:60
	v_add_u32_e32 v218, 0x200, v75
	v_ashrrev_i32_e32 v252, 31, v218
	v_lshrrev_b32_e32 v252, 23, v252
	v_add_lshl_u32 v252, v218, v252, 7
	v_and_b32_e32 v252, 0xffff0000, v252
	v_add_u32_e32 v219, v20, v252
	ds_read2st64_b64 v[220:223], v219 offset0:8 offset1:12
	ds_read2st64_b64 v[224:227], v219 offset1:4
	ds_read2st64_b64 v[228:231], v219 offset0:16 offset1:20
	ds_read2st64_b64 v[232:235], v219 offset0:24 offset1:28
	ds_read2st64_b64 v[236:239], v219 offset0:32 offset1:36
	ds_read2st64_b64 v[244:247], v219 offset0:40 offset1:44
	ds_read2st64_b64 v[248:251], v219 offset0:48 offset1:52
	ds_read2st64_b64 v[252:255], v219 offset0:56 offset1:60
	s_waitcnt lgkmcnt(12)
	v_mov_b32_e32 v123, v85
	s_waitcnt lgkmcnt(11)
	v_mov_b32_e32 v122, v89
	v_pk_mul_f32 v[122:123], v[56:57], v[122:123]
	v_mov_b32_e32 v124, v88
	v_mov_b32_e32 v125, v84
	v_pk_fma_f32 v[122:123], v[10:11], v[124:125], v[122:123]
	s_waitcnt lgkmcnt(10)
; DI float2 twid(float r) { return float2{__builtin_amdgcn_cosf(r), -__builtin_amdgcn_sinf(r)}; }
; DI void bfly_inv(float2 s0, float2 s1, float2 s2, float2 s3, float r, float2& o0, float2& o1, float2& o2, float2& o3) {
;   float2 w1 = twid(r), w2 = cmul(w1, w1), w3 = cmul(w2, w1);
;   float2 c0 = s0, c1 = cmulc(s1, w1), c2 = cmulc(s2, w2), c3 = cmulc(s3, w3);
;   float2 t0 = {c0.x + c2.x, c0.y + c2.y}, t1 = {c0.x - c2.x, c0.y - c2.y}, t2 = {c1.x + c3.x, c1.y + c3.y}, t3 = {c1.x - c3.x, c1.y - c3.y};
;   o0 = float2{t0.x + t2.x, t0.y + t2.y}; o2 = float2{t0.x - t2.x, t0.y - t2.y}; o1 = float2{t1.x - t3.y, t1.y + t3.x}; o3 = float2{t1.x + t3.y, t1.y - t3.x};
; }
;     ...
;   for (int gg = tid; gg < NBT * (N / 16); gg += NTHR) { const int g = gg & (N / 16 - 1); float2* z = z0 + (gg / (N / 16)) * N; const int jp = g & (Q2 - 1), base = ((g >> lq2) << (lq2 + 4)) + jp; float2 x[4][4];
; #pragma unroll
;     for (int q1 = 0; q1 < 4; ++q1)
; #pragma unroll
;       for (int q2 = 0; q2 < 4; ++q2) x[q1][q2] = z[base + q1 * Q1 + q2 * Q2];
; #pragma unroll
;     for (int q1 = 0; q1 < 4; ++q1) bfly_inv(x[q1][0], x[q1][1], x[q1][2], x[q1][3], (float)jp * invM2, x[q1][0], x[q1][1], x[q1][2], x[q1][3]);
; #pragma unroll
;     for (int q2 = 0; q2 < 4; ++q2) bfly_inv(x[0][q2], x[1][q2], x[2][q2], x[3][q2], (float)(jp + q2 * Q2) * invM1, x[0][q2], x[1][q2], x[2][q2], x[3][q2]);
; #pragma unroll
;     for (int q1 = 0; q1 < 4; ++q1)
; #pragma unroll
;       for (int q2 = 0; q2 < 4; ++q2) z[base + q1 * Q1 + q2 * Q2] = x[q1][q2]; }
	v_pk_mov_b32 v[124:125], v[90:91], v[82:83] op_sel:[1,0]
	v_mov_b32_e32 v82, v90
	v_pk_mul_f32 v[130:131], v[8:9], v[82:83]
	s_waitcnt lgkmcnt(8)
	v_mov_b32_e32 v132, v99
	v_mov_b32_e32 v99, v90
	v_mov_b32_e32 v126, v97
	v_mov_b32_e32 v127, v89
	v_mov_b32_e32 v133, v91
	v_pk_mul_f32 v[90:91], v[8:9], v[98:99]
	v_pk_fma_f32 v[134:135], v[6:7], v[124:125], v[130:131]
	v_pk_fma_f32 v[130:131], v[6:7], v[124:125], v[130:131] neg_lo:[0,0,1] neg_hi:[0,0,1]
	v_pk_mov_b32 v[138:139], v[78:79], v[92:93] op_sel:[1,0]
	v_pk_mul_f32 v[124:125], v[8:9], v[124:125]
	v_pk_mul_f32 v[128:129], v[4:5], v[126:127]
	v_mov_b32_e32 v97, v88
	v_mov_b32_e32 v136, v78
	v_mov_b32_e32 v137, v93
	v_pk_mul_f32 v[138:139], v[66:67], v[138:139]
	v_mov_b32_e32 v140, v101
	v_mov_b32_e32 v101, v92
	v_pk_fma_f32 v[90:91], v[6:7], v[132:133], v[90:91] neg_lo:[0,0,1] neg_hi:[0,0,1]
	v_mov_b32_e32 v158, v88
	v_mov_b32_e32 v159, v85
	v_pk_mov_b32 v[84:85], v[88:89], v[84:85] op_sel:[1,0]
	v_pk_mul_f32 v[88:89], v[62:63], v[126:127]
	v_pk_mul_f32 v[126:127], v[8:9], v[132:133]
	v_pk_fma_f32 v[132:133], v[6:7], v[82:83], v[124:125] neg_lo:[0,0,1] neg_hi:[0,0,1]
	v_pk_fma_f32 v[82:83], v[6:7], v[82:83], v[124:125]
	v_mov_b32_e32 v125, v92
	v_mov_b32_e32 v92, v79
	v_mov_b32_e32 v131, v135
	v_pk_fma_f32 v[136:137], v[64:65], v[136:137], v[138:139] neg_lo:[0,0,1] neg_hi:[0,0,1]
	v_pk_mov_b32 v[138:139], v[86:87], v[76:77] op_sel:[1,0]
	v_pk_mul_f32 v[84:85], v[66:67], v[84:85]
	v_mov_b32_e32 v124, v78
	v_pk_mul_f32 v[78:79], v[56:57], v[92:93]
	v_pk_add_f32 v[138:139], v[138:139], v[130:131]
	v_pk_add_f32 v[144:145], v[136:137], v[122:123] op_sel:[1,0] op_sel_hi:[0,1]
	v_pk_fma_f32 v[84:85], v[64:65], v[158:159], v[84:85] neg_lo:[0,0,1] neg_hi:[0,0,1]
	v_mov_b32_e32 v83, v133
	v_pk_fma_f32 v[78:79], v[10:11], v[124:125], v[78:79]
	v_mov_b32_e32 v124, v86
	v_mov_b32_e32 v125, v77
	v_mov_b32_e32 v141, v93
	v_pk_mul_f32 v[142:143], v[70:71], v[100:101]
	v_pk_fma_f32 v[128:129], v[62:63], v[96:97], v[128:129]
	v_mov_b32_e32 v108, v139
	v_mov_b32_e32 v110, v145
	v_pk_add_f32 v[124:125], v[124:125], v[82:83]
	v_pk_fma_f32 v[88:89], v[4:5], v[96:97], v[88:89] neg_lo:[0,0,1] neg_hi:[0,0,1]
	v_pk_add_f32 v[96:97], v[78:79], v[84:85] op_sel:[1,0] op_sel_hi:[0,1]
	v_pk_fma_f32 v[142:143], v[68:69], v[140:141], v[142:143] neg_lo:[0,0,1] neg_hi:[0,0,1]
	v_pk_add_f32 v[108:109], v[108:109], v[110:111]
	v_mov_b32_e32 v110, v95
	v_mov_b32_e32 v111, v87
	v_pk_mul_f32 v[92:93], v[70:71], v[140:141]
	v_mov_b32_e32 v116, v125
	v_mov_b32_e32 v118, v97
	v_pk_add_f32 v[110:111], v[110:111], v[90:91]
	v_pk_add_f32 v[146:147], v[128:129], v[142:143]
	v_pk_fma_f32 v[98:99], v[6:7], v[98:99], v[126:127]
	v_pk_fma_f32 v[92:93], v[68:69], v[100:101], v[92:93]
	v_pk_add_f32 v[100:101], v[116:117], v[118:119]
	v_mov_b32_e32 v116, v94
	v_mov_b32_e32 v117, v86
	v_mov_b32_e32 v113, v110
	v_mov_b32_e32 v115, v146
	v_pk_add_f32 v[116:117], v[116:117], v[98:99]
	v_pk_add_f32 v[118:119], v[88:89], v[92:93]
	v_pk_add_f32 v[156:157], v[112:113], v[114:115]
	v_pk_add_f32 v[112:113], v[112:113], v[114:115] neg_lo:[0,1] neg_hi:[0,1]
	v_mov_b32_e32 v107, v116
	v_mov_b32_e32 v105, v118
	v_pk_mov_b32 v[160:161], v[80:81], v[80:81] op_sel:[1,0]
	v_mov_b32_e32 v114, v112
	v_mov_b32_e32 v115, v157
	v_pk_add_f32 v[104:105], v[106:107], v[104:105]
	v_mov_b32_e32 v13, v161
	v_mov_b32_e32 v121, v21
	v_mov_b32_e32 v161, v60
	v_pk_add_f32 v[106:107], v[124:125], v[96:97]
	v_pk_mul_f32 v[170:171], v[120:121], v[104:105]
	v_pk_add_f32 v[172:173], v[120:121], v[104:105]
	v_pk_mul_f32 v[156:157], v[160:161], v[156:157]
	v_pk_add_f32 v[114:115], v[160:161], v[114:115]
	v_pk_add_f32 v[126:127], v[138:139], v[144:145]
	v_mov_b32_e32 v170, v172
	v_mov_b32_e32 v156, v114
	v_pk_mul_f32 v[106:107], v[18:19], v[106:107]
	v_mov_b32_e32 v15, v102
	v_pk_add_f32 v[162:163], v[12:13], v[108:109]
	v_pk_mul_f32 v[164:165], v[12:13], v[108:109]
	v_pk_fma_f32 v[106:107], v[22:23], v[126:127], v[106:107] neg_lo:[0,0,1] neg_hi:[0,0,1]
	v_pk_add_f32 v[126:127], v[170:171], v[156:157]
	v_pk_mov_b32 v[108:109], v[108:109], v[112:113] op_sel:[1,0]
	v_mov_b32_e32 v105, v102
	v_mov_b32_e32 v121, v101
	v_pk_mov_b32 v[170:171], v[84:85], v[92:93] op_sel:[1,0]
	v_mov_b32_e32 v89, v136
	v_mov_b32_e32 v93, v123
	v_pk_add_f32 v[140:141], v[14:15], v[100:101]
	v_pk_mul_f32 v[158:159], v[14:15], v[100:101]
	v_pk_add_f32 v[80:81], v[80:81], v[108:109] neg_lo:[0,1] neg_hi:[0,1]
	v_pk_add_f32 v[100:101], v[104:105], v[120:121] neg_lo:[0,1] neg_hi:[0,1]
	v_mov_b32_e32 v108, v94
	v_mov_b32_e32 v109, v76
	v_mov_b32_e32 v112, v98
	v_mov_b32_e32 v113, v135
	v_pk_mov_b32 v[120:121], v[134:135], v[90:91] op_sel:[1,0]
	v_mov_b32_e32 v129, v78
	v_mov_b32_e32 v134, v78
	v_mov_b32_e32 v135, v88
	v_pk_add_f32 v[88:89], v[88:89], v[92:93] neg_lo:[0,1] neg_hi:[0,1]
	v_pk_mov_b32 v[92:93], v[122:123], v[142:143] op_sel:[1,0]
	v_mov_b32_e32 v83, v130
	v_mov_b32_e32 v123, v84
	v_mov_b32_e32 v78, v137
	v_pk_add_f32 v[108:109], v[108:109], v[112:113] neg_lo:[0,1] neg_hi:[0,1]
	v_mov_b32_e32 v112, v76
	v_mov_b32_e32 v113, v95
	v_pk_mov_b32 v[174:175], v[76:77], v[94:95] op_sel:[1,0]
	v_mov_b32_e32 v76, v95
	v_mov_b32_e32 v91, v133
	v_pk_add_f32 v[82:83], v[86:87], v[82:83] neg_lo:[0,1] neg_hi:[0,1]
	v_pk_add_f32 v[78:79], v[122:123], v[78:79] neg_lo:[0,1] neg_hi:[0,1]
	v_pk_add_f32 v[112:113], v[112:113], v[120:121] neg_lo:[0,1] neg_hi:[0,1]
	v_mov_b32_e32 v120, v142
	v_mov_b32_e32 v121, v85
	v_pk_mov_b32 v[98:99], v[132:133], v[98:99] op_sel:[1,0]
	v_pk_add_f32 v[76:77], v[76:77], v[90:91] neg_lo:[0,1] neg_hi:[0,1]
	v_mov_b32_e32 v90, v136
	v_mov_b32_e32 v91, v128
; DI float2 twid(float r) { return float2{__builtin_amdgcn_cosf(r), -__builtin_amdgcn_sinf(r)}; }
; DI void bfly_inv(float2 s0, float2 s1, float2 s2, float2 s3, float r, float2& o0, float2& o1, float2& o2, float2& o3) {
;   float2 w1 = twid(r), w2 = cmul(w1, w1), w3 = cmul(w2, w1);
;   float2 c0 = s0, c1 = cmulc(s1, w1), c2 = cmulc(s2, w2), c3 = cmulc(s3, w3);
;   float2 t0 = {c0.x + c2.x, c0.y + c2.y}, t1 = {c0.x - c2.x, c0.y - c2.y}, t2 = {c1.x + c3.x, c1.y + c3.y}, t3 = {c1.x - c3.x, c1.y - c3.y};
;   o0 = float2{t0.x + t2.x, t0.y + t2.y}; o2 = float2{t0.x - t2.x, t0.y - t2.y}; o1 = float2{t1.x - t3.y, t1.y + t3.x}; o3 = float2{t1.x + t3.y, t1.y - t3.x};
; }
;     ...
;   for (int gg = tid; gg < NBT * (N / 16); gg += NTHR) { const int g = gg & (N / 16 - 1); float2* z = z0 + (gg / (N / 16)) * N; const int jp = g & (Q2 - 1), base = ((g >> lq2) << (lq2 + 4)) + jp; float2 x[4][4];
; #pragma unroll
;     for (int q1 = 0; q1 < 4; ++q1)
; #pragma unroll
;       for (int q2 = 0; q2 < 4; ++q2) x[q1][q2] = z[base + q1 * Q1 + q2 * Q2];
; #pragma unroll
;     for (int q1 = 0; q1 < 4; ++q1) bfly_inv(x[q1][0], x[q1][1], x[q1][2], x[q1][3], (float)jp * invM2, x[q1][0], x[q1][1], x[q1][2], x[q1][3]);
; #pragma unroll
;     for (int q2 = 0; q2 < 4; ++q2) bfly_inv(x[0][q2], x[1][q2], x[2][q2], x[3][q2], (float)(jp + q2 * Q2) * invM1, x[0][q2], x[1][q2], x[2][q2], x[3][q2]);
; #pragma unroll
;     for (int q1 = 0; q1 < 4; ++q1)
; #pragma unroll
;       for (int q2 = 0; q2 < 4; ++q2) z[base + q1 * Q1 + q2 * Q2] = x[q1][q2]; }
	v_pk_add_f32 v[84:85], v[82:83], v[78:79] neg_lo:[0,1] neg_hi:[0,1]
	v_pk_add_f32 v[86:87], v[82:83], v[78:79]
	v_pk_add_f32 v[166:167], v[116:117], v[118:119]
	v_pk_mov_b32 v[156:157], v[160:161], v[22:23] op_sel:[1,0]
	v_pk_add_f32 v[120:121], v[128:129], v[120:121] neg_lo:[0,1] neg_hi:[0,1]
	v_pk_add_f32 v[98:99], v[174:175], v[98:99] neg_lo:[0,1] neg_hi:[0,1]
	v_pk_add_f32 v[90:91], v[90:91], v[92:93] neg_lo:[0,1] neg_hi:[0,1]
	v_mov_b32_e32 v95, v87
	v_pk_mov_b32 v[86:87], v[86:87], v[84:85] op_sel:[1,0]
	v_pk_add_f32 v[168:169], v[110:111], v[146:147]
	v_pk_mul_f32 v[156:157], v[156:157], v[166:167]
	v_pk_add_f32 v[134:135], v[134:135], v[170:171] neg_lo:[0,1] neg_hi:[0,1]
	v_pk_add_f32 v[92:93], v[98:99], v[90:91] neg_lo:[0,1] neg_hi:[0,1]
	v_mov_b32_e32 v94, v84
	v_pk_add_f32 v[108:109], v[108:109], v[120:121] neg_lo:[0,1] neg_hi:[0,1]
	v_pk_add_f32 v[120:121], v[98:99], v[90:91]
	v_pk_mul_f32 v[86:87], v[30:31], v[86:87]
	v_mov_b32_e32 v159, v141
	v_mov_b32_e32 v165, v163
	v_pk_fma_f32 v[160:161], v[72:73], v[168:169], v[156:157]
	v_pk_fma_f32 v[156:157], v[72:73], v[168:169], v[156:157] neg_lo:[0,0,1] neg_hi:[0,0,1]
	v_pk_add_f32 v[170:171], v[112:113], v[134:135]
	v_mov_b32_e32 v121, v93
	v_pk_add_f32 v[122:123], v[112:113], v[134:135] neg_lo:[0,1] neg_hi:[0,1]
	v_pk_add_f32 v[76:77], v[76:77], v[88:89]
	v_pk_fma_f32 v[84:85], v[28:29], v[84:85], v[86:87]
	v_pk_fma_f32 v[86:87], v[28:29], v[94:95], v[86:87] neg_lo:[0,0,1] neg_hi:[0,0,1]
	v_pk_add_f32 v[158:159], v[164:165], v[158:159]
	v_mov_b32_e32 v157, v161
	v_pk_add_f32 v[102:103], v[80:81], v[100:101] neg_lo:[0,1] neg_hi:[0,1]
	v_pk_add_f32 v[104:105], v[80:81], v[100:101]
	v_mov_b32_e32 v123, v171
	v_mov_b32_e32 v85, v87
	v_pk_mul_f32 v[76:77], v[26:27], v[76:77]
	v_pk_mul_f32 v[86:87], v[50:51], v[120:121]
	v_pk_add_f32 v[164:165], v[106:107], v[126:127]
	v_pk_add_f32 v[166:167], v[158:159], v[156:157]
	v_mov_b32_e32 v104, v102
	v_pk_fma_f32 v[76:77], v[24:25], v[108:109], v[76:77]
	v_pk_fma_f32 v[86:87], v[48:49], v[122:123], v[86:87] neg_lo:[0,0,1] neg_hi:[0,0,1]
	v_pk_add_f32 v[168:169], v[164:165], v[166:167]
	v_pk_add_f32 v[88:89], v[104:105], v[84:85]
	v_pk_add_f32 v[94:95], v[86:87], v[76:77]
	v_pk_mov_b32 v[168:169], v[168:169], v[168:169] op_sel:[1,0]
	v_pk_add_f32 v[108:109], v[88:89], v[94:95]
	ds_write2st64_b64 v176, v[168:169], v[108:109] offset1:4
	v_pk_mov_b32 v[108:109], v[162:163], v[114:115] op_sel:[1,0]
	v_pk_mov_b32 v[114:115], v[140:141], v[172:173] op_sel:[1,0]
	v_mov_b32_e32 v120, v96
	v_pk_add_f32 v[108:109], v[108:109], v[114:115] neg_lo:[0,1] neg_hi:[0,1]
	v_mov_b32_e32 v114, v124
	v_mov_b32_e32 v115, v138
	v_mov_b32_e32 v121, v144
	v_pk_add_f32 v[114:115], v[114:115], v[120:121] neg_lo:[0,1] neg_hi:[0,1]
	v_mov_b32_e32 v120, v116
	v_mov_b32_e32 v121, v139
	v_mov_b32_e32 v122, v118
	v_mov_b32_e32 v123, v145
	v_pk_mov_b32 v[116:117], v[124:125], v[116:117] op_sel:[1,0]
	v_pk_mov_b32 v[118:119], v[96:97], v[118:119] op_sel:[1,0]
	v_mov_b32_e32 v98, v82
	v_mov_b32_e32 v90, v78
	v_pk_add_f32 v[120:121], v[120:121], v[122:123] neg_lo:[0,1] neg_hi:[0,1]
	v_pk_add_f32 v[116:117], v[116:117], v[118:119] neg_lo:[0,1] neg_hi:[0,1]
	v_pk_mov_b32 v[118:119], v[138:139], v[110:111] op_sel:[1,0]
	v_pk_mov_b32 v[122:123], v[144:145], v[146:147] op_sel:[1,0]
	v_mov_b32_e32 v111, v125
	v_mov_b32_e32 v147, v97
	v_pk_add_f32 v[90:91], v[98:99], v[90:91]
	v_mov_b32_e32 v112, v83
	v_mov_b32_e32 v134, v79
	v_pk_add_f32 v[96:97], v[110:111], v[146:147] neg_lo:[0,1] neg_hi:[0,1]
	v_pk_mul_f32 v[110:111], v[38:39], v[114:115] op_sel:[0,1] op_sel_hi:[1,0]
	v_pk_add_f32 v[78:79], v[112:113], v[134:135] neg_lo:[0,1] neg_hi:[0,1]
	v_mov_b32_e32 v93, v90
	v_mul_f32_e32 v101, v42, v92
	v_pk_add_f32 v[118:119], v[118:119], v[122:123] neg_lo:[0,1] neg_hi:[0,1]
	v_pk_fma_f32 v[122:123], v[36:37], v[114:115], v[110:111]
	v_pk_fma_f32 v[110:111], v[36:37], v[114:115], v[110:111] neg_lo:[0,0,1] neg_hi:[0,0,1]
	v_pk_mul_f32 v[82:83], v[40:41], v[92:93]
	v_mov_b32_e32 v92, v91
	v_mov_b32_e32 v93, v79
	v_mul_f32_e32 v0, v47, v79
	v_pk_mul_f32 v[90:91], v[44:45], v[90:91]
	v_mul_f32_e32 v81, v40, v170
	v_mov_b32_e32 v123, v111
	v_pk_mul_f32 v[96:97], v[34:35], v[96:97]
	v_pk_mul_f32 v[110:111], v[54:55], v[116:117]
	v_mov_b32_e32 v171, v78
	v_pk_fma_f32 v[92:93], v[46:47], v[92:93], v[0:1] op_sel_hi:[1,1,0]
	v_pk_fma_f32 v[98:99], v[58:59], v[78:79], v[90:91]
	v_pk_fma_f32 v[78:79], v[58:59], v[78:79], v[90:91] neg_lo:[0,0,1] neg_hi:[0,0,1]
	v_pk_fma_f32 v[96:97], v[32:33], v[120:121], v[96:97]
	v_pk_fma_f32 v[110:111], v[52:53], v[118:119], v[110:111] neg_lo:[0,0,1] neg_hi:[0,0,1]
	v_pk_add_f32 v[80:81], v[80:81], v[100:101]
	v_pk_fma_f32 v[82:83], v[42:43], v[170:171], v[82:83] neg_lo:[0,0,1] neg_hi:[0,0,1]
	v_mov_b32_e32 v99, v79
	v_mov_b32_e32 v102, v92
	v_pk_add_f32 v[114:115], v[108:109], v[122:123]
	v_pk_add_f32 v[116:117], v[110:111], v[96:97]
	v_pk_add_f32 v[90:91], v[82:83], v[102:103]
	v_pk_add_f32 v[100:101], v[80:81], v[98:99]
	v_pk_add_f32 v[118:119], v[114:115], v[116:117]
	v_pk_add_f32 v[112:113], v[90:91], v[100:101]
	ds_write2st64_b64 v176, v[118:119], v[112:113] offset0:8 offset1:12
	v_pk_mov_b32 v[112:113], v[158:159], v[126:127] op_sel:[1,0]
	v_pk_mov_b32 v[118:119], v[160:161], v[106:107] op_sel:[1,0]
	v_mov_b32_e32 v159, v107
	v_mov_b32_e32 v157, v127
	v_pk_add_f32 v[84:85], v[104:105], v[84:85] neg_lo:[0,1] neg_hi:[0,1]
	v_pk_mov_b32 v[104:105], v[76:77], v[86:87] op_sel:[1,0]
	v_pk_mov_b32 v[76:77], v[86:87], v[76:77] op_sel:[1,0]
	v_pk_add_f32 v[112:113], v[112:113], v[118:119] neg_lo:[0,1] neg_hi:[0,1]
	v_pk_add_f32 v[106:107], v[158:159], v[156:157] neg_lo:[0,1] neg_hi:[0,1]
; DI float2 twid(float r) { return float2{__builtin_amdgcn_cosf(r), -__builtin_amdgcn_sinf(r)}; }
; DI void bfly_inv(float2 s0, float2 s1, float2 s2, float2 s3, float r, float2& o0, float2& o1, float2& o2, float2& o3) {
;   float2 w1 = twid(r), w2 = cmul(w1, w1), w3 = cmul(w2, w1);
;   float2 c0 = s0, c1 = cmulc(s1, w1), c2 = cmulc(s2, w2), c3 = cmulc(s3, w3);
;   float2 t0 = {c0.x + c2.x, c0.y + c2.y}, t1 = {c0.x - c2.x, c0.y - c2.y}, t2 = {c1.x + c3.x, c1.y + c3.y}, t3 = {c1.x - c3.x, c1.y - c3.y};
;   o0 = float2{t0.x + t2.x, t0.y + t2.y}; o2 = float2{t0.x - t2.x, t0.y - t2.y}; o1 = float2{t1.x - t3.y, t1.y + t3.x}; o3 = float2{t1.x + t3.y, t1.y - t3.x};
; }
;     ...
;   for (int gg = tid; gg < NBT * (N / 16); gg += NTHR) { const int g = gg & (N / 16 - 1); float2* z = z0 + (gg / (N / 16)) * N; const int jp = g & (Q2 - 1), base = ((g >> lq2) << (lq2 + 4)) + jp; float2 x[4][4];
; #pragma unroll
;     for (int q1 = 0; q1 < 4; ++q1)
; #pragma unroll
;       for (int q2 = 0; q2 < 4; ++q2) x[q1][q2] = z[base + q1 * Q1 + q2 * Q2];
; #pragma unroll
;     for (int q1 = 0; q1 < 4; ++q1) bfly_inv(x[q1][0], x[q1][1], x[q1][2], x[q1][3], (float)jp * invM2, x[q1][0], x[q1][1], x[q1][2], x[q1][3]);
; #pragma unroll
;     for (int q2 = 0; q2 < 4; ++q2) bfly_inv(x[0][q2], x[1][q2], x[2][q2], x[3][q2], (float)(jp + q2 * Q2) * invM1, x[0][q2], x[1][q2], x[2][q2], x[3][q2]);
; #pragma unroll
;     for (int q1 = 0; q1 < 4; ++q1)
; #pragma unroll
;       for (int q2 = 0; q2 < 4; ++q2) z[base + q1 * Q1 + q2 * Q2] = x[q1][q2]; }
	v_pk_add_f32 v[76:77], v[104:105], v[76:77] neg_lo:[0,1] neg_hi:[0,1]
	v_pk_add_f32 v[118:119], v[112:113], v[106:107] neg_lo:[0,1] neg_hi:[0,1]
	v_pk_add_f32 v[106:107], v[112:113], v[106:107]
	v_pk_add_f32 v[86:87], v[84:85], v[76:77] neg_lo:[0,1] neg_hi:[0,1]
	v_pk_add_f32 v[76:77], v[84:85], v[76:77]
	v_mov_b32_e32 v112, v118
	v_mov_b32_e32 v113, v107
	v_mov_b32_e32 v84, v86
	v_mov_b32_e32 v85, v77
	v_pk_mov_b32 v[104:105], v[96:97], v[110:111] op_sel:[1,0]
	v_pk_mov_b32 v[96:97], v[110:111], v[96:97] op_sel:[1,0]
	v_mov_b32_e32 v102, v80
	v_mov_b32_e32 v99, v83
	v_pk_mov_b32 v[80:81], v[80:81], v[82:83] op_sel:[1,0]
	v_pk_mov_b32 v[78:79], v[78:79], v[92:93] op_sel:[1,0]
	ds_write2st64_b64 v176, v[112:113], v[84:85] offset0:16 offset1:20
	v_pk_add_f32 v[84:85], v[108:109], v[122:123] neg_lo:[0,1] neg_hi:[0,1]
	v_pk_add_f32 v[96:97], v[104:105], v[96:97] neg_lo:[0,1] neg_hi:[0,1]
	v_pk_add_f32 v[98:99], v[102:103], v[98:99] neg_lo:[0,1] neg_hi:[0,1]
	v_pk_add_f32 v[78:79], v[80:81], v[78:79] neg_lo:[0,1] neg_hi:[0,1]
	v_pk_add_f32 v[104:105], v[84:85], v[96:97] neg_lo:[0,1] neg_hi:[0,1]
	v_pk_add_f32 v[84:85], v[84:85], v[96:97]
	v_pk_add_f32 v[80:81], v[98:99], v[78:79] neg_lo:[0,1] neg_hi:[0,1]
	v_pk_add_f32 v[78:79], v[98:99], v[78:79]
	v_mov_b32_e32 v96, v104
	v_mov_b32_e32 v97, v85
	v_mov_b32_e32 v82, v80
	v_mov_b32_e32 v83, v79
	ds_write2st64_b64 v176, v[96:97], v[82:83] offset0:24 offset1:28
	v_pk_mov_b32 v[82:83], v[166:167], v[164:165] op_sel:[1,0]
	v_pk_mov_b32 v[92:93], v[164:165], v[166:167] op_sel:[1,0]
	v_pk_add_f32 v[88:89], v[88:89], v[94:95] neg_lo:[0,1] neg_hi:[0,1]
	v_pk_add_f32 v[82:83], v[82:83], v[92:93] neg_lo:[0,1] neg_hi:[0,1]
	ds_write2st64_b64 v176, v[82:83], v[88:89] offset0:32 offset1:36
	v_mov_b32_e32 v88, v100
	v_mov_b32_e32 v89, v91
	v_mov_b32_e32 v91, v101
	s_nop 0
	v_pk_add_f32 v[82:83], v[114:115], v[116:117] neg_lo:[0,1] neg_hi:[0,1]
	v_pk_add_f32 v[88:89], v[88:89], v[90:91] neg_lo:[0,1] neg_hi:[0,1]
	v_mov_b32_e32 v107, v119
	v_mov_b32_e32 v77, v87
	v_mov_b32_e32 v85, v105
	v_mov_b32_e32 v79, v81
	s_nop 0
	ds_write2st64_b64 v176, v[82:83], v[88:89] offset0:40 offset1:44
	ds_write2st64_b64 v176, v[106:107], v[76:77] offset0:48 offset1:52
	ds_write2st64_b64 v176, v[84:85], v[78:79] offset0:56 offset1:60
	s_nop 0
	v_add_u32_e32 v75, 0x200, v75
	s_nop 0
	s_waitcnt lgkmcnt(15)
	v_mul_f32_e32 v109, v7, v220
	s_waitcnt lgkmcnt(14)
	v_mul_f32_e32 v0, v3, v227
	v_pk_fma_f32 v[102:103], v[2:3], v[226:227], v[0:1] op_sel_hi:[1,1,0] neg_lo:[0,0,1] neg_hi:[0,0,1]
	v_mul_f32_e32 v0, v17, v223
	v_mul_f32_e32 v104, v4, v227
	v_mul_f32_e32 v106, v3, v226
	v_mul_f32_e32 v111, v8, v221
	v_mul_f32_e32 v112, v7, v221
	v_mul_f32_e32 v114, v8, v220
	v_pk_mul_f32 v[116:117], v[16:17], v[222:223] op_sel_hi:[1,0]
	v_pk_mul_f32 v[118:119], v[60:61], v[222:223]
	v_pk_fma_f32 v[120:121], v[16:17], v[222:223], v[0:1] op_sel_hi:[1,1,0] neg_lo:[1,0,0] neg_hi:[1,0,0]
	s_nop 0
	s_waitcnt lgkmcnt(12)
	v_mov_b32_e32 v123, v235
	s_waitcnt lgkmcnt(11)
	v_mov_b32_e32 v122, v239
	v_pk_mul_f32 v[122:123], v[56:57], v[122:123]
	v_mov_b32_e32 v124, v238
	v_mov_b32_e32 v125, v234
	v_pk_fma_f32 v[122:123], v[10:11], v[124:125], v[122:123]
	s_waitcnt lgkmcnt(10)
	v_pk_mov_b32 v[124:125], v[244:245], v[232:233] op_sel:[1,0]
	v_mov_b32_e32 v232, v244
	v_pk_mul_f32 v[130:131], v[8:9], v[232:233]
	s_waitcnt lgkmcnt(8)
	v_mov_b32_e32 v132, v253
	v_mov_b32_e32 v253, v244
	v_mov_b32_e32 v126, v251
	v_mov_b32_e32 v127, v239
	v_mov_b32_e32 v133, v245
	v_pk_mul_f32 v[244:245], v[8:9], v[252:253]
	v_pk_fma_f32 v[134:135], v[6:7], v[124:125], v[130:131]
	v_pk_fma_f32 v[130:131], v[6:7], v[124:125], v[130:131] neg_lo:[0,0,1] neg_hi:[0,0,1]
	v_pk_mov_b32 v[138:139], v[230:231], v[246:247] op_sel:[1,0]
	v_pk_mul_f32 v[124:125], v[8:9], v[124:125]
	v_pk_mul_f32 v[128:129], v[4:5], v[126:127]
	v_mov_b32_e32 v251, v238
	v_mov_b32_e32 v136, v230
	v_mov_b32_e32 v137, v247
	v_pk_mul_f32 v[138:139], v[66:67], v[138:139]
	v_mov_b32_e32 v140, v255
	v_mov_b32_e32 v255, v246
	v_pk_fma_f32 v[244:245], v[6:7], v[132:133], v[244:245] neg_lo:[0,0,1] neg_hi:[0,0,1]
	v_mov_b32_e32 v158, v238
	v_mov_b32_e32 v159, v235
	v_pk_mov_b32 v[234:235], v[238:239], v[234:235] op_sel:[1,0]
	v_pk_mul_f32 v[238:239], v[62:63], v[126:127]
	v_pk_mul_f32 v[126:127], v[8:9], v[132:133]
	v_pk_fma_f32 v[132:133], v[6:7], v[232:233], v[124:125] neg_lo:[0,0,1] neg_hi:[0,0,1]
	v_pk_fma_f32 v[232:233], v[6:7], v[232:233], v[124:125]
	v_mov_b32_e32 v125, v246
	v_mov_b32_e32 v246, v231
	v_mov_b32_e32 v131, v135
	v_pk_fma_f32 v[136:137], v[64:65], v[136:137], v[138:139] neg_lo:[0,0,1] neg_hi:[0,0,1]
	v_pk_mov_b32 v[138:139], v[236:237], v[228:229] op_sel:[1,0]
	v_pk_mul_f32 v[234:235], v[66:67], v[234:235]
	v_mov_b32_e32 v124, v230
	v_pk_mul_f32 v[230:231], v[56:57], v[246:247]
	v_pk_add_f32 v[138:139], v[138:139], v[130:131]
	v_pk_add_f32 v[144:145], v[136:137], v[122:123] op_sel:[1,0] op_sel_hi:[0,1]
	v_pk_fma_f32 v[234:235], v[64:65], v[158:159], v[234:235] neg_lo:[0,0,1] neg_hi:[0,0,1]
	v_mov_b32_e32 v233, v133
	v_pk_fma_f32 v[230:231], v[10:11], v[124:125], v[230:231]
	v_mov_b32_e32 v124, v236
	v_mov_b32_e32 v125, v229
	v_mov_b32_e32 v141, v247
	v_pk_mul_f32 v[142:143], v[70:71], v[254:255]
	v_pk_fma_f32 v[128:129], v[62:63], v[250:251], v[128:129]
	v_mov_b32_e32 v108, v139
	v_mov_b32_e32 v110, v145
	v_pk_add_f32 v[124:125], v[124:125], v[232:233]
	v_pk_fma_f32 v[238:239], v[4:5], v[250:251], v[238:239] neg_lo:[0,0,1] neg_hi:[0,0,1]
	v_pk_add_f32 v[250:251], v[230:231], v[234:235] op_sel:[1,0] op_sel_hi:[0,1]
	v_pk_fma_f32 v[142:143], v[68:69], v[140:141], v[142:143] neg_lo:[0,0,1] neg_hi:[0,0,1]
; DI float2 twid(float r) { return float2{__builtin_amdgcn_cosf(r), -__builtin_amdgcn_sinf(r)}; }
; DI void bfly_inv(float2 s0, float2 s1, float2 s2, float2 s3, float r, float2& o0, float2& o1, float2& o2, float2& o3) {
;   float2 w1 = twid(r), w2 = cmul(w1, w1), w3 = cmul(w2, w1);
;   float2 c0 = s0, c1 = cmulc(s1, w1), c2 = cmulc(s2, w2), c3 = cmulc(s3, w3);
;   float2 t0 = {c0.x + c2.x, c0.y + c2.y}, t1 = {c0.x - c2.x, c0.y - c2.y}, t2 = {c1.x + c3.x, c1.y + c3.y}, t3 = {c1.x - c3.x, c1.y - c3.y};
;   o0 = float2{t0.x + t2.x, t0.y + t2.y}; o2 = float2{t0.x - t2.x, t0.y - t2.y}; o1 = float2{t1.x - t3.y, t1.y + t3.x}; o3 = float2{t1.x + t3.y, t1.y - t3.x};
; }
;     ...
;   for (int gg = tid; gg < NBT * (N / 16); gg += NTHR) { const int g = gg & (N / 16 - 1); float2* z = z0 + (gg / (N / 16)) * N; const int jp = g & (Q2 - 1), base = ((g >> lq2) << (lq2 + 4)) + jp; float2 x[4][4];
; #pragma unroll
;     for (int q1 = 0; q1 < 4; ++q1)
; #pragma unroll
;       for (int q2 = 0; q2 < 4; ++q2) x[q1][q2] = z[base + q1 * Q1 + q2 * Q2];
; #pragma unroll
;     for (int q1 = 0; q1 < 4; ++q1) bfly_inv(x[q1][0], x[q1][1], x[q1][2], x[q1][3], (float)jp * invM2, x[q1][0], x[q1][1], x[q1][2], x[q1][3]);
; #pragma unroll
;     for (int q2 = 0; q2 < 4; ++q2) bfly_inv(x[0][q2], x[1][q2], x[2][q2], x[3][q2], (float)(jp + q2 * Q2) * invM1, x[0][q2], x[1][q2], x[2][q2], x[3][q2]);
; #pragma unroll
;     for (int q1 = 0; q1 < 4; ++q1)
; #pragma unroll
;       for (int q2 = 0; q2 < 4; ++q2) z[base + q1 * Q1 + q2 * Q2] = x[q1][q2]; }
	v_pk_add_f32 v[108:109], v[108:109], v[110:111]
	v_mov_b32_e32 v110, v249
	v_mov_b32_e32 v111, v237
	v_pk_mul_f32 v[246:247], v[70:71], v[140:141]
	v_mov_b32_e32 v116, v125
	v_mov_b32_e32 v118, v251
	v_pk_add_f32 v[110:111], v[110:111], v[244:245]
	v_pk_add_f32 v[146:147], v[128:129], v[142:143]
	v_pk_fma_f32 v[252:253], v[6:7], v[252:253], v[126:127]
	v_pk_fma_f32 v[246:247], v[68:69], v[254:255], v[246:247]
	v_pk_add_f32 v[254:255], v[116:117], v[118:119]
	v_mov_b32_e32 v116, v248
	v_mov_b32_e32 v117, v236
	v_mov_b32_e32 v113, v110
	v_mov_b32_e32 v115, v146
	v_pk_add_f32 v[116:117], v[116:117], v[252:253]
	v_pk_add_f32 v[118:119], v[238:239], v[246:247]
	v_pk_add_f32 v[156:157], v[112:113], v[114:115]
	v_pk_add_f32 v[112:113], v[112:113], v[114:115] neg_lo:[0,1] neg_hi:[0,1]
	v_mov_b32_e32 v107, v116
	v_mov_b32_e32 v105, v118
	v_pk_mov_b32 v[160:161], v[224:225], v[224:225] op_sel:[1,0]
	v_mov_b32_e32 v114, v112
	v_mov_b32_e32 v115, v157
	v_pk_add_f32 v[104:105], v[106:107], v[104:105]
	v_mov_b32_e32 v13, v161
	v_mov_b32_e32 v121, v21
	v_mov_b32_e32 v161, v60
	v_pk_add_f32 v[106:107], v[124:125], v[250:251]
	v_pk_mul_f32 v[170:171], v[120:121], v[104:105]
	v_pk_add_f32 v[172:173], v[120:121], v[104:105]
	v_pk_mul_f32 v[156:157], v[160:161], v[156:157]
	v_pk_add_f32 v[114:115], v[160:161], v[114:115]
	v_pk_add_f32 v[126:127], v[138:139], v[144:145]
	v_mov_b32_e32 v170, v172
	v_mov_b32_e32 v156, v114
	v_pk_mul_f32 v[106:107], v[18:19], v[106:107]
	v_mov_b32_e32 v15, v102
	v_pk_add_f32 v[162:163], v[12:13], v[108:109]
	v_pk_mul_f32 v[164:165], v[12:13], v[108:109]
	v_pk_fma_f32 v[106:107], v[22:23], v[126:127], v[106:107] neg_lo:[0,0,1] neg_hi:[0,0,1]
	v_pk_add_f32 v[126:127], v[170:171], v[156:157]
	v_pk_mov_b32 v[108:109], v[108:109], v[112:113] op_sel:[1,0]
	v_mov_b32_e32 v105, v102
	v_mov_b32_e32 v121, v255
	v_pk_mov_b32 v[170:171], v[234:235], v[246:247] op_sel:[1,0]
	v_mov_b32_e32 v239, v136
	v_mov_b32_e32 v247, v123
	v_pk_add_f32 v[140:141], v[14:15], v[254:255]
	v_pk_mul_f32 v[158:159], v[14:15], v[254:255]
	v_pk_add_f32 v[224:225], v[224:225], v[108:109] neg_lo:[0,1] neg_hi:[0,1]
	v_pk_add_f32 v[254:255], v[104:105], v[120:121] neg_lo:[0,1] neg_hi:[0,1]
	v_mov_b32_e32 v108, v248
	v_mov_b32_e32 v109, v228
	v_mov_b32_e32 v112, v252
	v_mov_b32_e32 v113, v135
	v_pk_mov_b32 v[120:121], v[134:135], v[244:245] op_sel:[1,0]
	v_mov_b32_e32 v129, v230
	v_mov_b32_e32 v134, v230
	v_mov_b32_e32 v135, v238
	v_pk_add_f32 v[238:239], v[238:239], v[246:247] neg_lo:[0,1] neg_hi:[0,1]
	v_pk_mov_b32 v[246:247], v[122:123], v[142:143] op_sel:[1,0]
	v_mov_b32_e32 v233, v130
	v_mov_b32_e32 v123, v234
	v_mov_b32_e32 v230, v137
	v_pk_add_f32 v[108:109], v[108:109], v[112:113] neg_lo:[0,1] neg_hi:[0,1]
	v_mov_b32_e32 v112, v228
	v_mov_b32_e32 v113, v249
	v_pk_mov_b32 v[174:175], v[228:229], v[248:249] op_sel:[1,0]
	v_mov_b32_e32 v228, v249
	v_mov_b32_e32 v245, v133
	v_pk_add_f32 v[232:233], v[236:237], v[232:233] neg_lo:[0,1] neg_hi:[0,1]
	v_pk_add_f32 v[230:231], v[122:123], v[230:231] neg_lo:[0,1] neg_hi:[0,1]
	v_pk_add_f32 v[112:113], v[112:113], v[120:121] neg_lo:[0,1] neg_hi:[0,1]
	v_mov_b32_e32 v120, v142
	v_mov_b32_e32 v121, v235
	v_pk_mov_b32 v[252:253], v[132:133], v[252:253] op_sel:[1,0]
	v_pk_add_f32 v[228:229], v[228:229], v[244:245] neg_lo:[0,1] neg_hi:[0,1]
	v_mov_b32_e32 v244, v136
	v_mov_b32_e32 v245, v128
	v_pk_add_f32 v[234:235], v[232:233], v[230:231] neg_lo:[0,1] neg_hi:[0,1]
	v_pk_add_f32 v[236:237], v[232:233], v[230:231]
	v_pk_add_f32 v[166:167], v[116:117], v[118:119]
	v_pk_mov_b32 v[156:157], v[160:161], v[22:23] op_sel:[1,0]
	v_pk_add_f32 v[120:121], v[128:129], v[120:121] neg_lo:[0,1] neg_hi:[0,1]
	v_pk_add_f32 v[252:253], v[174:175], v[252:253] neg_lo:[0,1] neg_hi:[0,1]
	v_pk_add_f32 v[244:245], v[244:245], v[246:247] neg_lo:[0,1] neg_hi:[0,1]
	v_mov_b32_e32 v249, v237
	v_pk_mov_b32 v[236:237], v[236:237], v[234:235] op_sel:[1,0]
	v_pk_add_f32 v[168:169], v[110:111], v[146:147]
	v_pk_mul_f32 v[156:157], v[156:157], v[166:167]
	v_pk_add_f32 v[134:135], v[134:135], v[170:171] neg_lo:[0,1] neg_hi:[0,1]
	v_pk_add_f32 v[246:247], v[252:253], v[244:245] neg_lo:[0,1] neg_hi:[0,1]
	v_mov_b32_e32 v248, v234
	v_pk_add_f32 v[108:109], v[108:109], v[120:121] neg_lo:[0,1] neg_hi:[0,1]
	v_pk_add_f32 v[120:121], v[252:253], v[244:245]
	v_pk_mul_f32 v[236:237], v[30:31], v[236:237]
	v_mov_b32_e32 v159, v141
	v_mov_b32_e32 v165, v163
	v_pk_fma_f32 v[160:161], v[72:73], v[168:169], v[156:157]
	v_pk_fma_f32 v[156:157], v[72:73], v[168:169], v[156:157] neg_lo:[0,0,1] neg_hi:[0,0,1]
	v_pk_add_f32 v[170:171], v[112:113], v[134:135]
	v_mov_b32_e32 v121, v247
	v_pk_add_f32 v[122:123], v[112:113], v[134:135] neg_lo:[0,1] neg_hi:[0,1]
	v_pk_add_f32 v[228:229], v[228:229], v[238:239]
	v_pk_fma_f32 v[234:235], v[28:29], v[234:235], v[236:237]
	v_pk_fma_f32 v[236:237], v[28:29], v[248:249], v[236:237] neg_lo:[0,0,1] neg_hi:[0,0,1]
	v_pk_add_f32 v[158:159], v[164:165], v[158:159]
	v_mov_b32_e32 v157, v161
	v_pk_add_f32 v[102:103], v[224:225], v[254:255] neg_lo:[0,1] neg_hi:[0,1]
	v_pk_add_f32 v[104:105], v[224:225], v[254:255]
	v_mov_b32_e32 v123, v171
	v_mov_b32_e32 v235, v237
	v_pk_mul_f32 v[228:229], v[26:27], v[228:229]
	v_pk_mul_f32 v[236:237], v[50:51], v[120:121]
	v_pk_add_f32 v[164:165], v[106:107], v[126:127]
	v_pk_add_f32 v[166:167], v[158:159], v[156:157]
	v_mov_b32_e32 v104, v102
	v_pk_fma_f32 v[228:229], v[24:25], v[108:109], v[228:229]
	v_pk_fma_f32 v[236:237], v[48:49], v[122:123], v[236:237] neg_lo:[0,0,1] neg_hi:[0,0,1]
	v_pk_add_f32 v[168:169], v[164:165], v[166:167]
	v_pk_add_f32 v[238:239], v[104:105], v[234:235]
; DI float2 twid(float r) { return float2{__builtin_amdgcn_cosf(r), -__builtin_amdgcn_sinf(r)}; }
; DI void bfly_inv(float2 s0, float2 s1, float2 s2, float2 s3, float r, float2& o0, float2& o1, float2& o2, float2& o3) {
;   float2 w1 = twid(r), w2 = cmul(w1, w1), w3 = cmul(w2, w1);
;   float2 c0 = s0, c1 = cmulc(s1, w1), c2 = cmulc(s2, w2), c3 = cmulc(s3, w3);
;   float2 t0 = {c0.x + c2.x, c0.y + c2.y}, t1 = {c0.x - c2.x, c0.y - c2.y}, t2 = {c1.x + c3.x, c1.y + c3.y}, t3 = {c1.x - c3.x, c1.y - c3.y};
;   o0 = float2{t0.x + t2.x, t0.y + t2.y}; o2 = float2{t0.x - t2.x, t0.y - t2.y}; o1 = float2{t1.x - t3.y, t1.y + t3.x}; o3 = float2{t1.x + t3.y, t1.y - t3.x};
; }
;     ...
;   for (int gg = tid; gg < NBT * (N / 16); gg += NTHR) { const int g = gg & (N / 16 - 1); float2* z = z0 + (gg / (N / 16)) * N; const int jp = g & (Q2 - 1), base = ((g >> lq2) << (lq2 + 4)) + jp; float2 x[4][4];
; #pragma unroll
;     for (int q1 = 0; q1 < 4; ++q1)
; #pragma unroll
;       for (int q2 = 0; q2 < 4; ++q2) x[q1][q2] = z[base + q1 * Q1 + q2 * Q2];
; #pragma unroll
;     for (int q1 = 0; q1 < 4; ++q1) bfly_inv(x[q1][0], x[q1][1], x[q1][2], x[q1][3], (float)jp * invM2, x[q1][0], x[q1][1], x[q1][2], x[q1][3]);
; #pragma unroll
;     for (int q2 = 0; q2 < 4; ++q2) bfly_inv(x[0][q2], x[1][q2], x[2][q2], x[3][q2], (float)(jp + q2 * Q2) * invM1, x[0][q2], x[1][q2], x[2][q2], x[3][q2]);
; #pragma unroll
;     for (int q1 = 0; q1 < 4; ++q1)
; #pragma unroll
;       for (int q2 = 0; q2 < 4; ++q2) z[base + q1 * Q1 + q2 * Q2] = x[q1][q2]; }
	v_pk_add_f32 v[248:249], v[236:237], v[228:229]
	v_pk_mov_b32 v[168:169], v[168:169], v[168:169] op_sel:[1,0]
	v_pk_add_f32 v[108:109], v[238:239], v[248:249]
	ds_write2st64_b64 v219, v[168:169], v[108:109] offset1:4
	v_pk_mov_b32 v[108:109], v[162:163], v[114:115] op_sel:[1,0]
	v_pk_mov_b32 v[114:115], v[140:141], v[172:173] op_sel:[1,0]
	v_mov_b32_e32 v120, v250
	v_pk_add_f32 v[108:109], v[108:109], v[114:115] neg_lo:[0,1] neg_hi:[0,1]
	v_mov_b32_e32 v114, v124
	v_mov_b32_e32 v115, v138
	v_mov_b32_e32 v121, v144
	v_pk_add_f32 v[114:115], v[114:115], v[120:121] neg_lo:[0,1] neg_hi:[0,1]
	v_mov_b32_e32 v120, v116
	v_mov_b32_e32 v121, v139
	v_mov_b32_e32 v122, v118
	v_mov_b32_e32 v123, v145
	v_pk_mov_b32 v[116:117], v[124:125], v[116:117] op_sel:[1,0]
	v_pk_mov_b32 v[118:119], v[250:251], v[118:119] op_sel:[1,0]
	v_mov_b32_e32 v252, v232
	v_mov_b32_e32 v244, v230
	v_pk_add_f32 v[120:121], v[120:121], v[122:123] neg_lo:[0,1] neg_hi:[0,1]
	v_pk_add_f32 v[116:117], v[116:117], v[118:119] neg_lo:[0,1] neg_hi:[0,1]
	v_pk_mov_b32 v[118:119], v[138:139], v[110:111] op_sel:[1,0]
	v_pk_mov_b32 v[122:123], v[144:145], v[146:147] op_sel:[1,0]
	v_mov_b32_e32 v111, v125
	v_mov_b32_e32 v147, v251
	v_pk_add_f32 v[244:245], v[252:253], v[244:245]
	v_mov_b32_e32 v112, v233
	v_mov_b32_e32 v134, v231
	v_pk_add_f32 v[250:251], v[110:111], v[146:147] neg_lo:[0,1] neg_hi:[0,1]
	v_pk_mul_f32 v[110:111], v[38:39], v[114:115] op_sel:[0,1] op_sel_hi:[1,0]
	v_pk_add_f32 v[230:231], v[112:113], v[134:135] neg_lo:[0,1] neg_hi:[0,1]
	v_mov_b32_e32 v247, v244
	v_mul_f32_e32 v255, v42, v246
	v_pk_add_f32 v[118:119], v[118:119], v[122:123] neg_lo:[0,1] neg_hi:[0,1]
	v_pk_fma_f32 v[122:123], v[36:37], v[114:115], v[110:111]
	v_pk_fma_f32 v[110:111], v[36:37], v[114:115], v[110:111] neg_lo:[0,0,1] neg_hi:[0,0,1]
	v_pk_mul_f32 v[232:233], v[40:41], v[246:247]
	v_mov_b32_e32 v246, v245
	v_mov_b32_e32 v247, v231
	v_mul_f32_e32 v0, v47, v231
	v_pk_mul_f32 v[244:245], v[44:45], v[244:245]
	v_mul_f32_e32 v225, v40, v170
	v_mov_b32_e32 v123, v111
	v_pk_mul_f32 v[250:251], v[34:35], v[250:251]
	v_pk_mul_f32 v[110:111], v[54:55], v[116:117]
	v_mov_b32_e32 v171, v230
	v_pk_fma_f32 v[246:247], v[46:47], v[246:247], v[0:1] op_sel_hi:[1,1,0]
	v_pk_fma_f32 v[252:253], v[58:59], v[230:231], v[244:245]
	v_pk_fma_f32 v[230:231], v[58:59], v[230:231], v[244:245] neg_lo:[0,0,1] neg_hi:[0,0,1]
	v_pk_fma_f32 v[250:251], v[32:33], v[120:121], v[250:251]
	v_pk_fma_f32 v[110:111], v[52:53], v[118:119], v[110:111] neg_lo:[0,0,1] neg_hi:[0,0,1]
	v_pk_add_f32 v[224:225], v[224:225], v[254:255]
	v_pk_fma_f32 v[232:233], v[42:43], v[170:171], v[232:233] neg_lo:[0,0,1] neg_hi:[0,0,1]
	v_mov_b32_e32 v253, v231
	v_mov_b32_e32 v102, v246
	v_pk_add_f32 v[114:115], v[108:109], v[122:123]
	v_pk_add_f32 v[116:117], v[110:111], v[250:251]
	v_pk_add_f32 v[244:245], v[232:233], v[102:103]
	v_pk_add_f32 v[254:255], v[224:225], v[252:253]
	v_pk_add_f32 v[118:119], v[114:115], v[116:117]
	v_pk_add_f32 v[112:113], v[244:245], v[254:255]
	ds_write2st64_b64 v219, v[118:119], v[112:113] offset0:8 offset1:12
	v_pk_mov_b32 v[112:113], v[158:159], v[126:127] op_sel:[1,0]
	v_pk_mov_b32 v[118:119], v[160:161], v[106:107] op_sel:[1,0]
	v_mov_b32_e32 v159, v107
	v_mov_b32_e32 v157, v127
	v_pk_add_f32 v[234:235], v[104:105], v[234:235] neg_lo:[0,1] neg_hi:[0,1]
	v_pk_mov_b32 v[104:105], v[228:229], v[236:237] op_sel:[1,0]
	v_pk_mov_b32 v[228:229], v[236:237], v[228:229] op_sel:[1,0]
	v_pk_add_f32 v[112:113], v[112:113], v[118:119] neg_lo:[0,1] neg_hi:[0,1]
	v_pk_add_f32 v[106:107], v[158:159], v[156:157] neg_lo:[0,1] neg_hi:[0,1]
	v_pk_add_f32 v[228:229], v[104:105], v[228:229] neg_lo:[0,1] neg_hi:[0,1]
	v_pk_add_f32 v[118:119], v[112:113], v[106:107] neg_lo:[0,1] neg_hi:[0,1]
	v_pk_add_f32 v[106:107], v[112:113], v[106:107]
	v_pk_add_f32 v[236:237], v[234:235], v[228:229] neg_lo:[0,1] neg_hi:[0,1]
	v_pk_add_f32 v[228:229], v[234:235], v[228:229]
	v_mov_b32_e32 v112, v118
	v_mov_b32_e32 v113, v107
	v_mov_b32_e32 v234, v236
	v_mov_b32_e32 v235, v229
	v_pk_mov_b32 v[104:105], v[250:251], v[110:111] op_sel:[1,0]
	v_pk_mov_b32 v[250:251], v[110:111], v[250:251] op_sel:[1,0]
	v_mov_b32_e32 v102, v224
	v_mov_b32_e32 v253, v233
	v_pk_mov_b32 v[224:225], v[224:225], v[232:233] op_sel:[1,0]
	v_pk_mov_b32 v[230:231], v[230:231], v[246:247] op_sel:[1,0]
	ds_write2st64_b64 v219, v[112:113], v[234:235] offset0:16 offset1:20
	v_pk_add_f32 v[234:235], v[108:109], v[122:123] neg_lo:[0,1] neg_hi:[0,1]
	v_pk_add_f32 v[250:251], v[104:105], v[250:251] neg_lo:[0,1] neg_hi:[0,1]
	v_pk_add_f32 v[252:253], v[102:103], v[252:253] neg_lo:[0,1] neg_hi:[0,1]
	v_pk_add_f32 v[230:231], v[224:225], v[230:231] neg_lo:[0,1] neg_hi:[0,1]
	v_pk_add_f32 v[104:105], v[234:235], v[250:251] neg_lo:[0,1] neg_hi:[0,1]
	v_pk_add_f32 v[234:235], v[234:235], v[250:251]
	v_pk_add_f32 v[224:225], v[252:253], v[230:231] neg_lo:[0,1] neg_hi:[0,1]
	v_pk_add_f32 v[230:231], v[252:253], v[230:231]
	v_mov_b32_e32 v250, v104
	v_mov_b32_e32 v251, v235
	v_mov_b32_e32 v232, v224
	v_mov_b32_e32 v233, v231
	ds_write2st64_b64 v219, v[250:251], v[232:233] offset0:24 offset1:28
	v_pk_mov_b32 v[232:233], v[166:167], v[164:165] op_sel:[1,0]
	v_pk_mov_b32 v[246:247], v[164:165], v[166:167] op_sel:[1,0]
	v_pk_add_f32 v[238:239], v[238:239], v[248:249] neg_lo:[0,1] neg_hi:[0,1]
	v_pk_add_f32 v[232:233], v[232:233], v[246:247] neg_lo:[0,1] neg_hi:[0,1]
	ds_write2st64_b64 v219, v[232:233], v[238:239] offset0:32 offset1:36
	v_mov_b32_e32 v238, v254
	v_mov_b32_e32 v239, v245
	v_mov_b32_e32 v245, v255
	s_nop 0
	v_pk_add_f32 v[232:233], v[114:115], v[116:117] neg_lo:[0,1] neg_hi:[0,1]
	v_pk_add_f32 v[238:239], v[238:239], v[244:245] neg_lo:[0,1] neg_hi:[0,1]
	v_mov_b32_e32 v107, v119
	v_mov_b32_e32 v229, v237
	v_mov_b32_e32 v235, v105
	v_mov_b32_e32 v231, v225
	s_nop 0
	ds_write2st64_b64 v219, v[232:233], v[238:239] offset0:40 offset1:44
	ds_write2st64_b64 v219, v[106:107], v[228:229] offset0:48 offset1:52
	ds_write2st64_b64 v219, v[234:235], v[230:231] offset0:56 offset1:60
	s_nop 0
	v_add_u32_e32 v0, 0x200, v75
	s_nop 0
	v_mov_b32_e32 v75, v0

;   const int lq2 = lq1 - 2, Q1 = 1 << lq1, Q2 = 1 << lq2; const float invM1 = 1.f / (float)(4 << lq1), invM2 = 1.f / (float)(4 << lq2);
;   for (int gg = tid; gg < NBT * (N / 16); gg += NTHR) { const int g = gg & (N / 16 - 1); float2* z = z0 + (gg / (N / 16)) * N; const int jp = g & (Q2 - 1), base = ((g >> lq2) << (lq2 + 4)) + jp; float2 x[4][4];
; #pragma unroll
;     for (int q1 = 0; q1 < 4; ++q1)
; #pragma unroll
;       for (int q2 = 0; q2 < 4; ++q2) x[q1][q2] = z[base + q1 * Q1 + q2 * Q2];
; #pragma unroll
;     for (int q2 = 0; q2 < 4; ++q2) bfly_fwd(x[0][q2], x[1][q2], x[2][q2], x[3][q2], (float)(jp + q2 * Q2) * invM1, x[0][q2], x[1][q2], x[2][q2], x[3][q2]);
; #pragma unroll
;     for (int q1 = 0; q1 < 4; ++q1) bfly_fwd(x[q1][0], x[q1][1], x[q1][2], x[q1][3], (float)jp * invM2, x[q1][0], x[q1][1], x[q1][2], x[q1][3]);
; #pragma unroll
;     for (int q1 = 0; q1 < 4; ++q1)
; #pragma unroll
;       for (int q2 = 0; q2 < 4; ++q2) z[base + q1 * Q1 + q2 * Q2] = x[q1][q2]; }
; template <int LOGN, bool R2DONE = false> DI void fft_fwd(float2* z, int tid) {
;     ...
;     fft_pair_fwd<N>(z, tid, 10); fft_pair_fwd<N>(z, tid, 6); fft_level_fwd<N>(z, tid, 2); fft_level_fwd<N>(z, tid, 0);
;   } else {
;     if constexpr (!R2DONE) fft_level_fwd<N>(z, tid, 12);
;     fft_pair_fwd<N>(z, tid, 10); fft_pair_fwd<N>(z, tid, 6); fft_level_fwd<N>(z, tid, 2); fft_level_fwd<N>(z, tid, 0);
.LBB0_1630:
	s_or_b64 exec, exec, s[0:1]
	s_movk_i32 s0, 0x400
	v_cmp_gt_i32_e32 vcc, s0, v76
	s_movk_i32 s0, 0x100
	v_or_b32_sdwa v80, v76, s0 dst_sel:DWORD dst_unused:UNUSED_PAD src0_sel:BYTE_0 src1_sel:DWORD
	s_movk_i32 s0, 0x200
	v_cvt_f32_ubyte0_e32 v4, v76
	v_or_b32_sdwa v79, v76, s0 dst_sel:DWORD dst_unused:UNUSED_PAD src0_sel:BYTE_0 src1_sel:DWORD
	s_movk_i32 s0, 0x300
	v_mul_f32_e32 v81, 0x39800000, v4
	v_or_b32_sdwa v78, v76, s0 dst_sel:DWORD dst_unused:UNUSED_PAD src0_sel:BYTE_0 src1_sel:DWORD
	v_mul_f32_e32 v82, 0x3a800000, v4
	v_lshlrev_b32_e32 v77, 4, v76
	s_waitcnt lgkmcnt(0)
	s_barrier
	s_and_saveexec_b64 s[0:1], vcc
	s_cbranch_execz .LBB0_1633
	v_lshlrev_b32_e32 v64, 4, v76
	v_mov_b32_e32 v65, v76
	v_ashrrev_i32_e32 v66, 31, v65
	v_lshrrev_b32_e32 v66, 22, v66
	v_add_lshl_u32 v66, v65, v66, 7
	v_and_b32_e32 v66, 0xfffe0000, v66
	v_and_b32_e32 v67, 0x3000, v64
	v_add_u32_e32 v66, 16, v66
	v_lshlrev_b32_e32 v67, 3, v67
	v_lshlrev_b32_sdwa v68, v151, v76 dst_sel:DWORD dst_unused:UNUSED_PAD src0_sel:DWORD src1_sel:BYTE_0
	v_add3_u32 v83, v66, v67, v68
	ds_read2st64_b64 v[66:69], v83 offset1:4
	ds_read2st64_b64 v[70:73], v83 offset0:8 offset1:12
	ds_read2st64_b64 v[84:87], v83 offset0:16 offset1:20
	ds_read2st64_b64 v[88:91], v83 offset0:24 offset1:28
	ds_read2st64_b64 v[92:95], v83 offset0:32 offset1:36
	ds_read2st64_b64 v[96:99], v83 offset0:40 offset1:44
	ds_read2st64_b64 v[100:103], v83 offset0:48 offset1:52
	ds_read2st64_b64 v[104:107], v83 offset0:56 offset1:60
	v_add_u32_e32 v218, 0x200, v65
	v_add_u32_e32 v241, 0x2000, v64
	v_ashrrev_i32_e32 v252, 31, v218
	v_lshrrev_b32_e32 v252, 22, v252
	v_add_lshl_u32 v252, v218, v252, 7
	v_and_b32_e32 v252, 0xfffe0000, v252
	v_and_b32_e32 v253, 0x3000, v241
	v_add_u32_e32 v252, 16, v252
	v_lshlrev_b32_e32 v253, 3, v253
	v_lshlrev_b32_sdwa v254, v151, v76 dst_sel:DWORD dst_unused:UNUSED_PAD src0_sel:DWORD src1_sel:BYTE_0
	v_add3_u32 v219, v252, v253, v254
	ds_read2st64_b64 v[220:223], v219 offset1:4
	ds_read2st64_b64 v[224:227], v219 offset0:8 offset1:12
	ds_read2st64_b64 v[228:231], v219 offset0:16 offset1:20
	ds_read2st64_b64 v[232:235], v219 offset0:24 offset1:28
	ds_read2st64_b64 v[236:239], v219 offset0:32 offset1:36
	ds_read2st64_b64 v[244:247], v219 offset0:40 offset1:44
	ds_read2st64_b64 v[248:251], v219 offset0:48 offset1:52
	ds_read2st64_b64 v[252:255], v219 offset0:56 offset1:60
	v_cvt_f32_u32_e32 v5, v80
	v_sin_f32_e32 v4, v81
	v_cos_f32_e32 v6, v81
	v_sin_f32_e32 v50, v82
	v_mul_f32_e32 v5, 0x39800000, v5
	v_sin_f32_e32 v14, v5
	v_mul_f32_e32 v7, v4, v4
	v_cos_f32_e32 v16, v5
	v_mul_f32_e64 v9, v6, -v4
	v_fma_f32 v8, v6, v6, -v7
	v_cvt_f32_u32_e32 v7, v79
	v_add_f32_e32 v10, v9, v9
	v_mul_f32_e32 v5, v4, v8
	v_fma_f32 v18, v6, v10, -v5
	v_mul_f32_e32 v5, v14, v14
	v_fma_f32 v20, v16, v16, -v5
	v_mul_f32_e64 v5, v16, -v14
	v_add_f32_e32 v22, v5, v5
	v_mul_f32_e32 v5, 0x39800000, v7
	v_sin_f32_e32 v26, v5
	v_cos_f32_e32 v28, v5
	v_cvt_f32_u32_e32 v7, v78
	v_mul_f32_e32 v5, v14, v20
	v_fma_f32 v30, v16, v22, -v5
	v_mul_f32_e32 v5, v26, v26
	v_fma_f32 v32, v28, v28, -v5
	v_mul_f32_e64 v5, v28, -v26
	v_add_f32_e32 v34, v5, v5
	v_mul_f32_e32 v5, 0x39800000, v7
	v_sin_f32_e32 v38, v5
	v_cos_f32_e32 v40, v5
	v_mul_f32_e32 v5, v26, v32
	v_fma_f32 v42, v28, v34, -v5
	v_mul_f32_e32 v5, v38, v38
	v_cos_f32_e32 v52, v82
	v_fma_f32 v44, v40, v40, -v5
	v_mul_f32_e64 v5, v40, -v38
	v_add_f32_e32 v46, v5, v5
	v_mul_f32_e32 v5, v38, v44
	v_fma_f32 v54, v40, v46, -v5
	v_mul_f32_e32 v5, v50, v50
	v_fma_f32 v56, v52, v52, -v5
	v_mul_f32_e64 v5, v52, -v50
	v_add_f32_e32 v58, v5, v5
	v_mul_f32_e32 v12, v4, v10
	v_mul_f32_e32 v24, v14, v22
	v_mul_f32_e32 v36, v26, v34
	v_mul_f32_e32 v48, v38, v46
	v_mul_f32_e32 v60, v50, v58
	v_mul_f32_e32 v5, v50, v56
	v_fmac_f32_e32 v12, v6, v8
	v_fmac_f32_e32 v24, v16, v20
	v_fmac_f32_e32 v36, v28, v32
	v_fmac_f32_e32 v48, v40, v44
	v_fmac_f32_e32 v60, v52, v56
	v_fma_f32 v62, v52, v58, -v5
	v_mov_b32_e32 v53, v52
	v_mov_b32_e32 v51, v50
	v_mov_b32_e32 v57, v56
	v_mov_b32_e32 v59, v58
	v_mov_b32_e32 v61, v60
	v_mov_b32_e32 v63, v62
	v_mov_b32_e32 v7, v6
	v_mov_b32_e32 v5, v4
	v_mov_b32_e32 v29, v28
	v_mov_b32_e32 v27, v26
	v_mov_b32_e32 v17, v16
	v_mov_b32_e32 v15, v14
	v_mov_b32_e32 v41, v40
	v_mov_b32_e32 v39, v38
	v_mov_b32_e32 v9, v8
	v_mov_b32_e32 v33, v32
	v_mov_b32_e32 v21, v20
	v_mov_b32_e32 v45, v44
	v_mov_b32_e32 v13, v12
	v_mov_b32_e32 v19, v18
	v_mov_b32_e32 v37, v36
	v_mov_b32_e32 v43, v42
	v_mov_b32_e32 v25, v24
	v_mov_b32_e32 v31, v30
	v_mov_b32_e32 v49, v48
	v_mov_b32_e32 v55, v54
	v_mov_b32_e32 v11, v10
	v_mov_b32_e32 v23, v22
	v_mov_b32_e32 v35, v34
	v_mov_b32_e32 v47, v46
	s_mov_b64 s[14:15], 0
	s_nop 0
	s_waitcnt lgkmcnt(11)
	v_pk_add_f32 v[74:75], v[66:67], v[92:93]
	v_pk_add_f32 v[112:113], v[68:69], v[94:95]
	s_waitcnt lgkmcnt(9)
	v_pk_add_f32 v[108:109], v[84:85], v[100:101]
	v_pk_add_f32 v[114:115], v[86:87], v[102:103]
	v_pk_add_f32 v[118:119], v[70:71], v[96:97]
	s_waitcnt lgkmcnt(8)
; DI float2 twid(float r) { return float2{__builtin_amdgcn_cosf(r), -__builtin_amdgcn_sinf(r)}; }
; DI void bfly_fwd(float2 a0, float2 a1, float2 a2, float2 a3, float r, float2& o0, float2& o1, float2& o2, float2& o3) {
;   float2 t0 = {a0.x + a2.x, a0.y + a2.y}, t1 = {a0.x - a2.x, a0.y - a2.y}, t2 = {a1.x + a3.x, a1.y + a3.y}, t3 = {a1.x - a3.x, a1.y - a3.y};
;   float2 b0 = {t0.x + t2.x, t0.y + t2.y}, b2 = {t0.x - t2.x, t0.y - t2.y}, b1 = {t1.x + t3.y, t1.y - t3.x}, b3 = {t1.x - t3.y, t1.y + t3.x};
;   float2 w1 = twid(r), w2 = cmul(w1, w1), w3 = cmul(w2, w1);
;   o0 = b0; o1 = cmul(b1, w1); o2 = cmul(b2, w2); o3 = cmul(b3, w3);
; }
;     ...
;   for (int gg = tid; gg < NBT * (N / 16); gg += NTHR) { const int g = gg & (N / 16 - 1); float2* z = z0 + (gg / (N / 16)) * N; const int jp = g & (Q2 - 1), base = ((g >> lq2) << (lq2 + 4)) + jp; float2 x[4][4];
; #pragma unroll
;     for (int q1 = 0; q1 < 4; ++q1)
; #pragma unroll
;       for (int q2 = 0; q2 < 4; ++q2) x[q1][q2] = z[base + q1 * Q1 + q2 * Q2];
; #pragma unroll
;     for (int q2 = 0; q2 < 4; ++q2) bfly_fwd(x[0][q2], x[1][q2], x[2][q2], x[3][q2], (float)(jp + q2 * Q2) * invM1, x[0][q2], x[1][q2], x[2][q2], x[3][q2]);
; #pragma unroll
;     for (int q1 = 0; q1 < 4; ++q1) bfly_fwd(x[q1][0], x[q1][1], x[q1][2], x[q1][3], (float)jp * invM2, x[q1][0], x[q1][1], x[q1][2], x[q1][3]);
; #pragma unroll
;     for (int q1 = 0; q1 < 4; ++q1)
; #pragma unroll
;       for (int q2 = 0; q2 < 4; ++q2) z[base + q1 * Q1 + q2 * Q2] = x[q1][q2]; }
	v_pk_add_f32 v[120:121], v[88:89], v[104:105]
	v_pk_add_f32 v[124:125], v[72:73], v[98:99]
	v_pk_add_f32 v[126:127], v[90:91], v[106:107]
	v_pk_add_f32 v[110:111], v[74:75], v[108:109]
	v_pk_add_f32 v[116:117], v[112:113], v[114:115]
	v_pk_add_f32 v[122:123], v[118:119], v[120:121]
	v_pk_add_f32 v[128:129], v[124:125], v[126:127]
	v_pk_add_f32 v[130:131], v[110:111], v[122:123]
	v_pk_add_f32 v[132:133], v[116:117], v[128:129]
	v_pk_add_f32 v[110:111], v[110:111], v[122:123] neg_lo:[0,1] neg_hi:[0,1]
	v_pk_add_f32 v[116:117], v[116:117], v[128:129] neg_lo:[0,1] neg_hi:[0,1]
	v_pk_add_f32 v[134:135], v[130:131], v[132:133]
	v_pk_add_f32 v[122:123], v[110:111], v[116:117] op_sel:[0,1] op_sel_hi:[1,0]
	v_pk_add_f32 v[110:111], v[110:111], v[116:117] op_sel:[0,1] op_sel_hi:[1,0] neg_lo:[0,1] neg_hi:[0,1]
	v_mov_b32_e32 v116, v122
	v_pk_mov_b32 v[128:129], v[110:111], v[122:123] op_sel:[1,0]
	v_mov_b32_e32 v117, v111
	v_pk_mul_f32 v[128:129], v[50:51], v[128:129]
	v_pk_add_f32 v[66:67], v[66:67], v[92:93] neg_lo:[0,1] neg_hi:[0,1]
	v_pk_fma_f32 v[136:137], v[52:53], v[122:123], v[128:129]
	v_pk_fma_f32 v[116:117], v[52:53], v[116:117], v[128:129] neg_lo:[0,0,1] neg_hi:[0,0,1]
	v_pk_add_f32 v[84:85], v[84:85], v[100:101] neg_lo:[0,1] neg_hi:[0,1]
	v_mov_b32_e32 v137, v117
	v_pk_add_f32 v[116:117], v[130:131], v[132:133] neg_lo:[0,1] neg_hi:[0,1]
	v_pk_add_f32 v[92:93], v[66:67], v[84:85] op_sel:[0,1] op_sel_hi:[1,0]
	v_pk_mul_f32 v[128:129], v[58:59], v[116:117]
	v_pk_add_f32 v[66:67], v[66:67], v[84:85] op_sel:[0,1] op_sel_hi:[1,0] neg_lo:[0,1] neg_hi:[0,1]
	v_pk_fma_f32 v[130:131], v[56:57], v[116:117], v[128:129] op_sel:[0,0,1] op_sel_hi:[1,1,0] neg_lo:[0,0,1] neg_hi:[0,0,1]
	v_pk_fma_f32 v[116:117], v[56:57], v[116:117], v[128:129] op_sel:[0,0,1] op_sel_hi:[1,1,0]
	v_pk_mov_b32 v[100:101], v[66:67], v[92:93] op_sel:[1,0]
	v_mov_b32_e32 v131, v117
	v_mov_b32_e32 v117, v123
	v_pk_mov_b32 v[122:123], v[122:123], v[110:111] op_sel:[1,0]
	v_mov_b32_e32 v116, v110
	v_pk_mul_f32 v[122:123], v[62:63], v[122:123]
	v_mov_b32_e32 v84, v92
	v_pk_fma_f32 v[110:111], v[60:61], v[110:111], v[122:123] neg_lo:[0,0,1] neg_hi:[0,0,1]
	v_pk_fma_f32 v[116:117], v[60:61], v[116:117], v[122:123]
	v_mov_b32_e32 v85, v67
	v_mov_b32_e32 v111, v117
	v_pk_mul_f32 v[100:101], v[4:5], v[100:101]
	ds_write2st64_b64 v83, v[130:131], v[110:111] offset0:8 offset1:12
	v_pk_fma_f32 v[110:111], v[6:7], v[92:93], v[100:101]
	v_pk_fma_f32 v[84:85], v[6:7], v[84:85], v[100:101] neg_lo:[0,0,1] neg_hi:[0,0,1]
	v_pk_add_f32 v[68:69], v[68:69], v[94:95] neg_lo:[0,1] neg_hi:[0,1]
	v_mov_b32_e32 v111, v85
	v_pk_add_f32 v[84:85], v[86:87], v[102:103] neg_lo:[0,1] neg_hi:[0,1]
	v_pk_add_f32 v[70:71], v[70:71], v[96:97] neg_lo:[0,1] neg_hi:[0,1]
	v_pk_add_f32 v[86:87], v[68:69], v[84:85] op_sel:[0,1] op_sel_hi:[1,0]
	v_pk_add_f32 v[68:69], v[68:69], v[84:85] op_sel:[0,1] op_sel_hi:[1,0] neg_lo:[0,1] neg_hi:[0,1]
	v_mov_b32_e32 v84, v86
	v_pk_mov_b32 v[94:95], v[68:69], v[86:87] op_sel:[1,0]
	v_mov_b32_e32 v85, v69
	v_pk_mul_f32 v[94:95], v[14:15], v[94:95]
	v_pk_add_f32 v[72:73], v[72:73], v[98:99] neg_lo:[0,1] neg_hi:[0,1]
	v_pk_fma_f32 v[100:101], v[16:17], v[86:87], v[94:95]
	v_pk_fma_f32 v[84:85], v[16:17], v[84:85], v[94:95] neg_lo:[0,0,1] neg_hi:[0,0,1]
	v_pk_add_f32 v[74:75], v[74:75], v[108:109] neg_lo:[0,1] neg_hi:[0,1]
	v_mov_b32_e32 v101, v85
	v_pk_add_f32 v[84:85], v[88:89], v[104:105] neg_lo:[0,1] neg_hi:[0,1]
	v_add_u32_e32 v64, 0x2000, v64
	v_pk_add_f32 v[88:89], v[70:71], v[84:85] op_sel:[0,1] op_sel_hi:[1,0]
	v_pk_add_f32 v[70:71], v[70:71], v[84:85] op_sel:[0,1] op_sel_hi:[1,0] neg_lo:[0,1] neg_hi:[0,1]
	v_mov_b32_e32 v84, v88
	v_pk_mov_b32 v[94:95], v[70:71], v[88:89] op_sel:[1,0]
	v_mov_b32_e32 v85, v71
	v_pk_mul_f32 v[94:95], v[26:27], v[94:95]
	s_nop 0
	v_pk_fma_f32 v[96:97], v[28:29], v[88:89], v[94:95]
	v_pk_fma_f32 v[84:85], v[28:29], v[84:85], v[94:95] neg_lo:[0,0,1] neg_hi:[0,0,1]
	ds_write2st64_b64 v83, v[134:135], v[136:137] offset1:4
	v_mov_b32_e32 v97, v85
	v_pk_add_f32 v[84:85], v[90:91], v[106:107] neg_lo:[0,1] neg_hi:[0,1]
	s_nop 0
	v_pk_add_f32 v[90:91], v[72:73], v[84:85] op_sel:[0,1] op_sel_hi:[1,0]
	v_pk_add_f32 v[72:73], v[72:73], v[84:85] op_sel:[0,1] op_sel_hi:[1,0] neg_lo:[0,1] neg_hi:[0,1]
	v_mov_b32_e32 v84, v90
	v_pk_mov_b32 v[94:95], v[72:73], v[90:91] op_sel:[1,0]
	v_mov_b32_e32 v85, v73
	v_pk_mul_f32 v[94:95], v[38:39], v[94:95]
	s_nop 0
	v_pk_fma_f32 v[98:99], v[40:41], v[90:91], v[94:95]
	v_pk_fma_f32 v[84:85], v[40:41], v[84:85], v[94:95] neg_lo:[0,0,1] neg_hi:[0,0,1]
	s_nop 0
	v_mov_b32_e32 v99, v85
	v_pk_add_f32 v[84:85], v[110:111], v[96:97]
	v_pk_add_f32 v[94:95], v[100:101], v[98:99]
	v_pk_add_f32 v[96:97], v[110:111], v[96:97] neg_lo:[0,1] neg_hi:[0,1]
	v_pk_add_f32 v[98:99], v[100:101], v[98:99] neg_lo:[0,1] neg_hi:[0,1]
	v_pk_add_f32 v[102:103], v[84:85], v[94:95]
	v_pk_add_f32 v[100:101], v[96:97], v[98:99] op_sel:[0,1] op_sel_hi:[1,0]
	v_pk_add_f32 v[96:97], v[96:97], v[98:99] op_sel:[0,1] op_sel_hi:[1,0] neg_lo:[0,1] neg_hi:[0,1]
	v_mov_b32_e32 v98, v100
	v_pk_mov_b32 v[104:105], v[96:97], v[100:101] op_sel:[1,0]
	v_mov_b32_e32 v99, v97
	v_pk_mul_f32 v[104:105], v[50:51], v[104:105]
	v_pk_add_f32 v[84:85], v[84:85], v[94:95] neg_lo:[0,1] neg_hi:[0,1]
	v_pk_fma_f32 v[106:107], v[52:53], v[100:101], v[104:105]
	v_pk_fma_f32 v[98:99], v[52:53], v[98:99], v[104:105] neg_lo:[0,0,1] neg_hi:[0,0,1]
	v_pk_mul_f32 v[94:95], v[58:59], v[84:85]
	v_mov_b32_e32 v107, v99
	v_pk_fma_f32 v[98:99], v[56:57], v[84:85], v[94:95] op_sel:[0,0,1] op_sel_hi:[1,1,0] neg_lo:[0,0,1] neg_hi:[0,0,1]
	v_pk_fma_f32 v[84:85], v[56:57], v[84:85], v[94:95] op_sel:[0,0,1] op_sel_hi:[1,1,0]
; DI float2 twid(float r) { return float2{__builtin_amdgcn_cosf(r), -__builtin_amdgcn_sinf(r)}; }
; DI void bfly_fwd(float2 a0, float2 a1, float2 a2, float2 a3, float r, float2& o0, float2& o1, float2& o2, float2& o3) {
;   float2 t0 = {a0.x + a2.x, a0.y + a2.y}, t1 = {a0.x - a2.x, a0.y - a2.y}, t2 = {a1.x + a3.x, a1.y + a3.y}, t3 = {a1.x - a3.x, a1.y - a3.y};
;   float2 b0 = {t0.x + t2.x, t0.y + t2.y}, b2 = {t0.x - t2.x, t0.y - t2.y}, b1 = {t1.x + t3.y, t1.y - t3.x}, b3 = {t1.x - t3.y, t1.y + t3.x};
;   float2 w1 = twid(r), w2 = cmul(w1, w1), w3 = cmul(w2, w1);
;   o0 = b0; o1 = cmul(b1, w1); o2 = cmul(b2, w2); o3 = cmul(b3, w3);
; }
;     ...
;   for (int gg = tid; gg < NBT * (N / 16); gg += NTHR) { const int g = gg & (N / 16 - 1); float2* z = z0 + (gg / (N / 16)) * N; const int jp = g & (Q2 - 1), base = ((g >> lq2) << (lq2 + 4)) + jp; float2 x[4][4];
; #pragma unroll
;     for (int q1 = 0; q1 < 4; ++q1)
; #pragma unroll
;       for (int q2 = 0; q2 < 4; ++q2) x[q1][q2] = z[base + q1 * Q1 + q2 * Q2];
; #pragma unroll
;     for (int q2 = 0; q2 < 4; ++q2) bfly_fwd(x[0][q2], x[1][q2], x[2][q2], x[3][q2], (float)(jp + q2 * Q2) * invM1, x[0][q2], x[1][q2], x[2][q2], x[3][q2]);
; #pragma unroll
;     for (int q1 = 0; q1 < 4; ++q1) bfly_fwd(x[q1][0], x[q1][1], x[q1][2], x[q1][3], (float)jp * invM2, x[q1][0], x[q1][1], x[q1][2], x[q1][3]);
; #pragma unroll
;     for (int q1 = 0; q1 < 4; ++q1)
; #pragma unroll
;       for (int q2 = 0; q2 < 4; ++q2) z[base + q1 * Q1 + q2 * Q2] = x[q1][q2]; }
	v_pk_mov_b32 v[94:95], v[100:101], v[96:97] op_sel:[1,0]
	v_mov_b32_e32 v99, v85
	v_mov_b32_e32 v84, v96
	v_mov_b32_e32 v85, v101
	v_pk_mul_f32 v[94:95], v[62:63], v[94:95]
	ds_write2st64_b64 v83, v[102:103], v[106:107] offset0:16 offset1:20
	v_pk_fma_f32 v[96:97], v[60:61], v[96:97], v[94:95] neg_lo:[0,0,1] neg_hi:[0,0,1]
	v_pk_fma_f32 v[84:85], v[60:61], v[84:85], v[94:95]
	s_nop 0
	v_mov_b32_e32 v97, v85
	v_pk_mul_f32 v[84:85], v[10:11], v[74:75] op_sel:[0,1] op_sel_hi:[1,0]
	ds_write2st64_b64 v83, v[98:99], v[96:97] offset0:24 offset1:28
	v_pk_fma_f32 v[94:95], v[8:9], v[74:75], v[84:85] neg_lo:[0,0,1] neg_hi:[0,0,1]
	v_pk_fma_f32 v[74:75], v[8:9], v[74:75], v[84:85]
	s_nop 0
	v_mov_b32_e32 v95, v75
	v_pk_add_f32 v[74:75], v[112:113], v[114:115] neg_lo:[0,1] neg_hi:[0,1]
	s_nop 0
	v_pk_mul_f32 v[84:85], v[22:23], v[74:75] op_sel:[0,1] op_sel_hi:[1,0]
	s_nop 0
	v_pk_fma_f32 v[96:97], v[20:21], v[74:75], v[84:85] neg_lo:[0,0,1] neg_hi:[0,0,1]
	v_pk_fma_f32 v[74:75], v[20:21], v[74:75], v[84:85]
	s_nop 0
	v_mov_b32_e32 v97, v75
	v_pk_add_f32 v[74:75], v[118:119], v[120:121] neg_lo:[0,1] neg_hi:[0,1]
	s_nop 0
	v_pk_mul_f32 v[84:85], v[34:35], v[74:75] op_sel:[0,1] op_sel_hi:[1,0]
	s_nop 0
	v_pk_fma_f32 v[98:99], v[32:33], v[74:75], v[84:85] neg_lo:[0,0,1] neg_hi:[0,0,1]
	v_pk_fma_f32 v[74:75], v[32:33], v[74:75], v[84:85]
	s_nop 0
	v_mov_b32_e32 v99, v75
	v_pk_add_f32 v[74:75], v[124:125], v[126:127] neg_lo:[0,1] neg_hi:[0,1]
	s_nop 0
	v_pk_mul_f32 v[84:85], v[46:47], v[74:75] op_sel:[0,1] op_sel_hi:[1,0]
	s_nop 0
	v_pk_fma_f32 v[100:101], v[44:45], v[74:75], v[84:85] neg_lo:[0,0,1] neg_hi:[0,0,1]
	v_pk_fma_f32 v[74:75], v[44:45], v[74:75], v[84:85]
	s_nop 0
	v_mov_b32_e32 v101, v75
	v_pk_add_f32 v[74:75], v[94:95], v[98:99]
	v_pk_add_f32 v[84:85], v[96:97], v[100:101]
	v_pk_add_f32 v[94:95], v[94:95], v[98:99] neg_lo:[0,1] neg_hi:[0,1]
	v_pk_add_f32 v[96:97], v[96:97], v[100:101] neg_lo:[0,1] neg_hi:[0,1]
	v_pk_add_f32 v[102:103], v[74:75], v[84:85]
	v_pk_add_f32 v[98:99], v[94:95], v[96:97] op_sel:[0,1] op_sel_hi:[1,0]
	v_pk_add_f32 v[94:95], v[94:95], v[96:97] op_sel:[0,1] op_sel_hi:[1,0] neg_lo:[0,1] neg_hi:[0,1]
	v_mov_b32_e32 v96, v98
	v_pk_mov_b32 v[100:101], v[94:95], v[98:99] op_sel:[1,0]
	v_mov_b32_e32 v97, v95
	v_pk_mul_f32 v[100:101], v[50:51], v[100:101]
	v_pk_add_f32 v[74:75], v[74:75], v[84:85] neg_lo:[0,1] neg_hi:[0,1]
	v_pk_fma_f32 v[104:105], v[52:53], v[98:99], v[100:101]
	v_pk_fma_f32 v[96:97], v[52:53], v[96:97], v[100:101] neg_lo:[0,0,1] neg_hi:[0,0,1]
	v_pk_mul_f32 v[84:85], v[58:59], v[74:75]
	v_mov_b32_e32 v105, v97
	v_pk_fma_f32 v[96:97], v[56:57], v[74:75], v[84:85] op_sel:[0,0,1] op_sel_hi:[1,1,0] neg_lo:[0,0,1] neg_hi:[0,0,1]
	v_pk_fma_f32 v[74:75], v[56:57], v[74:75], v[84:85] op_sel:[0,0,1] op_sel_hi:[1,1,0]
	v_pk_mov_b32 v[84:85], v[98:99], v[94:95] op_sel:[1,0]
	v_mov_b32_e32 v97, v75
	v_mov_b32_e32 v74, v94
	v_mov_b32_e32 v75, v99
	v_pk_mul_f32 v[84:85], v[62:63], v[84:85]
	ds_write2st64_b64 v83, v[102:103], v[104:105] offset0:32 offset1:36
	v_pk_fma_f32 v[94:95], v[60:61], v[94:95], v[84:85] neg_lo:[0,0,1] neg_hi:[0,0,1]
	v_pk_fma_f32 v[74:75], v[60:61], v[74:75], v[84:85]
	v_pk_mov_b32 v[84:85], v[92:93], v[66:67] op_sel:[1,0]
	v_mov_b32_e32 v95, v75
	v_mov_b32_e32 v74, v66
	v_mov_b32_e32 v75, v93
	v_pk_mul_f32 v[84:85], v[18:19], v[84:85]
	ds_write2st64_b64 v83, v[96:97], v[94:95] offset0:40 offset1:44
	v_pk_fma_f32 v[66:67], v[12:13], v[66:67], v[84:85] neg_lo:[0,0,1] neg_hi:[0,0,1]
	v_pk_fma_f32 v[74:75], v[12:13], v[74:75], v[84:85]
	v_pk_mov_b32 v[84:85], v[86:87], v[68:69] op_sel:[1,0]
	v_mov_b32_e32 v67, v75
	v_mov_b32_e32 v74, v68
	v_mov_b32_e32 v75, v87
	v_pk_mul_f32 v[84:85], v[30:31], v[84:85]
	s_nop 0
	v_pk_fma_f32 v[68:69], v[24:25], v[68:69], v[84:85] neg_lo:[0,0,1] neg_hi:[0,0,1]
	v_pk_fma_f32 v[74:75], v[24:25], v[74:75], v[84:85]
	v_pk_mov_b32 v[84:85], v[88:89], v[70:71] op_sel:[1,0]
	v_mov_b32_e32 v69, v75
	v_mov_b32_e32 v74, v70
	v_mov_b32_e32 v75, v89
	v_pk_mul_f32 v[84:85], v[42:43], v[84:85]
	s_nop 0
	v_pk_fma_f32 v[70:71], v[36:37], v[70:71], v[84:85] neg_lo:[0,0,1] neg_hi:[0,0,1]
	v_pk_fma_f32 v[74:75], v[36:37], v[74:75], v[84:85]
	v_pk_mov_b32 v[84:85], v[90:91], v[72:73] op_sel:[1,0]
	v_mov_b32_e32 v71, v75
	v_mov_b32_e32 v74, v72
	v_mov_b32_e32 v75, v91
	v_pk_mul_f32 v[84:85], v[54:55], v[84:85]
	s_nop 0
	v_pk_fma_f32 v[72:73], v[48:49], v[72:73], v[84:85] neg_lo:[0,0,1] neg_hi:[0,0,1]
	v_pk_fma_f32 v[74:75], v[48:49], v[74:75], v[84:85]
	s_nop 0
	v_mov_b32_e32 v73, v75
	v_pk_add_f32 v[74:75], v[66:67], v[70:71]
	v_pk_add_f32 v[84:85], v[68:69], v[72:73]
	v_pk_add_f32 v[66:67], v[66:67], v[70:71] neg_lo:[0,1] neg_hi:[0,1]
	v_pk_add_f32 v[68:69], v[68:69], v[72:73] neg_lo:[0,1] neg_hi:[0,1]
	v_pk_add_f32 v[86:87], v[74:75], v[84:85]
	v_pk_add_f32 v[70:71], v[66:67], v[68:69] op_sel:[0,1] op_sel_hi:[1,0]
	v_pk_add_f32 v[66:67], v[66:67], v[68:69] op_sel:[0,1] op_sel_hi:[1,0] neg_lo:[0,1] neg_hi:[0,1]
	v_mov_b32_e32 v68, v70
	v_pk_mov_b32 v[72:73], v[66:67], v[70:71] op_sel:[1,0]
	v_mov_b32_e32 v69, v67
	v_pk_mul_f32 v[72:73], v[50:51], v[72:73]
	s_nop 0
	v_pk_fma_f32 v[88:89], v[52:53], v[70:71], v[72:73]
	v_pk_fma_f32 v[68:69], v[52:53], v[68:69], v[72:73] neg_lo:[0,0,1] neg_hi:[0,0,1]
	s_nop 0
	v_mov_b32_e32 v89, v69
	v_pk_add_f32 v[68:69], v[74:75], v[84:85] neg_lo:[0,1] neg_hi:[0,1]
	ds_write2st64_b64 v83, v[86:87], v[88:89] offset0:48 offset1:52
	v_pk_mul_f32 v[72:73], v[58:59], v[68:69]
	s_nop 0
	v_pk_fma_f32 v[74:75], v[56:57], v[68:69], v[72:73] op_sel:[0,0,1] op_sel_hi:[1,1,0] neg_lo:[0,0,1] neg_hi:[0,0,1]
	v_pk_fma_f32 v[68:69], v[56:57], v[68:69], v[72:73] op_sel:[0,0,1] op_sel_hi:[1,1,0]
	s_nop 0
	v_mov_b32_e32 v75, v69
	v_mov_b32_e32 v69, v71
	v_pk_mov_b32 v[70:71], v[70:71], v[66:67] op_sel:[1,0]
	v_mov_b32_e32 v68, v66
	v_pk_mul_f32 v[70:71], v[62:63], v[70:71]
	s_nop 0
	v_pk_fma_f32 v[66:67], v[60:61], v[66:67], v[70:71] neg_lo:[0,0,1] neg_hi:[0,0,1]
	v_pk_fma_f32 v[68:69], v[60:61], v[68:69], v[70:71]
	s_nop 0
	v_mov_b32_e32 v67, v69
	ds_write2st64_b64 v83, v[74:75], v[66:67] offset0:56 offset1:60
	s_nop 0
	v_add_u32_e32 v65, 0x200, v65
	s_nop 0
	s_waitcnt lgkmcnt(11)
; DI float2 twid(float r) { return float2{__builtin_amdgcn_cosf(r), -__builtin_amdgcn_sinf(r)}; }
; DI void bfly_fwd(float2 a0, float2 a1, float2 a2, float2 a3, float r, float2& o0, float2& o1, float2& o2, float2& o3) {
;   float2 t0 = {a0.x + a2.x, a0.y + a2.y}, t1 = {a0.x - a2.x, a0.y - a2.y}, t2 = {a1.x + a3.x, a1.y + a3.y}, t3 = {a1.x - a3.x, a1.y - a3.y};
;   float2 b0 = {t0.x + t2.x, t0.y + t2.y}, b2 = {t0.x - t2.x, t0.y - t2.y}, b1 = {t1.x + t3.y, t1.y - t3.x}, b3 = {t1.x - t3.y, t1.y + t3.x};
;   float2 w1 = twid(r), w2 = cmul(w1, w1), w3 = cmul(w2, w1);
;   o0 = b0; o1 = cmul(b1, w1); o2 = cmul(b2, w2); o3 = cmul(b3, w3);
; }
;     ...
;   for (int gg = tid; gg < NBT * (N / 16); gg += NTHR) { const int g = gg & (N / 16 - 1); float2* z = z0 + (gg / (N / 16)) * N; const int jp = g & (Q2 - 1), base = ((g >> lq2) << (lq2 + 4)) + jp; float2 x[4][4];
; #pragma unroll
;     for (int q1 = 0; q1 < 4; ++q1)
; #pragma unroll
;       for (int q2 = 0; q2 < 4; ++q2) x[q1][q2] = z[base + q1 * Q1 + q2 * Q2];
; #pragma unroll
;     for (int q2 = 0; q2 < 4; ++q2) bfly_fwd(x[0][q2], x[1][q2], x[2][q2], x[3][q2], (float)(jp + q2 * Q2) * invM1, x[0][q2], x[1][q2], x[2][q2], x[3][q2]);
; #pragma unroll
;     for (int q1 = 0; q1 < 4; ++q1) bfly_fwd(x[q1][0], x[q1][1], x[q1][2], x[q1][3], (float)jp * invM2, x[q1][0], x[q1][1], x[q1][2], x[q1][3]);
; #pragma unroll
;     for (int q1 = 0; q1 < 4; ++q1)
; #pragma unroll
;       for (int q2 = 0; q2 < 4; ++q2) z[base + q1 * Q1 + q2 * Q2] = x[q1][q2]; }
	v_pk_add_f32 v[74:75], v[220:221], v[236:237]
	v_pk_add_f32 v[112:113], v[222:223], v[238:239]
	s_waitcnt lgkmcnt(9)
	v_pk_add_f32 v[108:109], v[228:229], v[248:249]
	v_pk_add_f32 v[114:115], v[230:231], v[250:251]
	v_pk_add_f32 v[118:119], v[224:225], v[244:245]
	s_waitcnt lgkmcnt(8)
	v_pk_add_f32 v[120:121], v[232:233], v[252:253]
	v_pk_add_f32 v[124:125], v[226:227], v[246:247]
	v_pk_add_f32 v[126:127], v[234:235], v[254:255]
	v_pk_add_f32 v[110:111], v[74:75], v[108:109]
	v_pk_add_f32 v[116:117], v[112:113], v[114:115]
	v_pk_add_f32 v[122:123], v[118:119], v[120:121]
	v_pk_add_f32 v[128:129], v[124:125], v[126:127]
	v_pk_add_f32 v[130:131], v[110:111], v[122:123]
	v_pk_add_f32 v[132:133], v[116:117], v[128:129]
	v_pk_add_f32 v[110:111], v[110:111], v[122:123] neg_lo:[0,1] neg_hi:[0,1]
	v_pk_add_f32 v[116:117], v[116:117], v[128:129] neg_lo:[0,1] neg_hi:[0,1]
	v_pk_add_f32 v[134:135], v[130:131], v[132:133]
	v_pk_add_f32 v[122:123], v[110:111], v[116:117] op_sel:[0,1] op_sel_hi:[1,0]
	v_pk_add_f32 v[110:111], v[110:111], v[116:117] op_sel:[0,1] op_sel_hi:[1,0] neg_lo:[0,1] neg_hi:[0,1]
	v_mov_b32_e32 v116, v122
	v_pk_mov_b32 v[128:129], v[110:111], v[122:123] op_sel:[1,0]
	v_mov_b32_e32 v117, v111
	v_pk_mul_f32 v[128:129], v[50:51], v[128:129]
	v_pk_add_f32 v[220:221], v[220:221], v[236:237] neg_lo:[0,1] neg_hi:[0,1]
	v_pk_fma_f32 v[136:137], v[52:53], v[122:123], v[128:129]
	v_pk_fma_f32 v[116:117], v[52:53], v[116:117], v[128:129] neg_lo:[0,0,1] neg_hi:[0,0,1]
	v_pk_add_f32 v[228:229], v[228:229], v[248:249] neg_lo:[0,1] neg_hi:[0,1]
	v_mov_b32_e32 v137, v117
	v_pk_add_f32 v[116:117], v[130:131], v[132:133] neg_lo:[0,1] neg_hi:[0,1]
	v_pk_add_f32 v[236:237], v[220:221], v[228:229] op_sel:[0,1] op_sel_hi:[1,0]
	v_pk_mul_f32 v[128:129], v[58:59], v[116:117]
	v_pk_add_f32 v[220:221], v[220:221], v[228:229] op_sel:[0,1] op_sel_hi:[1,0] neg_lo:[0,1] neg_hi:[0,1]
	v_pk_fma_f32 v[130:131], v[56:57], v[116:117], v[128:129] op_sel:[0,0,1] op_sel_hi:[1,1,0] neg_lo:[0,0,1] neg_hi:[0,0,1]
	v_pk_fma_f32 v[116:117], v[56:57], v[116:117], v[128:129] op_sel:[0,0,1] op_sel_hi:[1,1,0]
	v_pk_mov_b32 v[248:249], v[220:221], v[236:237] op_sel:[1,0]
	v_mov_b32_e32 v131, v117
	v_mov_b32_e32 v117, v123
	v_pk_mov_b32 v[122:123], v[122:123], v[110:111] op_sel:[1,0]
	v_mov_b32_e32 v116, v110
	v_pk_mul_f32 v[122:123], v[62:63], v[122:123]
	v_mov_b32_e32 v228, v236
	v_pk_fma_f32 v[110:111], v[60:61], v[110:111], v[122:123] neg_lo:[0,0,1] neg_hi:[0,0,1]
	v_pk_fma_f32 v[116:117], v[60:61], v[116:117], v[122:123]
	v_mov_b32_e32 v229, v221
	v_mov_b32_e32 v111, v117
	v_pk_mul_f32 v[248:249], v[4:5], v[248:249]
	ds_write2st64_b64 v219, v[130:131], v[110:111] offset0:8 offset1:12
	v_pk_fma_f32 v[110:111], v[6:7], v[236:237], v[248:249]
	v_pk_fma_f32 v[228:229], v[6:7], v[228:229], v[248:249] neg_lo:[0,0,1] neg_hi:[0,0,1]
	v_pk_add_f32 v[222:223], v[222:223], v[238:239] neg_lo:[0,1] neg_hi:[0,1]
	v_mov_b32_e32 v111, v229
	v_pk_add_f32 v[228:229], v[230:231], v[250:251] neg_lo:[0,1] neg_hi:[0,1]
	v_pk_add_f32 v[224:225], v[224:225], v[244:245] neg_lo:[0,1] neg_hi:[0,1]
	v_pk_add_f32 v[230:231], v[222:223], v[228:229] op_sel:[0,1] op_sel_hi:[1,0]
	v_pk_add_f32 v[222:223], v[222:223], v[228:229] op_sel:[0,1] op_sel_hi:[1,0] neg_lo:[0,1] neg_hi:[0,1]
	v_mov_b32_e32 v228, v230
	v_pk_mov_b32 v[238:239], v[222:223], v[230:231] op_sel:[1,0]
	v_mov_b32_e32 v229, v223
	v_pk_mul_f32 v[238:239], v[14:15], v[238:239]
	v_pk_add_f32 v[226:227], v[226:227], v[246:247] neg_lo:[0,1] neg_hi:[0,1]
	v_pk_fma_f32 v[248:249], v[16:17], v[230:231], v[238:239]
	v_pk_fma_f32 v[228:229], v[16:17], v[228:229], v[238:239] neg_lo:[0,0,1] neg_hi:[0,0,1]
	v_pk_add_f32 v[74:75], v[74:75], v[108:109] neg_lo:[0,1] neg_hi:[0,1]
	v_mov_b32_e32 v249, v229
	v_pk_add_f32 v[228:229], v[232:233], v[252:253] neg_lo:[0,1] neg_hi:[0,1]
	v_add_u32_e32 v64, 0x2000, v64
	v_pk_add_f32 v[232:233], v[224:225], v[228:229] op_sel:[0,1] op_sel_hi:[1,0]
	v_pk_add_f32 v[224:225], v[224:225], v[228:229] op_sel:[0,1] op_sel_hi:[1,0] neg_lo:[0,1] neg_hi:[0,1]
	v_mov_b32_e32 v228, v232
	v_pk_mov_b32 v[238:239], v[224:225], v[232:233] op_sel:[1,0]
	v_mov_b32_e32 v229, v225
	v_pk_mul_f32 v[238:239], v[26:27], v[238:239]
	s_nop 0
	v_pk_fma_f32 v[244:245], v[28:29], v[232:233], v[238:239]
	v_pk_fma_f32 v[228:229], v[28:29], v[228:229], v[238:239] neg_lo:[0,0,1] neg_hi:[0,0,1]
	ds_write2st64_b64 v219, v[134:135], v[136:137] offset1:4
	v_mov_b32_e32 v245, v229
	v_pk_add_f32 v[228:229], v[234:235], v[254:255] neg_lo:[0,1] neg_hi:[0,1]
	s_nop 0
	v_pk_add_f32 v[234:235], v[226:227], v[228:229] op_sel:[0,1] op_sel_hi:[1,0]
	v_pk_add_f32 v[226:227], v[226:227], v[228:229] op_sel:[0,1] op_sel_hi:[1,0] neg_lo:[0,1] neg_hi:[0,1]
	v_mov_b32_e32 v228, v234
	v_pk_mov_b32 v[238:239], v[226:227], v[234:235] op_sel:[1,0]
	v_mov_b32_e32 v229, v227
	v_pk_mul_f32 v[238:239], v[38:39], v[238:239]
	s_nop 0
	v_pk_fma_f32 v[246:247], v[40:41], v[234:235], v[238:239]
	v_pk_fma_f32 v[228:229], v[40:41], v[228:229], v[238:239] neg_lo:[0,0,1] neg_hi:[0,0,1]
	s_nop 0
	v_mov_b32_e32 v247, v229
	v_pk_add_f32 v[228:229], v[110:111], v[244:245]
	v_pk_add_f32 v[238:239], v[248:249], v[246:247]
	v_pk_add_f32 v[244:245], v[110:111], v[244:245] neg_lo:[0,1] neg_hi:[0,1]
	v_pk_add_f32 v[246:247], v[248:249], v[246:247] neg_lo:[0,1] neg_hi:[0,1]
	v_pk_add_f32 v[250:251], v[228:229], v[238:239]
	v_pk_add_f32 v[248:249], v[244:245], v[246:247] op_sel:[0,1] op_sel_hi:[1,0]
	v_pk_add_f32 v[244:245], v[244:245], v[246:247] op_sel:[0,1] op_sel_hi:[1,0] neg_lo:[0,1] neg_hi:[0,1]
	v_mov_b32_e32 v246, v248
	v_pk_mov_b32 v[252:253], v[244:245], v[248:249] op_sel:[1,0]
; DI float2 twid(float r) { return float2{__builtin_amdgcn_cosf(r), -__builtin_amdgcn_sinf(r)}; }
; DI void bfly_fwd(float2 a0, float2 a1, float2 a2, float2 a3, float r, float2& o0, float2& o1, float2& o2, float2& o3) {
;   float2 t0 = {a0.x + a2.x, a0.y + a2.y}, t1 = {a0.x - a2.x, a0.y - a2.y}, t2 = {a1.x + a3.x, a1.y + a3.y}, t3 = {a1.x - a3.x, a1.y - a3.y};
;   float2 b0 = {t0.x + t2.x, t0.y + t2.y}, b2 = {t0.x - t2.x, t0.y - t2.y}, b1 = {t1.x + t3.y, t1.y - t3.x}, b3 = {t1.x - t3.y, t1.y + t3.x};
;   float2 w1 = twid(r), w2 = cmul(w1, w1), w3 = cmul(w2, w1);
;   o0 = b0; o1 = cmul(b1, w1); o2 = cmul(b2, w2); o3 = cmul(b3, w3);
; }
;     ...
;   for (int gg = tid; gg < NBT * (N / 16); gg += NTHR) { const int g = gg & (N / 16 - 1); float2* z = z0 + (gg / (N / 16)) * N; const int jp = g & (Q2 - 1), base = ((g >> lq2) << (lq2 + 4)) + jp; float2 x[4][4];
; #pragma unroll
;     for (int q1 = 0; q1 < 4; ++q1)
; #pragma unroll
;       for (int q2 = 0; q2 < 4; ++q2) x[q1][q2] = z[base + q1 * Q1 + q2 * Q2];
; #pragma unroll
;     for (int q2 = 0; q2 < 4; ++q2) bfly_fwd(x[0][q2], x[1][q2], x[2][q2], x[3][q2], (float)(jp + q2 * Q2) * invM1, x[0][q2], x[1][q2], x[2][q2], x[3][q2]);
; #pragma unroll
;     for (int q1 = 0; q1 < 4; ++q1) bfly_fwd(x[q1][0], x[q1][1], x[q1][2], x[q1][3], (float)jp * invM2, x[q1][0], x[q1][1], x[q1][2], x[q1][3]);
; #pragma unroll
;     for (int q1 = 0; q1 < 4; ++q1)
; #pragma unroll
;       for (int q2 = 0; q2 < 4; ++q2) z[base + q1 * Q1 + q2 * Q2] = x[q1][q2]; }
	v_mov_b32_e32 v247, v245
	v_pk_mul_f32 v[252:253], v[50:51], v[252:253]
	v_pk_add_f32 v[228:229], v[228:229], v[238:239] neg_lo:[0,1] neg_hi:[0,1]
	v_pk_fma_f32 v[254:255], v[52:53], v[248:249], v[252:253]
	v_pk_fma_f32 v[246:247], v[52:53], v[246:247], v[252:253] neg_lo:[0,0,1] neg_hi:[0,0,1]
	v_pk_mul_f32 v[238:239], v[58:59], v[228:229]
	v_mov_b32_e32 v255, v247
	v_pk_fma_f32 v[246:247], v[56:57], v[228:229], v[238:239] op_sel:[0,0,1] op_sel_hi:[1,1,0] neg_lo:[0,0,1] neg_hi:[0,0,1]
	v_pk_fma_f32 v[228:229], v[56:57], v[228:229], v[238:239] op_sel:[0,0,1] op_sel_hi:[1,1,0]
	v_pk_mov_b32 v[238:239], v[248:249], v[244:245] op_sel:[1,0]
	v_mov_b32_e32 v247, v229
	v_mov_b32_e32 v228, v244
	v_mov_b32_e32 v229, v249
	v_pk_mul_f32 v[238:239], v[62:63], v[238:239]
	ds_write2st64_b64 v219, v[250:251], v[254:255] offset0:16 offset1:20
	v_pk_fma_f32 v[244:245], v[60:61], v[244:245], v[238:239] neg_lo:[0,0,1] neg_hi:[0,0,1]
	v_pk_fma_f32 v[228:229], v[60:61], v[228:229], v[238:239]
	s_nop 0
	v_mov_b32_e32 v245, v229
	v_pk_mul_f32 v[228:229], v[10:11], v[74:75] op_sel:[0,1] op_sel_hi:[1,0]
	ds_write2st64_b64 v219, v[246:247], v[244:245] offset0:24 offset1:28
	v_pk_fma_f32 v[238:239], v[8:9], v[74:75], v[228:229] neg_lo:[0,0,1] neg_hi:[0,0,1]
	v_pk_fma_f32 v[74:75], v[8:9], v[74:75], v[228:229]
	s_nop 0
	v_mov_b32_e32 v239, v75
	v_pk_add_f32 v[74:75], v[112:113], v[114:115] neg_lo:[0,1] neg_hi:[0,1]
	s_nop 0
	v_pk_mul_f32 v[228:229], v[22:23], v[74:75] op_sel:[0,1] op_sel_hi:[1,0]
	s_nop 0
	v_pk_fma_f32 v[244:245], v[20:21], v[74:75], v[228:229] neg_lo:[0,0,1] neg_hi:[0,0,1]
	v_pk_fma_f32 v[74:75], v[20:21], v[74:75], v[228:229]
	s_nop 0
	v_mov_b32_e32 v245, v75
	v_pk_add_f32 v[74:75], v[118:119], v[120:121] neg_lo:[0,1] neg_hi:[0,1]
	s_nop 0
	v_pk_mul_f32 v[228:229], v[34:35], v[74:75] op_sel:[0,1] op_sel_hi:[1,0]
	s_nop 0
	v_pk_fma_f32 v[246:247], v[32:33], v[74:75], v[228:229] neg_lo:[0,0,1] neg_hi:[0,0,1]
	v_pk_fma_f32 v[74:75], v[32:33], v[74:75], v[228:229]
	s_nop 0
	v_mov_b32_e32 v247, v75
	v_pk_add_f32 v[74:75], v[124:125], v[126:127] neg_lo:[0,1] neg_hi:[0,1]
	s_nop 0
	v_pk_mul_f32 v[228:229], v[46:47], v[74:75] op_sel:[0,1] op_sel_hi:[1,0]
	s_nop 0
	v_pk_fma_f32 v[248:249], v[44:45], v[74:75], v[228:229] neg_lo:[0,0,1] neg_hi:[0,0,1]
	v_pk_fma_f32 v[74:75], v[44:45], v[74:75], v[228:229]
	s_nop 0
	v_mov_b32_e32 v249, v75
	v_pk_add_f32 v[74:75], v[238:239], v[246:247]
	v_pk_add_f32 v[228:229], v[244:245], v[248:249]
	v_pk_add_f32 v[238:239], v[238:239], v[246:247] neg_lo:[0,1] neg_hi:[0,1]
	v_pk_add_f32 v[244:245], v[244:245], v[248:249] neg_lo:[0,1] neg_hi:[0,1]
	v_pk_add_f32 v[250:251], v[74:75], v[228:229]
	v_pk_add_f32 v[246:247], v[238:239], v[244:245] op_sel:[0,1] op_sel_hi:[1,0]
	v_pk_add_f32 v[238:239], v[238:239], v[244:245] op_sel:[0,1] op_sel_hi:[1,0] neg_lo:[0,1] neg_hi:[0,1]
	v_mov_b32_e32 v244, v246
	v_pk_mov_b32 v[248:249], v[238:239], v[246:247] op_sel:[1,0]
	v_mov_b32_e32 v245, v239
	v_pk_mul_f32 v[248:249], v[50:51], v[248:249]
	v_pk_add_f32 v[74:75], v[74:75], v[228:229] neg_lo:[0,1] neg_hi:[0,1]
	v_pk_fma_f32 v[252:253], v[52:53], v[246:247], v[248:249]
	v_pk_fma_f32 v[244:245], v[52:53], v[244:245], v[248:249] neg_lo:[0,0,1] neg_hi:[0,0,1]
	v_pk_mul_f32 v[228:229], v[58:59], v[74:75]
	v_mov_b32_e32 v253, v245
	v_pk_fma_f32 v[244:245], v[56:57], v[74:75], v[228:229] op_sel:[0,0,1] op_sel_hi:[1,1,0] neg_lo:[0,0,1] neg_hi:[0,0,1]
	v_pk_fma_f32 v[74:75], v[56:57], v[74:75], v[228:229] op_sel:[0,0,1] op_sel_hi:[1,1,0]
	v_pk_mov_b32 v[228:229], v[246:247], v[238:239] op_sel:[1,0]
	v_mov_b32_e32 v245, v75
	v_mov_b32_e32 v74, v238
	v_mov_b32_e32 v75, v247
	v_pk_mul_f32 v[228:229], v[62:63], v[228:229]
	ds_write2st64_b64 v219, v[250:251], v[252:253] offset0:32 offset1:36
	v_pk_fma_f32 v[238:239], v[60:61], v[238:239], v[228:229] neg_lo:[0,0,1] neg_hi:[0,0,1]
	v_pk_fma_f32 v[74:75], v[60:61], v[74:75], v[228:229]
	v_pk_mov_b32 v[228:229], v[236:237], v[220:221] op_sel:[1,0]
	v_mov_b32_e32 v239, v75
	v_mov_b32_e32 v74, v220
	v_mov_b32_e32 v75, v237
	v_pk_mul_f32 v[228:229], v[18:19], v[228:229]
	ds_write2st64_b64 v219, v[244:245], v[238:239] offset0:40 offset1:44
	v_pk_fma_f32 v[220:221], v[12:13], v[220:221], v[228:229] neg_lo:[0,0,1] neg_hi:[0,0,1]
	v_pk_fma_f32 v[74:75], v[12:13], v[74:75], v[228:229]
	v_pk_mov_b32 v[228:229], v[230:231], v[222:223] op_sel:[1,0]
	v_mov_b32_e32 v221, v75
	v_mov_b32_e32 v74, v222
	v_mov_b32_e32 v75, v231
	v_pk_mul_f32 v[228:229], v[30:31], v[228:229]
	s_nop 0
	v_pk_fma_f32 v[222:223], v[24:25], v[222:223], v[228:229] neg_lo:[0,0,1] neg_hi:[0,0,1]
	v_pk_fma_f32 v[74:75], v[24:25], v[74:75], v[228:229]
	v_pk_mov_b32 v[228:229], v[232:233], v[224:225] op_sel:[1,0]
	v_mov_b32_e32 v223, v75
	v_mov_b32_e32 v74, v224
	v_mov_b32_e32 v75, v233
	v_pk_mul_f32 v[228:229], v[42:43], v[228:229]
	s_nop 0
	v_pk_fma_f32 v[224:225], v[36:37], v[224:225], v[228:229] neg_lo:[0,0,1] neg_hi:[0,0,1]
	v_pk_fma_f32 v[74:75], v[36:37], v[74:75], v[228:229]
	v_pk_mov_b32 v[228:229], v[234:235], v[226:227] op_sel:[1,0]
	v_mov_b32_e32 v225, v75
	v_mov_b32_e32 v74, v226
	v_mov_b32_e32 v75, v235
	v_pk_mul_f32 v[228:229], v[54:55], v[228:229]
	s_nop 0
	v_pk_fma_f32 v[226:227], v[48:49], v[226:227], v[228:229] neg_lo:[0,0,1] neg_hi:[0,0,1]
	v_pk_fma_f32 v[74:75], v[48:49], v[74:75], v[228:229]
	s_nop 0
	v_mov_b32_e32 v227, v75
	v_pk_add_f32 v[74:75], v[220:221], v[224:225]
	v_pk_add_f32 v[228:229], v[222:223], v[226:227]
	v_pk_add_f32 v[220:221], v[220:221], v[224:225] neg_lo:[0,1] neg_hi:[0,1]
	v_pk_add_f32 v[222:223], v[222:223], v[226:227] neg_lo:[0,1] neg_hi:[0,1]
	v_pk_add_f32 v[230:231], v[74:75], v[228:229]
; DI float2 twid(float r) { return float2{__builtin_amdgcn_cosf(r), -__builtin_amdgcn_sinf(r)}; }
; DI void bfly_fwd(float2 a0, float2 a1, float2 a2, float2 a3, float r, float2& o0, float2& o1, float2& o2, float2& o3) {
;   float2 t0 = {a0.x + a2.x, a0.y + a2.y}, t1 = {a0.x - a2.x, a0.y - a2.y}, t2 = {a1.x + a3.x, a1.y + a3.y}, t3 = {a1.x - a3.x, a1.y - a3.y};
;   float2 b0 = {t0.x + t2.x, t0.y + t2.y}, b2 = {t0.x - t2.x, t0.y - t2.y}, b1 = {t1.x + t3.y, t1.y - t3.x}, b3 = {t1.x - t3.y, t1.y + t3.x};
;   float2 w1 = twid(r), w2 = cmul(w1, w1), w3 = cmul(w2, w1);
;   o0 = b0; o1 = cmul(b1, w1); o2 = cmul(b2, w2); o3 = cmul(b3, w3);
; }
;     ...
;   for (int gg = tid; gg < NBT * (N / 16); gg += NTHR) { const int g = gg & (N / 16 - 1); float2* z = z0 + (gg / (N / 16)) * N; const int jp = g & (Q2 - 1), base = ((g >> lq2) << (lq2 + 4)) + jp; float2 x[4][4];
; #pragma unroll
;     for (int q1 = 0; q1 < 4; ++q1)
; #pragma unroll
;       for (int q2 = 0; q2 < 4; ++q2) x[q1][q2] = z[base + q1 * Q1 + q2 * Q2];
; #pragma unroll
;     for (int q2 = 0; q2 < 4; ++q2) bfly_fwd(x[0][q2], x[1][q2], x[2][q2], x[3][q2], (float)(jp + q2 * Q2) * invM1, x[0][q2], x[1][q2], x[2][q2], x[3][q2]);
; #pragma unroll
;     for (int q1 = 0; q1 < 4; ++q1) bfly_fwd(x[q1][0], x[q1][1], x[q1][2], x[q1][3], (float)jp * invM2, x[q1][0], x[q1][1], x[q1][2], x[q1][3]);
; #pragma unroll
;     for (int q1 = 0; q1 < 4; ++q1)
; #pragma unroll
;       for (int q2 = 0; q2 < 4; ++q2) z[base + q1 * Q1 + q2 * Q2] = x[q1][q2]; }
	v_pk_add_f32 v[224:225], v[220:221], v[222:223] op_sel:[0,1] op_sel_hi:[1,0]
	v_pk_add_f32 v[220:221], v[220:221], v[222:223] op_sel:[0,1] op_sel_hi:[1,0] neg_lo:[0,1] neg_hi:[0,1]
	v_mov_b32_e32 v222, v224
	v_pk_mov_b32 v[226:227], v[220:221], v[224:225] op_sel:[1,0]
	v_mov_b32_e32 v223, v221
	v_pk_mul_f32 v[226:227], v[50:51], v[226:227]
	s_nop 0
	v_pk_fma_f32 v[232:233], v[52:53], v[224:225], v[226:227]
	v_pk_fma_f32 v[222:223], v[52:53], v[222:223], v[226:227] neg_lo:[0,0,1] neg_hi:[0,0,1]
	s_nop 0
	v_mov_b32_e32 v233, v223
	v_pk_add_f32 v[222:223], v[74:75], v[228:229] neg_lo:[0,1] neg_hi:[0,1]
	ds_write2st64_b64 v219, v[230:231], v[232:233] offset0:48 offset1:52
	v_pk_mul_f32 v[226:227], v[58:59], v[222:223]
	s_nop 0
	v_pk_fma_f32 v[74:75], v[56:57], v[222:223], v[226:227] op_sel:[0,0,1] op_sel_hi:[1,1,0] neg_lo:[0,0,1] neg_hi:[0,0,1]
	v_pk_fma_f32 v[222:223], v[56:57], v[222:223], v[226:227] op_sel:[0,0,1] op_sel_hi:[1,1,0]
	s_nop 0
	v_mov_b32_e32 v75, v223
	v_mov_b32_e32 v223, v225
	v_pk_mov_b32 v[224:225], v[224:225], v[220:221] op_sel:[1,0]
	v_mov_b32_e32 v222, v220
	v_pk_mul_f32 v[224:225], v[62:63], v[224:225]
	s_nop 0
	v_pk_fma_f32 v[220:221], v[60:61], v[220:221], v[224:225] neg_lo:[0,0,1] neg_hi:[0,0,1]
	v_pk_fma_f32 v[222:223], v[60:61], v[222:223], v[224:225]
	s_nop 0
	v_mov_b32_e32 v221, v223
	ds_write2st64_b64 v219, v[74:75], v[220:221] offset0:56 offset1:60
	s_nop 0
	v_add_u32_e32 v66, 0x200, v65
	s_nop 0
	v_mov_b32_e32 v65, v66
.LBB0_1633:
	s_or_b64 exec, exec, s[0:1]
	v_and_b32_e32 v83, 15, v76
	v_cvt_f32_ubyte0_e32 v67, v83
	v_or_b32_e32 v66, 16, v83
	v_or_b32_e32 v65, 32, v83
	v_or_b32_e32 v64, 48, v83
	s_waitcnt lgkmcnt(0)
	s_barrier
	s_and_saveexec_b64 s[0:1], vcc
	s_cbranch_execz .LBB0_1636
	v_lshlrev_b32_e32 v68, 4, v76
	v_mov_b32_e32 v69, v76
	v_ashrrev_i32_e32 v70, 31, v69
	v_lshrrev_b32_e32 v70, 22, v70
	v_add_lshl_u32 v70, v69, v70, 7
	v_and_b32_e32 v70, 0xfffe0000, v70
	v_and_b32_e32 v71, 0x3f00, v68
	v_add_u32_e32 v70, 16, v70
	v_lshlrev_b32_e32 v71, 3, v71
	v_lshlrev_b32_e32 v72, 3, v83
	v_add3_u32 v142, v70, v71, v72
	ds_read2_b64 v[70:73], v142 offset1:16
	ds_read2_b64 v[84:87], v142 offset0:32 offset1:48
	ds_read2_b64 v[88:91], v142 offset0:64 offset1:80
	ds_read2_b64 v[92:95], v142 offset0:96 offset1:112
	ds_read2_b64 v[96:99], v142 offset0:128 offset1:144
	ds_read2_b64 v[100:103], v142 offset0:160 offset1:176
	ds_read2_b64 v[104:107], v142 offset0:192 offset1:208
	ds_read2_b64 v[108:111], v142 offset0:224 offset1:240
	v_add_u32_e32 v218, 0x200, v69
	v_add_u32_e32 v241, 0x2000, v68
	v_ashrrev_i32_e32 v252, 31, v218
	v_lshrrev_b32_e32 v252, 22, v252
	v_add_lshl_u32 v252, v218, v252, 7
	v_and_b32_e32 v252, 0xfffe0000, v252
	v_and_b32_e32 v253, 0x3f00, v241
	v_add_u32_e32 v252, 16, v252
	v_lshlrev_b32_e32 v253, 3, v253
	v_lshlrev_b32_e32 v254, 3, v83
	v_add3_u32 v219, v252, v253, v254
	ds_read2_b64 v[220:223], v219 offset1:16
	ds_read2_b64 v[224:227], v219 offset0:32 offset1:48
	ds_read2_b64 v[228:231], v219 offset0:64 offset1:80
	ds_read2_b64 v[232:235], v219 offset0:96 offset1:112
	ds_read2_b64 v[236:239], v219 offset0:128 offset1:144
	ds_read2_b64 v[244:247], v219 offset0:160 offset1:176
	ds_read2_b64 v[248:251], v219 offset0:192 offset1:208
	ds_read2_b64 v[252:255], v219 offset0:224 offset1:240
	v_mul_f32_e32 v5, 0x3b800000, v67
	v_sin_f32_e32 v4, v5
	v_cos_f32_e32 v6, v5
	s_mov_b64 s[14:15], 0
	v_mul_f32_e32 v5, v4, v4
	v_fma_f32 v8, v6, v6, -v5
	v_cvt_f32_ubyte0_e32 v5, v66
	v_mul_f32_e32 v5, 0x3b800000, v5
	v_sin_f32_e32 v14, v5
	v_cos_f32_e32 v16, v5
	v_mul_f32_e64 v7, v6, -v4
	v_add_f32_e32 v10, v7, v7
	v_mul_f32_e32 v5, v4, v8
	v_fma_f32 v18, v6, v10, -v5
	v_mul_f32_e32 v5, v14, v14
	v_fma_f32 v20, v16, v16, -v5
	v_mul_f32_e64 v5, v16, -v14
	v_add_f32_e32 v22, v5, v5
	v_cvt_f32_ubyte0_e32 v5, v65
	v_mul_f32_e32 v5, 0x3b800000, v5
	v_sin_f32_e32 v26, v5
	v_cos_f32_e32 v28, v5
	v_mul_f32_e32 v5, v14, v20
	v_fma_f32 v30, v16, v22, -v5
	v_mul_f32_e32 v5, v26, v26
	v_fma_f32 v32, v28, v28, -v5
	v_mul_f32_e64 v5, v28, -v26
	v_add_f32_e32 v34, v5, v5
	v_cvt_f32_ubyte0_e32 v5, v64
	v_mul_f32_e32 v5, 0x3b800000, v5
	v_sin_f32_e32 v38, v5
	v_cos_f32_e32 v40, v5
	v_mul_f32_e32 v5, v26, v32
	v_fma_f32 v42, v28, v34, -v5
	v_mul_f32_e32 v5, v38, v38
	v_fma_f32 v44, v40, v40, -v5
	v_mul_f32_e64 v5, v40, -v38
	v_add_f32_e32 v46, v5, v5
	v_mul_f32_e32 v5, 0x3c800000, v67
	v_sin_f32_e32 v50, v5
	v_cos_f32_e32 v52, v5
	v_mul_f32_e32 v5, v38, v44
	v_fma_f32 v54, v40, v46, -v5
	v_mul_f32_e32 v5, v50, v50
	v_fma_f32 v56, v52, v52, -v5
	v_mul_f32_e64 v5, v52, -v50
	v_add_f32_e32 v58, v5, v5
	v_mul_f32_e32 v12, v4, v10
	v_mul_f32_e32 v24, v14, v22
	v_mul_f32_e32 v36, v26, v34
	v_mul_f32_e32 v48, v38, v46
	v_mul_f32_e32 v60, v50, v58
	v_mul_f32_e32 v5, v50, v56
	v_fmac_f32_e32 v12, v6, v8
	v_fmac_f32_e32 v24, v16, v20
	v_fmac_f32_e32 v36, v28, v32
	v_fmac_f32_e32 v48, v40, v44
	v_fmac_f32_e32 v60, v52, v56
	v_fma_f32 v62, v52, v58, -v5
	v_mov_b32_e32 v53, v52
	v_mov_b32_e32 v51, v50
	v_mov_b32_e32 v57, v56
	v_mov_b32_e32 v59, v58
	v_mov_b32_e32 v61, v60
	v_mov_b32_e32 v63, v62
	v_mov_b32_e32 v7, v6
	v_mov_b32_e32 v5, v4
	v_mov_b32_e32 v29, v28
	v_mov_b32_e32 v27, v26
	v_mov_b32_e32 v17, v16
	v_mov_b32_e32 v15, v14
	v_mov_b32_e32 v41, v40
	v_mov_b32_e32 v39, v38
	v_mov_b32_e32 v9, v8
	v_mov_b32_e32 v33, v32
	v_mov_b32_e32 v21, v20
	v_mov_b32_e32 v45, v44
	v_mov_b32_e32 v13, v12
	v_mov_b32_e32 v19, v18
	v_mov_b32_e32 v37, v36
	v_mov_b32_e32 v43, v42
	v_mov_b32_e32 v25, v24
	v_mov_b32_e32 v31, v30
	v_mov_b32_e32 v49, v48
	v_mov_b32_e32 v55, v54
	v_mov_b32_e32 v11, v10
	v_mov_b32_e32 v23, v22
	v_mov_b32_e32 v35, v34
	v_mov_b32_e32 v47, v46
	s_nop 0
	s_waitcnt lgkmcnt(11)
; DI float2 twid(float r) { return float2{__builtin_amdgcn_cosf(r), -__builtin_amdgcn_sinf(r)}; }
; DI void bfly_fwd(float2 a0, float2 a1, float2 a2, float2 a3, float r, float2& o0, float2& o1, float2& o2, float2& o3) {
;   float2 t0 = {a0.x + a2.x, a0.y + a2.y}, t1 = {a0.x - a2.x, a0.y - a2.y}, t2 = {a1.x + a3.x, a1.y + a3.y}, t3 = {a1.x - a3.x, a1.y - a3.y};
;   float2 b0 = {t0.x + t2.x, t0.y + t2.y}, b2 = {t0.x - t2.x, t0.y - t2.y}, b1 = {t1.x + t3.y, t1.y - t3.x}, b3 = {t1.x - t3.y, t1.y + t3.x};
;   float2 w1 = twid(r), w2 = cmul(w1, w1), w3 = cmul(w2, w1);
;   o0 = b0; o1 = cmul(b1, w1); o2 = cmul(b2, w2); o3 = cmul(b3, w3);
; }
;     ...
;   for (int gg = tid; gg < NBT * (N / 16); gg += NTHR) { const int g = gg & (N / 16 - 1); float2* z = z0 + (gg / (N / 16)) * N; const int jp = g & (Q2 - 1), base = ((g >> lq2) << (lq2 + 4)) + jp; float2 x[4][4];
; #pragma unroll
;     for (int q1 = 0; q1 < 4; ++q1)
; #pragma unroll
;       for (int q2 = 0; q2 < 4; ++q2) x[q1][q2] = z[base + q1 * Q1 + q2 * Q2];
; #pragma unroll
;     for (int q2 = 0; q2 < 4; ++q2) bfly_fwd(x[0][q2], x[1][q2], x[2][q2], x[3][q2], (float)(jp + q2 * Q2) * invM1, x[0][q2], x[1][q2], x[2][q2], x[3][q2]);
; #pragma unroll
;     for (int q1 = 0; q1 < 4; ++q1) bfly_fwd(x[q1][0], x[q1][1], x[q1][2], x[q1][3], (float)jp * invM2, x[q1][0], x[q1][1], x[q1][2], x[q1][3]);
; #pragma unroll
;     for (int q1 = 0; q1 < 4; ++q1)
; #pragma unroll
;       for (int q2 = 0; q2 < 4; ++q2) z[base + q1 * Q1 + q2 * Q2] = x[q1][q2]; }
	v_pk_add_f32 v[74:75], v[70:71], v[96:97]
	v_pk_add_f32 v[116:117], v[72:73], v[98:99]
	s_waitcnt lgkmcnt(9)
	v_pk_add_f32 v[112:113], v[88:89], v[104:105]
	v_pk_add_f32 v[118:119], v[90:91], v[106:107]
	v_pk_add_f32 v[122:123], v[84:85], v[100:101]
	s_waitcnt lgkmcnt(8)
	v_pk_add_f32 v[124:125], v[92:93], v[108:109]
	v_pk_add_f32 v[128:129], v[86:87], v[102:103]
	v_pk_add_f32 v[130:131], v[94:95], v[110:111]
	v_pk_add_f32 v[114:115], v[74:75], v[112:113]
	v_pk_add_f32 v[120:121], v[116:117], v[118:119]
	v_pk_add_f32 v[126:127], v[122:123], v[124:125]
	v_pk_add_f32 v[132:133], v[128:129], v[130:131]
	v_pk_add_f32 v[134:135], v[114:115], v[126:127]
	v_pk_add_f32 v[136:137], v[120:121], v[132:133]
	v_pk_add_f32 v[114:115], v[114:115], v[126:127] neg_lo:[0,1] neg_hi:[0,1]
	v_pk_add_f32 v[120:121], v[120:121], v[132:133] neg_lo:[0,1] neg_hi:[0,1]
	v_pk_add_f32 v[138:139], v[134:135], v[136:137]
	v_pk_add_f32 v[126:127], v[114:115], v[120:121] op_sel:[0,1] op_sel_hi:[1,0]
	v_pk_add_f32 v[114:115], v[114:115], v[120:121] op_sel:[0,1] op_sel_hi:[1,0] neg_lo:[0,1] neg_hi:[0,1]
	v_mov_b32_e32 v120, v126
	v_pk_mov_b32 v[132:133], v[114:115], v[126:127] op_sel:[1,0]
	v_mov_b32_e32 v121, v115
	v_pk_mul_f32 v[132:133], v[50:51], v[132:133]
	v_pk_add_f32 v[70:71], v[70:71], v[96:97] neg_lo:[0,1] neg_hi:[0,1]
	v_pk_fma_f32 v[140:141], v[52:53], v[126:127], v[132:133]
	v_pk_fma_f32 v[120:121], v[52:53], v[120:121], v[132:133] neg_lo:[0,0,1] neg_hi:[0,0,1]
	v_pk_add_f32 v[88:89], v[88:89], v[104:105] neg_lo:[0,1] neg_hi:[0,1]
	v_mov_b32_e32 v141, v121
	v_pk_add_f32 v[120:121], v[134:135], v[136:137] neg_lo:[0,1] neg_hi:[0,1]
	v_pk_add_f32 v[96:97], v[70:71], v[88:89] op_sel:[0,1] op_sel_hi:[1,0]
	v_pk_mul_f32 v[132:133], v[58:59], v[120:121]
	v_pk_add_f32 v[70:71], v[70:71], v[88:89] op_sel:[0,1] op_sel_hi:[1,0] neg_lo:[0,1] neg_hi:[0,1]
	v_pk_fma_f32 v[134:135], v[56:57], v[120:121], v[132:133] op_sel:[0,0,1] op_sel_hi:[1,1,0] neg_lo:[0,0,1] neg_hi:[0,0,1]
	v_pk_fma_f32 v[120:121], v[56:57], v[120:121], v[132:133] op_sel:[0,0,1] op_sel_hi:[1,1,0]
	v_pk_mov_b32 v[104:105], v[70:71], v[96:97] op_sel:[1,0]
	v_mov_b32_e32 v135, v121
	v_mov_b32_e32 v121, v127
	v_pk_mov_b32 v[126:127], v[126:127], v[114:115] op_sel:[1,0]
	v_mov_b32_e32 v120, v114
	v_pk_mul_f32 v[126:127], v[62:63], v[126:127]
	v_mov_b32_e32 v88, v96
	v_pk_fma_f32 v[114:115], v[60:61], v[114:115], v[126:127] neg_lo:[0,0,1] neg_hi:[0,0,1]
	v_pk_fma_f32 v[120:121], v[60:61], v[120:121], v[126:127]
	v_mov_b32_e32 v89, v71
	v_mov_b32_e32 v115, v121
	v_pk_mul_f32 v[104:105], v[4:5], v[104:105]
	ds_write2_b64 v142, v[134:135], v[114:115] offset0:32 offset1:48
	v_pk_fma_f32 v[114:115], v[6:7], v[96:97], v[104:105]
	v_pk_fma_f32 v[88:89], v[6:7], v[88:89], v[104:105] neg_lo:[0,0,1] neg_hi:[0,0,1]
	v_pk_add_f32 v[72:73], v[72:73], v[98:99] neg_lo:[0,1] neg_hi:[0,1]
	v_mov_b32_e32 v115, v89
	v_pk_add_f32 v[88:89], v[90:91], v[106:107] neg_lo:[0,1] neg_hi:[0,1]
	v_pk_add_f32 v[84:85], v[84:85], v[100:101] neg_lo:[0,1] neg_hi:[0,1]
	v_pk_add_f32 v[90:91], v[72:73], v[88:89] op_sel:[0,1] op_sel_hi:[1,0]
	v_pk_add_f32 v[72:73], v[72:73], v[88:89] op_sel:[0,1] op_sel_hi:[1,0] neg_lo:[0,1] neg_hi:[0,1]
	v_mov_b32_e32 v88, v90
	v_pk_mov_b32 v[98:99], v[72:73], v[90:91] op_sel:[1,0]
	v_mov_b32_e32 v89, v73
	v_pk_mul_f32 v[98:99], v[14:15], v[98:99]
	v_pk_add_f32 v[86:87], v[86:87], v[102:103] neg_lo:[0,1] neg_hi:[0,1]
	v_pk_fma_f32 v[104:105], v[16:17], v[90:91], v[98:99]
	v_pk_fma_f32 v[88:89], v[16:17], v[88:89], v[98:99] neg_lo:[0,0,1] neg_hi:[0,0,1]
	v_pk_add_f32 v[74:75], v[74:75], v[112:113] neg_lo:[0,1] neg_hi:[0,1]
	v_mov_b32_e32 v105, v89
	v_pk_add_f32 v[88:89], v[92:93], v[108:109] neg_lo:[0,1] neg_hi:[0,1]
	v_add_u32_e32 v68, 0x2000, v68
	v_pk_add_f32 v[92:93], v[84:85], v[88:89] op_sel:[0,1] op_sel_hi:[1,0]
	v_pk_add_f32 v[84:85], v[84:85], v[88:89] op_sel:[0,1] op_sel_hi:[1,0] neg_lo:[0,1] neg_hi:[0,1]
	v_mov_b32_e32 v88, v92
	v_pk_mov_b32 v[98:99], v[84:85], v[92:93] op_sel:[1,0]
	v_mov_b32_e32 v89, v85
	v_pk_mul_f32 v[98:99], v[26:27], v[98:99]
	s_nop 0
	v_pk_fma_f32 v[100:101], v[28:29], v[92:93], v[98:99]
	v_pk_fma_f32 v[88:89], v[28:29], v[88:89], v[98:99] neg_lo:[0,0,1] neg_hi:[0,0,1]
	ds_write2_b64 v142, v[138:139], v[140:141] offset1:16
	v_mov_b32_e32 v101, v89
	v_pk_add_f32 v[88:89], v[94:95], v[110:111] neg_lo:[0,1] neg_hi:[0,1]
	s_nop 0
	v_pk_add_f32 v[94:95], v[86:87], v[88:89] op_sel:[0,1] op_sel_hi:[1,0]
	v_pk_add_f32 v[86:87], v[86:87], v[88:89] op_sel:[0,1] op_sel_hi:[1,0] neg_lo:[0,1] neg_hi:[0,1]
	v_mov_b32_e32 v88, v94
	v_pk_mov_b32 v[98:99], v[86:87], v[94:95] op_sel:[1,0]
	v_mov_b32_e32 v89, v87
	v_pk_mul_f32 v[98:99], v[38:39], v[98:99]
	s_nop 0
	v_pk_fma_f32 v[102:103], v[40:41], v[94:95], v[98:99]
	v_pk_fma_f32 v[88:89], v[40:41], v[88:89], v[98:99] neg_lo:[0,0,1] neg_hi:[0,0,1]
	s_nop 0
	v_mov_b32_e32 v103, v89
	v_pk_add_f32 v[88:89], v[114:115], v[100:101]
	v_pk_add_f32 v[98:99], v[104:105], v[102:103]
	v_pk_add_f32 v[100:101], v[114:115], v[100:101] neg_lo:[0,1] neg_hi:[0,1]
	v_pk_add_f32 v[102:103], v[104:105], v[102:103] neg_lo:[0,1] neg_hi:[0,1]
	v_pk_add_f32 v[106:107], v[88:89], v[98:99]
	v_pk_add_f32 v[104:105], v[100:101], v[102:103] op_sel:[0,1] op_sel_hi:[1,0]
	v_pk_add_f32 v[100:101], v[100:101], v[102:103] op_sel:[0,1] op_sel_hi:[1,0] neg_lo:[0,1] neg_hi:[0,1]
	v_mov_b32_e32 v102, v104
	v_pk_mov_b32 v[108:109], v[100:101], v[104:105] op_sel:[1,0]
	v_mov_b32_e32 v103, v101
	v_pk_mul_f32 v[108:109], v[50:51], v[108:109]
	v_pk_add_f32 v[88:89], v[88:89], v[98:99] neg_lo:[0,1] neg_hi:[0,1]
	v_pk_fma_f32 v[110:111], v[52:53], v[104:105], v[108:109]
; DI float2 twid(float r) { return float2{__builtin_amdgcn_cosf(r), -__builtin_amdgcn_sinf(r)}; }
; DI void bfly_fwd(float2 a0, float2 a1, float2 a2, float2 a3, float r, float2& o0, float2& o1, float2& o2, float2& o3) {
;   float2 t0 = {a0.x + a2.x, a0.y + a2.y}, t1 = {a0.x - a2.x, a0.y - a2.y}, t2 = {a1.x + a3.x, a1.y + a3.y}, t3 = {a1.x - a3.x, a1.y - a3.y};
;   float2 b0 = {t0.x + t2.x, t0.y + t2.y}, b2 = {t0.x - t2.x, t0.y - t2.y}, b1 = {t1.x + t3.y, t1.y - t3.x}, b3 = {t1.x - t3.y, t1.y + t3.x};
;   float2 w1 = twid(r), w2 = cmul(w1, w1), w3 = cmul(w2, w1);
;   o0 = b0; o1 = cmul(b1, w1); o2 = cmul(b2, w2); o3 = cmul(b3, w3);
; }
;     ...
;   for (int gg = tid; gg < NBT * (N / 16); gg += NTHR) { const int g = gg & (N / 16 - 1); float2* z = z0 + (gg / (N / 16)) * N; const int jp = g & (Q2 - 1), base = ((g >> lq2) << (lq2 + 4)) + jp; float2 x[4][4];
; #pragma unroll
;     for (int q1 = 0; q1 < 4; ++q1)
; #pragma unroll
;       for (int q2 = 0; q2 < 4; ++q2) x[q1][q2] = z[base + q1 * Q1 + q2 * Q2];
; #pragma unroll
;     for (int q2 = 0; q2 < 4; ++q2) bfly_fwd(x[0][q2], x[1][q2], x[2][q2], x[3][q2], (float)(jp + q2 * Q2) * invM1, x[0][q2], x[1][q2], x[2][q2], x[3][q2]);
; #pragma unroll
;     for (int q1 = 0; q1 < 4; ++q1) bfly_fwd(x[q1][0], x[q1][1], x[q1][2], x[q1][3], (float)jp * invM2, x[q1][0], x[q1][1], x[q1][2], x[q1][3]);
; #pragma unroll
;     for (int q1 = 0; q1 < 4; ++q1)
; #pragma unroll
;       for (int q2 = 0; q2 < 4; ++q2) z[base + q1 * Q1 + q2 * Q2] = x[q1][q2]; }
	v_pk_fma_f32 v[102:103], v[52:53], v[102:103], v[108:109] neg_lo:[0,0,1] neg_hi:[0,0,1]
	v_pk_mul_f32 v[98:99], v[58:59], v[88:89]
	v_mov_b32_e32 v111, v103
	v_pk_fma_f32 v[102:103], v[56:57], v[88:89], v[98:99] op_sel:[0,0,1] op_sel_hi:[1,1,0] neg_lo:[0,0,1] neg_hi:[0,0,1]
	v_pk_fma_f32 v[88:89], v[56:57], v[88:89], v[98:99] op_sel:[0,0,1] op_sel_hi:[1,1,0]
	v_pk_mov_b32 v[98:99], v[104:105], v[100:101] op_sel:[1,0]
	v_mov_b32_e32 v103, v89
	v_mov_b32_e32 v88, v100
	v_mov_b32_e32 v89, v105
	v_pk_mul_f32 v[98:99], v[62:63], v[98:99]
	ds_write2_b64 v142, v[106:107], v[110:111] offset0:64 offset1:80
	v_pk_fma_f32 v[100:101], v[60:61], v[100:101], v[98:99] neg_lo:[0,0,1] neg_hi:[0,0,1]
	v_pk_fma_f32 v[88:89], v[60:61], v[88:89], v[98:99]
	s_nop 0
	v_mov_b32_e32 v101, v89
	v_pk_mul_f32 v[88:89], v[10:11], v[74:75] op_sel:[0,1] op_sel_hi:[1,0]
	ds_write2_b64 v142, v[102:103], v[100:101] offset0:96 offset1:112
	v_pk_fma_f32 v[98:99], v[8:9], v[74:75], v[88:89] neg_lo:[0,0,1] neg_hi:[0,0,1]
	v_pk_fma_f32 v[74:75], v[8:9], v[74:75], v[88:89]
	s_nop 0
	v_mov_b32_e32 v99, v75
	v_pk_add_f32 v[74:75], v[116:117], v[118:119] neg_lo:[0,1] neg_hi:[0,1]
	s_nop 0
	v_pk_mul_f32 v[88:89], v[22:23], v[74:75] op_sel:[0,1] op_sel_hi:[1,0]
	s_nop 0
	v_pk_fma_f32 v[100:101], v[20:21], v[74:75], v[88:89] neg_lo:[0,0,1] neg_hi:[0,0,1]
	v_pk_fma_f32 v[74:75], v[20:21], v[74:75], v[88:89]
	s_nop 0
	v_mov_b32_e32 v101, v75
	v_pk_add_f32 v[74:75], v[122:123], v[124:125] neg_lo:[0,1] neg_hi:[0,1]
	s_nop 0
	v_pk_mul_f32 v[88:89], v[34:35], v[74:75] op_sel:[0,1] op_sel_hi:[1,0]
	s_nop 0
	v_pk_fma_f32 v[102:103], v[32:33], v[74:75], v[88:89] neg_lo:[0,0,1] neg_hi:[0,0,1]
	v_pk_fma_f32 v[74:75], v[32:33], v[74:75], v[88:89]
	s_nop 0
	v_mov_b32_e32 v103, v75
	v_pk_add_f32 v[74:75], v[128:129], v[130:131] neg_lo:[0,1] neg_hi:[0,1]
	s_nop 0
	v_pk_mul_f32 v[88:89], v[46:47], v[74:75] op_sel:[0,1] op_sel_hi:[1,0]
	s_nop 0
	v_pk_fma_f32 v[104:105], v[44:45], v[74:75], v[88:89] neg_lo:[0,0,1] neg_hi:[0,0,1]
	v_pk_fma_f32 v[74:75], v[44:45], v[74:75], v[88:89]
	s_nop 0
	v_mov_b32_e32 v105, v75
	v_pk_add_f32 v[74:75], v[98:99], v[102:103]
	v_pk_add_f32 v[88:89], v[100:101], v[104:105]
	v_pk_add_f32 v[98:99], v[98:99], v[102:103] neg_lo:[0,1] neg_hi:[0,1]
	v_pk_add_f32 v[100:101], v[100:101], v[104:105] neg_lo:[0,1] neg_hi:[0,1]
	v_pk_add_f32 v[106:107], v[74:75], v[88:89]
	v_pk_add_f32 v[102:103], v[98:99], v[100:101] op_sel:[0,1] op_sel_hi:[1,0]
	v_pk_add_f32 v[98:99], v[98:99], v[100:101] op_sel:[0,1] op_sel_hi:[1,0] neg_lo:[0,1] neg_hi:[0,1]
	v_mov_b32_e32 v100, v102
	v_pk_mov_b32 v[104:105], v[98:99], v[102:103] op_sel:[1,0]
	v_mov_b32_e32 v101, v99
	v_pk_mul_f32 v[104:105], v[50:51], v[104:105]
	v_pk_add_f32 v[74:75], v[74:75], v[88:89] neg_lo:[0,1] neg_hi:[0,1]
	v_pk_fma_f32 v[108:109], v[52:53], v[102:103], v[104:105]
	v_pk_fma_f32 v[100:101], v[52:53], v[100:101], v[104:105] neg_lo:[0,0,1] neg_hi:[0,0,1]
	v_pk_mul_f32 v[88:89], v[58:59], v[74:75]
	v_mov_b32_e32 v109, v101
	v_pk_fma_f32 v[100:101], v[56:57], v[74:75], v[88:89] op_sel:[0,0,1] op_sel_hi:[1,1,0] neg_lo:[0,0,1] neg_hi:[0,0,1]
	v_pk_fma_f32 v[74:75], v[56:57], v[74:75], v[88:89] op_sel:[0,0,1] op_sel_hi:[1,1,0]
	v_pk_mov_b32 v[88:89], v[102:103], v[98:99] op_sel:[1,0]
	v_mov_b32_e32 v101, v75
	v_mov_b32_e32 v74, v98
	v_mov_b32_e32 v75, v103
	v_pk_mul_f32 v[88:89], v[62:63], v[88:89]
	ds_write2_b64 v142, v[106:107], v[108:109] offset0:128 offset1:144
	v_pk_fma_f32 v[98:99], v[60:61], v[98:99], v[88:89] neg_lo:[0,0,1] neg_hi:[0,0,1]
	v_pk_fma_f32 v[74:75], v[60:61], v[74:75], v[88:89]
	v_pk_mov_b32 v[88:89], v[96:97], v[70:71] op_sel:[1,0]
	v_mov_b32_e32 v99, v75
	v_mov_b32_e32 v74, v70
	v_mov_b32_e32 v75, v97
	v_pk_mul_f32 v[88:89], v[18:19], v[88:89]
	ds_write2_b64 v142, v[100:101], v[98:99] offset0:160 offset1:176
	v_pk_fma_f32 v[70:71], v[12:13], v[70:71], v[88:89] neg_lo:[0,0,1] neg_hi:[0,0,1]
	v_pk_fma_f32 v[74:75], v[12:13], v[74:75], v[88:89]
	v_pk_mov_b32 v[88:89], v[90:91], v[72:73] op_sel:[1,0]
	v_mov_b32_e32 v71, v75
	v_mov_b32_e32 v74, v72
	v_mov_b32_e32 v75, v91
	v_pk_mul_f32 v[88:89], v[30:31], v[88:89]
	s_nop 0
	v_pk_fma_f32 v[72:73], v[24:25], v[72:73], v[88:89] neg_lo:[0,0,1] neg_hi:[0,0,1]
	v_pk_fma_f32 v[74:75], v[24:25], v[74:75], v[88:89]
	v_pk_mov_b32 v[88:89], v[92:93], v[84:85] op_sel:[1,0]
	v_mov_b32_e32 v73, v75
	v_mov_b32_e32 v74, v84
	v_mov_b32_e32 v75, v93
	v_pk_mul_f32 v[88:89], v[42:43], v[88:89]
	s_nop 0
	v_pk_fma_f32 v[84:85], v[36:37], v[84:85], v[88:89] neg_lo:[0,0,1] neg_hi:[0,0,1]
	v_pk_fma_f32 v[74:75], v[36:37], v[74:75], v[88:89]
	v_pk_mov_b32 v[88:89], v[94:95], v[86:87] op_sel:[1,0]
	v_mov_b32_e32 v85, v75
	v_mov_b32_e32 v74, v86
	v_mov_b32_e32 v75, v95
	v_pk_mul_f32 v[88:89], v[54:55], v[88:89]
	s_nop 0
	v_pk_fma_f32 v[86:87], v[48:49], v[86:87], v[88:89] neg_lo:[0,0,1] neg_hi:[0,0,1]
	v_pk_fma_f32 v[74:75], v[48:49], v[74:75], v[88:89]
	s_nop 0
	v_mov_b32_e32 v87, v75
	v_pk_add_f32 v[74:75], v[70:71], v[84:85]
	v_pk_add_f32 v[88:89], v[72:73], v[86:87]
	v_pk_add_f32 v[70:71], v[70:71], v[84:85] neg_lo:[0,1] neg_hi:[0,1]
	v_pk_add_f32 v[72:73], v[72:73], v[86:87] neg_lo:[0,1] neg_hi:[0,1]
	v_pk_add_f32 v[90:91], v[74:75], v[88:89]
	v_pk_add_f32 v[84:85], v[70:71], v[72:73] op_sel:[0,1] op_sel_hi:[1,0]
	v_pk_add_f32 v[70:71], v[70:71], v[72:73] op_sel:[0,1] op_sel_hi:[1,0] neg_lo:[0,1] neg_hi:[0,1]
	v_mov_b32_e32 v72, v84
	v_pk_mov_b32 v[86:87], v[70:71], v[84:85] op_sel:[1,0]
	v_mov_b32_e32 v73, v71
	v_pk_mul_f32 v[86:87], v[50:51], v[86:87]
	s_nop 0
	v_pk_fma_f32 v[92:93], v[52:53], v[84:85], v[86:87]
	v_pk_fma_f32 v[72:73], v[52:53], v[72:73], v[86:87] neg_lo:[0,0,1] neg_hi:[0,0,1]
	s_nop 0
	v_mov_b32_e32 v93, v73
	v_pk_add_f32 v[72:73], v[74:75], v[88:89] neg_lo:[0,1] neg_hi:[0,1]
	ds_write2_b64 v142, v[90:91], v[92:93] offset0:192 offset1:208
	v_pk_mul_f32 v[74:75], v[58:59], v[72:73]
	s_nop 0
	v_pk_fma_f32 v[86:87], v[56:57], v[72:73], v[74:75] op_sel:[0,0,1] op_sel_hi:[1,1,0] neg_lo:[0,0,1] neg_hi:[0,0,1]
	v_pk_fma_f32 v[72:73], v[56:57], v[72:73], v[74:75] op_sel:[0,0,1] op_sel_hi:[1,1,0]
	v_pk_mov_b32 v[74:75], v[84:85], v[70:71] op_sel:[1,0]
	v_mov_b32_e32 v87, v73
	v_mov_b32_e32 v72, v70
	v_mov_b32_e32 v73, v85
	v_pk_mul_f32 v[74:75], v[62:63], v[74:75]
	s_nop 0
	v_pk_fma_f32 v[70:71], v[60:61], v[70:71], v[74:75] neg_lo:[0,0,1] neg_hi:[0,0,1]
	v_pk_fma_f32 v[72:73], v[60:61], v[72:73], v[74:75]
	s_nop 0
	v_mov_b32_e32 v71, v73
	ds_write2_b64 v142, v[86:87], v[70:71] offset0:224 offset1:240
	s_nop 0
	v_add_u32_e32 v69, 0x200, v69
	s_nop 0
	s_waitcnt lgkmcnt(11)
; DI float2 twid(float r) { return float2{__builtin_amdgcn_cosf(r), -__builtin_amdgcn_sinf(r)}; }
; DI void bfly_fwd(float2 a0, float2 a1, float2 a2, float2 a3, float r, float2& o0, float2& o1, float2& o2, float2& o3) {
;   float2 t0 = {a0.x + a2.x, a0.y + a2.y}, t1 = {a0.x - a2.x, a0.y - a2.y}, t2 = {a1.x + a3.x, a1.y + a3.y}, t3 = {a1.x - a3.x, a1.y - a3.y};
;   float2 b0 = {t0.x + t2.x, t0.y + t2.y}, b2 = {t0.x - t2.x, t0.y - t2.y}, b1 = {t1.x + t3.y, t1.y - t3.x}, b3 = {t1.x - t3.y, t1.y + t3.x};
;   float2 w1 = twid(r), w2 = cmul(w1, w1), w3 = cmul(w2, w1);
;   o0 = b0; o1 = cmul(b1, w1); o2 = cmul(b2, w2); o3 = cmul(b3, w3);
; }
;     ...
;   for (int gg = tid; gg < NBT * (N / 16); gg += NTHR) { const int g = gg & (N / 16 - 1); float2* z = z0 + (gg / (N / 16)) * N; const int jp = g & (Q2 - 1), base = ((g >> lq2) << (lq2 + 4)) + jp; float2 x[4][4];
; #pragma unroll
;     for (int q1 = 0; q1 < 4; ++q1)
; #pragma unroll
;       for (int q2 = 0; q2 < 4; ++q2) x[q1][q2] = z[base + q1 * Q1 + q2 * Q2];
; #pragma unroll
;     for (int q2 = 0; q2 < 4; ++q2) bfly_fwd(x[0][q2], x[1][q2], x[2][q2], x[3][q2], (float)(jp + q2 * Q2) * invM1, x[0][q2], x[1][q2], x[2][q2], x[3][q2]);
; #pragma unroll
;     for (int q1 = 0; q1 < 4; ++q1) bfly_fwd(x[q1][0], x[q1][1], x[q1][2], x[q1][3], (float)jp * invM2, x[q1][0], x[q1][1], x[q1][2], x[q1][3]);
; #pragma unroll
;     for (int q1 = 0; q1 < 4; ++q1)
; #pragma unroll
;       for (int q2 = 0; q2 < 4; ++q2) z[base + q1 * Q1 + q2 * Q2] = x[q1][q2]; }
	v_pk_add_f32 v[74:75], v[220:221], v[236:237]
	v_pk_add_f32 v[116:117], v[222:223], v[238:239]
	s_waitcnt lgkmcnt(9)
	v_pk_add_f32 v[112:113], v[228:229], v[248:249]
	v_pk_add_f32 v[118:119], v[230:231], v[250:251]
	v_pk_add_f32 v[122:123], v[224:225], v[244:245]
	s_waitcnt lgkmcnt(8)
	v_pk_add_f32 v[124:125], v[232:233], v[252:253]
	v_pk_add_f32 v[128:129], v[226:227], v[246:247]
	v_pk_add_f32 v[130:131], v[234:235], v[254:255]
	v_pk_add_f32 v[114:115], v[74:75], v[112:113]
	v_pk_add_f32 v[120:121], v[116:117], v[118:119]
	v_pk_add_f32 v[126:127], v[122:123], v[124:125]
	v_pk_add_f32 v[132:133], v[128:129], v[130:131]
	v_pk_add_f32 v[134:135], v[114:115], v[126:127]
	v_pk_add_f32 v[136:137], v[120:121], v[132:133]
	v_pk_add_f32 v[114:115], v[114:115], v[126:127] neg_lo:[0,1] neg_hi:[0,1]
	v_pk_add_f32 v[120:121], v[120:121], v[132:133] neg_lo:[0,1] neg_hi:[0,1]
	v_pk_add_f32 v[138:139], v[134:135], v[136:137]
	v_pk_add_f32 v[126:127], v[114:115], v[120:121] op_sel:[0,1] op_sel_hi:[1,0]
	v_pk_add_f32 v[114:115], v[114:115], v[120:121] op_sel:[0,1] op_sel_hi:[1,0] neg_lo:[0,1] neg_hi:[0,1]
	v_mov_b32_e32 v120, v126
	v_pk_mov_b32 v[132:133], v[114:115], v[126:127] op_sel:[1,0]
	v_mov_b32_e32 v121, v115
	v_pk_mul_f32 v[132:133], v[50:51], v[132:133]
	v_pk_add_f32 v[220:221], v[220:221], v[236:237] neg_lo:[0,1] neg_hi:[0,1]
	v_pk_fma_f32 v[140:141], v[52:53], v[126:127], v[132:133]
	v_pk_fma_f32 v[120:121], v[52:53], v[120:121], v[132:133] neg_lo:[0,0,1] neg_hi:[0,0,1]
	v_pk_add_f32 v[228:229], v[228:229], v[248:249] neg_lo:[0,1] neg_hi:[0,1]
	v_mov_b32_e32 v141, v121
	v_pk_add_f32 v[120:121], v[134:135], v[136:137] neg_lo:[0,1] neg_hi:[0,1]
	v_pk_add_f32 v[236:237], v[220:221], v[228:229] op_sel:[0,1] op_sel_hi:[1,0]
	v_pk_mul_f32 v[132:133], v[58:59], v[120:121]
	v_pk_add_f32 v[220:221], v[220:221], v[228:229] op_sel:[0,1] op_sel_hi:[1,0] neg_lo:[0,1] neg_hi:[0,1]
	v_pk_fma_f32 v[134:135], v[56:57], v[120:121], v[132:133] op_sel:[0,0,1] op_sel_hi:[1,1,0] neg_lo:[0,0,1] neg_hi:[0,0,1]
	v_pk_fma_f32 v[120:121], v[56:57], v[120:121], v[132:133] op_sel:[0,0,1] op_sel_hi:[1,1,0]
	v_pk_mov_b32 v[248:249], v[220:221], v[236:237] op_sel:[1,0]
	v_mov_b32_e32 v135, v121
	v_mov_b32_e32 v121, v127
	v_pk_mov_b32 v[126:127], v[126:127], v[114:115] op_sel:[1,0]
	v_mov_b32_e32 v120, v114
	v_pk_mul_f32 v[126:127], v[62:63], v[126:127]
	v_mov_b32_e32 v228, v236
	v_pk_fma_f32 v[114:115], v[60:61], v[114:115], v[126:127] neg_lo:[0,0,1] neg_hi:[0,0,1]
	v_pk_fma_f32 v[120:121], v[60:61], v[120:121], v[126:127]
	v_mov_b32_e32 v229, v221
	v_mov_b32_e32 v115, v121
	v_pk_mul_f32 v[248:249], v[4:5], v[248:249]
	ds_write2_b64 v219, v[134:135], v[114:115] offset0:32 offset1:48
	v_pk_fma_f32 v[114:115], v[6:7], v[236:237], v[248:249]
	v_pk_fma_f32 v[228:229], v[6:7], v[228:229], v[248:249] neg_lo:[0,0,1] neg_hi:[0,0,1]
	v_pk_add_f32 v[222:223], v[222:223], v[238:239] neg_lo:[0,1] neg_hi:[0,1]
	v_mov_b32_e32 v115, v229
	v_pk_add_f32 v[228:229], v[230:231], v[250:251] neg_lo:[0,1] neg_hi:[0,1]
	v_pk_add_f32 v[224:225], v[224:225], v[244:245] neg_lo:[0,1] neg_hi:[0,1]
	v_pk_add_f32 v[230:231], v[222:223], v[228:229] op_sel:[0,1] op_sel_hi:[1,0]
	v_pk_add_f32 v[222:223], v[222:223], v[228:229] op_sel:[0,1] op_sel_hi:[1,0] neg_lo:[0,1] neg_hi:[0,1]
	v_mov_b32_e32 v228, v230
	v_pk_mov_b32 v[238:239], v[222:223], v[230:231] op_sel:[1,0]
	v_mov_b32_e32 v229, v223
	v_pk_mul_f32 v[238:239], v[14:15], v[238:239]
	v_pk_add_f32 v[226:227], v[226:227], v[246:247] neg_lo:[0,1] neg_hi:[0,1]
	v_pk_fma_f32 v[248:249], v[16:17], v[230:231], v[238:239]
	v_pk_fma_f32 v[228:229], v[16:17], v[228:229], v[238:239] neg_lo:[0,0,1] neg_hi:[0,0,1]
	v_pk_add_f32 v[74:75], v[74:75], v[112:113] neg_lo:[0,1] neg_hi:[0,1]
	v_mov_b32_e32 v249, v229
	v_pk_add_f32 v[228:229], v[232:233], v[252:253] neg_lo:[0,1] neg_hi:[0,1]
	v_add_u32_e32 v68, 0x2000, v68
	v_pk_add_f32 v[232:233], v[224:225], v[228:229] op_sel:[0,1] op_sel_hi:[1,0]
	v_pk_add_f32 v[224:225], v[224:225], v[228:229] op_sel:[0,1] op_sel_hi:[1,0] neg_lo:[0,1] neg_hi:[0,1]
	v_mov_b32_e32 v228, v232
	v_pk_mov_b32 v[238:239], v[224:225], v[232:233] op_sel:[1,0]
	v_mov_b32_e32 v229, v225
	v_pk_mul_f32 v[238:239], v[26:27], v[238:239]
	s_nop 0
	v_pk_fma_f32 v[244:245], v[28:29], v[232:233], v[238:239]
	v_pk_fma_f32 v[228:229], v[28:29], v[228:229], v[238:239] neg_lo:[0,0,1] neg_hi:[0,0,1]
	ds_write2_b64 v219, v[138:139], v[140:141] offset1:16
	v_mov_b32_e32 v245, v229
	v_pk_add_f32 v[228:229], v[234:235], v[254:255] neg_lo:[0,1] neg_hi:[0,1]
	s_nop 0
	v_pk_add_f32 v[234:235], v[226:227], v[228:229] op_sel:[0,1] op_sel_hi:[1,0]
	v_pk_add_f32 v[226:227], v[226:227], v[228:229] op_sel:[0,1] op_sel_hi:[1,0] neg_lo:[0,1] neg_hi:[0,1]
	v_mov_b32_e32 v228, v234
	v_pk_mov_b32 v[238:239], v[226:227], v[234:235] op_sel:[1,0]
	v_mov_b32_e32 v229, v227
	v_pk_mul_f32 v[238:239], v[38:39], v[238:239]
	s_nop 0
	v_pk_fma_f32 v[246:247], v[40:41], v[234:235], v[238:239]
	v_pk_fma_f32 v[228:229], v[40:41], v[228:229], v[238:239] neg_lo:[0,0,1] neg_hi:[0,0,1]
	s_nop 0
	v_mov_b32_e32 v247, v229
	v_pk_add_f32 v[228:229], v[114:115], v[244:245]
	v_pk_add_f32 v[238:239], v[248:249], v[246:247]
	v_pk_add_f32 v[244:245], v[114:115], v[244:245] neg_lo:[0,1] neg_hi:[0,1]
	v_pk_add_f32 v[246:247], v[248:249], v[246:247] neg_lo:[0,1] neg_hi:[0,1]
	v_pk_add_f32 v[250:251], v[228:229], v[238:239]
	v_pk_add_f32 v[248:249], v[244:245], v[246:247] op_sel:[0,1] op_sel_hi:[1,0]
	v_pk_add_f32 v[244:245], v[244:245], v[246:247] op_sel:[0,1] op_sel_hi:[1,0] neg_lo:[0,1] neg_hi:[0,1]
	v_mov_b32_e32 v246, v248
	v_pk_mov_b32 v[252:253], v[244:245], v[248:249] op_sel:[1,0]
; DI float2 twid(float r) { return float2{__builtin_amdgcn_cosf(r), -__builtin_amdgcn_sinf(r)}; }
; DI void bfly_fwd(float2 a0, float2 a1, float2 a2, float2 a3, float r, float2& o0, float2& o1, float2& o2, float2& o3) {
;   float2 t0 = {a0.x + a2.x, a0.y + a2.y}, t1 = {a0.x - a2.x, a0.y - a2.y}, t2 = {a1.x + a3.x, a1.y + a3.y}, t3 = {a1.x - a3.x, a1.y - a3.y};
;   float2 b0 = {t0.x + t2.x, t0.y + t2.y}, b2 = {t0.x - t2.x, t0.y - t2.y}, b1 = {t1.x + t3.y, t1.y - t3.x}, b3 = {t1.x - t3.y, t1.y + t3.x};
;   float2 w1 = twid(r), w2 = cmul(w1, w1), w3 = cmul(w2, w1);
;   o0 = b0; o1 = cmul(b1, w1); o2 = cmul(b2, w2); o3 = cmul(b3, w3);
; }
;     ...
;   for (int gg = tid; gg < NBT * (N / 16); gg += NTHR) { const int g = gg & (N / 16 - 1); float2* z = z0 + (gg / (N / 16)) * N; const int jp = g & (Q2 - 1), base = ((g >> lq2) << (lq2 + 4)) + jp; float2 x[4][4];
; #pragma unroll
;     for (int q1 = 0; q1 < 4; ++q1)
; #pragma unroll
;       for (int q2 = 0; q2 < 4; ++q2) x[q1][q2] = z[base + q1 * Q1 + q2 * Q2];
; #pragma unroll
;     for (int q2 = 0; q2 < 4; ++q2) bfly_fwd(x[0][q2], x[1][q2], x[2][q2], x[3][q2], (float)(jp + q2 * Q2) * invM1, x[0][q2], x[1][q2], x[2][q2], x[3][q2]);
; #pragma unroll
;     for (int q1 = 0; q1 < 4; ++q1) bfly_fwd(x[q1][0], x[q1][1], x[q1][2], x[q1][3], (float)jp * invM2, x[q1][0], x[q1][1], x[q1][2], x[q1][3]);
; #pragma unroll
;     for (int q1 = 0; q1 < 4; ++q1)
; #pragma unroll
;       for (int q2 = 0; q2 < 4; ++q2) z[base + q1 * Q1 + q2 * Q2] = x[q1][q2]; }
	v_mov_b32_e32 v247, v245
	v_pk_mul_f32 v[252:253], v[50:51], v[252:253]
	v_pk_add_f32 v[228:229], v[228:229], v[238:239] neg_lo:[0,1] neg_hi:[0,1]
	v_pk_fma_f32 v[254:255], v[52:53], v[248:249], v[252:253]
	v_pk_fma_f32 v[246:247], v[52:53], v[246:247], v[252:253] neg_lo:[0,0,1] neg_hi:[0,0,1]
	v_pk_mul_f32 v[238:239], v[58:59], v[228:229]
	v_mov_b32_e32 v255, v247
	v_pk_fma_f32 v[246:247], v[56:57], v[228:229], v[238:239] op_sel:[0,0,1] op_sel_hi:[1,1,0] neg_lo:[0,0,1] neg_hi:[0,0,1]
	v_pk_fma_f32 v[228:229], v[56:57], v[228:229], v[238:239] op_sel:[0,0,1] op_sel_hi:[1,1,0]
	v_pk_mov_b32 v[238:239], v[248:249], v[244:245] op_sel:[1,0]
	v_mov_b32_e32 v247, v229
	v_mov_b32_e32 v228, v244
	v_mov_b32_e32 v229, v249
	v_pk_mul_f32 v[238:239], v[62:63], v[238:239]
	ds_write2_b64 v219, v[250:251], v[254:255] offset0:64 offset1:80
	v_pk_fma_f32 v[244:245], v[60:61], v[244:245], v[238:239] neg_lo:[0,0,1] neg_hi:[0,0,1]
	v_pk_fma_f32 v[228:229], v[60:61], v[228:229], v[238:239]
	s_nop 0
	v_mov_b32_e32 v245, v229
	v_pk_mul_f32 v[228:229], v[10:11], v[74:75] op_sel:[0,1] op_sel_hi:[1,0]
	ds_write2_b64 v219, v[246:247], v[244:245] offset0:96 offset1:112
	v_pk_fma_f32 v[238:239], v[8:9], v[74:75], v[228:229] neg_lo:[0,0,1] neg_hi:[0,0,1]
	v_pk_fma_f32 v[74:75], v[8:9], v[74:75], v[228:229]
	s_nop 0
	v_mov_b32_e32 v239, v75
	v_pk_add_f32 v[74:75], v[116:117], v[118:119] neg_lo:[0,1] neg_hi:[0,1]
	s_nop 0
	v_pk_mul_f32 v[228:229], v[22:23], v[74:75] op_sel:[0,1] op_sel_hi:[1,0]
	s_nop 0
	v_pk_fma_f32 v[244:245], v[20:21], v[74:75], v[228:229] neg_lo:[0,0,1] neg_hi:[0,0,1]
	v_pk_fma_f32 v[74:75], v[20:21], v[74:75], v[228:229]
	s_nop 0
	v_mov_b32_e32 v245, v75
	v_pk_add_f32 v[74:75], v[122:123], v[124:125] neg_lo:[0,1] neg_hi:[0,1]
	s_nop 0
	v_pk_mul_f32 v[228:229], v[34:35], v[74:75] op_sel:[0,1] op_sel_hi:[1,0]
	s_nop 0
	v_pk_fma_f32 v[246:247], v[32:33], v[74:75], v[228:229] neg_lo:[0,0,1] neg_hi:[0,0,1]
	v_pk_fma_f32 v[74:75], v[32:33], v[74:75], v[228:229]
	s_nop 0
	v_mov_b32_e32 v247, v75
	v_pk_add_f32 v[74:75], v[128:129], v[130:131] neg_lo:[0,1] neg_hi:[0,1]
	s_nop 0
	v_pk_mul_f32 v[228:229], v[46:47], v[74:75] op_sel:[0,1] op_sel_hi:[1,0]
	s_nop 0
	v_pk_fma_f32 v[248:249], v[44:45], v[74:75], v[228:229] neg_lo:[0,0,1] neg_hi:[0,0,1]
	v_pk_fma_f32 v[74:75], v[44:45], v[74:75], v[228:229]
	s_nop 0
	v_mov_b32_e32 v249, v75
	v_pk_add_f32 v[74:75], v[238:239], v[246:247]
	v_pk_add_f32 v[228:229], v[244:245], v[248:249]
	v_pk_add_f32 v[238:239], v[238:239], v[246:247] neg_lo:[0,1] neg_hi:[0,1]
	v_pk_add_f32 v[244:245], v[244:245], v[248:249] neg_lo:[0,1] neg_hi:[0,1]
	v_pk_add_f32 v[250:251], v[74:75], v[228:229]
	v_pk_add_f32 v[246:247], v[238:239], v[244:245] op_sel:[0,1] op_sel_hi:[1,0]
	v_pk_add_f32 v[238:239], v[238:239], v[244:245] op_sel:[0,1] op_sel_hi:[1,0] neg_lo:[0,1] neg_hi:[0,1]
	v_mov_b32_e32 v244, v246
	v_pk_mov_b32 v[248:249], v[238:239], v[246:247] op_sel:[1,0]
	v_mov_b32_e32 v245, v239
	v_pk_mul_f32 v[248:249], v[50:51], v[248:249]
	v_pk_add_f32 v[74:75], v[74:75], v[228:229] neg_lo:[0,1] neg_hi:[0,1]
	v_pk_fma_f32 v[252:253], v[52:53], v[246:247], v[248:249]
	v_pk_fma_f32 v[244:245], v[52:53], v[244:245], v[248:249] neg_lo:[0,0,1] neg_hi:[0,0,1]
	v_pk_mul_f32 v[228:229], v[58:59], v[74:75]
	v_mov_b32_e32 v253, v245
	v_pk_fma_f32 v[244:245], v[56:57], v[74:75], v[228:229] op_sel:[0,0,1] op_sel_hi:[1,1,0] neg_lo:[0,0,1] neg_hi:[0,0,1]
	v_pk_fma_f32 v[74:75], v[56:57], v[74:75], v[228:229] op_sel:[0,0,1] op_sel_hi:[1,1,0]
	v_pk_mov_b32 v[228:229], v[246:247], v[238:239] op_sel:[1,0]
; DI float2 twid(float r) { return float2{__builtin_amdgcn_cosf(r), -__builtin_amdgcn_sinf(r)}; }
; DI void bfly_fwd(float2 a0, float2 a1, float2 a2, float2 a3, float r, float2& o0, float2& o1, float2& o2, float2& o3) {
;   float2 t0 = {a0.x + a2.x, a0.y + a2.y}, t1 = {a0.x - a2.x, a0.y - a2.y}, t2 = {a1.x + a3.x, a1.y + a3.y}, t3 = {a1.x - a3.x, a1.y - a3.y};
;   float2 b0 = {t0.x + t2.x, t0.y + t2.y}, b2 = {t0.x - t2.x, t0.y - t2.y}, b1 = {t1.x + t3.y, t1.y - t3.x}, b3 = {t1.x - t3.y, t1.y + t3.x};
;   float2 w1 = twid(r), w2 = cmul(w1, w1), w3 = cmul(w2, w1);
;   o0 = b0; o1 = cmul(b1, w1); o2 = cmul(b2, w2); o3 = cmul(b3, w3);
; }
;     ...
;   for (int gg = tid; gg < NBT * (N / 16); gg += NTHR) { const int g = gg & (N / 16 - 1); float2* z = z0 + (gg / (N / 16)) * N; const int jp = g & (Q2 - 1), base = ((g >> lq2) << (lq2 + 4)) + jp; float2 x[4][4];
; #pragma unroll
;     for (int q1 = 0; q1 < 4; ++q1)
; #pragma unroll
;       for (int q2 = 0; q2 < 4; ++q2) x[q1][q2] = z[base + q1 * Q1 + q2 * Q2];
; #pragma unroll
;     for (int q2 = 0; q2 < 4; ++q2) bfly_fwd(x[0][q2], x[1][q2], x[2][q2], x[3][q2], (float)(jp + q2 * Q2) * invM1, x[0][q2], x[1][q2], x[2][q2], x[3][q2]);
; #pragma unroll
;     for (int q1 = 0; q1 < 4; ++q1) bfly_fwd(x[q1][0], x[q1][1], x[q1][2], x[q1][3], (float)jp * invM2, x[q1][0], x[q1][1], x[q1][2], x[q1][3]);
; #pragma unroll
;     for (int q1 = 0; q1 < 4; ++q1)
; #pragma unroll
;       for (int q2 = 0; q2 < 4; ++q2) z[base + q1 * Q1 + q2 * Q2] = x[q1][q2]; }
	v_mov_b32_e32 v245, v75
	v_mov_b32_e32 v74, v238
	v_mov_b32_e32 v75, v247
	v_pk_mul_f32 v[228:229], v[62:63], v[228:229]
	ds_write2_b64 v219, v[250:251], v[252:253] offset0:128 offset1:144
	v_pk_fma_f32 v[238:239], v[60:61], v[238:239], v[228:229] neg_lo:[0,0,1] neg_hi:[0,0,1]
	v_pk_fma_f32 v[74:75], v[60:61], v[74:75], v[228:229]
	v_pk_mov_b32 v[228:229], v[236:237], v[220:221] op_sel:[1,0]
	v_mov_b32_e32 v239, v75
	v_mov_b32_e32 v74, v220
	v_mov_b32_e32 v75, v237
	v_pk_mul_f32 v[228:229], v[18:19], v[228:229]
	ds_write2_b64 v219, v[244:245], v[238:239] offset0:160 offset1:176
	v_pk_fma_f32 v[220:221], v[12:13], v[220:221], v[228:229] neg_lo:[0,0,1] neg_hi:[0,0,1]
	v_pk_fma_f32 v[74:75], v[12:13], v[74:75], v[228:229]
	v_pk_mov_b32 v[228:229], v[230:231], v[222:223] op_sel:[1,0]
	v_mov_b32_e32 v221, v75
	v_mov_b32_e32 v74, v222
	v_mov_b32_e32 v75, v231
	v_pk_mul_f32 v[228:229], v[30:31], v[228:229]
	s_nop 0
	v_pk_fma_f32 v[222:223], v[24:25], v[222:223], v[228:229] neg_lo:[0,0,1] neg_hi:[0,0,1]
	v_pk_fma_f32 v[74:75], v[24:25], v[74:75], v[228:229]
	v_pk_mov_b32 v[228:229], v[232:233], v[224:225] op_sel:[1,0]
	v_mov_b32_e32 v223, v75
	v_mov_b32_e32 v74, v224
	v_mov_b32_e32 v75, v233
	v_pk_mul_f32 v[228:229], v[42:43], v[228:229]
	s_nop 0
	v_pk_fma_f32 v[224:225], v[36:37], v[224:225], v[228:229] neg_lo:[0,0,1] neg_hi:[0,0,1]
	v_pk_fma_f32 v[74:75], v[36:37], v[74:75], v[228:229]
	v_pk_mov_b32 v[228:229], v[234:235], v[226:227] op_sel:[1,0]
	v_mov_b32_e32 v225, v75
	v_mov_b32_e32 v74, v226
	v_mov_b32_e32 v75, v235
	v_pk_mul_f32 v[228:229], v[54:55], v[228:229]
	s_nop 0
	v_pk_fma_f32 v[226:227], v[48:49], v[226:227], v[228:229] neg_lo:[0,0,1] neg_hi:[0,0,1]
	v_pk_fma_f32 v[74:75], v[48:49], v[74:75], v[228:229]
	s_nop 0
	v_mov_b32_e32 v227, v75
	v_pk_add_f32 v[74:75], v[220:221], v[224:225]
	v_pk_add_f32 v[228:229], v[222:223], v[226:227]
	v_pk_add_f32 v[220:221], v[220:221], v[224:225] neg_lo:[0,1] neg_hi:[0,1]
	v_pk_add_f32 v[222:223], v[222:223], v[226:227] neg_lo:[0,1] neg_hi:[0,1]
	v_pk_add_f32 v[230:231], v[74:75], v[228:229]
	v_pk_add_f32 v[224:225], v[220:221], v[222:223] op_sel:[0,1] op_sel_hi:[1,0]
	v_pk_add_f32 v[220:221], v[220:221], v[222:223] op_sel:[0,1] op_sel_hi:[1,0] neg_lo:[0,1] neg_hi:[0,1]
	v_mov_b32_e32 v222, v224
	v_pk_mov_b32 v[226:227], v[220:221], v[224:225] op_sel:[1,0]
	v_mov_b32_e32 v223, v221
	v_pk_mul_f32 v[226:227], v[50:51], v[226:227]
	s_nop 0
	v_pk_fma_f32 v[232:233], v[52:53], v[224:225], v[226:227]
	v_pk_fma_f32 v[222:223], v[52:53], v[222:223], v[226:227] neg_lo:[0,0,1] neg_hi:[0,0,1]
	s_nop 0
	v_mov_b32_e32 v233, v223
	v_pk_add_f32 v[222:223], v[74:75], v[228:229] neg_lo:[0,1] neg_hi:[0,1]
	ds_write2_b64 v219, v[230:231], v[232:233] offset0:192 offset1:208
	v_pk_mul_f32 v[74:75], v[58:59], v[222:223]
	s_nop 0
	v_pk_fma_f32 v[226:227], v[56:57], v[222:223], v[74:75] op_sel:[0,0,1] op_sel_hi:[1,1,0] neg_lo:[0,0,1] neg_hi:[0,0,1]
	v_pk_fma_f32 v[222:223], v[56:57], v[222:223], v[74:75] op_sel:[0,0,1] op_sel_hi:[1,1,0]
	v_pk_mov_b32 v[74:75], v[224:225], v[220:221] op_sel:[1,0]
	v_mov_b32_e32 v227, v223
	v_mov_b32_e32 v222, v220
	v_mov_b32_e32 v223, v225
	v_pk_mul_f32 v[74:75], v[62:63], v[74:75]
	s_nop 0
	v_pk_fma_f32 v[220:221], v[60:61], v[220:221], v[74:75] neg_lo:[0,0,1] neg_hi:[0,0,1]
	v_pk_fma_f32 v[222:223], v[60:61], v[222:223], v[74:75]
	s_nop 0
	v_mov_b32_e32 v221, v223
	ds_write2_b64 v219, v[226:227], v[220:221] offset0:224 offset1:240
	s_nop 0
	v_add_u32_e32 v70, 0x200, v69
	s_nop 0
	v_mov_b32_e32 v69, v70

; DI float2 twid(float r) { return float2{__builtin_amdgcn_cosf(r), -__builtin_amdgcn_sinf(r)}; }
; DI void bfly_inv(float2 s0, float2 s1, float2 s2, float2 s3, float r, float2& o0, float2& o1, float2& o2, float2& o3) {
;   float2 w1 = twid(r), w2 = cmul(w1, w1), w3 = cmul(w2, w1);
;   float2 c0 = s0, c1 = cmulc(s1, w1), c2 = cmulc(s2, w2), c3 = cmulc(s3, w3);
;   float2 t0 = {c0.x + c2.x, c0.y + c2.y}, t1 = {c0.x - c2.x, c0.y - c2.y}, t2 = {c1.x + c3.x, c1.y + c3.y}, t3 = {c1.x - c3.x, c1.y - c3.y};
;   o0 = float2{t0.x + t2.x, t0.y + t2.y}; o2 = float2{t0.x - t2.x, t0.y - t2.y}; o1 = float2{t1.x - t3.y, t1.y + t3.x}; o3 = float2{t1.x + t3.y, t1.y - t3.x};
; }
;     ...
;   for (int gg = tid; gg < NBT * (N / 16); gg += NTHR) { const int g = gg & (N / 16 - 1); float2* z = z0 + (gg / (N / 16)) * N; const int jp = g & (Q2 - 1), base = ((g >> lq2) << (lq2 + 4)) + jp; float2 x[4][4];
; #pragma unroll
;     for (int q1 = 0; q1 < 4; ++q1)
; #pragma unroll
;       for (int q2 = 0; q2 < 4; ++q2) x[q1][q2] = z[base + q1 * Q1 + q2 * Q2];
; #pragma unroll
;     for (int q1 = 0; q1 < 4; ++q1) bfly_inv(x[q1][0], x[q1][1], x[q1][2], x[q1][3], (float)jp * invM2, x[q1][0], x[q1][1], x[q1][2], x[q1][3]);
; #pragma unroll
;     for (int q2 = 0; q2 < 4; ++q2) bfly_inv(x[0][q2], x[1][q2], x[2][q2], x[3][q2], (float)(jp + q2 * Q2) * invM1, x[0][q2], x[1][q2], x[2][q2], x[3][q2]);
; #pragma unroll
;     for (int q1 = 0; q1 < 4; ++q1)
; #pragma unroll
;       for (int q2 = 0; q2 < 4; ++q2) z[base + q1 * Q1 + q2 * Q2] = x[q1][q2]; }
.LBB0_1648:
	s_or_b64 exec, exec, s[0:1]
	s_waitcnt lgkmcnt(0)
	s_barrier
	s_and_saveexec_b64 s[14:15], vcc
	s_cbranch_execz .LBB0_1651
	v_mul_f32_e32 v4, 0x3c800000, v67
	v_sin_f32_e32 v5, v4
	v_cos_f32_e32 v6, v4
	s_mov_b64 s[0:1], 0
	v_mov_b32_e32 v84, v76
	v_xor_b32_e32 v10, 0x80000000, v5
	v_mov_b32_e32 v4, v6
	v_mov_b32_e32 v8, v10
	v_mov_b32_e32 v9, v5
	v_mov_b32_e32 v7, v6
	v_mov_b32_e32 v11, v6
	v_pk_mul_f32 v[12:13], v[4:5], v[8:9]
	v_mov_b32_e32 v58, v6
	v_pk_fma_f32 v[8:9], v[6:7], v[10:11], v[12:13] op_sel_hi:[0,1,1] neg_lo:[0,0,1] neg_hi:[0,0,1]
	v_pk_fma_f32 v[10:11], v[6:7], v[10:11], v[12:13] op_sel_hi:[0,1,1]
	s_nop 0
	v_pk_mov_b32 v[12:13], v[8:9], v[10:11] op_sel:[1,0]
	v_mul_f32_e32 v8, 0x3b800000, v67
	v_sin_f32_e32 v14, v8
	v_cos_f32_e32 v16, v8
	v_mov_b32_e32 v18, v10
	v_mov_b32_e32 v19, v9
	v_mul_f32_e32 v8, v14, v14
	v_fma_f32 v24, v16, v16, -v8
	v_cvt_f32_ubyte0_e32 v8, v66
	v_mul_f32_e32 v8, 0x3b800000, v8
	v_sin_f32_e32 v27, v8
	v_cos_f32_e32 v29, v8
	v_pk_mul_f32 v[20:21], v[4:5], v[12:13] op_sel:[1,0]
	v_mul_f32_e64 v11, v16, -v14
	v_pk_fma_f32 v[12:13], v[6:7], v[18:19], v[20:21] op_sel_hi:[0,1,1]
	v_pk_fma_f32 v[18:19], v[6:7], v[18:19], v[20:21] op_sel_hi:[0,1,1] neg_lo:[0,0,1] neg_hi:[0,0,1]
	v_add_f32_e32 v20, v11, v11
	v_mul_f32_e32 v8, v14, v24
	v_fma_f32 v22, v16, v20, -v8
	v_mul_f32_e32 v8, v27, v27
	v_fma_f32 v30, v29, v29, -v8
	v_mul_f32_e64 v8, v29, -v27
	v_add_f32_e32 v32, v8, v8
	v_cvt_f32_ubyte0_e32 v8, v65
	v_mul_f32_e32 v8, 0x3b800000, v8
	v_sin_f32_e32 v35, v8
	v_cos_f32_e32 v37, v8
	v_mul_f32_e32 v8, v27, v30
	v_fma_f32 v28, v29, v32, -v8
	v_mul_f32_e32 v8, v35, v35
	v_fma_f32 v38, v37, v37, -v8
	v_mul_f32_e64 v8, v37, -v35
	v_add_f32_e32 v40, v8, v8
	v_cvt_f32_ubyte0_e32 v8, v64
	v_mul_f32_e32 v8, 0x3b800000, v8
	v_sin_f32_e32 v42, v8
	v_cos_f32_e32 v44, v8
	v_mul_f32_e32 v23, v14, v20
	v_mul_f32_e32 v26, v27, v32
	v_xor_b32_e32 v45, 0x80000000, v42
	v_mov_b32_e32 v43, v44
	v_mov_b32_e32 v46, v42
	v_mov_b32_e32 v47, v45
	v_pk_mul_f32 v[48:49], v[42:43], v[46:47]
	v_mul_f32_e32 v34, v35, v40
	v_pk_fma_f32 v[46:47], v[44:45], v[44:45], v[48:49] op_sel_hi:[0,1,1] neg_lo:[0,0,1] neg_hi:[0,0,1]
	v_pk_fma_f32 v[62:63], v[44:45], v[44:45], v[48:49] op_sel_hi:[0,1,1]
	s_nop 0
	v_pk_mov_b32 v[50:51], v[62:63], v[46:47] op_sel:[1,0]
	v_mul_f32_e32 v8, v35, v38
	v_mov_b32_e32 v48, v46
	v_mov_b32_e32 v49, v63
	v_pk_mul_f32 v[50:51], v[42:43], v[50:51] op_sel_hi:[0,1]
	v_fmac_f32_e32 v23, v16, v24
	v_fmac_f32_e32 v26, v29, v30
	v_fmac_f32_e32 v34, v37, v38
	v_fma_f32 v36, v37, v40, -v8
	v_pk_fma_f32 v[60:61], v[44:45], v[48:49], v[50:51] op_sel_hi:[0,1,1]
	v_pk_fma_f32 v[48:49], v[44:45], v[48:49], v[50:51] op_sel_hi:[0,1,1] neg_lo:[0,0,1] neg_hi:[0,0,1]
	v_mov_b32_e32 v21, v14
	v_mov_b32_e32 v19, v13
	v_mov_b32_e32 v48, v60
	v_mov_b32_e32 v11, v10
	v_mov_b32_e32 v31, v30
	v_mov_b32_e32 v33, v32
	v_pk_mov_b32 v[50:51], v[28:29], v[26:27] op_sel:[1,0]
	v_pk_mov_b32 v[52:53], v[26:27], v[28:29] op_sel:[1,0]
	v_mov_b32_e32 v39, v38
	v_pk_mov_b32 v[54:55], v[36:37], v[34:35] op_sel:[1,0]
	v_pk_mov_b32 v[56:57], v[34:35], v[36:37] op_sel:[1,0]
	v_mov_b32_e32 v59, v18
	v_mov_b32_e32 v12, v5
	v_pk_mov_b32 v[60:61], v[62:63], v[60:61] op_sel:[1,0]
	v_mov_b32_e32 v47, v49
	v_mov_b32_e32 v45, v46
	v_mov_b32_e32 v43, v63
	v_mov_b32_e32 v63, v18
	v_mov_b32_e32 v64, v5
	v_mov_b32_e32 v65, v5
	v_mov_b32_e32 v8, v9
	v_mov_b32_e32 v66, v6
	v_mov_b32_e32 v67, v13
	v_mov_b32_e32 v68, v5
	v_mov_b32_e32 v69, v18
	v_mov_b32_e32 v70, v13
	v_mov_b32_e32 v71, v13
	v_mov_b32_e32 v72, v18
	v_mov_b32_e32 v73, v18
	v_mov_b32_e32 v25, v16
	v_pk_mov_b32 v[74:75], v[22:23], v[20:21] op_sel:[1,0]
	v_mov_b32_e32 v41, v40
	v_lshlrev_b32_e32 v62, 4, v76
	v_ashrrev_i32_e32 v15, 31, v84
	v_lshrrev_b32_e32 v15, 22, v15
	v_add_lshl_u32 v15, v84, v15, 7
	v_and_b32_e32 v15, 0xfffe0000, v15
	v_and_b32_e32 v17, 0x3f00, v62
	v_add_u32_e32 v15, 16, v15
	v_lshlrev_b32_e32 v17, 3, v17
	v_lshlrev_b32_e32 v85, 3, v83
	v_add3_u32 v85, v15, v17, v85
	ds_read2_b64 v[86:89], v85 offset0:32 offset1:48
	ds_read2_b64 v[90:93], v85 offset1:16
	s_nop 0
	s_waitcnt lgkmcnt(1)
	v_mul_f32_e32 v119, v9, v86
	s_waitcnt lgkmcnt(0)
	v_mul_f32_e32 v94, v5, v93
	v_mul_f32_e32 v124, v10, v86
	v_mul_f32_e32 v86, v19, v89
	v_pk_fma_f32 v[112:113], v[4:5], v[92:93], v[94:95] op_sel_hi:[1,1,0] neg_lo:[0,0,1] neg_hi:[0,0,1]
	v_mul_f32_e32 v114, v6, v93
	v_mul_f32_e32 v116, v5, v92
	v_mul_f32_e32 v121, v10, v87
	v_mul_f32_e32 v122, v9, v87
	v_pk_mul_f32 v[126:127], v[18:19], v[88:89] op_sel_hi:[1,0]
	v_pk_mul_f32 v[128:129], v[62:63], v[88:89]
	v_pk_fma_f32 v[130:131], v[18:19], v[88:89], v[86:87] op_sel_hi:[1,1,0] neg_lo:[1,0,0] neg_hi:[1,0,0]
	ds_read2_b64 v[86:89], v85 offset0:64 offset1:80
	ds_read2_b64 v[92:95], v85 offset0:96 offset1:112
	ds_read2_b64 v[96:99], v85 offset0:128 offset1:144
	ds_read2_b64 v[100:103], v85 offset0:160 offset1:176
	ds_read2_b64 v[104:107], v85 offset0:192 offset1:208
	ds_read2_b64 v[108:111], v85 offset0:224 offset1:240
	v_add_u32_e32 v218, 0x200, v84
	v_add_u32_e32 v241, 0x2000, v62
	v_ashrrev_i32_e32 v252, 31, v218
	v_lshrrev_b32_e32 v252, 22, v252
	v_add_lshl_u32 v252, v218, v252, 7
	v_and_b32_e32 v252, 0xfffe0000, v252
	v_and_b32_e32 v253, 0x3f00, v241
	v_add_u32_e32 v252, 16, v252
	v_lshlrev_b32_e32 v253, 3, v253
	v_lshlrev_b32_e32 v219, 3, v83
	v_add3_u32 v219, v252, v253, v219
	ds_read2_b64 v[220:223], v219 offset0:32 offset1:48
	ds_read2_b64 v[224:227], v219 offset1:16
	ds_read2_b64 v[228:231], v219 offset0:64 offset1:80
	ds_read2_b64 v[232:235], v219 offset0:96 offset1:112
	ds_read2_b64 v[236:239], v219 offset0:128 offset1:144
	ds_read2_b64 v[244:247], v219 offset0:160 offset1:176
	ds_read2_b64 v[248:251], v219 offset0:192 offset1:208
	ds_read2_b64 v[252:255], v219 offset0:224 offset1:240
	s_waitcnt lgkmcnt(12)
; DI float2 twid(float r) { return float2{__builtin_amdgcn_cosf(r), -__builtin_amdgcn_sinf(r)}; }
; DI void bfly_inv(float2 s0, float2 s1, float2 s2, float2 s3, float r, float2& o0, float2& o1, float2& o2, float2& o3) {
;   float2 w1 = twid(r), w2 = cmul(w1, w1), w3 = cmul(w2, w1);
;   float2 c0 = s0, c1 = cmulc(s1, w1), c2 = cmulc(s2, w2), c3 = cmulc(s3, w3);
;   float2 t0 = {c0.x + c2.x, c0.y + c2.y}, t1 = {c0.x - c2.x, c0.y - c2.y}, t2 = {c1.x + c3.x, c1.y + c3.y}, t3 = {c1.x - c3.x, c1.y - c3.y};
;   o0 = float2{t0.x + t2.x, t0.y + t2.y}; o2 = float2{t0.x - t2.x, t0.y - t2.y}; o1 = float2{t1.x - t3.y, t1.y + t3.x}; o3 = float2{t1.x + t3.y, t1.y - t3.x};
; }
;     ...
;   for (int gg = tid; gg < NBT * (N / 16); gg += NTHR) { const int g = gg & (N / 16 - 1); float2* z = z0 + (gg / (N / 16)) * N; const int jp = g & (Q2 - 1), base = ((g >> lq2) << (lq2 + 4)) + jp; float2 x[4][4];
; #pragma unroll
;     for (int q1 = 0; q1 < 4; ++q1)
; #pragma unroll
;       for (int q2 = 0; q2 < 4; ++q2) x[q1][q2] = z[base + q1 * Q1 + q2 * Q2];
; #pragma unroll
;     for (int q1 = 0; q1 < 4; ++q1) bfly_inv(x[q1][0], x[q1][1], x[q1][2], x[q1][3], (float)jp * invM2, x[q1][0], x[q1][1], x[q1][2], x[q1][3]);
; #pragma unroll
;     for (int q2 = 0; q2 < 4; ++q2) bfly_inv(x[0][q2], x[1][q2], x[2][q2], x[3][q2], (float)(jp + q2 * Q2) * invM1, x[0][q2], x[1][q2], x[2][q2], x[3][q2]);
; #pragma unroll
;     for (int q1 = 0; q1 < 4; ++q1)
; #pragma unroll
;       for (int q2 = 0; q2 < 4; ++q2) z[base + q1 * Q1 + q2 * Q2] = x[q1][q2]; }
	v_mov_b32_e32 v133, v95
	s_waitcnt lgkmcnt(11)
	v_mov_b32_e32 v132, v99
	v_pk_mul_f32 v[132:133], v[58:59], v[132:133]
	v_mov_b32_e32 v134, v98
	v_mov_b32_e32 v135, v94
	v_pk_fma_f32 v[132:133], v[12:13], v[134:135], v[132:133]
	s_waitcnt lgkmcnt(10)
	v_pk_mov_b32 v[134:135], v[100:101], v[92:93] op_sel:[1,0]
	v_mov_b32_e32 v92, v100
	v_pk_mul_f32 v[140:141], v[10:11], v[92:93]
	s_waitcnt lgkmcnt(8)
	v_mov_b32_e32 v142, v109
	v_mov_b32_e32 v109, v100
	v_mov_b32_e32 v136, v107
	v_mov_b32_e32 v137, v99
	v_mov_b32_e32 v143, v101
	v_pk_mul_f32 v[100:101], v[10:11], v[108:109]
	v_pk_fma_f32 v[144:145], v[8:9], v[134:135], v[140:141]
	v_pk_fma_f32 v[140:141], v[8:9], v[134:135], v[140:141] neg_lo:[0,0,1] neg_hi:[0,0,1]
	v_pk_mov_b32 v[156:157], v[88:89], v[102:103] op_sel:[1,0]
	v_pk_mul_f32 v[134:135], v[10:11], v[134:135]
	v_pk_mul_f32 v[138:139], v[6:7], v[136:137]
	v_mov_b32_e32 v107, v98
	v_mov_b32_e32 v146, v88
	v_mov_b32_e32 v147, v103
	v_pk_mul_f32 v[156:157], v[68:69], v[156:157]
	v_mov_b32_e32 v158, v111
	v_mov_b32_e32 v111, v102
	v_pk_fma_f32 v[100:101], v[8:9], v[142:143], v[100:101] neg_lo:[0,0,1] neg_hi:[0,0,1]
	v_mov_b32_e32 v168, v98
	v_mov_b32_e32 v169, v95
	v_pk_mov_b32 v[94:95], v[98:99], v[94:95] op_sel:[1,0]
	v_pk_mul_f32 v[98:99], v[64:65], v[136:137]
	v_pk_mul_f32 v[136:137], v[10:11], v[142:143]
	v_pk_fma_f32 v[142:143], v[8:9], v[92:93], v[134:135] neg_lo:[0,0,1] neg_hi:[0,0,1]
	v_pk_fma_f32 v[92:93], v[8:9], v[92:93], v[134:135]
	v_mov_b32_e32 v135, v102
	v_mov_b32_e32 v102, v89
	v_mov_b32_e32 v141, v145
	v_pk_fma_f32 v[146:147], v[66:67], v[146:147], v[156:157] neg_lo:[0,0,1] neg_hi:[0,0,1]
	v_pk_mov_b32 v[156:157], v[96:97], v[86:87] op_sel:[1,0]
	v_pk_mul_f32 v[94:95], v[68:69], v[94:95]
	v_mov_b32_e32 v134, v88
	v_pk_mul_f32 v[88:89], v[58:59], v[102:103]
	v_pk_add_f32 v[156:157], v[156:157], v[140:141]
	v_pk_add_f32 v[162:163], v[146:147], v[132:133] op_sel:[1,0] op_sel_hi:[0,1]
	v_pk_fma_f32 v[94:95], v[66:67], v[168:169], v[94:95] neg_lo:[0,0,1] neg_hi:[0,0,1]
	v_mov_b32_e32 v93, v143
	v_pk_fma_f32 v[88:89], v[12:13], v[134:135], v[88:89]
	v_mov_b32_e32 v134, v96
	v_mov_b32_e32 v135, v87
	v_mov_b32_e32 v159, v103
	v_pk_mul_f32 v[160:161], v[72:73], v[110:111]
	v_pk_fma_f32 v[138:139], v[64:65], v[106:107], v[138:139]
	v_mov_b32_e32 v118, v157
	v_mov_b32_e32 v120, v163
	v_pk_add_f32 v[134:135], v[134:135], v[92:93]
	v_pk_fma_f32 v[98:99], v[6:7], v[106:107], v[98:99] neg_lo:[0,0,1] neg_hi:[0,0,1]
	v_pk_add_f32 v[106:107], v[88:89], v[94:95] op_sel:[1,0] op_sel_hi:[0,1]
	v_pk_fma_f32 v[160:161], v[70:71], v[158:159], v[160:161] neg_lo:[0,0,1] neg_hi:[0,0,1]
	v_pk_add_f32 v[118:119], v[118:119], v[120:121]
	v_mov_b32_e32 v120, v105
	v_mov_b32_e32 v121, v97
	v_pk_mul_f32 v[102:103], v[72:73], v[158:159]
	v_mov_b32_e32 v126, v135
	v_mov_b32_e32 v128, v107
	v_pk_add_f32 v[120:121], v[120:121], v[100:101]
	v_pk_add_f32 v[164:165], v[138:139], v[160:161]
	v_pk_fma_f32 v[108:109], v[8:9], v[108:109], v[136:137]
	v_pk_fma_f32 v[102:103], v[70:71], v[110:111], v[102:103]
	v_pk_add_f32 v[110:111], v[126:127], v[128:129]
	v_mov_b32_e32 v126, v104
	v_mov_b32_e32 v127, v96
	v_mov_b32_e32 v123, v120
	v_mov_b32_e32 v125, v164
	v_pk_add_f32 v[126:127], v[126:127], v[108:109]
	v_pk_add_f32 v[128:129], v[98:99], v[102:103]
	v_pk_add_f32 v[166:167], v[122:123], v[124:125]
	v_pk_add_f32 v[122:123], v[122:123], v[124:125] neg_lo:[0,1] neg_hi:[0,1]
	v_mov_b32_e32 v117, v126
	v_mov_b32_e32 v115, v128
	v_pk_mov_b32 v[170:171], v[90:91], v[90:91] op_sel:[1,0]
	v_mov_b32_e32 v124, v122
	v_mov_b32_e32 v125, v167
	v_pk_add_f32 v[114:115], v[116:117], v[114:115]
	v_mov_b32_e32 v15, v171
	v_mov_b32_e32 v131, v23
	v_mov_b32_e32 v171, v22
	v_pk_add_f32 v[116:117], v[134:135], v[106:107]
	v_pk_mul_f32 v[182:183], v[130:131], v[114:115]
	v_pk_add_f32 v[184:185], v[130:131], v[114:115]
	v_pk_mul_f32 v[166:167], v[170:171], v[166:167]
	v_pk_add_f32 v[124:125], v[170:171], v[124:125]
	v_pk_add_f32 v[136:137], v[156:157], v[162:163]
	v_mov_b32_e32 v182, v184
	v_mov_b32_e32 v166, v124
	v_pk_mul_f32 v[116:117], v[20:21], v[116:117]
	v_mov_b32_e32 v17, v112
	v_pk_add_f32 v[172:173], v[14:15], v[118:119]
	v_pk_mul_f32 v[174:175], v[14:15], v[118:119]
	v_pk_fma_f32 v[116:117], v[24:25], v[136:137], v[116:117] neg_lo:[0,0,1] neg_hi:[0,0,1]
	v_pk_add_f32 v[136:137], v[182:183], v[166:167]
	v_pk_mov_b32 v[118:119], v[118:119], v[122:123] op_sel:[1,0]
	v_mov_b32_e32 v115, v112
	v_mov_b32_e32 v131, v111
	v_pk_mov_b32 v[182:183], v[94:95], v[102:103] op_sel:[1,0]
	v_mov_b32_e32 v99, v146
	v_mov_b32_e32 v103, v133
	v_pk_add_f32 v[158:159], v[16:17], v[110:111]
	v_pk_mul_f32 v[168:169], v[16:17], v[110:111]
	v_pk_add_f32 v[90:91], v[90:91], v[118:119] neg_lo:[0,1] neg_hi:[0,1]
	v_pk_add_f32 v[110:111], v[114:115], v[130:131] neg_lo:[0,1] neg_hi:[0,1]
	v_mov_b32_e32 v118, v104
	v_mov_b32_e32 v119, v86
	v_mov_b32_e32 v122, v108
	v_mov_b32_e32 v123, v145
	v_pk_mov_b32 v[130:131], v[144:145], v[100:101] op_sel:[1,0]
	v_mov_b32_e32 v139, v88
	v_mov_b32_e32 v144, v88
	v_mov_b32_e32 v145, v98
	v_pk_add_f32 v[98:99], v[98:99], v[102:103] neg_lo:[0,1] neg_hi:[0,1]
	v_pk_mov_b32 v[102:103], v[132:133], v[160:161] op_sel:[1,0]
	v_mov_b32_e32 v93, v140
	v_mov_b32_e32 v133, v94
	v_mov_b32_e32 v88, v147
	v_pk_add_f32 v[118:119], v[118:119], v[122:123] neg_lo:[0,1] neg_hi:[0,1]
	v_mov_b32_e32 v122, v86
	v_mov_b32_e32 v123, v105
	v_pk_mov_b32 v[186:187], v[86:87], v[104:105] op_sel:[1,0]
	v_mov_b32_e32 v86, v105
	v_mov_b32_e32 v101, v143
	v_pk_add_f32 v[92:93], v[96:97], v[92:93] neg_lo:[0,1] neg_hi:[0,1]
	v_pk_add_f32 v[88:89], v[132:133], v[88:89] neg_lo:[0,1] neg_hi:[0,1]
; DI float2 twid(float r) { return float2{__builtin_amdgcn_cosf(r), -__builtin_amdgcn_sinf(r)}; }
; DI void bfly_inv(float2 s0, float2 s1, float2 s2, float2 s3, float r, float2& o0, float2& o1, float2& o2, float2& o3) {
;   float2 w1 = twid(r), w2 = cmul(w1, w1), w3 = cmul(w2, w1);
;   float2 c0 = s0, c1 = cmulc(s1, w1), c2 = cmulc(s2, w2), c3 = cmulc(s3, w3);
;   float2 t0 = {c0.x + c2.x, c0.y + c2.y}, t1 = {c0.x - c2.x, c0.y - c2.y}, t2 = {c1.x + c3.x, c1.y + c3.y}, t3 = {c1.x - c3.x, c1.y - c3.y};
;   o0 = float2{t0.x + t2.x, t0.y + t2.y}; o2 = float2{t0.x - t2.x, t0.y - t2.y}; o1 = float2{t1.x - t3.y, t1.y + t3.x}; o3 = float2{t1.x + t3.y, t1.y - t3.x};
; }
;     ...
;   for (int gg = tid; gg < NBT * (N / 16); gg += NTHR) { const int g = gg & (N / 16 - 1); float2* z = z0 + (gg / (N / 16)) * N; const int jp = g & (Q2 - 1), base = ((g >> lq2) << (lq2 + 4)) + jp; float2 x[4][4];
; #pragma unroll
;     for (int q1 = 0; q1 < 4; ++q1)
; #pragma unroll
;       for (int q2 = 0; q2 < 4; ++q2) x[q1][q2] = z[base + q1 * Q1 + q2 * Q2];
; #pragma unroll
;     for (int q1 = 0; q1 < 4; ++q1) bfly_inv(x[q1][0], x[q1][1], x[q1][2], x[q1][3], (float)jp * invM2, x[q1][0], x[q1][1], x[q1][2], x[q1][3]);
; #pragma unroll
;     for (int q2 = 0; q2 < 4; ++q2) bfly_inv(x[0][q2], x[1][q2], x[2][q2], x[3][q2], (float)(jp + q2 * Q2) * invM1, x[0][q2], x[1][q2], x[2][q2], x[3][q2]);
; #pragma unroll
;     for (int q1 = 0; q1 < 4; ++q1)
; #pragma unroll
;       for (int q2 = 0; q2 < 4; ++q2) z[base + q1 * Q1 + q2 * Q2] = x[q1][q2]; }
	v_pk_add_f32 v[122:123], v[122:123], v[130:131] neg_lo:[0,1] neg_hi:[0,1]
	v_mov_b32_e32 v130, v160
	v_mov_b32_e32 v131, v95
	v_pk_mov_b32 v[108:109], v[142:143], v[108:109] op_sel:[1,0]
	v_pk_add_f32 v[86:87], v[86:87], v[100:101] neg_lo:[0,1] neg_hi:[0,1]
	v_mov_b32_e32 v100, v146
	v_mov_b32_e32 v101, v138
	v_pk_add_f32 v[94:95], v[92:93], v[88:89] neg_lo:[0,1] neg_hi:[0,1]
	v_pk_add_f32 v[96:97], v[92:93], v[88:89]
	v_pk_add_f32 v[176:177], v[126:127], v[128:129]
	v_pk_mov_b32 v[166:167], v[170:171], v[24:25] op_sel:[1,0]
	v_pk_add_f32 v[130:131], v[138:139], v[130:131] neg_lo:[0,1] neg_hi:[0,1]
	v_pk_add_f32 v[108:109], v[186:187], v[108:109] neg_lo:[0,1] neg_hi:[0,1]
	v_pk_add_f32 v[100:101], v[100:101], v[102:103] neg_lo:[0,1] neg_hi:[0,1]
	v_mov_b32_e32 v105, v97
	v_pk_mov_b32 v[96:97], v[96:97], v[94:95] op_sel:[1,0]
	v_pk_add_f32 v[178:179], v[120:121], v[164:165]
	v_pk_mul_f32 v[166:167], v[166:167], v[176:177]
	v_pk_add_f32 v[144:145], v[144:145], v[182:183] neg_lo:[0,1] neg_hi:[0,1]
	v_pk_add_f32 v[102:103], v[108:109], v[100:101] neg_lo:[0,1] neg_hi:[0,1]
	v_mov_b32_e32 v104, v94
	v_pk_add_f32 v[118:119], v[118:119], v[130:131] neg_lo:[0,1] neg_hi:[0,1]
	v_pk_add_f32 v[130:131], v[108:109], v[100:101]
	v_pk_mul_f32 v[96:97], v[32:33], v[96:97]
	v_mov_b32_e32 v169, v159
	v_mov_b32_e32 v175, v173
	v_pk_fma_f32 v[170:171], v[74:75], v[178:179], v[166:167]
	v_pk_fma_f32 v[166:167], v[74:75], v[178:179], v[166:167] neg_lo:[0,0,1] neg_hi:[0,0,1]
	v_pk_add_f32 v[182:183], v[122:123], v[144:145]
	v_mov_b32_e32 v131, v103
	v_pk_add_f32 v[132:133], v[122:123], v[144:145] neg_lo:[0,1] neg_hi:[0,1]
	v_pk_add_f32 v[86:87], v[86:87], v[98:99]
	v_pk_fma_f32 v[94:95], v[30:31], v[94:95], v[96:97]
	v_pk_fma_f32 v[96:97], v[30:31], v[104:105], v[96:97] neg_lo:[0,0,1] neg_hi:[0,0,1]
	v_pk_add_f32 v[168:169], v[174:175], v[168:169]
	v_mov_b32_e32 v167, v171
	v_pk_add_f32 v[112:113], v[90:91], v[110:111] neg_lo:[0,1] neg_hi:[0,1]
	v_pk_add_f32 v[114:115], v[90:91], v[110:111]
	v_mov_b32_e32 v133, v183
	v_mov_b32_e32 v95, v97
	v_pk_mul_f32 v[86:87], v[28:29], v[86:87]
	v_pk_mul_f32 v[96:97], v[52:53], v[130:131]
	v_pk_add_f32 v[174:175], v[116:117], v[136:137]
	v_pk_add_f32 v[176:177], v[168:169], v[166:167]
	v_mov_b32_e32 v114, v112
	v_pk_fma_f32 v[86:87], v[26:27], v[118:119], v[86:87]
	v_pk_fma_f32 v[96:97], v[50:51], v[132:133], v[96:97] neg_lo:[0,0,1] neg_hi:[0,0,1]
	v_pk_add_f32 v[178:179], v[174:175], v[176:177]
	v_pk_add_f32 v[98:99], v[114:115], v[94:95]
	v_pk_add_f32 v[104:105], v[96:97], v[86:87]
	v_pk_mov_b32 v[178:179], v[178:179], v[178:179] op_sel:[1,0]
	v_pk_add_f32 v[118:119], v[98:99], v[104:105]
	ds_write2_b64 v85, v[178:179], v[118:119] offset1:16
	v_pk_mov_b32 v[118:119], v[172:173], v[124:125] op_sel:[1,0]
	v_pk_mov_b32 v[124:125], v[158:159], v[184:185] op_sel:[1,0]
	v_mov_b32_e32 v130, v106
	v_pk_add_f32 v[118:119], v[118:119], v[124:125] neg_lo:[0,1] neg_hi:[0,1]
	v_mov_b32_e32 v124, v134
	v_mov_b32_e32 v125, v156
	v_mov_b32_e32 v131, v162
	v_pk_add_f32 v[124:125], v[124:125], v[130:131] neg_lo:[0,1] neg_hi:[0,1]
	v_mov_b32_e32 v130, v126
	v_mov_b32_e32 v131, v157
	v_mov_b32_e32 v132, v128
	v_mov_b32_e32 v133, v163
	v_pk_mov_b32 v[126:127], v[134:135], v[126:127] op_sel:[1,0]
	v_pk_mov_b32 v[128:129], v[106:107], v[128:129] op_sel:[1,0]
	v_mov_b32_e32 v108, v92
	v_mov_b32_e32 v100, v88
	v_pk_add_f32 v[130:131], v[130:131], v[132:133] neg_lo:[0,1] neg_hi:[0,1]
	v_pk_add_f32 v[126:127], v[126:127], v[128:129] neg_lo:[0,1] neg_hi:[0,1]
	v_pk_mov_b32 v[128:129], v[156:157], v[120:121] op_sel:[1,0]
	v_pk_mov_b32 v[132:133], v[162:163], v[164:165] op_sel:[1,0]
	v_mov_b32_e32 v121, v135
	v_mov_b32_e32 v165, v107
	v_pk_add_f32 v[100:101], v[108:109], v[100:101]
	v_mov_b32_e32 v122, v93
	v_mov_b32_e32 v144, v89
	v_pk_add_f32 v[106:107], v[120:121], v[164:165] neg_lo:[0,1] neg_hi:[0,1]
	v_pk_mul_f32 v[120:121], v[40:41], v[124:125] op_sel:[0,1] op_sel_hi:[1,0]
	v_pk_add_f32 v[88:89], v[122:123], v[144:145] neg_lo:[0,1] neg_hi:[0,1]
	v_mov_b32_e32 v103, v100
	v_mul_f32_e32 v111, v44, v102
	v_pk_add_f32 v[128:129], v[128:129], v[132:133] neg_lo:[0,1] neg_hi:[0,1]
	v_pk_fma_f32 v[132:133], v[38:39], v[124:125], v[120:121]
	v_pk_fma_f32 v[120:121], v[38:39], v[124:125], v[120:121] neg_lo:[0,0,1] neg_hi:[0,0,1]
	v_pk_mul_f32 v[92:93], v[42:43], v[102:103]
	v_mov_b32_e32 v102, v101
	v_mov_b32_e32 v103, v89
	v_mul_f32_e32 v108, v49, v89
	v_pk_mul_f32 v[100:101], v[46:47], v[100:101]
	v_mul_f32_e32 v91, v42, v182
	v_mov_b32_e32 v133, v121
	v_pk_mul_f32 v[106:107], v[36:37], v[106:107]
	v_pk_mul_f32 v[120:121], v[56:57], v[126:127]
	v_mov_b32_e32 v183, v88
	v_pk_fma_f32 v[102:103], v[48:49], v[102:103], v[108:109] op_sel_hi:[1,1,0]
	v_pk_fma_f32 v[108:109], v[60:61], v[88:89], v[100:101]
	v_pk_fma_f32 v[88:89], v[60:61], v[88:89], v[100:101] neg_lo:[0,0,1] neg_hi:[0,0,1]
	v_pk_fma_f32 v[106:107], v[34:35], v[130:131], v[106:107]
	v_pk_fma_f32 v[120:121], v[54:55], v[128:129], v[120:121] neg_lo:[0,0,1] neg_hi:[0,0,1]
	v_pk_add_f32 v[90:91], v[90:91], v[110:111]
	v_pk_fma_f32 v[92:93], v[44:45], v[182:183], v[92:93] neg_lo:[0,0,1] neg_hi:[0,0,1]
	v_mov_b32_e32 v109, v89
	v_mov_b32_e32 v112, v102
	v_pk_add_f32 v[124:125], v[118:119], v[132:133]
	v_pk_add_f32 v[126:127], v[120:121], v[106:107]
	v_pk_add_f32 v[100:101], v[92:93], v[112:113]
	v_pk_add_f32 v[110:111], v[90:91], v[108:109]
	v_pk_add_f32 v[128:129], v[124:125], v[126:127]
	v_pk_add_f32 v[122:123], v[100:101], v[110:111]
	ds_write2_b64 v85, v[128:129], v[122:123] offset0:32 offset1:48
	v_pk_mov_b32 v[122:123], v[168:169], v[136:137] op_sel:[1,0]
	v_pk_mov_b32 v[128:129], v[170:171], v[116:117] op_sel:[1,0]
; DI float2 twid(float r) { return float2{__builtin_amdgcn_cosf(r), -__builtin_amdgcn_sinf(r)}; }
; DI void bfly_inv(float2 s0, float2 s1, float2 s2, float2 s3, float r, float2& o0, float2& o1, float2& o2, float2& o3) {
;   float2 w1 = twid(r), w2 = cmul(w1, w1), w3 = cmul(w2, w1);
;   float2 c0 = s0, c1 = cmulc(s1, w1), c2 = cmulc(s2, w2), c3 = cmulc(s3, w3);
;   float2 t0 = {c0.x + c2.x, c0.y + c2.y}, t1 = {c0.x - c2.x, c0.y - c2.y}, t2 = {c1.x + c3.x, c1.y + c3.y}, t3 = {c1.x - c3.x, c1.y - c3.y};
;   o0 = float2{t0.x + t2.x, t0.y + t2.y}; o2 = float2{t0.x - t2.x, t0.y - t2.y}; o1 = float2{t1.x - t3.y, t1.y + t3.x}; o3 = float2{t1.x + t3.y, t1.y - t3.x};
; }
;     ...
;   for (int gg = tid; gg < NBT * (N / 16); gg += NTHR) { const int g = gg & (N / 16 - 1); float2* z = z0 + (gg / (N / 16)) * N; const int jp = g & (Q2 - 1), base = ((g >> lq2) << (lq2 + 4)) + jp; float2 x[4][4];
; #pragma unroll
;     for (int q1 = 0; q1 < 4; ++q1)
; #pragma unroll
;       for (int q2 = 0; q2 < 4; ++q2) x[q1][q2] = z[base + q1 * Q1 + q2 * Q2];
; #pragma unroll
;     for (int q1 = 0; q1 < 4; ++q1) bfly_inv(x[q1][0], x[q1][1], x[q1][2], x[q1][3], (float)jp * invM2, x[q1][0], x[q1][1], x[q1][2], x[q1][3]);
; #pragma unroll
;     for (int q2 = 0; q2 < 4; ++q2) bfly_inv(x[0][q2], x[1][q2], x[2][q2], x[3][q2], (float)(jp + q2 * Q2) * invM1, x[0][q2], x[1][q2], x[2][q2], x[3][q2]);
; #pragma unroll
;     for (int q1 = 0; q1 < 4; ++q1)
; #pragma unroll
;       for (int q2 = 0; q2 < 4; ++q2) z[base + q1 * Q1 + q2 * Q2] = x[q1][q2]; }
	v_mov_b32_e32 v169, v117
	v_mov_b32_e32 v167, v137
	v_pk_add_f32 v[94:95], v[114:115], v[94:95] neg_lo:[0,1] neg_hi:[0,1]
	v_pk_mov_b32 v[114:115], v[86:87], v[96:97] op_sel:[1,0]
	v_pk_mov_b32 v[86:87], v[96:97], v[86:87] op_sel:[1,0]
	v_pk_add_f32 v[122:123], v[122:123], v[128:129] neg_lo:[0,1] neg_hi:[0,1]
	v_pk_add_f32 v[116:117], v[168:169], v[166:167] neg_lo:[0,1] neg_hi:[0,1]
	v_pk_add_f32 v[86:87], v[114:115], v[86:87] neg_lo:[0,1] neg_hi:[0,1]
	v_pk_add_f32 v[128:129], v[122:123], v[116:117] neg_lo:[0,1] neg_hi:[0,1]
	v_pk_add_f32 v[116:117], v[122:123], v[116:117]
	v_pk_add_f32 v[96:97], v[94:95], v[86:87] neg_lo:[0,1] neg_hi:[0,1]
	v_pk_add_f32 v[86:87], v[94:95], v[86:87]
	v_mov_b32_e32 v122, v128
	v_mov_b32_e32 v123, v117
	v_mov_b32_e32 v94, v96
	v_mov_b32_e32 v95, v87
	v_pk_mov_b32 v[114:115], v[106:107], v[120:121] op_sel:[1,0]
	v_pk_mov_b32 v[106:107], v[120:121], v[106:107] op_sel:[1,0]
	v_mov_b32_e32 v112, v90
	v_mov_b32_e32 v109, v93
	v_pk_mov_b32 v[90:91], v[90:91], v[92:93] op_sel:[1,0]
	v_pk_mov_b32 v[88:89], v[88:89], v[102:103] op_sel:[1,0]
	ds_write2_b64 v85, v[122:123], v[94:95] offset0:64 offset1:80
	v_pk_add_f32 v[94:95], v[118:119], v[132:133] neg_lo:[0,1] neg_hi:[0,1]
	v_pk_add_f32 v[106:107], v[114:115], v[106:107] neg_lo:[0,1] neg_hi:[0,1]
	v_pk_add_f32 v[108:109], v[112:113], v[108:109] neg_lo:[0,1] neg_hi:[0,1]
	v_pk_add_f32 v[88:89], v[90:91], v[88:89] neg_lo:[0,1] neg_hi:[0,1]
	v_pk_add_f32 v[114:115], v[94:95], v[106:107] neg_lo:[0,1] neg_hi:[0,1]
	v_pk_add_f32 v[94:95], v[94:95], v[106:107]
	v_pk_add_f32 v[90:91], v[108:109], v[88:89] neg_lo:[0,1] neg_hi:[0,1]
	v_pk_add_f32 v[88:89], v[108:109], v[88:89]
	v_mov_b32_e32 v106, v114
	v_mov_b32_e32 v107, v95
	v_mov_b32_e32 v92, v90
	v_mov_b32_e32 v93, v89
	ds_write2_b64 v85, v[106:107], v[92:93] offset0:96 offset1:112
	v_pk_mov_b32 v[92:93], v[176:177], v[174:175] op_sel:[1,0]
	v_pk_mov_b32 v[102:103], v[174:175], v[176:177] op_sel:[1,0]
	v_pk_add_f32 v[98:99], v[98:99], v[104:105] neg_lo:[0,1] neg_hi:[0,1]
	v_pk_add_f32 v[92:93], v[92:93], v[102:103] neg_lo:[0,1] neg_hi:[0,1]
	ds_write2_b64 v85, v[92:93], v[98:99] offset0:128 offset1:144
	v_mov_b32_e32 v98, v110
	v_mov_b32_e32 v99, v101
	v_mov_b32_e32 v101, v111
	s_nop 0
	v_pk_add_f32 v[92:93], v[124:125], v[126:127] neg_lo:[0,1] neg_hi:[0,1]
	v_pk_add_f32 v[98:99], v[98:99], v[100:101] neg_lo:[0,1] neg_hi:[0,1]
	v_mov_b32_e32 v117, v129
	v_mov_b32_e32 v87, v97
	v_mov_b32_e32 v95, v115
	v_mov_b32_e32 v89, v91
	v_add_u32_e32 v62, 0x2000, v62
	s_nop 0
	ds_write2_b64 v85, v[92:93], v[98:99] offset0:160 offset1:176
	ds_write2_b64 v85, v[116:117], v[86:87] offset0:192 offset1:208
	ds_write2_b64 v85, v[94:95], v[88:89] offset0:224 offset1:240
	s_nop 0
	v_add_u32_e32 v84, 0x200, v84
	s_nop 0
	s_waitcnt lgkmcnt(15)
	v_mul_f32_e32 v119, v9, v220
	s_waitcnt lgkmcnt(14)
	v_mul_f32_e32 v94, v5, v227
	v_mul_f32_e32 v124, v10, v220
	v_mul_f32_e32 v220, v19, v223
	v_pk_fma_f32 v[112:113], v[4:5], v[226:227], v[94:95] op_sel_hi:[1,1,0] neg_lo:[0,0,1] neg_hi:[0,0,1]
	v_mul_f32_e32 v114, v6, v227
	v_mul_f32_e32 v116, v5, v226
	v_mul_f32_e32 v121, v10, v221
	v_mul_f32_e32 v122, v9, v221
	v_pk_mul_f32 v[126:127], v[18:19], v[222:223] op_sel_hi:[1,0]
	v_pk_mul_f32 v[128:129], v[62:63], v[222:223]
	v_pk_fma_f32 v[130:131], v[18:19], v[222:223], v[220:221] op_sel_hi:[1,1,0] neg_lo:[1,0,0] neg_hi:[1,0,0]
	s_nop 0
	s_waitcnt lgkmcnt(12)
	v_mov_b32_e32 v133, v235
	s_waitcnt lgkmcnt(11)
	v_mov_b32_e32 v132, v239
	v_pk_mul_f32 v[132:133], v[58:59], v[132:133]
	v_mov_b32_e32 v134, v238
	v_mov_b32_e32 v135, v234
	v_pk_fma_f32 v[132:133], v[12:13], v[134:135], v[132:133]
	s_waitcnt lgkmcnt(10)
	v_pk_mov_b32 v[134:135], v[244:245], v[232:233] op_sel:[1,0]
	v_mov_b32_e32 v232, v244
	v_pk_mul_f32 v[140:141], v[10:11], v[232:233]
	s_waitcnt lgkmcnt(8)
	v_mov_b32_e32 v142, v253
	v_mov_b32_e32 v253, v244
	v_mov_b32_e32 v136, v251
	v_mov_b32_e32 v137, v239
	v_mov_b32_e32 v143, v245
	v_pk_mul_f32 v[244:245], v[10:11], v[252:253]
	v_pk_fma_f32 v[144:145], v[8:9], v[134:135], v[140:141]
	v_pk_fma_f32 v[140:141], v[8:9], v[134:135], v[140:141] neg_lo:[0,0,1] neg_hi:[0,0,1]
	v_pk_mov_b32 v[156:157], v[230:231], v[246:247] op_sel:[1,0]
	v_pk_mul_f32 v[134:135], v[10:11], v[134:135]
	v_pk_mul_f32 v[138:139], v[6:7], v[136:137]
	v_mov_b32_e32 v251, v238
	v_mov_b32_e32 v146, v230
	v_mov_b32_e32 v147, v247
	v_pk_mul_f32 v[156:157], v[68:69], v[156:157]
	v_mov_b32_e32 v158, v255
	v_mov_b32_e32 v255, v246
	v_pk_fma_f32 v[244:245], v[8:9], v[142:143], v[244:245] neg_lo:[0,0,1] neg_hi:[0,0,1]
	v_mov_b32_e32 v168, v238
	v_mov_b32_e32 v169, v235
	v_pk_mov_b32 v[234:235], v[238:239], v[234:235] op_sel:[1,0]
	v_pk_mul_f32 v[238:239], v[64:65], v[136:137]
	v_pk_mul_f32 v[136:137], v[10:11], v[142:143]
	v_pk_fma_f32 v[142:143], v[8:9], v[232:233], v[134:135] neg_lo:[0,0,1] neg_hi:[0,0,1]
	v_pk_fma_f32 v[232:233], v[8:9], v[232:233], v[134:135]
	v_mov_b32_e32 v135, v246
	v_mov_b32_e32 v246, v231
	v_mov_b32_e32 v141, v145
	v_pk_fma_f32 v[146:147], v[66:67], v[146:147], v[156:157] neg_lo:[0,0,1] neg_hi:[0,0,1]
	v_pk_mov_b32 v[156:157], v[236:237], v[228:229] op_sel:[1,0]
	v_pk_mul_f32 v[234:235], v[68:69], v[234:235]
	v_mov_b32_e32 v134, v230
	v_pk_mul_f32 v[230:231], v[58:59], v[246:247]
	v_pk_add_f32 v[156:157], v[156:157], v[140:141]
	v_pk_add_f32 v[162:163], v[146:147], v[132:133] op_sel:[1,0] op_sel_hi:[0,1]
	v_pk_fma_f32 v[234:235], v[66:67], v[168:169], v[234:235] neg_lo:[0,0,1] neg_hi:[0,0,1]
	v_mov_b32_e32 v233, v143
	v_pk_fma_f32 v[230:231], v[12:13], v[134:135], v[230:231]
	v_mov_b32_e32 v134, v236
	v_mov_b32_e32 v135, v229
	v_mov_b32_e32 v159, v247
; DI float2 twid(float r) { return float2{__builtin_amdgcn_cosf(r), -__builtin_amdgcn_sinf(r)}; }
; DI void bfly_inv(float2 s0, float2 s1, float2 s2, float2 s3, float r, float2& o0, float2& o1, float2& o2, float2& o3) {
;   float2 w1 = twid(r), w2 = cmul(w1, w1), w3 = cmul(w2, w1);
;   float2 c0 = s0, c1 = cmulc(s1, w1), c2 = cmulc(s2, w2), c3 = cmulc(s3, w3);
;   float2 t0 = {c0.x + c2.x, c0.y + c2.y}, t1 = {c0.x - c2.x, c0.y - c2.y}, t2 = {c1.x + c3.x, c1.y + c3.y}, t3 = {c1.x - c3.x, c1.y - c3.y};
;   o0 = float2{t0.x + t2.x, t0.y + t2.y}; o2 = float2{t0.x - t2.x, t0.y - t2.y}; o1 = float2{t1.x - t3.y, t1.y + t3.x}; o3 = float2{t1.x + t3.y, t1.y - t3.x};
; }
;     ...
;   for (int gg = tid; gg < NBT * (N / 16); gg += NTHR) { const int g = gg & (N / 16 - 1); float2* z = z0 + (gg / (N / 16)) * N; const int jp = g & (Q2 - 1), base = ((g >> lq2) << (lq2 + 4)) + jp; float2 x[4][4];
; #pragma unroll
;     for (int q1 = 0; q1 < 4; ++q1)
; #pragma unroll
;       for (int q2 = 0; q2 < 4; ++q2) x[q1][q2] = z[base + q1 * Q1 + q2 * Q2];
; #pragma unroll
;     for (int q1 = 0; q1 < 4; ++q1) bfly_inv(x[q1][0], x[q1][1], x[q1][2], x[q1][3], (float)jp * invM2, x[q1][0], x[q1][1], x[q1][2], x[q1][3]);
; #pragma unroll
;     for (int q2 = 0; q2 < 4; ++q2) bfly_inv(x[0][q2], x[1][q2], x[2][q2], x[3][q2], (float)(jp + q2 * Q2) * invM1, x[0][q2], x[1][q2], x[2][q2], x[3][q2]);
; #pragma unroll
;     for (int q1 = 0; q1 < 4; ++q1)
; #pragma unroll
;       for (int q2 = 0; q2 < 4; ++q2) z[base + q1 * Q1 + q2 * Q2] = x[q1][q2]; }
	v_pk_mul_f32 v[160:161], v[72:73], v[254:255]
	v_pk_fma_f32 v[138:139], v[64:65], v[250:251], v[138:139]
	v_mov_b32_e32 v118, v157
	v_mov_b32_e32 v120, v163
	v_pk_add_f32 v[134:135], v[134:135], v[232:233]
	v_pk_fma_f32 v[238:239], v[6:7], v[250:251], v[238:239] neg_lo:[0,0,1] neg_hi:[0,0,1]
	v_pk_add_f32 v[250:251], v[230:231], v[234:235] op_sel:[1,0] op_sel_hi:[0,1]
	v_pk_fma_f32 v[160:161], v[70:71], v[158:159], v[160:161] neg_lo:[0,0,1] neg_hi:[0,0,1]
	v_pk_add_f32 v[118:119], v[118:119], v[120:121]
	v_mov_b32_e32 v120, v249
	v_mov_b32_e32 v121, v237
	v_pk_mul_f32 v[246:247], v[72:73], v[158:159]
	v_mov_b32_e32 v126, v135
	v_mov_b32_e32 v128, v251
	v_pk_add_f32 v[120:121], v[120:121], v[244:245]
	v_pk_add_f32 v[164:165], v[138:139], v[160:161]
	v_pk_fma_f32 v[252:253], v[8:9], v[252:253], v[136:137]
	v_pk_fma_f32 v[246:247], v[70:71], v[254:255], v[246:247]
	v_pk_add_f32 v[254:255], v[126:127], v[128:129]
	v_mov_b32_e32 v126, v248
	v_mov_b32_e32 v127, v236
	v_mov_b32_e32 v123, v120
	v_mov_b32_e32 v125, v164
	v_pk_add_f32 v[126:127], v[126:127], v[252:253]
	v_pk_add_f32 v[128:129], v[238:239], v[246:247]
	v_pk_add_f32 v[166:167], v[122:123], v[124:125]
	v_pk_add_f32 v[122:123], v[122:123], v[124:125] neg_lo:[0,1] neg_hi:[0,1]
	v_mov_b32_e32 v117, v126
	v_mov_b32_e32 v115, v128
	v_pk_mov_b32 v[170:171], v[224:225], v[224:225] op_sel:[1,0]
	v_mov_b32_e32 v124, v122
	v_mov_b32_e32 v125, v167
	v_pk_add_f32 v[114:115], v[116:117], v[114:115]
	v_mov_b32_e32 v15, v171
	v_mov_b32_e32 v131, v23
	v_mov_b32_e32 v171, v22
	v_pk_add_f32 v[116:117], v[134:135], v[250:251]
	v_pk_mul_f32 v[182:183], v[130:131], v[114:115]
	v_pk_add_f32 v[184:185], v[130:131], v[114:115]
	v_pk_mul_f32 v[166:167], v[170:171], v[166:167]
	v_pk_add_f32 v[124:125], v[170:171], v[124:125]
	v_pk_add_f32 v[136:137], v[156:157], v[162:163]
	v_mov_b32_e32 v182, v184
	v_mov_b32_e32 v166, v124
	v_pk_mul_f32 v[116:117], v[20:21], v[116:117]
	v_mov_b32_e32 v17, v112
	v_pk_add_f32 v[172:173], v[14:15], v[118:119]
	v_pk_mul_f32 v[174:175], v[14:15], v[118:119]
	v_pk_fma_f32 v[116:117], v[24:25], v[136:137], v[116:117] neg_lo:[0,0,1] neg_hi:[0,0,1]
	v_pk_add_f32 v[136:137], v[182:183], v[166:167]
	v_pk_mov_b32 v[118:119], v[118:119], v[122:123] op_sel:[1,0]
	v_mov_b32_e32 v115, v112
	v_mov_b32_e32 v131, v255
	v_pk_mov_b32 v[182:183], v[234:235], v[246:247] op_sel:[1,0]
	v_mov_b32_e32 v239, v146
	v_mov_b32_e32 v247, v133
	v_pk_add_f32 v[158:159], v[16:17], v[254:255]
	v_pk_mul_f32 v[168:169], v[16:17], v[254:255]
	v_pk_add_f32 v[224:225], v[224:225], v[118:119] neg_lo:[0,1] neg_hi:[0,1]
	v_pk_add_f32 v[254:255], v[114:115], v[130:131] neg_lo:[0,1] neg_hi:[0,1]
	v_mov_b32_e32 v118, v248
	v_mov_b32_e32 v119, v228
	v_mov_b32_e32 v122, v252
	v_mov_b32_e32 v123, v145
	v_pk_mov_b32 v[130:131], v[144:145], v[244:245] op_sel:[1,0]
	v_mov_b32_e32 v139, v230
	v_mov_b32_e32 v144, v230
	v_mov_b32_e32 v145, v238
	v_pk_add_f32 v[238:239], v[238:239], v[246:247] neg_lo:[0,1] neg_hi:[0,1]
	v_pk_mov_b32 v[246:247], v[132:133], v[160:161] op_sel:[1,0]
	v_mov_b32_e32 v233, v140
	v_mov_b32_e32 v133, v234
	v_mov_b32_e32 v230, v147
	v_pk_add_f32 v[118:119], v[118:119], v[122:123] neg_lo:[0,1] neg_hi:[0,1]
	v_mov_b32_e32 v122, v228
	v_mov_b32_e32 v123, v249
	v_pk_mov_b32 v[186:187], v[228:229], v[248:249] op_sel:[1,0]
	v_mov_b32_e32 v228, v249
	v_mov_b32_e32 v245, v143
	v_pk_add_f32 v[232:233], v[236:237], v[232:233] neg_lo:[0,1] neg_hi:[0,1]
	v_pk_add_f32 v[230:231], v[132:133], v[230:231] neg_lo:[0,1] neg_hi:[0,1]
	v_pk_add_f32 v[122:123], v[122:123], v[130:131] neg_lo:[0,1] neg_hi:[0,1]
	v_mov_b32_e32 v130, v160
	v_mov_b32_e32 v131, v235
	v_pk_mov_b32 v[252:253], v[142:143], v[252:253] op_sel:[1,0]
	v_pk_add_f32 v[228:229], v[228:229], v[244:245] neg_lo:[0,1] neg_hi:[0,1]
	v_mov_b32_e32 v244, v146
	v_mov_b32_e32 v245, v138
	v_pk_add_f32 v[234:235], v[232:233], v[230:231] neg_lo:[0,1] neg_hi:[0,1]
	v_pk_add_f32 v[236:237], v[232:233], v[230:231]
	v_pk_add_f32 v[176:177], v[126:127], v[128:129]
	v_pk_mov_b32 v[166:167], v[170:171], v[24:25] op_sel:[1,0]
	v_pk_add_f32 v[130:131], v[138:139], v[130:131] neg_lo:[0,1] neg_hi:[0,1]
	v_pk_add_f32 v[252:253], v[186:187], v[252:253] neg_lo:[0,1] neg_hi:[0,1]
	v_pk_add_f32 v[244:245], v[244:245], v[246:247] neg_lo:[0,1] neg_hi:[0,1]
	v_mov_b32_e32 v249, v237
	v_pk_mov_b32 v[236:237], v[236:237], v[234:235] op_sel:[1,0]
	v_pk_add_f32 v[178:179], v[120:121], v[164:165]
	v_pk_mul_f32 v[166:167], v[166:167], v[176:177]
	v_pk_add_f32 v[144:145], v[144:145], v[182:183] neg_lo:[0,1] neg_hi:[0,1]
	v_pk_add_f32 v[246:247], v[252:253], v[244:245] neg_lo:[0,1] neg_hi:[0,1]
	v_mov_b32_e32 v248, v234
	v_pk_add_f32 v[118:119], v[118:119], v[130:131] neg_lo:[0,1] neg_hi:[0,1]
	v_pk_add_f32 v[130:131], v[252:253], v[244:245]
	v_pk_mul_f32 v[236:237], v[32:33], v[236:237]
	v_mov_b32_e32 v169, v159
	v_mov_b32_e32 v175, v173
	v_pk_fma_f32 v[170:171], v[74:75], v[178:179], v[166:167]
	v_pk_fma_f32 v[166:167], v[74:75], v[178:179], v[166:167] neg_lo:[0,0,1] neg_hi:[0,0,1]
	v_pk_add_f32 v[182:183], v[122:123], v[144:145]
	v_mov_b32_e32 v131, v247
	v_pk_add_f32 v[132:133], v[122:123], v[144:145] neg_lo:[0,1] neg_hi:[0,1]
	v_pk_add_f32 v[228:229], v[228:229], v[238:239]
	v_pk_fma_f32 v[234:235], v[30:31], v[234:235], v[236:237]
	v_pk_fma_f32 v[236:237], v[30:31], v[248:249], v[236:237] neg_lo:[0,0,1] neg_hi:[0,0,1]
	v_pk_add_f32 v[168:169], v[174:175], v[168:169]
	v_mov_b32_e32 v167, v171
	v_pk_add_f32 v[112:113], v[224:225], v[254:255] neg_lo:[0,1] neg_hi:[0,1]
	v_pk_add_f32 v[114:115], v[224:225], v[254:255]
	v_mov_b32_e32 v133, v183
	v_mov_b32_e32 v235, v237
; DI float2 twid(float r) { return float2{__builtin_amdgcn_cosf(r), -__builtin_amdgcn_sinf(r)}; }
; DI void bfly_inv(float2 s0, float2 s1, float2 s2, float2 s3, float r, float2& o0, float2& o1, float2& o2, float2& o3) {
;   float2 w1 = twid(r), w2 = cmul(w1, w1), w3 = cmul(w2, w1);
;   float2 c0 = s0, c1 = cmulc(s1, w1), c2 = cmulc(s2, w2), c3 = cmulc(s3, w3);
;   float2 t0 = {c0.x + c2.x, c0.y + c2.y}, t1 = {c0.x - c2.x, c0.y - c2.y}, t2 = {c1.x + c3.x, c1.y + c3.y}, t3 = {c1.x - c3.x, c1.y - c3.y};
;   o0 = float2{t0.x + t2.x, t0.y + t2.y}; o2 = float2{t0.x - t2.x, t0.y - t2.y}; o1 = float2{t1.x - t3.y, t1.y + t3.x}; o3 = float2{t1.x + t3.y, t1.y - t3.x};
; }
;     ...
;   for (int gg = tid; gg < NBT * (N / 16); gg += NTHR) { const int g = gg & (N / 16 - 1); float2* z = z0 + (gg / (N / 16)) * N; const int jp = g & (Q2 - 1), base = ((g >> lq2) << (lq2 + 4)) + jp; float2 x[4][4];
; #pragma unroll
;     for (int q1 = 0; q1 < 4; ++q1)
; #pragma unroll
;       for (int q2 = 0; q2 < 4; ++q2) x[q1][q2] = z[base + q1 * Q1 + q2 * Q2];
; #pragma unroll
;     for (int q1 = 0; q1 < 4; ++q1) bfly_inv(x[q1][0], x[q1][1], x[q1][2], x[q1][3], (float)jp * invM2, x[q1][0], x[q1][1], x[q1][2], x[q1][3]);
; #pragma unroll
;     for (int q2 = 0; q2 < 4; ++q2) bfly_inv(x[0][q2], x[1][q2], x[2][q2], x[3][q2], (float)(jp + q2 * Q2) * invM1, x[0][q2], x[1][q2], x[2][q2], x[3][q2]);
; #pragma unroll
;     for (int q1 = 0; q1 < 4; ++q1)
; #pragma unroll
;       for (int q2 = 0; q2 < 4; ++q2) z[base + q1 * Q1 + q2 * Q2] = x[q1][q2]; }
	v_pk_mul_f32 v[228:229], v[28:29], v[228:229]
	v_pk_mul_f32 v[236:237], v[52:53], v[130:131]
	v_pk_add_f32 v[174:175], v[116:117], v[136:137]
	v_pk_add_f32 v[176:177], v[168:169], v[166:167]
	v_mov_b32_e32 v114, v112
	v_pk_fma_f32 v[228:229], v[26:27], v[118:119], v[228:229]
	v_pk_fma_f32 v[236:237], v[50:51], v[132:133], v[236:237] neg_lo:[0,0,1] neg_hi:[0,0,1]
	v_pk_add_f32 v[178:179], v[174:175], v[176:177]
	v_pk_add_f32 v[238:239], v[114:115], v[234:235]
	v_pk_add_f32 v[248:249], v[236:237], v[228:229]
	v_pk_mov_b32 v[178:179], v[178:179], v[178:179] op_sel:[1,0]
	v_pk_add_f32 v[118:119], v[238:239], v[248:249]
	ds_write2_b64 v219, v[178:179], v[118:119] offset1:16
	v_pk_mov_b32 v[118:119], v[172:173], v[124:125] op_sel:[1,0]
	v_pk_mov_b32 v[124:125], v[158:159], v[184:185] op_sel:[1,0]
	v_mov_b32_e32 v130, v250
	v_pk_add_f32 v[118:119], v[118:119], v[124:125] neg_lo:[0,1] neg_hi:[0,1]
	v_mov_b32_e32 v124, v134
	v_mov_b32_e32 v125, v156
	v_mov_b32_e32 v131, v162
	v_pk_add_f32 v[124:125], v[124:125], v[130:131] neg_lo:[0,1] neg_hi:[0,1]
	v_mov_b32_e32 v130, v126
	v_mov_b32_e32 v131, v157
	v_mov_b32_e32 v132, v128
	v_mov_b32_e32 v133, v163
	v_pk_mov_b32 v[126:127], v[134:135], v[126:127] op_sel:[1,0]
	v_pk_mov_b32 v[128:129], v[250:251], v[128:129] op_sel:[1,0]
	v_mov_b32_e32 v252, v232
	v_mov_b32_e32 v244, v230
	v_pk_add_f32 v[130:131], v[130:131], v[132:133] neg_lo:[0,1] neg_hi:[0,1]
	v_pk_add_f32 v[126:127], v[126:127], v[128:129] neg_lo:[0,1] neg_hi:[0,1]
	v_pk_mov_b32 v[128:129], v[156:157], v[120:121] op_sel:[1,0]
	v_pk_mov_b32 v[132:133], v[162:163], v[164:165] op_sel:[1,0]
	v_mov_b32_e32 v121, v135
	v_mov_b32_e32 v165, v251
	v_pk_add_f32 v[244:245], v[252:253], v[244:245]
	v_mov_b32_e32 v122, v233
	v_mov_b32_e32 v144, v231
	v_pk_add_f32 v[250:251], v[120:121], v[164:165] neg_lo:[0,1] neg_hi:[0,1]
	v_pk_mul_f32 v[120:121], v[40:41], v[124:125] op_sel:[0,1] op_sel_hi:[1,0]
	v_pk_add_f32 v[230:231], v[122:123], v[144:145] neg_lo:[0,1] neg_hi:[0,1]
	v_mov_b32_e32 v247, v244
	v_mul_f32_e32 v255, v44, v246
	v_pk_add_f32 v[128:129], v[128:129], v[132:133] neg_lo:[0,1] neg_hi:[0,1]
	v_pk_fma_f32 v[132:133], v[38:39], v[124:125], v[120:121]
	v_pk_fma_f32 v[120:121], v[38:39], v[124:125], v[120:121] neg_lo:[0,0,1] neg_hi:[0,0,1]
	v_pk_mul_f32 v[232:233], v[42:43], v[246:247]
	v_mov_b32_e32 v246, v245
	v_mov_b32_e32 v247, v231
	v_mul_f32_e32 v252, v49, v231
	v_pk_mul_f32 v[244:245], v[46:47], v[244:245]
	v_mul_f32_e32 v225, v42, v182
	v_mov_b32_e32 v133, v121
	v_pk_mul_f32 v[250:251], v[36:37], v[250:251]
	v_pk_mul_f32 v[120:121], v[56:57], v[126:127]
	v_mov_b32_e32 v183, v230
	v_pk_fma_f32 v[246:247], v[48:49], v[246:247], v[252:253] op_sel_hi:[1,1,0]
	v_pk_fma_f32 v[252:253], v[60:61], v[230:231], v[244:245]
	v_pk_fma_f32 v[230:231], v[60:61], v[230:231], v[244:245] neg_lo:[0,0,1] neg_hi:[0,0,1]
	v_pk_fma_f32 v[250:251], v[34:35], v[130:131], v[250:251]
	v_pk_fma_f32 v[120:121], v[54:55], v[128:129], v[120:121] neg_lo:[0,0,1] neg_hi:[0,0,1]
	v_pk_add_f32 v[224:225], v[224:225], v[254:255]
	v_pk_fma_f32 v[232:233], v[44:45], v[182:183], v[232:233] neg_lo:[0,0,1] neg_hi:[0,0,1]
	v_mov_b32_e32 v253, v231
	v_mov_b32_e32 v112, v246
	v_pk_add_f32 v[124:125], v[118:119], v[132:133]
	v_pk_add_f32 v[126:127], v[120:121], v[250:251]
	v_pk_add_f32 v[244:245], v[232:233], v[112:113]
	v_pk_add_f32 v[254:255], v[224:225], v[252:253]
	v_pk_add_f32 v[128:129], v[124:125], v[126:127]
	v_pk_add_f32 v[122:123], v[244:245], v[254:255]
	ds_write2_b64 v219, v[128:129], v[122:123] offset0:32 offset1:48
	v_pk_mov_b32 v[122:123], v[168:169], v[136:137] op_sel:[1,0]
	v_pk_mov_b32 v[128:129], v[170:171], v[116:117] op_sel:[1,0]
	v_mov_b32_e32 v169, v117
	v_mov_b32_e32 v167, v137
	v_pk_add_f32 v[234:235], v[114:115], v[234:235] neg_lo:[0,1] neg_hi:[0,1]
	v_pk_mov_b32 v[114:115], v[228:229], v[236:237] op_sel:[1,0]
	v_pk_mov_b32 v[228:229], v[236:237], v[228:229] op_sel:[1,0]
	v_pk_add_f32 v[122:123], v[122:123], v[128:129] neg_lo:[0,1] neg_hi:[0,1]
	v_pk_add_f32 v[116:117], v[168:169], v[166:167] neg_lo:[0,1] neg_hi:[0,1]
	v_pk_add_f32 v[228:229], v[114:115], v[228:229] neg_lo:[0,1] neg_hi:[0,1]
	v_pk_add_f32 v[128:129], v[122:123], v[116:117] neg_lo:[0,1] neg_hi:[0,1]
	v_pk_add_f32 v[116:117], v[122:123], v[116:117]
	v_pk_add_f32 v[236:237], v[234:235], v[228:229] neg_lo:[0,1] neg_hi:[0,1]
	v_pk_add_f32 v[228:229], v[234:235], v[228:229]
	v_mov_b32_e32 v122, v128
	v_mov_b32_e32 v123, v117
	v_mov_b32_e32 v234, v236
	v_mov_b32_e32 v235, v229
	v_pk_mov_b32 v[114:115], v[250:251], v[120:121] op_sel:[1,0]
	v_pk_mov_b32 v[250:251], v[120:121], v[250:251] op_sel:[1,0]
	v_mov_b32_e32 v112, v224
	v_mov_b32_e32 v253, v233
	v_pk_mov_b32 v[224:225], v[224:225], v[232:233] op_sel:[1,0]
	v_pk_mov_b32 v[230:231], v[230:231], v[246:247] op_sel:[1,0]
	ds_write2_b64 v219, v[122:123], v[234:235] offset0:64 offset1:80
	v_pk_add_f32 v[234:235], v[118:119], v[132:133] neg_lo:[0,1] neg_hi:[0,1]
	v_pk_add_f32 v[250:251], v[114:115], v[250:251] neg_lo:[0,1] neg_hi:[0,1]
	v_pk_add_f32 v[252:253], v[112:113], v[252:253] neg_lo:[0,1] neg_hi:[0,1]
	v_pk_add_f32 v[230:231], v[224:225], v[230:231] neg_lo:[0,1] neg_hi:[0,1]
	v_pk_add_f32 v[114:115], v[234:235], v[250:251] neg_lo:[0,1] neg_hi:[0,1]
	v_pk_add_f32 v[234:235], v[234:235], v[250:251]
	v_pk_add_f32 v[224:225], v[252:253], v[230:231] neg_lo:[0,1] neg_hi:[0,1]
	v_pk_add_f32 v[230:231], v[252:253], v[230:231]
	v_mov_b32_e32 v250, v114
	v_mov_b32_e32 v251, v235
	v_mov_b32_e32 v232, v224
	v_mov_b32_e32 v233, v231
	ds_write2_b64 v219, v[250:251], v[232:233] offset0:96 offset1:112
	v_pk_mov_b32 v[232:233], v[176:177], v[174:175] op_sel:[1,0]
	v_pk_mov_b32 v[246:247], v[174:175], v[176:177] op_sel:[1,0]
	v_pk_add_f32 v[238:239], v[238:239], v[248:249] neg_lo:[0,1] neg_hi:[0,1]
	v_pk_add_f32 v[232:233], v[232:233], v[246:247] neg_lo:[0,1] neg_hi:[0,1]
	ds_write2_b64 v219, v[232:233], v[238:239] offset0:128 offset1:144
	v_mov_b32_e32 v238, v254
	v_mov_b32_e32 v239, v245
	v_mov_b32_e32 v245, v255
	s_nop 0
	v_pk_add_f32 v[232:233], v[124:125], v[126:127] neg_lo:[0,1] neg_hi:[0,1]
	v_pk_add_f32 v[238:239], v[238:239], v[244:245] neg_lo:[0,1] neg_hi:[0,1]
	v_mov_b32_e32 v117, v129
	v_mov_b32_e32 v229, v237
	v_mov_b32_e32 v235, v115
	v_mov_b32_e32 v231, v225
	v_add_u32_e32 v62, 0x2000, v62
	s_nop 0
	ds_write2_b64 v219, v[232:233], v[238:239] offset0:160 offset1:176
	ds_write2_b64 v219, v[116:117], v[228:229] offset0:192 offset1:208
	ds_write2_b64 v219, v[234:235], v[230:231] offset0:224 offset1:240
	s_nop 0
	v_add_u32_e32 v15, 0x200, v84
	s_nop 0
	v_mov_b32_e32 v84, v15
; DI float2 twid(float r) { return float2{__builtin_amdgcn_cosf(r), -__builtin_amdgcn_sinf(r)}; }
; DI void bfly_inv(float2 s0, float2 s1, float2 s2, float2 s3, float r, float2& o0, float2& o1, float2& o2, float2& o3) {
;   float2 w1 = twid(r), w2 = cmul(w1, w1), w3 = cmul(w2, w1);
;   float2 c0 = s0, c1 = cmulc(s1, w1), c2 = cmulc(s2, w2), c3 = cmulc(s3, w3);
;   float2 t0 = {c0.x + c2.x, c0.y + c2.y}, t1 = {c0.x - c2.x, c0.y - c2.y}, t2 = {c1.x + c3.x, c1.y + c3.y}, t3 = {c1.x - c3.x, c1.y - c3.y};
;   o0 = float2{t0.x + t2.x, t0.y + t2.y}; o2 = float2{t0.x - t2.x, t0.y - t2.y}; o1 = float2{t1.x - t3.y, t1.y + t3.x}; o3 = float2{t1.x + t3.y, t1.y - t3.x};
; }
;     ...
;   for (int gg = tid; gg < NBT * (N / 16); gg += NTHR) { const int g = gg & (N / 16 - 1); float2* z = z0 + (gg / (N / 16)) * N; const int jp = g & (Q2 - 1), base = ((g >> lq2) << (lq2 + 4)) + jp; float2 x[4][4];
; #pragma unroll
;     for (int q1 = 0; q1 < 4; ++q1)
; #pragma unroll
;       for (int q2 = 0; q2 < 4; ++q2) x[q1][q2] = z[base + q1 * Q1 + q2 * Q2];
; #pragma unroll
;     for (int q1 = 0; q1 < 4; ++q1) bfly_inv(x[q1][0], x[q1][1], x[q1][2], x[q1][3], (float)jp * invM2, x[q1][0], x[q1][1], x[q1][2], x[q1][3]);
; #pragma unroll
;     for (int q2 = 0; q2 < 4; ++q2) bfly_inv(x[0][q2], x[1][q2], x[2][q2], x[3][q2], (float)(jp + q2 * Q2) * invM1, x[0][q2], x[1][q2], x[2][q2], x[3][q2]);
; #pragma unroll
;     for (int q1 = 0; q1 < 4; ++q1)
; #pragma unroll
;       for (int q2 = 0; q2 < 4; ++q2) z[base + q1 * Q1 + q2 * Q2] = x[q1][q2]; }
.LBB0_1651:
	s_or_b64 exec, exec, s[14:15]
	s_waitcnt lgkmcnt(0)
	s_barrier
	s_and_saveexec_b64 s[12:13], vcc
	s_cbranch_execz .LBB0_1654
	v_sin_f32_e32 v5, v82
	v_cos_f32_e32 v6, v82
	v_sin_f32_e32 v14, v81
	v_cos_f32_e32 v16, v81
	v_xor_b32_e32 v10, 0x80000000, v5
	v_mov_b32_e32 v4, v6
	v_mov_b32_e32 v8, v10
	v_mov_b32_e32 v9, v5
	v_mov_b32_e32 v7, v6
	v_mov_b32_e32 v11, v6
	v_pk_mul_f32 v[12:13], v[4:5], v[8:9]
	v_mov_b32_e32 v58, v6
	v_pk_fma_f32 v[8:9], v[6:7], v[10:11], v[12:13] op_sel_hi:[0,1,1] neg_lo:[0,0,1] neg_hi:[0,0,1]
	v_pk_fma_f32 v[10:11], v[6:7], v[10:11], v[12:13] op_sel_hi:[0,1,1]
	s_nop 0
	v_pk_mov_b32 v[12:13], v[8:9], v[10:11] op_sel:[1,0]
	v_mov_b32_e32 v18, v10
	v_mov_b32_e32 v19, v9
	v_pk_mul_f32 v[20:21], v[4:5], v[12:13] op_sel:[1,0]
	v_mul_f32_e64 v11, v16, -v14
	v_pk_fma_f32 v[12:13], v[6:7], v[18:19], v[20:21] op_sel_hi:[0,1,1]
	v_pk_fma_f32 v[18:19], v[6:7], v[18:19], v[20:21] op_sel_hi:[0,1,1] neg_lo:[0,0,1] neg_hi:[0,0,1]
	v_add_f32_e32 v20, v11, v11
	v_cvt_f32_u32_e32 v11, v80
	v_mul_f32_e32 v8, v14, v14
	v_fma_f32 v24, v16, v16, -v8
	v_mul_f32_e32 v23, v14, v20
	v_mul_f32_e32 v8, 0x39800000, v11
	v_sin_f32_e32 v27, v8
	v_cos_f32_e32 v29, v8
	v_cvt_f32_u32_e32 v11, v79
	v_mul_f32_e32 v8, v14, v24
	v_fma_f32 v22, v16, v20, -v8
	v_mul_f32_e32 v8, v27, v27
	v_fma_f32 v30, v29, v29, -v8
	v_mul_f32_e64 v8, v29, -v27
	v_add_f32_e32 v32, v8, v8
	v_mul_f32_e32 v8, 0x39800000, v11
	v_sin_f32_e32 v35, v8
	v_cos_f32_e32 v37, v8
	v_cvt_f32_u32_e32 v11, v78
	v_mul_f32_e32 v8, v27, v30
	v_fma_f32 v28, v29, v32, -v8
	v_mul_f32_e32 v8, v35, v35
	v_fma_f32 v38, v37, v37, -v8
	v_mul_f32_e64 v8, v37, -v35
	v_add_f32_e32 v40, v8, v8
	v_mul_f32_e32 v8, 0x39800000, v11
	v_sin_f32_e32 v42, v8
	v_cos_f32_e32 v44, v8
	v_mul_f32_e32 v26, v27, v32
	v_mul_f32_e32 v34, v35, v40
	v_xor_b32_e32 v45, 0x80000000, v42
	v_mov_b32_e32 v43, v44
	v_mov_b32_e32 v46, v42
	v_mov_b32_e32 v47, v45
	v_pk_mul_f32 v[48:49], v[42:43], v[46:47]
	v_mul_f32_e32 v8, v35, v38
	v_pk_fma_f32 v[46:47], v[44:45], v[44:45], v[48:49] op_sel_hi:[0,1,1] neg_lo:[0,0,1] neg_hi:[0,0,1]
	v_pk_fma_f32 v[62:63], v[44:45], v[44:45], v[48:49] op_sel_hi:[0,1,1]
	s_nop 0
	v_pk_mov_b32 v[50:51], v[62:63], v[46:47] op_sel:[1,0]
	v_mov_b32_e32 v48, v46
	v_mov_b32_e32 v49, v63
	v_pk_mul_f32 v[50:51], v[42:43], v[50:51] op_sel_hi:[0,1]
	v_fmac_f32_e32 v23, v16, v24
	v_fmac_f32_e32 v26, v29, v30
	v_fmac_f32_e32 v34, v37, v38
	v_fma_f32 v36, v37, v40, -v8
	v_pk_fma_f32 v[60:61], v[44:45], v[48:49], v[50:51] op_sel_hi:[0,1,1]
	v_pk_fma_f32 v[48:49], v[44:45], v[48:49], v[50:51] op_sel_hi:[0,1,1] neg_lo:[0,0,1] neg_hi:[0,0,1]
	v_mov_b32_e32 v21, v14
	v_mov_b32_e32 v19, v13
	v_mov_b32_e32 v48, v60
	v_mov_b32_e32 v11, v10
	v_mov_b32_e32 v31, v30
	v_mov_b32_e32 v33, v32
	v_pk_mov_b32 v[50:51], v[28:29], v[26:27] op_sel:[1,0]
	v_pk_mov_b32 v[52:53], v[26:27], v[28:29] op_sel:[1,0]
	v_mov_b32_e32 v39, v38
	v_pk_mov_b32 v[54:55], v[36:37], v[34:35] op_sel:[1,0]
	v_pk_mov_b32 v[56:57], v[34:35], v[36:37] op_sel:[1,0]
	v_mov_b32_e32 v59, v18
	v_mov_b32_e32 v12, v5
	v_pk_mov_b32 v[60:61], v[62:63], v[60:61] op_sel:[1,0]
	v_mov_b32_e32 v47, v49
	v_mov_b32_e32 v45, v46
	v_mov_b32_e32 v43, v63
	v_mov_b32_e32 v63, v18
	v_mov_b32_e32 v64, v5
	v_mov_b32_e32 v65, v5
	v_mov_b32_e32 v8, v9
	v_mov_b32_e32 v66, v6
	v_mov_b32_e32 v67, v13
	v_mov_b32_e32 v68, v5
	v_mov_b32_e32 v69, v18
	v_mov_b32_e32 v70, v13
	v_mov_b32_e32 v71, v13
	v_mov_b32_e32 v72, v18
	v_mov_b32_e32 v73, v18
	v_mov_b32_e32 v25, v16
	v_pk_mov_b32 v[74:75], v[22:23], v[20:21] op_sel:[1,0]
	v_mov_b32_e32 v41, v40
	s_mov_b64 s[0:1], 0
	v_mov_b32_e32 v62, v76
	v_ashrrev_i32_e32 v15, 31, v62
	v_lshrrev_b32_e32 v15, 22, v15
	v_add_lshl_u32 v15, v62, v15, 7
	v_and_b32_e32 v15, 0xfffe0000, v15
	v_and_b32_e32 v17, 0x3000, v77
	v_add_u32_e32 v15, 16, v15
	v_lshlrev_b32_e32 v17, 3, v17
	v_lshlrev_b32_sdwa v78, v151, v76 dst_sel:DWORD dst_unused:UNUSED_PAD src0_sel:DWORD src1_sel:BYTE_0
	v_add3_u32 v178, v15, v17, v78
	ds_read2st64_b64 v[78:81], v178 offset0:8 offset1:12
	ds_read2st64_b64 v[82:85], v178 offset1:4
	s_nop 0
	v_add_u32_e32 v77, 0x2000, v77
	s_nop 0
	s_waitcnt lgkmcnt(1)
	v_mul_f32_e32 v111, v9, v78
	s_waitcnt lgkmcnt(0)
	v_mul_f32_e32 v86, v5, v85
	v_mul_f32_e32 v116, v10, v78
	v_mul_f32_e32 v78, v19, v81
	v_pk_fma_f32 v[104:105], v[4:5], v[84:85], v[86:87] op_sel_hi:[1,1,0] neg_lo:[0,0,1] neg_hi:[0,0,1]
	v_mul_f32_e32 v106, v6, v85
	v_mul_f32_e32 v108, v5, v84
	v_mul_f32_e32 v113, v10, v79
	v_mul_f32_e32 v114, v9, v79
	v_pk_mul_f32 v[118:119], v[18:19], v[80:81] op_sel_hi:[1,0]
	v_pk_mul_f32 v[120:121], v[62:63], v[80:81]
	v_pk_fma_f32 v[122:123], v[18:19], v[80:81], v[78:79] op_sel_hi:[1,1,0] neg_lo:[1,0,0] neg_hi:[1,0,0]
	ds_read2st64_b64 v[78:81], v178 offset0:16 offset1:20
	ds_read2st64_b64 v[84:87], v178 offset0:24 offset1:28
	ds_read2st64_b64 v[88:91], v178 offset0:32 offset1:36
	ds_read2st64_b64 v[92:95], v178 offset0:40 offset1:44
	ds_read2st64_b64 v[96:99], v178 offset0:48 offset1:52
	ds_read2st64_b64 v[100:103], v178 offset0:56 offset1:60
	v_add_u32_e32 v218, 0x200, v62
	v_ashrrev_i32_e32 v252, 31, v218
	v_lshrrev_b32_e32 v252, 22, v252
	v_add_lshl_u32 v252, v218, v252, 7
	v_and_b32_e32 v252, 0xfffe0000, v252
	v_and_b32_e32 v253, 0x3000, v77
	v_add_u32_e32 v252, 16, v252
	v_lshlrev_b32_e32 v253, 3, v253
	v_lshlrev_b32_sdwa v254, v151, v76 dst_sel:DWORD dst_unused:UNUSED_PAD src0_sel:DWORD src1_sel:BYTE_0
	v_add3_u32 v219, v252, v253, v254
	ds_read2st64_b64 v[220:223], v219 offset0:8 offset1:12
	ds_read2st64_b64 v[224:227], v219 offset1:4
	ds_read2st64_b64 v[228:231], v219 offset0:16 offset1:20
	ds_read2st64_b64 v[232:235], v219 offset0:24 offset1:28
	ds_read2st64_b64 v[236:239], v219 offset0:32 offset1:36
	ds_read2st64_b64 v[244:247], v219 offset0:40 offset1:44
	ds_read2st64_b64 v[248:251], v219 offset0:48 offset1:52
	ds_read2st64_b64 v[252:255], v219 offset0:56 offset1:60
	s_waitcnt lgkmcnt(12)
; DI float2 twid(float r) { return float2{__builtin_amdgcn_cosf(r), -__builtin_amdgcn_sinf(r)}; }
; DI void bfly_inv(float2 s0, float2 s1, float2 s2, float2 s3, float r, float2& o0, float2& o1, float2& o2, float2& o3) {
;   float2 w1 = twid(r), w2 = cmul(w1, w1), w3 = cmul(w2, w1);
;   float2 c0 = s0, c1 = cmulc(s1, w1), c2 = cmulc(s2, w2), c3 = cmulc(s3, w3);
;   float2 t0 = {c0.x + c2.x, c0.y + c2.y}, t1 = {c0.x - c2.x, c0.y - c2.y}, t2 = {c1.x + c3.x, c1.y + c3.y}, t3 = {c1.x - c3.x, c1.y - c3.y};
;   o0 = float2{t0.x + t2.x, t0.y + t2.y}; o2 = float2{t0.x - t2.x, t0.y - t2.y}; o1 = float2{t1.x - t3.y, t1.y + t3.x}; o3 = float2{t1.x + t3.y, t1.y - t3.x};
; }
;     ...
;   for (int gg = tid; gg < NBT * (N / 16); gg += NTHR) { const int g = gg & (N / 16 - 1); float2* z = z0 + (gg / (N / 16)) * N; const int jp = g & (Q2 - 1), base = ((g >> lq2) << (lq2 + 4)) + jp; float2 x[4][4];
; #pragma unroll
;     for (int q1 = 0; q1 < 4; ++q1)
; #pragma unroll
;       for (int q2 = 0; q2 < 4; ++q2) x[q1][q2] = z[base + q1 * Q1 + q2 * Q2];
; #pragma unroll
;     for (int q1 = 0; q1 < 4; ++q1) bfly_inv(x[q1][0], x[q1][1], x[q1][2], x[q1][3], (float)jp * invM2, x[q1][0], x[q1][1], x[q1][2], x[q1][3]);
; #pragma unroll
;     for (int q2 = 0; q2 < 4; ++q2) bfly_inv(x[0][q2], x[1][q2], x[2][q2], x[3][q2], (float)(jp + q2 * Q2) * invM1, x[0][q2], x[1][q2], x[2][q2], x[3][q2]);
; #pragma unroll
;     for (int q1 = 0; q1 < 4; ++q1)
; #pragma unroll
;       for (int q2 = 0; q2 < 4; ++q2) z[base + q1 * Q1 + q2 * Q2] = x[q1][q2]; }
	v_mov_b32_e32 v125, v87
	s_waitcnt lgkmcnt(11)
	v_mov_b32_e32 v124, v91
	v_pk_mul_f32 v[124:125], v[58:59], v[124:125]
	v_mov_b32_e32 v126, v90
	v_mov_b32_e32 v127, v86
	v_pk_fma_f32 v[124:125], v[12:13], v[126:127], v[124:125]
	s_waitcnt lgkmcnt(10)
	v_pk_mov_b32 v[126:127], v[92:93], v[84:85] op_sel:[1,0]
	v_mov_b32_e32 v84, v92
	v_pk_mul_f32 v[132:133], v[10:11], v[84:85]
	s_waitcnt lgkmcnt(8)
	v_mov_b32_e32 v134, v101
	v_mov_b32_e32 v101, v92
	v_mov_b32_e32 v128, v99
	v_mov_b32_e32 v129, v91
	v_mov_b32_e32 v135, v93
	v_pk_mul_f32 v[92:93], v[10:11], v[100:101]
	v_pk_fma_f32 v[136:137], v[8:9], v[126:127], v[132:133]
	v_pk_fma_f32 v[132:133], v[8:9], v[126:127], v[132:133] neg_lo:[0,0,1] neg_hi:[0,0,1]
	v_pk_mov_b32 v[140:141], v[80:81], v[94:95] op_sel:[1,0]
	v_pk_mul_f32 v[126:127], v[10:11], v[126:127]
	v_pk_mul_f32 v[130:131], v[6:7], v[128:129]
	v_mov_b32_e32 v99, v90
	v_mov_b32_e32 v138, v80
	v_mov_b32_e32 v139, v95
	v_pk_mul_f32 v[140:141], v[68:69], v[140:141]
	v_mov_b32_e32 v142, v103
	v_mov_b32_e32 v103, v94
	v_pk_fma_f32 v[92:93], v[8:9], v[134:135], v[92:93] neg_lo:[0,0,1] neg_hi:[0,0,1]
	v_mov_b32_e32 v160, v90
	v_mov_b32_e32 v161, v87
	v_pk_mov_b32 v[86:87], v[90:91], v[86:87] op_sel:[1,0]
	v_pk_mul_f32 v[90:91], v[64:65], v[128:129]
	v_pk_mul_f32 v[128:129], v[10:11], v[134:135]
	v_pk_fma_f32 v[134:135], v[8:9], v[84:85], v[126:127] neg_lo:[0,0,1] neg_hi:[0,0,1]
	v_pk_fma_f32 v[84:85], v[8:9], v[84:85], v[126:127]
	v_mov_b32_e32 v127, v94
	v_mov_b32_e32 v94, v81
	v_mov_b32_e32 v133, v137
	v_pk_fma_f32 v[138:139], v[66:67], v[138:139], v[140:141] neg_lo:[0,0,1] neg_hi:[0,0,1]
	v_pk_mov_b32 v[140:141], v[88:89], v[78:79] op_sel:[1,0]
	v_pk_mul_f32 v[86:87], v[68:69], v[86:87]
	v_mov_b32_e32 v126, v80
	v_pk_mul_f32 v[80:81], v[58:59], v[94:95]
	v_pk_add_f32 v[140:141], v[140:141], v[132:133]
	v_pk_add_f32 v[146:147], v[138:139], v[124:125] op_sel:[1,0] op_sel_hi:[0,1]
	v_pk_fma_f32 v[86:87], v[66:67], v[160:161], v[86:87] neg_lo:[0,0,1] neg_hi:[0,0,1]
	v_mov_b32_e32 v85, v135
	v_pk_fma_f32 v[80:81], v[12:13], v[126:127], v[80:81]
	v_mov_b32_e32 v126, v88
	v_mov_b32_e32 v127, v79
	v_mov_b32_e32 v143, v95
	v_pk_mul_f32 v[144:145], v[72:73], v[102:103]
	v_pk_fma_f32 v[130:131], v[64:65], v[98:99], v[130:131]
	v_mov_b32_e32 v110, v141
	v_mov_b32_e32 v112, v147
	v_pk_add_f32 v[126:127], v[126:127], v[84:85]
	v_pk_fma_f32 v[90:91], v[6:7], v[98:99], v[90:91] neg_lo:[0,0,1] neg_hi:[0,0,1]
	v_pk_add_f32 v[98:99], v[80:81], v[86:87] op_sel:[1,0] op_sel_hi:[0,1]
	v_pk_fma_f32 v[144:145], v[70:71], v[142:143], v[144:145] neg_lo:[0,0,1] neg_hi:[0,0,1]
	v_pk_add_f32 v[110:111], v[110:111], v[112:113]
	v_mov_b32_e32 v112, v97
	v_mov_b32_e32 v113, v89
	v_pk_mul_f32 v[94:95], v[72:73], v[142:143]
	v_mov_b32_e32 v118, v127
	v_mov_b32_e32 v120, v99
	v_pk_add_f32 v[112:113], v[112:113], v[92:93]
	v_pk_add_f32 v[156:157], v[130:131], v[144:145]
	v_pk_fma_f32 v[100:101], v[8:9], v[100:101], v[128:129]
	v_pk_fma_f32 v[94:95], v[70:71], v[102:103], v[94:95]
	v_pk_add_f32 v[102:103], v[118:119], v[120:121]
	v_mov_b32_e32 v118, v96
	v_mov_b32_e32 v119, v88
	v_mov_b32_e32 v115, v112
	v_mov_b32_e32 v117, v156
	v_pk_add_f32 v[118:119], v[118:119], v[100:101]
	v_pk_add_f32 v[120:121], v[90:91], v[94:95]
	v_pk_add_f32 v[158:159], v[114:115], v[116:117]
	v_pk_add_f32 v[114:115], v[114:115], v[116:117] neg_lo:[0,1] neg_hi:[0,1]
	v_mov_b32_e32 v109, v118
	v_mov_b32_e32 v107, v120
	v_pk_mov_b32 v[162:163], v[82:83], v[82:83] op_sel:[1,0]
	v_mov_b32_e32 v116, v114
	v_mov_b32_e32 v117, v159
	v_pk_add_f32 v[106:107], v[108:109], v[106:107]
	v_mov_b32_e32 v15, v163
	v_mov_b32_e32 v123, v23
	v_mov_b32_e32 v163, v22
	v_pk_add_f32 v[108:109], v[126:127], v[98:99]
	v_pk_mul_f32 v[172:173], v[122:123], v[106:107]
	v_pk_add_f32 v[174:175], v[122:123], v[106:107]
	v_pk_mul_f32 v[158:159], v[162:163], v[158:159]
	v_pk_add_f32 v[116:117], v[162:163], v[116:117]
	v_pk_add_f32 v[128:129], v[140:141], v[146:147]
	v_mov_b32_e32 v172, v174
	v_mov_b32_e32 v158, v116
	v_pk_mul_f32 v[108:109], v[20:21], v[108:109]
	v_mov_b32_e32 v17, v104
	v_pk_add_f32 v[164:165], v[14:15], v[110:111]
	v_pk_mul_f32 v[166:167], v[14:15], v[110:111]
	v_pk_fma_f32 v[108:109], v[24:25], v[128:129], v[108:109] neg_lo:[0,0,1] neg_hi:[0,0,1]
	v_pk_add_f32 v[128:129], v[172:173], v[158:159]
	v_pk_mov_b32 v[110:111], v[110:111], v[114:115] op_sel:[1,0]
	v_mov_b32_e32 v107, v104
	v_mov_b32_e32 v123, v103
	v_pk_mov_b32 v[172:173], v[86:87], v[94:95] op_sel:[1,0]
	v_mov_b32_e32 v91, v138
	v_mov_b32_e32 v95, v125
	v_pk_add_f32 v[142:143], v[16:17], v[102:103]
	v_pk_mul_f32 v[160:161], v[16:17], v[102:103]
	v_pk_add_f32 v[82:83], v[82:83], v[110:111] neg_lo:[0,1] neg_hi:[0,1]
	v_pk_add_f32 v[102:103], v[106:107], v[122:123] neg_lo:[0,1] neg_hi:[0,1]
	v_mov_b32_e32 v110, v96
	v_mov_b32_e32 v111, v78
	v_mov_b32_e32 v114, v100
	v_mov_b32_e32 v115, v137
	v_pk_mov_b32 v[122:123], v[136:137], v[92:93] op_sel:[1,0]
	v_mov_b32_e32 v131, v80
	v_mov_b32_e32 v136, v80
	v_mov_b32_e32 v137, v90
	v_pk_add_f32 v[90:91], v[90:91], v[94:95] neg_lo:[0,1] neg_hi:[0,1]
	v_pk_mov_b32 v[94:95], v[124:125], v[144:145] op_sel:[1,0]
	v_mov_b32_e32 v85, v132
	v_mov_b32_e32 v125, v86
	v_mov_b32_e32 v80, v139
	v_pk_add_f32 v[110:111], v[110:111], v[114:115] neg_lo:[0,1] neg_hi:[0,1]
	v_mov_b32_e32 v114, v78
	v_mov_b32_e32 v115, v97
	v_pk_mov_b32 v[176:177], v[78:79], v[96:97] op_sel:[1,0]
	v_mov_b32_e32 v78, v97
	v_mov_b32_e32 v93, v135
	v_pk_add_f32 v[84:85], v[88:89], v[84:85] neg_lo:[0,1] neg_hi:[0,1]
	v_pk_add_f32 v[80:81], v[124:125], v[80:81] neg_lo:[0,1] neg_hi:[0,1]
	v_pk_add_f32 v[114:115], v[114:115], v[122:123] neg_lo:[0,1] neg_hi:[0,1]
; DI float2 twid(float r) { return float2{__builtin_amdgcn_cosf(r), -__builtin_amdgcn_sinf(r)}; }
; DI void bfly_inv(float2 s0, float2 s1, float2 s2, float2 s3, float r, float2& o0, float2& o1, float2& o2, float2& o3) {
;   float2 w1 = twid(r), w2 = cmul(w1, w1), w3 = cmul(w2, w1);
;   float2 c0 = s0, c1 = cmulc(s1, w1), c2 = cmulc(s2, w2), c3 = cmulc(s3, w3);
;   float2 t0 = {c0.x + c2.x, c0.y + c2.y}, t1 = {c0.x - c2.x, c0.y - c2.y}, t2 = {c1.x + c3.x, c1.y + c3.y}, t3 = {c1.x - c3.x, c1.y - c3.y};
;   o0 = float2{t0.x + t2.x, t0.y + t2.y}; o2 = float2{t0.x - t2.x, t0.y - t2.y}; o1 = float2{t1.x - t3.y, t1.y + t3.x}; o3 = float2{t1.x + t3.y, t1.y - t3.x};
; }
;     ...
;   for (int gg = tid; gg < NBT * (N / 16); gg += NTHR) { const int g = gg & (N / 16 - 1); float2* z = z0 + (gg / (N / 16)) * N; const int jp = g & (Q2 - 1), base = ((g >> lq2) << (lq2 + 4)) + jp; float2 x[4][4];
; #pragma unroll
;     for (int q1 = 0; q1 < 4; ++q1)
; #pragma unroll
;       for (int q2 = 0; q2 < 4; ++q2) x[q1][q2] = z[base + q1 * Q1 + q2 * Q2];
; #pragma unroll
;     for (int q1 = 0; q1 < 4; ++q1) bfly_inv(x[q1][0], x[q1][1], x[q1][2], x[q1][3], (float)jp * invM2, x[q1][0], x[q1][1], x[q1][2], x[q1][3]);
; #pragma unroll
;     for (int q2 = 0; q2 < 4; ++q2) bfly_inv(x[0][q2], x[1][q2], x[2][q2], x[3][q2], (float)(jp + q2 * Q2) * invM1, x[0][q2], x[1][q2], x[2][q2], x[3][q2]);
; #pragma unroll
;     for (int q1 = 0; q1 < 4; ++q1)
; #pragma unroll
;       for (int q2 = 0; q2 < 4; ++q2) z[base + q1 * Q1 + q2 * Q2] = x[q1][q2]; }
	v_mov_b32_e32 v122, v144
	v_mov_b32_e32 v123, v87
	v_pk_mov_b32 v[100:101], v[134:135], v[100:101] op_sel:[1,0]
	v_pk_add_f32 v[78:79], v[78:79], v[92:93] neg_lo:[0,1] neg_hi:[0,1]
	v_mov_b32_e32 v92, v138
	v_mov_b32_e32 v93, v130
	v_pk_add_f32 v[86:87], v[84:85], v[80:81] neg_lo:[0,1] neg_hi:[0,1]
	v_pk_add_f32 v[88:89], v[84:85], v[80:81]
	v_pk_add_f32 v[168:169], v[118:119], v[120:121]
	v_pk_mov_b32 v[158:159], v[162:163], v[24:25] op_sel:[1,0]
	v_pk_add_f32 v[122:123], v[130:131], v[122:123] neg_lo:[0,1] neg_hi:[0,1]
	v_pk_add_f32 v[100:101], v[176:177], v[100:101] neg_lo:[0,1] neg_hi:[0,1]
	v_pk_add_f32 v[92:93], v[92:93], v[94:95] neg_lo:[0,1] neg_hi:[0,1]
	v_mov_b32_e32 v97, v89
	v_pk_mov_b32 v[88:89], v[88:89], v[86:87] op_sel:[1,0]
	v_pk_add_f32 v[170:171], v[112:113], v[156:157]
	v_pk_mul_f32 v[158:159], v[158:159], v[168:169]
	v_pk_add_f32 v[136:137], v[136:137], v[172:173] neg_lo:[0,1] neg_hi:[0,1]
	v_pk_add_f32 v[94:95], v[100:101], v[92:93] neg_lo:[0,1] neg_hi:[0,1]
	v_mov_b32_e32 v96, v86
	v_pk_add_f32 v[110:111], v[110:111], v[122:123] neg_lo:[0,1] neg_hi:[0,1]
	v_pk_add_f32 v[122:123], v[100:101], v[92:93]
	v_pk_mul_f32 v[88:89], v[32:33], v[88:89]
	v_mov_b32_e32 v161, v143
	v_mov_b32_e32 v167, v165
	v_pk_fma_f32 v[162:163], v[74:75], v[170:171], v[158:159]
	v_pk_fma_f32 v[158:159], v[74:75], v[170:171], v[158:159] neg_lo:[0,0,1] neg_hi:[0,0,1]
	v_pk_add_f32 v[172:173], v[114:115], v[136:137]
	v_mov_b32_e32 v123, v95
	v_pk_add_f32 v[124:125], v[114:115], v[136:137] neg_lo:[0,1] neg_hi:[0,1]
	v_pk_add_f32 v[78:79], v[78:79], v[90:91]
	v_pk_fma_f32 v[86:87], v[30:31], v[86:87], v[88:89]
	v_pk_fma_f32 v[88:89], v[30:31], v[96:97], v[88:89] neg_lo:[0,0,1] neg_hi:[0,0,1]
	v_pk_add_f32 v[160:161], v[166:167], v[160:161]
	v_mov_b32_e32 v159, v163
	v_pk_add_f32 v[104:105], v[82:83], v[102:103] neg_lo:[0,1] neg_hi:[0,1]
	v_pk_add_f32 v[106:107], v[82:83], v[102:103]
	v_mov_b32_e32 v125, v173
	v_mov_b32_e32 v87, v89
	v_pk_mul_f32 v[78:79], v[28:29], v[78:79]
	v_pk_mul_f32 v[88:89], v[52:53], v[122:123]
	v_pk_add_f32 v[166:167], v[108:109], v[128:129]
	v_pk_add_f32 v[168:169], v[160:161], v[158:159]
	v_mov_b32_e32 v106, v104
	v_pk_fma_f32 v[78:79], v[26:27], v[110:111], v[78:79]
	v_pk_fma_f32 v[88:89], v[50:51], v[124:125], v[88:89] neg_lo:[0,0,1] neg_hi:[0,0,1]
	v_pk_add_f32 v[170:171], v[166:167], v[168:169]
	v_pk_add_f32 v[90:91], v[106:107], v[86:87]
	v_pk_add_f32 v[96:97], v[88:89], v[78:79]
	v_pk_mov_b32 v[170:171], v[170:171], v[170:171] op_sel:[1,0]
	v_pk_add_f32 v[110:111], v[90:91], v[96:97]
	ds_write2st64_b64 v178, v[170:171], v[110:111] offset1:4
	v_pk_mov_b32 v[110:111], v[164:165], v[116:117] op_sel:[1,0]
	v_pk_mov_b32 v[116:117], v[142:143], v[174:175] op_sel:[1,0]
	v_mov_b32_e32 v122, v98
	v_pk_add_f32 v[110:111], v[110:111], v[116:117] neg_lo:[0,1] neg_hi:[0,1]
	v_mov_b32_e32 v116, v126
	v_mov_b32_e32 v117, v140
	v_mov_b32_e32 v123, v146
	v_pk_add_f32 v[116:117], v[116:117], v[122:123] neg_lo:[0,1] neg_hi:[0,1]
	v_mov_b32_e32 v122, v118
	v_mov_b32_e32 v123, v141
	v_mov_b32_e32 v124, v120
	v_mov_b32_e32 v125, v147
	v_pk_mov_b32 v[118:119], v[126:127], v[118:119] op_sel:[1,0]
	v_pk_mov_b32 v[120:121], v[98:99], v[120:121] op_sel:[1,0]
	v_mov_b32_e32 v100, v84
	v_mov_b32_e32 v92, v80
	v_pk_add_f32 v[122:123], v[122:123], v[124:125] neg_lo:[0,1] neg_hi:[0,1]
	v_pk_add_f32 v[118:119], v[118:119], v[120:121] neg_lo:[0,1] neg_hi:[0,1]
	v_pk_mov_b32 v[120:121], v[140:141], v[112:113] op_sel:[1,0]
	v_pk_mov_b32 v[124:125], v[146:147], v[156:157] op_sel:[1,0]
	v_mov_b32_e32 v113, v127
	v_mov_b32_e32 v157, v99
	v_pk_add_f32 v[92:93], v[100:101], v[92:93]
	v_mov_b32_e32 v114, v85
	v_mov_b32_e32 v136, v81
	v_pk_add_f32 v[98:99], v[112:113], v[156:157] neg_lo:[0,1] neg_hi:[0,1]
	v_pk_mul_f32 v[112:113], v[40:41], v[116:117] op_sel:[0,1] op_sel_hi:[1,0]
	v_pk_add_f32 v[80:81], v[114:115], v[136:137] neg_lo:[0,1] neg_hi:[0,1]
	v_mov_b32_e32 v95, v92
	v_mul_f32_e32 v103, v44, v94
	v_pk_add_f32 v[120:121], v[120:121], v[124:125] neg_lo:[0,1] neg_hi:[0,1]
	v_pk_fma_f32 v[124:125], v[38:39], v[116:117], v[112:113]
	v_pk_fma_f32 v[112:113], v[38:39], v[116:117], v[112:113] neg_lo:[0,0,1] neg_hi:[0,0,1]
	v_pk_mul_f32 v[84:85], v[42:43], v[94:95]
	v_mov_b32_e32 v94, v93
	v_mov_b32_e32 v95, v81
	v_mul_f32_e32 v100, v49, v81
	v_pk_mul_f32 v[92:93], v[46:47], v[92:93]
	v_mul_f32_e32 v83, v42, v172
	v_mov_b32_e32 v125, v113
	v_pk_mul_f32 v[98:99], v[36:37], v[98:99]
	v_pk_mul_f32 v[112:113], v[56:57], v[118:119]
	v_mov_b32_e32 v173, v80
	v_pk_fma_f32 v[94:95], v[48:49], v[94:95], v[100:101] op_sel_hi:[1,1,0]
	v_pk_fma_f32 v[100:101], v[60:61], v[80:81], v[92:93]
	v_pk_fma_f32 v[80:81], v[60:61], v[80:81], v[92:93] neg_lo:[0,0,1] neg_hi:[0,0,1]
	v_pk_fma_f32 v[98:99], v[34:35], v[122:123], v[98:99]
	v_pk_fma_f32 v[112:113], v[54:55], v[120:121], v[112:113] neg_lo:[0,0,1] neg_hi:[0,0,1]
	v_pk_add_f32 v[82:83], v[82:83], v[102:103]
	v_pk_fma_f32 v[84:85], v[44:45], v[172:173], v[84:85] neg_lo:[0,0,1] neg_hi:[0,0,1]
	v_mov_b32_e32 v101, v81
	v_mov_b32_e32 v104, v94
	v_pk_add_f32 v[116:117], v[110:111], v[124:125]
	v_pk_add_f32 v[118:119], v[112:113], v[98:99]
	v_pk_add_f32 v[92:93], v[84:85], v[104:105]
	v_pk_add_f32 v[102:103], v[82:83], v[100:101]
	v_pk_add_f32 v[120:121], v[116:117], v[118:119]
	v_pk_add_f32 v[114:115], v[92:93], v[102:103]
	ds_write2st64_b64 v178, v[120:121], v[114:115] offset0:8 offset1:12
	v_pk_mov_b32 v[114:115], v[160:161], v[128:129] op_sel:[1,0]
	v_pk_mov_b32 v[120:121], v[162:163], v[108:109] op_sel:[1,0]
	v_mov_b32_e32 v161, v109
	v_mov_b32_e32 v159, v129
	v_pk_add_f32 v[86:87], v[106:107], v[86:87] neg_lo:[0,1] neg_hi:[0,1]
; DI float2 twid(float r) { return float2{__builtin_amdgcn_cosf(r), -__builtin_amdgcn_sinf(r)}; }
; DI void bfly_inv(float2 s0, float2 s1, float2 s2, float2 s3, float r, float2& o0, float2& o1, float2& o2, float2& o3) {
;   float2 w1 = twid(r), w2 = cmul(w1, w1), w3 = cmul(w2, w1);
;   float2 c0 = s0, c1 = cmulc(s1, w1), c2 = cmulc(s2, w2), c3 = cmulc(s3, w3);
;   float2 t0 = {c0.x + c2.x, c0.y + c2.y}, t1 = {c0.x - c2.x, c0.y - c2.y}, t2 = {c1.x + c3.x, c1.y + c3.y}, t3 = {c1.x - c3.x, c1.y - c3.y};
;   o0 = float2{t0.x + t2.x, t0.y + t2.y}; o2 = float2{t0.x - t2.x, t0.y - t2.y}; o1 = float2{t1.x - t3.y, t1.y + t3.x}; o3 = float2{t1.x + t3.y, t1.y - t3.x};
; }
;     ...
;   for (int gg = tid; gg < NBT * (N / 16); gg += NTHR) { const int g = gg & (N / 16 - 1); float2* z = z0 + (gg / (N / 16)) * N; const int jp = g & (Q2 - 1), base = ((g >> lq2) << (lq2 + 4)) + jp; float2 x[4][4];
; #pragma unroll
;     for (int q1 = 0; q1 < 4; ++q1)
; #pragma unroll
;       for (int q2 = 0; q2 < 4; ++q2) x[q1][q2] = z[base + q1 * Q1 + q2 * Q2];
; #pragma unroll
;     for (int q1 = 0; q1 < 4; ++q1) bfly_inv(x[q1][0], x[q1][1], x[q1][2], x[q1][3], (float)jp * invM2, x[q1][0], x[q1][1], x[q1][2], x[q1][3]);
; #pragma unroll
;     for (int q2 = 0; q2 < 4; ++q2) bfly_inv(x[0][q2], x[1][q2], x[2][q2], x[3][q2], (float)(jp + q2 * Q2) * invM1, x[0][q2], x[1][q2], x[2][q2], x[3][q2]);
; #pragma unroll
;     for (int q1 = 0; q1 < 4; ++q1)
; #pragma unroll
;       for (int q2 = 0; q2 < 4; ++q2) z[base + q1 * Q1 + q2 * Q2] = x[q1][q2]; }
	v_pk_mov_b32 v[106:107], v[78:79], v[88:89] op_sel:[1,0]
	v_pk_mov_b32 v[78:79], v[88:89], v[78:79] op_sel:[1,0]
	v_pk_add_f32 v[114:115], v[114:115], v[120:121] neg_lo:[0,1] neg_hi:[0,1]
	v_pk_add_f32 v[108:109], v[160:161], v[158:159] neg_lo:[0,1] neg_hi:[0,1]
	v_pk_add_f32 v[78:79], v[106:107], v[78:79] neg_lo:[0,1] neg_hi:[0,1]
	v_pk_add_f32 v[120:121], v[114:115], v[108:109] neg_lo:[0,1] neg_hi:[0,1]
	v_pk_add_f32 v[108:109], v[114:115], v[108:109]
	v_pk_add_f32 v[88:89], v[86:87], v[78:79] neg_lo:[0,1] neg_hi:[0,1]
	v_pk_add_f32 v[78:79], v[86:87], v[78:79]
	v_mov_b32_e32 v114, v120
	v_mov_b32_e32 v115, v109
	v_mov_b32_e32 v86, v88
	v_mov_b32_e32 v87, v79
	v_pk_mov_b32 v[106:107], v[98:99], v[112:113] op_sel:[1,0]
	v_pk_mov_b32 v[98:99], v[112:113], v[98:99] op_sel:[1,0]
	v_mov_b32_e32 v104, v82
	v_mov_b32_e32 v101, v85
	v_pk_mov_b32 v[82:83], v[82:83], v[84:85] op_sel:[1,0]
	v_pk_mov_b32 v[80:81], v[80:81], v[94:95] op_sel:[1,0]
	ds_write2st64_b64 v178, v[114:115], v[86:87] offset0:16 offset1:20
	v_pk_add_f32 v[86:87], v[110:111], v[124:125] neg_lo:[0,1] neg_hi:[0,1]
	v_pk_add_f32 v[98:99], v[106:107], v[98:99] neg_lo:[0,1] neg_hi:[0,1]
	v_pk_add_f32 v[100:101], v[104:105], v[100:101] neg_lo:[0,1] neg_hi:[0,1]
	v_pk_add_f32 v[80:81], v[82:83], v[80:81] neg_lo:[0,1] neg_hi:[0,1]
	v_pk_add_f32 v[106:107], v[86:87], v[98:99] neg_lo:[0,1] neg_hi:[0,1]
	v_pk_add_f32 v[86:87], v[86:87], v[98:99]
	v_pk_add_f32 v[82:83], v[100:101], v[80:81] neg_lo:[0,1] neg_hi:[0,1]
	v_pk_add_f32 v[80:81], v[100:101], v[80:81]
	v_mov_b32_e32 v98, v106
	v_mov_b32_e32 v99, v87
	v_mov_b32_e32 v84, v82
	v_mov_b32_e32 v85, v81
	ds_write2st64_b64 v178, v[98:99], v[84:85] offset0:24 offset1:28
	v_pk_mov_b32 v[84:85], v[168:169], v[166:167] op_sel:[1,0]
	v_pk_mov_b32 v[94:95], v[166:167], v[168:169] op_sel:[1,0]
	v_pk_add_f32 v[90:91], v[90:91], v[96:97] neg_lo:[0,1] neg_hi:[0,1]
	v_pk_add_f32 v[84:85], v[84:85], v[94:95] neg_lo:[0,1] neg_hi:[0,1]
	ds_write2st64_b64 v178, v[84:85], v[90:91] offset0:32 offset1:36
	v_mov_b32_e32 v90, v102
	v_mov_b32_e32 v91, v93
	v_mov_b32_e32 v93, v103
	s_nop 0
	v_pk_add_f32 v[84:85], v[116:117], v[118:119] neg_lo:[0,1] neg_hi:[0,1]
	v_pk_add_f32 v[90:91], v[90:91], v[92:93] neg_lo:[0,1] neg_hi:[0,1]
	v_mov_b32_e32 v109, v121
	v_mov_b32_e32 v79, v89
	v_mov_b32_e32 v87, v107
	v_mov_b32_e32 v81, v83
	s_nop 0
	ds_write2st64_b64 v178, v[84:85], v[90:91] offset0:40 offset1:44
	ds_write2st64_b64 v178, v[108:109], v[78:79] offset0:48 offset1:52
	ds_write2st64_b64 v178, v[86:87], v[80:81] offset0:56 offset1:60
	s_nop 0
	v_add_u32_e32 v62, 0x200, v62
	s_nop 0
	v_add_u32_e32 v77, 0x2000, v77
	s_nop 0
	s_waitcnt lgkmcnt(15)
	v_mul_f32_e32 v111, v9, v220
	s_waitcnt lgkmcnt(14)
	v_mul_f32_e32 v86, v5, v227
	v_mul_f32_e32 v116, v10, v220
	v_mul_f32_e32 v220, v19, v223
	v_pk_fma_f32 v[104:105], v[4:5], v[226:227], v[86:87] op_sel_hi:[1,1,0] neg_lo:[0,0,1] neg_hi:[0,0,1]
	v_mul_f32_e32 v106, v6, v227
	v_mul_f32_e32 v108, v5, v226
	v_mul_f32_e32 v113, v10, v221
	v_mul_f32_e32 v114, v9, v221
	v_pk_mul_f32 v[118:119], v[18:19], v[222:223] op_sel_hi:[1,0]
	v_pk_mul_f32 v[120:121], v[62:63], v[222:223]
	v_pk_fma_f32 v[122:123], v[18:19], v[222:223], v[220:221] op_sel_hi:[1,1,0] neg_lo:[1,0,0] neg_hi:[1,0,0]
	s_nop 0
	s_waitcnt lgkmcnt(12)
	v_mov_b32_e32 v125, v235
	s_waitcnt lgkmcnt(11)
	v_mov_b32_e32 v124, v239
	v_pk_mul_f32 v[124:125], v[58:59], v[124:125]
	v_mov_b32_e32 v126, v238
	v_mov_b32_e32 v127, v234
	v_pk_fma_f32 v[124:125], v[12:13], v[126:127], v[124:125]
	s_waitcnt lgkmcnt(10)
	v_pk_mov_b32 v[126:127], v[244:245], v[232:233] op_sel:[1,0]
	v_mov_b32_e32 v232, v244
	v_pk_mul_f32 v[132:133], v[10:11], v[232:233]
	s_waitcnt lgkmcnt(8)
	v_mov_b32_e32 v134, v253
	v_mov_b32_e32 v253, v244
	v_mov_b32_e32 v128, v251
	v_mov_b32_e32 v129, v239
	v_mov_b32_e32 v135, v245
	v_pk_mul_f32 v[244:245], v[10:11], v[252:253]
	v_pk_fma_f32 v[136:137], v[8:9], v[126:127], v[132:133]
	v_pk_fma_f32 v[132:133], v[8:9], v[126:127], v[132:133] neg_lo:[0,0,1] neg_hi:[0,0,1]
	v_pk_mov_b32 v[140:141], v[230:231], v[246:247] op_sel:[1,0]
	v_pk_mul_f32 v[126:127], v[10:11], v[126:127]
	v_pk_mul_f32 v[130:131], v[6:7], v[128:129]
	v_mov_b32_e32 v251, v238
	v_mov_b32_e32 v138, v230
	v_mov_b32_e32 v139, v247
	v_pk_mul_f32 v[140:141], v[68:69], v[140:141]
	v_mov_b32_e32 v142, v255
	v_mov_b32_e32 v255, v246
	v_pk_fma_f32 v[244:245], v[8:9], v[134:135], v[244:245] neg_lo:[0,0,1] neg_hi:[0,0,1]
	v_mov_b32_e32 v160, v238
	v_mov_b32_e32 v161, v235
	v_pk_mov_b32 v[234:235], v[238:239], v[234:235] op_sel:[1,0]
	v_pk_mul_f32 v[238:239], v[64:65], v[128:129]
	v_pk_mul_f32 v[128:129], v[10:11], v[134:135]
	v_pk_fma_f32 v[134:135], v[8:9], v[232:233], v[126:127] neg_lo:[0,0,1] neg_hi:[0,0,1]
	v_pk_fma_f32 v[232:233], v[8:9], v[232:233], v[126:127]
	v_mov_b32_e32 v127, v246
	v_mov_b32_e32 v246, v231
	v_mov_b32_e32 v133, v137
	v_pk_fma_f32 v[138:139], v[66:67], v[138:139], v[140:141] neg_lo:[0,0,1] neg_hi:[0,0,1]
	v_pk_mov_b32 v[140:141], v[236:237], v[228:229] op_sel:[1,0]
	v_pk_mul_f32 v[234:235], v[68:69], v[234:235]
	v_mov_b32_e32 v126, v230
	v_pk_mul_f32 v[230:231], v[58:59], v[246:247]
	v_pk_add_f32 v[140:141], v[140:141], v[132:133]
	v_pk_add_f32 v[146:147], v[138:139], v[124:125] op_sel:[1,0] op_sel_hi:[0,1]
	v_pk_fma_f32 v[234:235], v[66:67], v[160:161], v[234:235] neg_lo:[0,0,1] neg_hi:[0,0,1]
	v_mov_b32_e32 v233, v135
	v_pk_fma_f32 v[230:231], v[12:13], v[126:127], v[230:231]
	v_mov_b32_e32 v126, v236
	v_mov_b32_e32 v127, v229
	v_mov_b32_e32 v143, v247
	v_pk_mul_f32 v[144:145], v[72:73], v[254:255]
	v_pk_fma_f32 v[130:131], v[64:65], v[250:251], v[130:131]
	v_mov_b32_e32 v110, v141
; DI float2 twid(float r) { return float2{__builtin_amdgcn_cosf(r), -__builtin_amdgcn_sinf(r)}; }
; DI void bfly_inv(float2 s0, float2 s1, float2 s2, float2 s3, float r, float2& o0, float2& o1, float2& o2, float2& o3) {
;   float2 w1 = twid(r), w2 = cmul(w1, w1), w3 = cmul(w2, w1);
;   float2 c0 = s0, c1 = cmulc(s1, w1), c2 = cmulc(s2, w2), c3 = cmulc(s3, w3);
;   float2 t0 = {c0.x + c2.x, c0.y + c2.y}, t1 = {c0.x - c2.x, c0.y - c2.y}, t2 = {c1.x + c3.x, c1.y + c3.y}, t3 = {c1.x - c3.x, c1.y - c3.y};
;   o0 = float2{t0.x + t2.x, t0.y + t2.y}; o2 = float2{t0.x - t2.x, t0.y - t2.y}; o1 = float2{t1.x - t3.y, t1.y + t3.x}; o3 = float2{t1.x + t3.y, t1.y - t3.x};
; }
;     ...
;   for (int gg = tid; gg < NBT * (N / 16); gg += NTHR) { const int g = gg & (N / 16 - 1); float2* z = z0 + (gg / (N / 16)) * N; const int jp = g & (Q2 - 1), base = ((g >> lq2) << (lq2 + 4)) + jp; float2 x[4][4];
; #pragma unroll
;     for (int q1 = 0; q1 < 4; ++q1)
; #pragma unroll
;       for (int q2 = 0; q2 < 4; ++q2) x[q1][q2] = z[base + q1 * Q1 + q2 * Q2];
; #pragma unroll
;     for (int q1 = 0; q1 < 4; ++q1) bfly_inv(x[q1][0], x[q1][1], x[q1][2], x[q1][3], (float)jp * invM2, x[q1][0], x[q1][1], x[q1][2], x[q1][3]);
; #pragma unroll
;     for (int q2 = 0; q2 < 4; ++q2) bfly_inv(x[0][q2], x[1][q2], x[2][q2], x[3][q2], (float)(jp + q2 * Q2) * invM1, x[0][q2], x[1][q2], x[2][q2], x[3][q2]);
; #pragma unroll
;     for (int q1 = 0; q1 < 4; ++q1)
; #pragma unroll
;       for (int q2 = 0; q2 < 4; ++q2) z[base + q1 * Q1 + q2 * Q2] = x[q1][q2]; }
	v_mov_b32_e32 v112, v147
	v_pk_add_f32 v[126:127], v[126:127], v[232:233]
	v_pk_fma_f32 v[238:239], v[6:7], v[250:251], v[238:239] neg_lo:[0,0,1] neg_hi:[0,0,1]
	v_pk_add_f32 v[250:251], v[230:231], v[234:235] op_sel:[1,0] op_sel_hi:[0,1]
	v_pk_fma_f32 v[144:145], v[70:71], v[142:143], v[144:145] neg_lo:[0,0,1] neg_hi:[0,0,1]
	v_pk_add_f32 v[110:111], v[110:111], v[112:113]
	v_mov_b32_e32 v112, v249
	v_mov_b32_e32 v113, v237
	v_pk_mul_f32 v[246:247], v[72:73], v[142:143]
	v_mov_b32_e32 v118, v127
	v_mov_b32_e32 v120, v251
	v_pk_add_f32 v[112:113], v[112:113], v[244:245]
	v_pk_add_f32 v[156:157], v[130:131], v[144:145]
	v_pk_fma_f32 v[252:253], v[8:9], v[252:253], v[128:129]
	v_pk_fma_f32 v[246:247], v[70:71], v[254:255], v[246:247]
	v_pk_add_f32 v[254:255], v[118:119], v[120:121]
	v_mov_b32_e32 v118, v248
	v_mov_b32_e32 v119, v236
	v_mov_b32_e32 v115, v112
	v_mov_b32_e32 v117, v156
	v_pk_add_f32 v[118:119], v[118:119], v[252:253]
	v_pk_add_f32 v[120:121], v[238:239], v[246:247]
	v_pk_add_f32 v[158:159], v[114:115], v[116:117]
	v_pk_add_f32 v[114:115], v[114:115], v[116:117] neg_lo:[0,1] neg_hi:[0,1]
	v_mov_b32_e32 v109, v118
	v_mov_b32_e32 v107, v120
	v_pk_mov_b32 v[162:163], v[224:225], v[224:225] op_sel:[1,0]
	v_mov_b32_e32 v116, v114
	v_mov_b32_e32 v117, v159
	v_pk_add_f32 v[106:107], v[108:109], v[106:107]
	v_mov_b32_e32 v15, v163
	v_mov_b32_e32 v123, v23
	v_mov_b32_e32 v163, v22
	v_pk_add_f32 v[108:109], v[126:127], v[250:251]
	v_pk_mul_f32 v[172:173], v[122:123], v[106:107]
	v_pk_add_f32 v[174:175], v[122:123], v[106:107]
	v_pk_mul_f32 v[158:159], v[162:163], v[158:159]
	v_pk_add_f32 v[116:117], v[162:163], v[116:117]
	v_pk_add_f32 v[128:129], v[140:141], v[146:147]
	v_mov_b32_e32 v172, v174
	v_mov_b32_e32 v158, v116
	v_pk_mul_f32 v[108:109], v[20:21], v[108:109]
	v_mov_b32_e32 v17, v104
	v_pk_add_f32 v[164:165], v[14:15], v[110:111]
	v_pk_mul_f32 v[166:167], v[14:15], v[110:111]
	v_pk_fma_f32 v[108:109], v[24:25], v[128:129], v[108:109] neg_lo:[0,0,1] neg_hi:[0,0,1]
	v_pk_add_f32 v[128:129], v[172:173], v[158:159]
	v_pk_mov_b32 v[110:111], v[110:111], v[114:115] op_sel:[1,0]
	v_mov_b32_e32 v107, v104
	v_mov_b32_e32 v123, v255
	v_pk_mov_b32 v[172:173], v[234:235], v[246:247] op_sel:[1,0]
	v_mov_b32_e32 v239, v138
	v_mov_b32_e32 v247, v125
	v_pk_add_f32 v[142:143], v[16:17], v[254:255]
	v_pk_mul_f32 v[160:161], v[16:17], v[254:255]
	v_pk_add_f32 v[224:225], v[224:225], v[110:111] neg_lo:[0,1] neg_hi:[0,1]
	v_pk_add_f32 v[254:255], v[106:107], v[122:123] neg_lo:[0,1] neg_hi:[0,1]
	v_mov_b32_e32 v110, v248
	v_mov_b32_e32 v111, v228
	v_mov_b32_e32 v114, v252
	v_mov_b32_e32 v115, v137
	v_pk_mov_b32 v[122:123], v[136:137], v[244:245] op_sel:[1,0]
	v_mov_b32_e32 v131, v230
	v_mov_b32_e32 v136, v230
	v_mov_b32_e32 v137, v238
	v_pk_add_f32 v[238:239], v[238:239], v[246:247] neg_lo:[0,1] neg_hi:[0,1]
	v_pk_mov_b32 v[246:247], v[124:125], v[144:145] op_sel:[1,0]
	v_mov_b32_e32 v233, v132
	v_mov_b32_e32 v125, v234
	v_mov_b32_e32 v230, v139
	v_pk_add_f32 v[110:111], v[110:111], v[114:115] neg_lo:[0,1] neg_hi:[0,1]
	v_mov_b32_e32 v114, v228
	v_mov_b32_e32 v115, v249
	v_pk_mov_b32 v[176:177], v[228:229], v[248:249] op_sel:[1,0]
	v_mov_b32_e32 v228, v249
	v_mov_b32_e32 v245, v135
	v_pk_add_f32 v[232:233], v[236:237], v[232:233] neg_lo:[0,1] neg_hi:[0,1]
	v_pk_add_f32 v[230:231], v[124:125], v[230:231] neg_lo:[0,1] neg_hi:[0,1]
	v_pk_add_f32 v[114:115], v[114:115], v[122:123] neg_lo:[0,1] neg_hi:[0,1]
	v_mov_b32_e32 v122, v144
	v_mov_b32_e32 v123, v235
	v_pk_mov_b32 v[252:253], v[134:135], v[252:253] op_sel:[1,0]
	v_pk_add_f32 v[228:229], v[228:229], v[244:245] neg_lo:[0,1] neg_hi:[0,1]
	v_mov_b32_e32 v244, v138
	v_mov_b32_e32 v245, v130
	v_pk_add_f32 v[234:235], v[232:233], v[230:231] neg_lo:[0,1] neg_hi:[0,1]
	v_pk_add_f32 v[236:237], v[232:233], v[230:231]
	v_pk_add_f32 v[168:169], v[118:119], v[120:121]
	v_pk_mov_b32 v[158:159], v[162:163], v[24:25] op_sel:[1,0]
	v_pk_add_f32 v[122:123], v[130:131], v[122:123] neg_lo:[0,1] neg_hi:[0,1]
	v_pk_add_f32 v[252:253], v[176:177], v[252:253] neg_lo:[0,1] neg_hi:[0,1]
	v_pk_add_f32 v[244:245], v[244:245], v[246:247] neg_lo:[0,1] neg_hi:[0,1]
	v_mov_b32_e32 v249, v237
	v_pk_mov_b32 v[236:237], v[236:237], v[234:235] op_sel:[1,0]
	v_pk_add_f32 v[170:171], v[112:113], v[156:157]
	v_pk_mul_f32 v[158:159], v[158:159], v[168:169]
	v_pk_add_f32 v[136:137], v[136:137], v[172:173] neg_lo:[0,1] neg_hi:[0,1]
	v_pk_add_f32 v[246:247], v[252:253], v[244:245] neg_lo:[0,1] neg_hi:[0,1]
	v_mov_b32_e32 v248, v234
	v_pk_add_f32 v[110:111], v[110:111], v[122:123] neg_lo:[0,1] neg_hi:[0,1]
	v_pk_add_f32 v[122:123], v[252:253], v[244:245]
	v_pk_mul_f32 v[236:237], v[32:33], v[236:237]
	v_mov_b32_e32 v161, v143
	v_mov_b32_e32 v167, v165
	v_pk_fma_f32 v[162:163], v[74:75], v[170:171], v[158:159]
	v_pk_fma_f32 v[158:159], v[74:75], v[170:171], v[158:159] neg_lo:[0,0,1] neg_hi:[0,0,1]
	v_pk_add_f32 v[172:173], v[114:115], v[136:137]
	v_mov_b32_e32 v123, v247
	v_pk_add_f32 v[124:125], v[114:115], v[136:137] neg_lo:[0,1] neg_hi:[0,1]
	v_pk_add_f32 v[228:229], v[228:229], v[238:239]
	v_pk_fma_f32 v[234:235], v[30:31], v[234:235], v[236:237]
	v_pk_fma_f32 v[236:237], v[30:31], v[248:249], v[236:237] neg_lo:[0,0,1] neg_hi:[0,0,1]
	v_pk_add_f32 v[160:161], v[166:167], v[160:161]
	v_mov_b32_e32 v159, v163
	v_pk_add_f32 v[104:105], v[224:225], v[254:255] neg_lo:[0,1] neg_hi:[0,1]
	v_pk_add_f32 v[106:107], v[224:225], v[254:255]
	v_mov_b32_e32 v125, v173
	v_mov_b32_e32 v235, v237
	v_pk_mul_f32 v[228:229], v[28:29], v[228:229]
	v_pk_mul_f32 v[236:237], v[52:53], v[122:123]
	v_pk_add_f32 v[166:167], v[108:109], v[128:129]
; DI float2 twid(float r) { return float2{__builtin_amdgcn_cosf(r), -__builtin_amdgcn_sinf(r)}; }
; DI void bfly_inv(float2 s0, float2 s1, float2 s2, float2 s3, float r, float2& o0, float2& o1, float2& o2, float2& o3) {
;   float2 w1 = twid(r), w2 = cmul(w1, w1), w3 = cmul(w2, w1);
;   float2 c0 = s0, c1 = cmulc(s1, w1), c2 = cmulc(s2, w2), c3 = cmulc(s3, w3);
;   float2 t0 = {c0.x + c2.x, c0.y + c2.y}, t1 = {c0.x - c2.x, c0.y - c2.y}, t2 = {c1.x + c3.x, c1.y + c3.y}, t3 = {c1.x - c3.x, c1.y - c3.y};
;   o0 = float2{t0.x + t2.x, t0.y + t2.y}; o2 = float2{t0.x - t2.x, t0.y - t2.y}; o1 = float2{t1.x - t3.y, t1.y + t3.x}; o3 = float2{t1.x + t3.y, t1.y - t3.x};
; }
;     ...
;   for (int gg = tid; gg < NBT * (N / 16); gg += NTHR) { const int g = gg & (N / 16 - 1); float2* z = z0 + (gg / (N / 16)) * N; const int jp = g & (Q2 - 1), base = ((g >> lq2) << (lq2 + 4)) + jp; float2 x[4][4];
; #pragma unroll
;     for (int q1 = 0; q1 < 4; ++q1)
; #pragma unroll
;       for (int q2 = 0; q2 < 4; ++q2) x[q1][q2] = z[base + q1 * Q1 + q2 * Q2];
; #pragma unroll
;     for (int q1 = 0; q1 < 4; ++q1) bfly_inv(x[q1][0], x[q1][1], x[q1][2], x[q1][3], (float)jp * invM2, x[q1][0], x[q1][1], x[q1][2], x[q1][3]);
; #pragma unroll
;     for (int q2 = 0; q2 < 4; ++q2) bfly_inv(x[0][q2], x[1][q2], x[2][q2], x[3][q2], (float)(jp + q2 * Q2) * invM1, x[0][q2], x[1][q2], x[2][q2], x[3][q2]);
; #pragma unroll
;     for (int q1 = 0; q1 < 4; ++q1)
; #pragma unroll
;       for (int q2 = 0; q2 < 4; ++q2) z[base + q1 * Q1 + q2 * Q2] = x[q1][q2]; }
	v_pk_add_f32 v[168:169], v[160:161], v[158:159]
	v_mov_b32_e32 v106, v104
	v_pk_fma_f32 v[228:229], v[26:27], v[110:111], v[228:229]
	v_pk_fma_f32 v[236:237], v[50:51], v[124:125], v[236:237] neg_lo:[0,0,1] neg_hi:[0,0,1]
	v_pk_add_f32 v[170:171], v[166:167], v[168:169]
	v_pk_add_f32 v[238:239], v[106:107], v[234:235]
	v_pk_add_f32 v[248:249], v[236:237], v[228:229]
	v_pk_mov_b32 v[170:171], v[170:171], v[170:171] op_sel:[1,0]
	v_pk_add_f32 v[110:111], v[238:239], v[248:249]
	ds_write2st64_b64 v219, v[170:171], v[110:111] offset1:4
	v_pk_mov_b32 v[110:111], v[164:165], v[116:117] op_sel:[1,0]
	v_pk_mov_b32 v[116:117], v[142:143], v[174:175] op_sel:[1,0]
	v_mov_b32_e32 v122, v250
	v_pk_add_f32 v[110:111], v[110:111], v[116:117] neg_lo:[0,1] neg_hi:[0,1]
	v_mov_b32_e32 v116, v126
	v_mov_b32_e32 v117, v140
	v_mov_b32_e32 v123, v146
	v_pk_add_f32 v[116:117], v[116:117], v[122:123] neg_lo:[0,1] neg_hi:[0,1]
	v_mov_b32_e32 v122, v118
	v_mov_b32_e32 v123, v141
	v_mov_b32_e32 v124, v120
	v_mov_b32_e32 v125, v147
	v_pk_mov_b32 v[118:119], v[126:127], v[118:119] op_sel:[1,0]
	v_pk_mov_b32 v[120:121], v[250:251], v[120:121] op_sel:[1,0]
	v_mov_b32_e32 v252, v232
	v_mov_b32_e32 v244, v230
	v_pk_add_f32 v[122:123], v[122:123], v[124:125] neg_lo:[0,1] neg_hi:[0,1]
	v_pk_add_f32 v[118:119], v[118:119], v[120:121] neg_lo:[0,1] neg_hi:[0,1]
	v_pk_mov_b32 v[120:121], v[140:141], v[112:113] op_sel:[1,0]
	v_pk_mov_b32 v[124:125], v[146:147], v[156:157] op_sel:[1,0]
	v_mov_b32_e32 v113, v127
	v_mov_b32_e32 v157, v251
	v_pk_add_f32 v[244:245], v[252:253], v[244:245]
	v_mov_b32_e32 v114, v233
	v_mov_b32_e32 v136, v231
	v_pk_add_f32 v[250:251], v[112:113], v[156:157] neg_lo:[0,1] neg_hi:[0,1]
	v_pk_mul_f32 v[112:113], v[40:41], v[116:117] op_sel:[0,1] op_sel_hi:[1,0]
	v_pk_add_f32 v[230:231], v[114:115], v[136:137] neg_lo:[0,1] neg_hi:[0,1]
	v_mov_b32_e32 v247, v244
	v_mul_f32_e32 v255, v44, v246
	v_pk_add_f32 v[120:121], v[120:121], v[124:125] neg_lo:[0,1] neg_hi:[0,1]
	v_pk_fma_f32 v[124:125], v[38:39], v[116:117], v[112:113]
	v_pk_fma_f32 v[112:113], v[38:39], v[116:117], v[112:113] neg_lo:[0,0,1] neg_hi:[0,0,1]
	v_pk_mul_f32 v[232:233], v[42:43], v[246:247]
	v_mov_b32_e32 v246, v245
	v_mov_b32_e32 v247, v231
	v_mul_f32_e32 v252, v49, v231
	v_pk_mul_f32 v[244:245], v[46:47], v[244:245]
	v_mul_f32_e32 v225, v42, v172
	v_mov_b32_e32 v125, v113
	v_pk_mul_f32 v[250:251], v[36:37], v[250:251]
	v_pk_mul_f32 v[112:113], v[56:57], v[118:119]
	v_mov_b32_e32 v173, v230
	v_pk_fma_f32 v[246:247], v[48:49], v[246:247], v[252:253] op_sel_hi:[1,1,0]
	v_pk_fma_f32 v[252:253], v[60:61], v[230:231], v[244:245]
	v_pk_fma_f32 v[230:231], v[60:61], v[230:231], v[244:245] neg_lo:[0,0,1] neg_hi:[0,0,1]
	v_pk_fma_f32 v[250:251], v[34:35], v[122:123], v[250:251]
	v_pk_fma_f32 v[112:113], v[54:55], v[120:121], v[112:113] neg_lo:[0,0,1] neg_hi:[0,0,1]
	v_pk_add_f32 v[224:225], v[224:225], v[254:255]
	v_pk_fma_f32 v[232:233], v[44:45], v[172:173], v[232:233] neg_lo:[0,0,1] neg_hi:[0,0,1]
	v_mov_b32_e32 v253, v231
	v_mov_b32_e32 v104, v246
	v_pk_add_f32 v[116:117], v[110:111], v[124:125]
	v_pk_add_f32 v[118:119], v[112:113], v[250:251]
	v_pk_add_f32 v[244:245], v[232:233], v[104:105]
	v_pk_add_f32 v[254:255], v[224:225], v[252:253]
	v_pk_add_f32 v[120:121], v[116:117], v[118:119]
	v_pk_add_f32 v[114:115], v[244:245], v[254:255]
	ds_write2st64_b64 v219, v[120:121], v[114:115] offset0:8 offset1:12
	v_pk_mov_b32 v[114:115], v[160:161], v[128:129] op_sel:[1,0]
	v_pk_mov_b32 v[120:121], v[162:163], v[108:109] op_sel:[1,0]
	v_mov_b32_e32 v161, v109
	v_mov_b32_e32 v159, v129
	v_pk_add_f32 v[234:235], v[106:107], v[234:235] neg_lo:[0,1] neg_hi:[0,1]
	v_pk_mov_b32 v[106:107], v[228:229], v[236:237] op_sel:[1,0]
	v_pk_mov_b32 v[228:229], v[236:237], v[228:229] op_sel:[1,0]
	v_pk_add_f32 v[114:115], v[114:115], v[120:121] neg_lo:[0,1] neg_hi:[0,1]
	v_pk_add_f32 v[108:109], v[160:161], v[158:159] neg_lo:[0,1] neg_hi:[0,1]
	v_pk_add_f32 v[228:229], v[106:107], v[228:229] neg_lo:[0,1] neg_hi:[0,1]
	v_pk_add_f32 v[120:121], v[114:115], v[108:109] neg_lo:[0,1] neg_hi:[0,1]
	v_pk_add_f32 v[108:109], v[114:115], v[108:109]
	v_pk_add_f32 v[236:237], v[234:235], v[228:229] neg_lo:[0,1] neg_hi:[0,1]
	v_pk_add_f32 v[228:229], v[234:235], v[228:229]
	v_mov_b32_e32 v114, v120
	v_mov_b32_e32 v115, v109
	v_mov_b32_e32 v234, v236
	v_mov_b32_e32 v235, v229
	v_pk_mov_b32 v[106:107], v[250:251], v[112:113] op_sel:[1,0]
	v_pk_mov_b32 v[250:251], v[112:113], v[250:251] op_sel:[1,0]
	v_mov_b32_e32 v104, v224
	v_mov_b32_e32 v253, v233
	v_pk_mov_b32 v[224:225], v[224:225], v[232:233] op_sel:[1,0]
	v_pk_mov_b32 v[230:231], v[230:231], v[246:247] op_sel:[1,0]
	ds_write2st64_b64 v219, v[114:115], v[234:235] offset0:16 offset1:20
	v_pk_add_f32 v[234:235], v[110:111], v[124:125] neg_lo:[0,1] neg_hi:[0,1]
	v_pk_add_f32 v[250:251], v[106:107], v[250:251] neg_lo:[0,1] neg_hi:[0,1]
	v_pk_add_f32 v[252:253], v[104:105], v[252:253] neg_lo:[0,1] neg_hi:[0,1]
	v_pk_add_f32 v[230:231], v[224:225], v[230:231] neg_lo:[0,1] neg_hi:[0,1]
	v_pk_add_f32 v[106:107], v[234:235], v[250:251] neg_lo:[0,1] neg_hi:[0,1]
	v_pk_add_f32 v[234:235], v[234:235], v[250:251]
	v_pk_add_f32 v[224:225], v[252:253], v[230:231] neg_lo:[0,1] neg_hi:[0,1]
	v_pk_add_f32 v[230:231], v[252:253], v[230:231]
	v_mov_b32_e32 v250, v106
	v_mov_b32_e32 v251, v235
	v_mov_b32_e32 v232, v224
	v_mov_b32_e32 v233, v231
	ds_write2st64_b64 v219, v[250:251], v[232:233] offset0:24 offset1:28
	v_pk_mov_b32 v[232:233], v[168:169], v[166:167] op_sel:[1,0]
	v_pk_mov_b32 v[246:247], v[166:167], v[168:169] op_sel:[1,0]
	v_pk_add_f32 v[238:239], v[238:239], v[248:249] neg_lo:[0,1] neg_hi:[0,1]
	v_pk_add_f32 v[232:233], v[232:233], v[246:247] neg_lo:[0,1] neg_hi:[0,1]
	ds_write2st64_b64 v219, v[232:233], v[238:239] offset0:32 offset1:36
	v_mov_b32_e32 v238, v254
	v_mov_b32_e32 v239, v245
	v_mov_b32_e32 v245, v255
	s_nop 0
	v_pk_add_f32 v[232:233], v[116:117], v[118:119] neg_lo:[0,1] neg_hi:[0,1]
	v_pk_add_f32 v[238:239], v[238:239], v[244:245] neg_lo:[0,1] neg_hi:[0,1]
	v_mov_b32_e32 v109, v121
	v_mov_b32_e32 v229, v237
	v_mov_b32_e32 v235, v107
	v_mov_b32_e32 v231, v225
	s_nop 0
	ds_write2st64_b64 v219, v[232:233], v[238:239] offset0:40 offset1:44
	ds_write2st64_b64 v219, v[108:109], v[228:229] offset0:48 offset1:52
	ds_write2st64_b64 v219, v[234:235], v[230:231] offset0:56 offset1:60
	s_nop 0
	v_add_u32_e32 v15, 0x200, v62
	s_nop 0
	v_mov_b32_e32 v62, v15

; #define LAS __attribute__((address_space(3)))
; __device__ __forceinline__ unsigned xb_ld(unsigned* p)              { return __hip_atomic_load(p, __ATOMIC_RELAXED, __HIP_MEMORY_SCOPE_AGENT); }
; #define GSYNC() xcd_barrier(xb)
; __global__ void __launch_bounds__(NTHR) mega(Params p) {
;   cg::grid_group grid = cg::this_grid();
;   if (threadIdx.x == 0) xb_words = make_uint4(0u, 0u, 0u, 0u);
;   __syncthreads();
;   XcdBarrier xb = xcd_barrier_post((unsigned*)(p.ws + OFF_BAR), (volatile LAS unsigned*)&xb_words);
;     ...
;   phase_prep(p); GSYNC();
;   if (threadIdx.x == 0) { unsigned idx = 0; for (unsigned j = 0; j < xb.x; ++j) idx += xb_ld(&xb.bar[XB_XCNT(j)]) > 0u ? 1u : 0u; xb_words.w = idx; }
;   __syncthreads();
;   phase_inproj0(p); GSYNC();
;   if (p.out == nullptr) grid.sync();
;   phase_mlaprep(p); phase_s5gen(p); GSYNC();
;   phase_s5step1(p); GSYNC();
;   phase_s5scan(p); GSYNC();
;   phase_s5step3(p); GSYNC();
;   for (int sg = 0; sg < 3; ++sg) { phase_upproj(p, sg); GSYNC(); phase_attn(p, sg); GSYNC(); }
;   phase_glu(p); GSYNC();
;   phase_outproj0(p); GSYNC();
;   phase_ple(p, 0, (const bft*)(p.ws + OFF_U), (bft*)(p.ws + OFF_A), LDP, (float*)(p.ws + OFF_SSQ1)); GSYNC();
;   convert_p(p, 1);
;   for (int ch = 0; ch < 8; ++ch) {
;     if (ch == 4) phase_outproj1(p, 0);
;     phase_inproj1(p, ch); phase_filter(p, ch); GSYNC();
;     phase_vx(p, ch); GSYNC();
;     phase_conv(p, ch); GSYNC();
;     phase_gate(p, ch); GSYNC();
;   }
;   phase_outproj1(p, 1); GSYNC();
;   phase_ple(p, 1, (const bft*)(p.ws + OFF_HB3), nullptr, 1024, (float*)(p.ws + OFF_SSQF)); GSYNC();
;   phase_final(p);
; }
	.amdhsa_kernel _Z4mega6Params
		.amdhsa_group_segment_fixed_size 16
		.amdhsa_private_segment_fixed_size 0
		.amdhsa_kernarg_size 816
		.amdhsa_user_sgpr_count 2
		.amdhsa_user_sgpr_dispatch_ptr 0
		.amdhsa_user_sgpr_queue_ptr 0
		.amdhsa_user_sgpr_kernarg_segment_ptr 1
		.amdhsa_user_sgpr_dispatch_id 0
		.amdhsa_user_sgpr_kernarg_preload_length 0
		.amdhsa_user_sgpr_kernarg_preload_offset 0
		.amdhsa_user_sgpr_private_segment_size 0
		.amdhsa_uses_dynamic_stack 0
		.amdhsa_enable_private_segment 0
		.amdhsa_system_sgpr_workgroup_id_x 1
		.amdhsa_system_sgpr_workgroup_id_y 0
		.amdhsa_system_sgpr_workgroup_id_z 0
		.amdhsa_system_sgpr_workgroup_info 0
		.amdhsa_system_vgpr_workitem_id 2
		.amdhsa_next_free_vgpr 256
		.amdhsa_next_free_sgpr 98
		.amdhsa_accum_offset 256
		.amdhsa_reserve_vcc 1
		.amdhsa_float_round_mode_32 0
		.amdhsa_float_round_mode_16_64 0
		.amdhsa_float_denorm_mode_32 3
		.amdhsa_float_denorm_mode_16_64 3
		.amdhsa_dx10_clamp 1
		.amdhsa_ieee_mode 1
		.amdhsa_fp16_overflow 0
		.amdhsa_tg_split 0
		.amdhsa_exception_fp_ieee_invalid_op 0
		.amdhsa_exception_fp_denorm_src 0
		.amdhsa_exception_fp_ieee_div_zero 0
		.amdhsa_exception_fp_ieee_overflow 0
		.amdhsa_exception_fp_ieee_underflow 0
		.amdhsa_exception_fp_ieee_inexact 0
		.amdhsa_exception_int_div_zero 0
	.end_amdhsa_kernel

; #define LAS __attribute__((address_space(3)))
; __device__ __forceinline__ unsigned xb_ld(unsigned* p)              { return __hip_atomic_load(p, __ATOMIC_RELAXED, __HIP_MEMORY_SCOPE_AGENT); }
; #define GSYNC() xcd_barrier(xb)
; __global__ void __launch_bounds__(NTHR) mega(Params p) {
;   cg::grid_group grid = cg::this_grid();
;   if (threadIdx.x == 0) xb_words = make_uint4(0u, 0u, 0u, 0u);
;   __syncthreads();
;   XcdBarrier xb = xcd_barrier_post((unsigned*)(p.ws + OFF_BAR), (volatile LAS unsigned*)&xb_words);
;     ...
;   phase_prep(p); GSYNC();
;   if (threadIdx.x == 0) { unsigned idx = 0; for (unsigned j = 0; j < xb.x; ++j) idx += xb_ld(&xb.bar[XB_XCNT(j)]) > 0u ? 1u : 0u; xb_words.w = idx; }
;   __syncthreads();
;   phase_inproj0(p); GSYNC();
;   if (p.out == nullptr) grid.sync();
;   phase_mlaprep(p); phase_s5gen(p); GSYNC();
;   phase_s5step1(p); GSYNC();
;   phase_s5scan(p); GSYNC();
;   phase_s5step3(p); GSYNC();
;   for (int sg = 0; sg < 3; ++sg) { phase_upproj(p, sg); GSYNC(); phase_attn(p, sg); GSYNC(); }
;   phase_glu(p); GSYNC();
;   phase_outproj0(p); GSYNC();
;   phase_ple(p, 0, (const bft*)(p.ws + OFF_U), (bft*)(p.ws + OFF_A), LDP, (float*)(p.ws + OFF_SSQ1)); GSYNC();
;   convert_p(p, 1);
;   for (int ch = 0; ch < 8; ++ch) {
;     if (ch == 4) phase_outproj1(p, 0);
;     phase_inproj1(p, ch); phase_filter(p, ch); GSYNC();
;     phase_vx(p, ch); GSYNC();
;     phase_conv(p, ch); GSYNC();
;     phase_gate(p, ch); GSYNC();
;   }
;   phase_outproj1(p, 1); GSYNC();
;   phase_ple(p, 1, (const bft*)(p.ws + OFF_HB3), nullptr, 1024, (float*)(p.ws + OFF_SSQF)); GSYNC();
;   phase_final(p);
; }
amdhsa.kernels:
  - .agpr_count:     0
    .args:
      - .offset:         0
        .size:           560
        .value_kind:     by_value
      - .offset:         560
        .size:           4
        .value_kind:     hidden_block_count_x
      - .offset:         564
        .size:           4
        .value_kind:     hidden_block_count_y
      - .offset:         568
        .size:           4
        .value_kind:     hidden_block_count_z
      - .offset:         572
        .size:           2
        .value_kind:     hidden_group_size_x
      - .offset:         574
        .size:           2
        .value_kind:     hidden_group_size_y
      - .offset:         576
        .size:           2
        .value_kind:     hidden_group_size_z
      - .offset:         578
        .size:           2
        .value_kind:     hidden_remainder_x
      - .offset:         580
        .size:           2
        .value_kind:     hidden_remainder_y
      - .offset:         582
        .size:           2
        .value_kind:     hidden_remainder_z
      - .offset:         600
        .size:           8
        .value_kind:     hidden_global_offset_x
      - .offset:         608
        .size:           8
        .value_kind:     hidden_global_offset_y
      - .offset:         616
        .size:           8
        .value_kind:     hidden_global_offset_z
      - .offset:         624
        .size:           2
        .value_kind:     hidden_grid_dims
      - .offset:         648
        .size:           8
        .value_kind:     hidden_multigrid_sync_arg
      - .offset:         680
        .size:           4
        .value_kind:     hidden_dynamic_lds_size
    .group_segment_fixed_size: 16
    .kernarg_segment_align: 8
    .kernarg_segment_size: 816
    .language:       OpenCL C
    .language_version:
      - 2
      - 0
    .max_flat_workgroup_size: 512
    .name:           _Z4mega6Params
    .private_segment_fixed_size: 0
    .sgpr_count:     104
    .sgpr_spill_count: 59
    .symbol:         _Z4mega6Params.kd
    .uniform_work_group_size: 1
    .uses_dynamic_stack: false
    .vgpr_count:     256
    .vgpr_spill_count: 0
    .wavefront_size: 64
